# write-through publish: all stores of the 12 GEMM phases sc1, XCD leader buffer_wbl2 dropped at those barriers
# baseline (speedup 1.0000x reference)
; __device__ __forceinline__ void finalize_cs(const Args& a, int tid, int lane, int wave) {
;     ...
;     for (int n = BID * 512 + tid; n < PSTR; n += GRD * 512) { float x = 0.f, y = 0.f;
; #pragma unroll
;         for (int kb = 0; kb < 16; ++kb) { x += pcs[(size_t)kb * PSTR + n]; y += pcb[(size_t)kb * PSTR + n]; }
;         cs[n] = x; lcb[n] = y; }
.LBB0_244:
	v_add_co_u32_e32 v6, vcc, 0x200000, v2
	global_load_dword v1, v[2:3], off
	s_nop 0
	v_addc_co_u32_e32 v7, vcc, 0, v3, vcc
	v_add_co_u32_e32 v8, vcc, 0x12000, v2
	v_add_u32_e32 v0, s12, v0
	s_nop 0
	v_addc_co_u32_e32 v9, vcc, 0, v3, vcc
	v_add_co_u32_e32 v10, vcc, 0x212000, v2
	global_load_dword v5, v[6:7], off
	global_load_dword v12, v[8:9], off
	v_addc_co_u32_e32 v11, vcc, 0, v3, vcc
	v_add_co_u32_e32 v6, vcc, 0x24000, v2
	s_waitcnt vmcnt(2)
	v_add_f32_e32 v1, 0, v1
	v_addc_co_u32_e32 v7, vcc, 0, v3, vcc
	v_add_co_u32_e32 v8, vcc, 0x224000, v2
	global_load_dword v13, v[10:11], off
	global_load_dword v14, v[6:7], off
	v_addc_co_u32_e32 v9, vcc, 0, v3, vcc
	v_add_co_u32_e32 v6, vcc, 0x36000, v2
	s_waitcnt vmcnt(3)
	v_add_f32_e32 v5, 0, v5
	v_addc_co_u32_e32 v7, vcc, 0, v3, vcc
	v_add_co_u32_e32 v10, vcc, 0x236000, v2
	global_load_dword v15, v[8:9], off
	global_load_dword v16, v[6:7], off
	v_addc_co_u32_e32 v11, vcc, 0, v3, vcc
	v_add_co_u32_e32 v6, vcc, 0x48000, v2
	s_waitcnt vmcnt(4)
	v_add_f32_e32 v1, v1, v12
	v_addc_co_u32_e32 v7, vcc, 0, v3, vcc
	v_add_co_u32_e32 v8, vcc, 0x248000, v2
	global_load_dword v17, v[10:11], off
	global_load_dword v18, v[6:7], off
	v_addc_co_u32_e32 v9, vcc, 0, v3, vcc
	v_add_co_u32_e32 v6, vcc, 0x5a000, v2
	s_waitcnt vmcnt(5)
	v_add_f32_e32 v5, v5, v13
	v_addc_co_u32_e32 v7, vcc, 0, v3, vcc
	v_add_co_u32_e32 v10, vcc, 0x25a000, v2
	global_load_dword v19, v[8:9], off
	global_load_dword v20, v[6:7], off
	v_addc_co_u32_e32 v11, vcc, 0, v3, vcc
	v_add_co_u32_e32 v6, vcc, 0x6c000, v2
	s_waitcnt vmcnt(6)
	v_add_f32_e32 v1, v1, v14
	v_addc_co_u32_e32 v7, vcc, 0, v3, vcc
	v_add_co_u32_e32 v8, vcc, 0x26c000, v2
	global_load_dword v21, v[10:11], off
	global_load_dword v22, v[6:7], off
	v_addc_co_u32_e32 v9, vcc, 0, v3, vcc
	v_add_co_u32_e32 v6, vcc, 0x7e000, v2
	s_waitcnt vmcnt(7)
	v_add_f32_e32 v5, v5, v15
	v_addc_co_u32_e32 v7, vcc, 0, v3, vcc
	v_add_co_u32_e32 v10, vcc, 0x27e000, v2
	global_load_dword v23, v[8:9], off
	global_load_dword v24, v[6:7], off
	v_addc_co_u32_e32 v11, vcc, 0, v3, vcc
	v_add_co_u32_e32 v6, vcc, 0x90000, v2
	s_waitcnt vmcnt(8)
	v_add_f32_e32 v1, v1, v16
	v_addc_co_u32_e32 v7, vcc, 0, v3, vcc
	v_add_co_u32_e32 v8, vcc, 0x290000, v2
	global_load_dword v25, v[10:11], off
	global_load_dword v26, v[6:7], off
	v_addc_co_u32_e32 v9, vcc, 0, v3, vcc
	v_add_co_u32_e32 v6, vcc, 0xa2000, v2
	s_waitcnt vmcnt(9)
	v_add_f32_e32 v5, v5, v17
	v_addc_co_u32_e32 v7, vcc, 0, v3, vcc
	v_add_co_u32_e32 v10, vcc, 0x2a2000, v2
	global_load_dword v27, v[8:9], off
	global_load_dword v28, v[6:7], off
	v_addc_co_u32_e32 v11, vcc, 0, v3, vcc
	v_add_co_u32_e32 v6, vcc, 0xb4000, v2
	s_waitcnt vmcnt(10)
	v_add_f32_e32 v1, v1, v18
	v_addc_co_u32_e32 v7, vcc, 0, v3, vcc
	v_add_co_u32_e32 v8, vcc, 0x2b4000, v2
	global_load_dword v29, v[10:11], off
	global_load_dword v30, v[6:7], off
	v_addc_co_u32_e32 v9, vcc, 0, v3, vcc
	v_add_co_u32_e32 v6, vcc, 0xc6000, v2
	s_waitcnt vmcnt(11)
	v_add_f32_e32 v5, v5, v19
	v_addc_co_u32_e32 v7, vcc, 0, v3, vcc
	v_add_co_u32_e32 v10, vcc, 0x2c6000, v2
	global_load_dword v31, v[8:9], off
	global_load_dword v32, v[6:7], off
	v_addc_co_u32_e32 v11, vcc, 0, v3, vcc
	v_add_co_u32_e32 v6, vcc, 0xd8000, v2
	s_waitcnt vmcnt(12)
	v_add_f32_e32 v1, v1, v20
	v_addc_co_u32_e32 v7, vcc, 0, v3, vcc
	v_add_co_u32_e32 v8, vcc, 0x2d8000, v2
	global_load_dword v33, v[10:11], off
	global_load_dword v34, v[6:7], off
	v_addc_co_u32_e32 v9, vcc, 0, v3, vcc
	v_add_co_u32_e32 v6, vcc, 0xea000, v2
	global_load_dword v35, v[8:9], off
	s_nop 0
	v_addc_co_u32_e32 v7, vcc, 0, v3, vcc
	v_add_co_u32_e32 v8, vcc, 0x2ea000, v2
	s_waitcnt vmcnt(14)
	v_add_f32_e32 v5, v5, v21
	v_addc_co_u32_e32 v9, vcc, 0, v3, vcc
	v_add_co_u32_e32 v10, vcc, 0xfc000, v2
	global_load_dword v36, v[6:7], off
	global_load_dword v37, v[8:9], off
	v_addc_co_u32_e32 v11, vcc, 0, v3, vcc
	v_add_co_u32_e32 v6, vcc, 0x2fc000, v2
	s_waitcnt vmcnt(15)
	v_add_f32_e32 v1, v1, v22
	v_addc_co_u32_e32 v7, vcc, 0, v3, vcc
	v_add_co_u32_e32 v8, vcc, 0x10e000, v2
	global_load_dword v38, v[10:11], off
	global_load_dword v39, v[6:7], off
	v_addc_co_u32_e32 v9, vcc, 0, v3, vcc
	v_add_co_u32_e32 v6, vcc, 0x30e000, v2
	s_waitcnt vmcnt(16)
	v_add_f32_e32 v5, v5, v23
	v_addc_co_u32_e32 v7, vcc, 0, v3, vcc
	global_load_dword v10, v[8:9], off
	global_load_dword v11, v[6:7], off
	s_waitcnt vmcnt(17)
	v_add_f32_e32 v1, v1, v24
	s_waitcnt vmcnt(16)
	v_add_f32_e32 v5, v5, v25
	s_waitcnt vmcnt(15)
	v_add_f32_e32 v1, v1, v26
	s_waitcnt vmcnt(14)
	v_add_f32_e32 v5, v5, v27
	s_waitcnt vmcnt(13)
	v_add_f32_e32 v1, v1, v28
	s_waitcnt vmcnt(12)
	v_add_f32_e32 v5, v5, v29
	s_waitcnt vmcnt(11)
	v_add_f32_e32 v1, v1, v30
	v_cmp_lt_i32_e32 vcc, s13, v0
	s_or_b64 s[16:17], vcc, s[16:17]
	v_add_co_u32_e32 v6, vcc, 0xe4410000, v2
	s_waitcnt vmcnt(10)
	v_add_f32_e32 v5, v5, v31
	s_waitcnt vmcnt(9)
	v_add_f32_e32 v1, v1, v32
	v_addc_co_u32_e32 v7, vcc, -1, v3, vcc
	v_add_co_u32_e32 v8, vcc, 0xe4430000, v2
	s_waitcnt vmcnt(8)
	v_add_f32_e32 v5, v5, v33
	s_waitcnt vmcnt(7)
	v_add_f32_e32 v1, v1, v34
	v_addc_co_u32_e32 v9, vcc, -1, v3, vcc
	v_lshl_add_u64 v[2:3], v[2:3], 0, s[14:15]
	s_waitcnt vmcnt(6)
	v_add_f32_e32 v5, v5, v35
	s_waitcnt vmcnt(5)
	v_add_f32_e32 v1, v1, v36
	s_waitcnt vmcnt(4)
	v_add_f32_e32 v5, v5, v37
	s_waitcnt vmcnt(3)
	v_add_f32_e32 v1, v1, v38
	s_waitcnt vmcnt(2)
	v_add_f32_e32 v5, v5, v39
	s_waitcnt vmcnt(1)
	v_add_f32_e32 v1, v1, v10
	s_waitcnt vmcnt(0)
	v_add_f32_e32 v5, v5, v11
	global_store_dword v[6:7], v1, off sc1
	global_store_dword v[8:9], v5, off sc1
	s_andn2_b64 exec, exec, s[16:17]
	s_cbranch_execnz .LBB0_244
; __device__ __forceinline__ void finalize_cs(const Args& a, int tid, int lane, int wave) {
;     ...
;     if (BID == GRD - 1) { float d = 0.f;
; #pragma unroll
;         for (int j = 0; j < 16; ++j) { const int k = lane + 64 * j; d += a.in[3][k] * a.in[7][(size_t)k * 3080 + 3072 + wave]; }
.LBB0_245:
	s_or_b64 exec, exec, s[10:11]
	s_add_i32 s20, s20, -1
	s_cmp_lg_u32 s19, s20
	s_cbranch_scc1 .LBB0_249
	v_and_b32_e32 v18, 63, v4
	s_ashr_i32 s12, s18, 6
	s_movk_i32 s10, 0x3020
	s_waitcnt lgkmcnt(0)
	v_mov_b64_e32 v[0:1], s[8:9]
	s_ashr_i32 s13, s12, 31
	v_mad_u64_u32 v[2:3], s[8:9], v18, s10, v[0:1]
	s_lshl_b64 s[8:9], s[12:13], 2
	s_nop 0
	v_lshl_add_u64 v[2:3], v[2:3], 0, s[8:9]
	v_or_b32_e32 v4, 64, v18
	v_add_co_u32_e32 v2, vcc, 0x3000, v2
	v_mad_u64_u32 v[4:5], s[12:13], v4, s10, v[0:1]
	s_nop 0
	v_addc_co_u32_e32 v3, vcc, 0, v3, vcc
	v_lshl_add_u64 v[4:5], v[4:5], 0, s[8:9]
	v_or_b32_e32 v6, 0x80, v18
	v_add_co_u32_e32 v4, vcc, 0x3000, v4
	v_mad_u64_u32 v[6:7], s[12:13], v6, s10, v[0:1]
	s_nop 0
	v_addc_co_u32_e32 v5, vcc, 0, v5, vcc
	v_lshl_add_u64 v[6:7], v[6:7], 0, s[8:9]
	v_or_b32_e32 v8, 0xc0, v18
	v_add_co_u32_e32 v6, vcc, 0x3000, v6
	v_mad_u64_u32 v[8:9], s[12:13], v8, s10, v[0:1]
	s_nop 0
	v_addc_co_u32_e32 v7, vcc, 0, v7, vcc
	v_lshl_add_u64 v[8:9], v[8:9], 0, s[8:9]
	v_or_b32_e32 v10, 0x100, v18
	v_add_co_u32_e32 v8, vcc, 0x3000, v8
	v_mad_u64_u32 v[10:11], s[12:13], v10, s10, v[0:1]
	s_nop 0
	v_addc_co_u32_e32 v9, vcc, 0, v9, vcc
	v_lshl_add_u64 v[10:11], v[10:11], 0, s[8:9]
	v_or_b32_e32 v12, 0x140, v18
	v_add_co_u32_e32 v10, vcc, 0x3000, v10
	v_mad_u64_u32 v[12:13], s[12:13], v12, s10, v[0:1]
	s_nop 0
	v_addc_co_u32_e32 v11, vcc, 0, v11, vcc
	v_lshl_add_u64 v[12:13], v[12:13], 0, s[8:9]
	v_or_b32_e32 v14, 0x180, v18
	v_add_co_u32_e32 v12, vcc, 0x3000, v12
	v_mad_u64_u32 v[14:15], s[12:13], v14, s10, v[0:1]
	s_nop 0
	v_addc_co_u32_e32 v13, vcc, 0, v13, vcc
	v_lshl_add_u64 v[14:15], v[14:15], 0, s[8:9]
	v_or_b32_e32 v16, 0x1c0, v18
	v_add_co_u32_e32 v14, vcc, 0x3000, v14
	v_mad_u64_u32 v[16:17], s[12:13], v16, s10, v[0:1]
	s_nop 0
	v_addc_co_u32_e32 v15, vcc, 0, v15, vcc
	v_lshl_add_u64 v[16:17], v[16:17], 0, s[8:9]
	v_lshlrev_b32_e32 v19, 2, v18
	v_add_co_u32_e32 v16, vcc, 0x3000, v16
	global_load_dword v20, v19, s[6:7]
	global_load_dword v21, v19, s[6:7] offset:256
	global_load_dword v22, v19, s[6:7] offset:512
	global_load_dword v23, v19, s[6:7] offset:768
	global_load_dword v24, v19, s[6:7] offset:1024
	global_load_dword v25, v19, s[6:7] offset:1280
	global_load_dword v26, v19, s[6:7] offset:1536
	global_load_dword v27, v19, s[6:7] offset:1792
	v_addc_co_u32_e32 v17, vcc, 0, v17, vcc
	global_load_dword v28, v[2:3], off
	global_load_dword v29, v[4:5], off
	global_load_dword v30, v[6:7], off
	global_load_dword v31, v[8:9], off
	global_load_dword v32, v[10:11], off
	global_load_dword v33, v[12:13], off
	global_load_dword v34, v[14:15], off
	global_load_dword v35, v[16:17], off
	v_or_b32_e32 v2, 0x200, v18
	v_mad_u64_u32 v[2:3], s[12:13], v2, s10, v[0:1]
	v_lshl_add_u64 v[2:3], v[2:3], 0, s[8:9]
	v_or_b32_e32 v4, 0x240, v18
	v_add_co_u32_e32 v2, vcc, 0x3000, v2
	v_mad_u64_u32 v[4:5], s[12:13], v4, s10, v[0:1]
	s_nop 0
	v_addc_co_u32_e32 v3, vcc, 0, v3, vcc
	v_lshl_add_u64 v[4:5], v[4:5], 0, s[8:9]
	v_or_b32_e32 v6, 0x280, v18
	v_add_co_u32_e32 v4, vcc, 0x3000, v4
	v_mad_u64_u32 v[6:7], s[12:13], v6, s10, v[0:1]
	s_nop 0
	v_addc_co_u32_e32 v5, vcc, 0, v5, vcc
	v_lshl_add_u64 v[6:7], v[6:7], 0, s[8:9]
	v_or_b32_e32 v8, 0x2c0, v18
	v_add_co_u32_e32 v6, vcc, 0x3000, v6
	v_mad_u64_u32 v[8:9], s[12:13], v8, s10, v[0:1]
	s_nop 0
	v_addc_co_u32_e32 v7, vcc, 0, v7, vcc
	v_lshl_add_u64 v[8:9], v[8:9], 0, s[8:9]
	v_or_b32_e32 v10, 0x300, v18
	v_add_co_u32_e32 v8, vcc, 0x3000, v8
	v_mad_u64_u32 v[10:11], s[12:13], v10, s10, v[0:1]
	s_nop 0
	v_addc_co_u32_e32 v9, vcc, 0, v9, vcc
	v_lshl_add_u64 v[10:11], v[10:11], 0, s[8:9]
	v_or_b32_e32 v12, 0x340, v18
	v_add_co_u32_e32 v10, vcc, 0x3000, v10
	v_mad_u64_u32 v[12:13], s[12:13], v12, s10, v[0:1]
	s_nop 0
	v_addc_co_u32_e32 v11, vcc, 0, v11, vcc
	v_lshl_add_u64 v[12:13], v[12:13], 0, s[8:9]
	v_or_b32_e32 v14, 0x380, v18
	v_add_co_u32_e32 v12, vcc, 0x3000, v12
	v_mad_u64_u32 v[14:15], s[12:13], v14, s10, v[0:1]
	s_nop 0
	v_addc_co_u32_e32 v13, vcc, 0, v13, vcc
	v_lshl_add_u64 v[14:15], v[14:15], 0, s[8:9]
	v_or_b32_e32 v16, 0x3c0, v18
	v_add_co_u32_e32 v14, vcc, 0x3000, v14
	global_load_dword v17, v19, s[6:7] offset:2048
	global_load_dword v36, v19, s[6:7] offset:2304
	global_load_dword v37, v19, s[6:7] offset:2560
	global_load_dword v38, v19, s[6:7] offset:2816
	global_load_dword v39, v19, s[6:7] offset:3072
	global_load_dword v40, v19, s[6:7] offset:3328
	global_load_dword v41, v19, s[6:7] offset:3584
	global_load_dword v42, v19, s[6:7] offset:3840
	v_mad_u64_u32 v[0:1], s[6:7], v16, s10, v[0:1]
	v_addc_co_u32_e32 v15, vcc, 0, v15, vcc
	v_lshl_add_u64 v[0:1], v[0:1], 0, s[8:9]
	v_add_co_u32_e32 v0, vcc, 0x3000, v0
	s_nop 1
	v_addc_co_u32_e32 v1, vcc, 0, v1, vcc
	global_load_dword v16, v[2:3], off
	global_load_dword v19, v[4:5], off
	global_load_dword v43, v[6:7], off
	global_load_dword v44, v[8:9], off
	global_load_dword v45, v[10:11], off
	global_load_dword v46, v[12:13], off
	global_load_dword v47, v[14:15], off
	global_load_dword v48, v[0:1], off
	v_mbcnt_lo_u32_b32 v1, -1, 0
	v_mbcnt_hi_u32_b32 v1, -1, v1
	v_and_b32_e32 v2, 64, v1
	v_add_u32_e32 v2, 64, v2
	v_xor_b32_e32 v3, 1, v1
	s_waitcnt vmcnt(23)
; __device__ __forceinline__ float wave_sum(float v) {
; #pragma unroll
;     for (int o = 1; o < 64; o <<= 1) v += __shfl_xor(v, o);
;     return v;
; }
; __device__ __forceinline__ void finalize_cs(const Args& a, int tid, int lane, int wave) {
;     ...
;         for (int j = 0; j < 16; ++j) { const int k = lane + 64 * j; d += a.in[3][k] * a.in[7][(size_t)k * 3080 + 3072 + wave]; }
;         d = wave_sum(d); if (lane == 0) ((float*)(ws + WS_CBF))[wave] = d; }
	v_fma_f32 v0, v20, v28, 0
	s_waitcnt vmcnt(22)
	v_fmac_f32_e32 v0, v21, v29
	s_waitcnt vmcnt(21)
	v_fmac_f32_e32 v0, v22, v30
	s_waitcnt vmcnt(20)
	v_fmac_f32_e32 v0, v23, v31
	s_waitcnt vmcnt(19)
	v_fmac_f32_e32 v0, v24, v32
	s_waitcnt vmcnt(18)
	v_fmac_f32_e32 v0, v25, v33
	s_waitcnt vmcnt(17)
	v_fmac_f32_e32 v0, v26, v34
	s_waitcnt vmcnt(16)
	v_fmac_f32_e32 v0, v27, v35
	v_cmp_lt_i32_e32 vcc, v3, v2
	s_waitcnt vmcnt(7)
	v_fmac_f32_e32 v0, v17, v16
	s_waitcnt vmcnt(6)
	v_fmac_f32_e32 v0, v36, v19
	s_waitcnt vmcnt(5)
	v_fmac_f32_e32 v0, v37, v43
	s_waitcnt vmcnt(4)
	v_fmac_f32_e32 v0, v38, v44
	s_waitcnt vmcnt(3)
	v_fmac_f32_e32 v0, v39, v45
	s_waitcnt vmcnt(2)
	v_fmac_f32_e32 v0, v40, v46
	s_waitcnt vmcnt(1)
	v_fmac_f32_e32 v0, v41, v47
	v_cndmask_b32_e32 v3, v1, v3, vcc
	s_waitcnt vmcnt(0)
	v_fmac_f32_e32 v0, v42, v48
	v_lshlrev_b32_e32 v3, 2, v3
	ds_bpermute_b32 v3, v3, v0
	s_waitcnt lgkmcnt(0)
	v_add_f32_e32 v0, v0, v3
	v_xor_b32_e32 v3, 2, v1
	v_cmp_lt_i32_e32 vcc, v3, v2
	s_nop 1
	v_cndmask_b32_e32 v3, v1, v3, vcc
	v_lshlrev_b32_e32 v3, 2, v3
	ds_bpermute_b32 v3, v3, v0
	s_waitcnt lgkmcnt(0)
	v_add_f32_e32 v0, v0, v3
	v_xor_b32_e32 v3, 4, v1
	v_cmp_lt_i32_e32 vcc, v3, v2
	s_nop 1
	v_cndmask_b32_e32 v3, v1, v3, vcc
	v_lshlrev_b32_e32 v3, 2, v3
	ds_bpermute_b32 v3, v3, v0
	s_waitcnt lgkmcnt(0)
	v_add_f32_e32 v0, v0, v3
	v_xor_b32_e32 v3, 8, v1
	v_cmp_lt_i32_e32 vcc, v3, v2
	s_nop 1
	v_cndmask_b32_e32 v3, v1, v3, vcc
	v_lshlrev_b32_e32 v3, 2, v3
	ds_bpermute_b32 v3, v3, v0
	s_waitcnt lgkmcnt(0)
	v_add_f32_e32 v0, v0, v3
	v_xor_b32_e32 v3, 16, v1
	v_cmp_lt_i32_e32 vcc, v3, v2
	s_nop 1
	v_cndmask_b32_e32 v3, v1, v3, vcc
	v_lshlrev_b32_e32 v3, 2, v3
	ds_bpermute_b32 v3, v3, v0
	s_waitcnt lgkmcnt(0)
	v_add_f32_e32 v0, v0, v3
	v_xor_b32_e32 v3, 32, v1
	v_cmp_lt_i32_e32 vcc, v3, v2
	s_nop 1
	v_cndmask_b32_e32 v1, v1, v3, vcc
	v_lshlrev_b32_e32 v1, 2, v1
	ds_bpermute_b32 v1, v1, v0
	v_cmp_eq_u32_e32 vcc, 0, v18
	s_and_saveexec_b64 s[6:7], vcc
	s_cbranch_execz .LBB0_248
	s_add_u32 s8, s4, s8
	s_waitcnt lgkmcnt(0)
	v_add_f32_e32 v0, v0, v1
	s_addc_u32 s9, s5, s9
	v_mov_b32_e32 v1, 0x50000
	global_store_dword v1, v0, s[8:9] sc1

; __device__ __forceinline__ unsigned cvt_pk_bf16(float lo, float hi) { unsigned r; asm("v_cvt_pk_bf16_f32 %0, %1, %2" : "=v"(r) : "v"(lo), "v"(hi)); return r; }
; __device__ __forceinline__ f32x4 ln_fix(const f32x4& a, float mu, float rs, const f32x4& cs, const f32x4& cb) { return (a - cs * mu) * rs + cb; }
; __device__ __forceinline__ float fast_sigmoid(float v) { return __builtin_amdgcn_rcpf(1.0f + __builtin_amdgcn_exp2f(-1.4426950408889634f * v)); }
;     __device__ __forceinline__ void operator()(const f32x4 (&acc)[2][2][4][2], const Unit& u, int wr, int wc, int fr_in, int fq_in) const {
;     ...
;             for (int m = 0; m < 4; ++m) { bf16_t* rowp = H + ((size_t)kt * mrows + (row0 + ai * HALF + m * 16)) * 64 + cin;
;                 float h[8];
; #pragma unroll
;                 for (int n = 0; n < 2; ++n) { f32x4 g = acc[ai][0][m][n], uu = acc[ai][1][m][n];
;                     if constexpr (LN) { g = ln_fix(g, rst.mu[ai][m], rst.rs[ai][m], csv[0][n], cbv[0][n]); uu = ln_fix(uu, rst.mu[ai][m], rst.rs[ai][m], csv[1][n], cbv[1][n]); }
; #pragma unroll
;                     for (int j = 0; j < 4; ++j) h[4 * n + j] = g[j] * fast_sigmoid(g[j]) * uu[j]; }
;                 u32x4 w; w.x = cvt_pk_bf16(h[0], h[1]); w.y = cvt_pk_bf16(h[2], h[3]); w.z = cvt_pk_bf16(h[4], h[5]); w.w = cvt_pk_bf16(h[6], h[7]);
;                 *(u32x4*)rowp = w; }
.LBB0_262:
	v_mov_b32_e32 v144, v146
	v_mov_b32_e32 v145, v147
	s_lshl_b32 s17, s24, 8
	s_lshl_b32 s19, s25, 1
	s_or_b32 s24, s19, s53
	s_add_i32 s17, s17, s49
	s_ashr_i32 s25, s24, 31
	v_add_u32_e32 v144, s17, v144
	v_lshl_add_u32 v152, v145, 3, s54
	s_lshl_b64 s[24:25], s[24:25], 15
	v_ashrrev_i32_e32 v145, 31, v144
	v_lshl_add_u64 v[154:155], s[24:25], 0, v[144:145]
	v_mul_f32_e32 v145, 0xbfb8aa3b, v124
	v_exp_f32_e32 v145, v145
	v_mul_f32_e32 v156, 0xbfb8aa3b, v125
	v_exp_f32_e32 v156, v156
	v_ashrrev_i32_e32 v153, 31, v152
	v_add_f32_e32 v145, 1.0, v145
	v_rcp_f32_e32 v145, v145
	v_add_f32_e32 v156, 1.0, v156
	v_rcp_f32_e32 v156, v156
	v_lshlrev_b64 v[154:155], 7, v[154:155]
	v_mul_f32_e32 v124, v124, v145
	v_mul_f32_e32 v120, v120, v124
	v_mul_f32_e32 v124, v125, v156
	v_mul_f32_e32 v125, 0xbfb8aa3b, v126
	v_exp_f32_e32 v125, v125
	v_mul_f32_e32 v145, 0xbfb8aa3b, v127
	v_exp_f32_e32 v145, v145
	v_mul_f32_e32 v121, v121, v124
	v_add_f32_e32 v124, 1.0, v125
	v_rcp_f32_e32 v124, v124
	v_add_f32_e32 v125, 1.0, v145
	v_mul_f32_e32 v145, 0xbfb8aa3b, v116
	v_rcp_f32_e32 v125, v125
	v_exp_f32_e32 v145, v145
	v_mul_f32_e32 v124, v126, v124
	v_mul_f32_e32 v122, v122, v124
	v_mul_f32_e32 v124, v127, v125
	v_add_f32_e32 v125, 1.0, v145
	v_rcp_f32_e32 v125, v125
	v_mul_f32_e32 v126, 0xbfb8aa3b, v117
	v_exp_f32_e32 v126, v126
	v_mul_f32_e32 v123, v123, v124
	v_mul_f32_e32 v116, v116, v125
	v_mul_f32_e32 v116, v112, v116
	v_add_f32_e32 v112, 1.0, v126
	v_mul_f32_e32 v124, 0xbfb8aa3b, v118
	v_rcp_f32_e32 v112, v112
	v_exp_f32_e32 v124, v124
	v_mul_f32_e32 v125, 0xbfb8aa3b, v119
	v_exp_f32_e32 v125, v125
	v_mul_f32_e32 v112, v117, v112
	v_add_f32_e32 v117, 1.0, v124
	v_rcp_f32_e32 v117, v117
	v_add_f32_e32 v124, 1.0, v125
	v_rcp_f32_e32 v124, v124
	v_mul_f32_e32 v125, v113, v112
	v_mul_f32_e32 v112, v118, v117
	v_mul_f32_e32 v117, v114, v112
	v_mul_f32_e32 v112, v119, v124
	v_lshl_add_u64 v[154:155], s[10:11], 0, v[154:155]
	v_mul_f32_e32 v124, v115, v112
	v_lshlrev_b64 v[112:113], 1, v[152:153]
	v_lshl_add_u64 v[118:119], v[154:155], 0, v[112:113]
	v_cvt_pk_bf16_f32 v116, v116, v125
	v_cvt_pk_bf16_f32 v114, v120, v121
	v_cvt_pk_bf16_f32 v115, v122, v123
	v_cvt_pk_bf16_f32 v117, v117, v124
	global_store_dwordx4 v[118:119], v[114:117], off sc1
	s_andn2_b64 vcc, exec, s[4:5]
	s_mov_b64 s[4:5], -1
	v_mul_f32_e32 v116, 0xbfb8aa3b, v108
	v_exp_f32_e32 v116, v116
	v_mul_f32_e32 v117, 0xbfb8aa3b, v109
	v_exp_f32_e32 v117, v117
	v_add_u32_e32 v114, 16, v144
	v_add_f32_e32 v116, 1.0, v116
	v_rcp_f32_e32 v116, v116
	v_add_f32_e32 v117, 1.0, v117
	v_rcp_f32_e32 v117, v117
	v_ashrrev_i32_e32 v115, 31, v114
	v_mul_f32_e32 v108, v108, v116
	v_mul_f32_e32 v104, v104, v108
	v_mul_f32_e32 v108, v109, v117
	v_mul_f32_e32 v109, 0xbfb8aa3b, v110
	v_exp_f32_e32 v109, v109
	v_mul_f32_e32 v116, 0xbfb8aa3b, v111
	v_exp_f32_e32 v116, v116
	v_mul_f32_e32 v105, v105, v108
	v_add_f32_e32 v108, 1.0, v109
	v_rcp_f32_e32 v108, v108
	v_add_f32_e32 v109, 1.0, v116
	v_mul_f32_e32 v116, 0xbfb8aa3b, v100
	v_rcp_f32_e32 v109, v109
	v_exp_f32_e32 v116, v116
	v_mul_f32_e32 v108, v110, v108
	v_mul_f32_e32 v106, v106, v108
	v_mul_f32_e32 v108, v111, v109
	v_add_f32_e32 v109, 1.0, v116
	v_rcp_f32_e32 v109, v109
	v_mul_f32_e32 v110, 0xbfb8aa3b, v101
	v_exp_f32_e32 v110, v110
	v_mul_f32_e32 v107, v107, v108
	v_mul_f32_e32 v100, v100, v109
	v_mul_f32_e32 v108, v96, v100
	v_mul_f32_e32 v100, 0xbfb8aa3b, v102
	v_add_f32_e32 v96, 1.0, v110
	v_exp_f32_e32 v100, v100
	v_mul_f32_e32 v109, 0xbfb8aa3b, v103
	v_rcp_f32_e32 v96, v96
	v_exp_f32_e32 v109, v109
	v_add_f32_e32 v100, 1.0, v100
	v_rcp_f32_e32 v100, v100
	v_mul_f32_e32 v96, v101, v96
	v_add_f32_e32 v101, 1.0, v109
	v_rcp_f32_e32 v101, v101
	v_lshl_add_u64 v[114:115], s[24:25], 0, v[114:115]
	v_lshlrev_b64 v[114:115], 7, v[114:115]
	v_mul_f32_e32 v109, v97, v96
	v_mul_f32_e32 v96, v102, v100
	v_lshl_add_u64 v[114:115], s[10:11], 0, v[114:115]
	v_mul_f32_e32 v102, v98, v96
	v_mul_f32_e32 v96, v103, v101
	v_mul_f32_e32 v99, v99, v96
	v_lshl_add_u64 v[100:101], v[114:115], 0, v[112:113]
	v_cvt_pk_bf16_f32 v98, v108, v109
	v_cvt_pk_bf16_f32 v96, v104, v105
	v_cvt_pk_bf16_f32 v97, v106, v107
	v_cvt_pk_bf16_f32 v99, v102, v99
	global_store_dwordx4 v[100:101], v[96:99], off sc1
	s_nop 1
	v_mul_f32_e32 v98, 0xbfb8aa3b, v92
	v_exp_f32_e32 v98, v98
	v_mul_f32_e32 v99, 0xbfb8aa3b, v93
	v_exp_f32_e32 v99, v99
	v_add_u32_e32 v96, 32, v144
	v_add_f32_e32 v98, 1.0, v98
	v_rcp_f32_e32 v98, v98
	v_add_f32_e32 v99, 1.0, v99
	v_rcp_f32_e32 v99, v99
	v_ashrrev_i32_e32 v97, 31, v96
	v_mul_f32_e32 v92, v92, v98
	v_mul_f32_e32 v88, v88, v92
	v_mul_f32_e32 v92, v93, v99
	v_mul_f32_e32 v93, 0xbfb8aa3b, v94
	v_exp_f32_e32 v93, v93
	v_mul_f32_e32 v98, 0xbfb8aa3b, v95
	v_exp_f32_e32 v98, v98
	v_mul_f32_e32 v89, v89, v92
	v_add_f32_e32 v92, 1.0, v93
	v_rcp_f32_e32 v92, v92
	v_add_f32_e32 v93, 1.0, v98
	v_mul_f32_e32 v98, 0xbfb8aa3b, v84
	v_rcp_f32_e32 v93, v93
	v_exp_f32_e32 v98, v98
	v_mul_f32_e32 v92, v94, v92
	v_mul_f32_e32 v90, v90, v92
	v_mul_f32_e32 v92, v95, v93
	v_add_f32_e32 v93, 1.0, v98
	v_rcp_f32_e32 v93, v93
	v_mul_f32_e32 v94, 0xbfb8aa3b, v85
	v_exp_f32_e32 v94, v94
	v_mul_f32_e32 v91, v91, v92
	v_mul_f32_e32 v84, v84, v93
	v_mul_f32_e32 v92, v80, v84
	v_mul_f32_e32 v84, 0xbfb8aa3b, v86
	v_add_f32_e32 v80, 1.0, v94
	v_exp_f32_e32 v84, v84
	v_mul_f32_e32 v93, 0xbfb8aa3b, v87
	v_rcp_f32_e32 v80, v80
	v_exp_f32_e32 v93, v93
	v_add_f32_e32 v84, 1.0, v84
	v_rcp_f32_e32 v84, v84
	v_mul_f32_e32 v80, v85, v80
	v_add_f32_e32 v85, 1.0, v93
	v_rcp_f32_e32 v85, v85
	v_lshl_add_u64 v[96:97], s[24:25], 0, v[96:97]
	v_lshlrev_b64 v[96:97], 7, v[96:97]
	v_mul_f32_e32 v93, v81, v80
; __device__ __forceinline__ unsigned cvt_pk_bf16(float lo, float hi) { unsigned r; asm("v_cvt_pk_bf16_f32 %0, %1, %2" : "=v"(r) : "v"(lo), "v"(hi)); return r; }
; __device__ __forceinline__ f32x4 ln_fix(const f32x4& a, float mu, float rs, const f32x4& cs, const f32x4& cb) { return (a - cs * mu) * rs + cb; }
; __device__ __forceinline__ float fast_sigmoid(float v) { return __builtin_amdgcn_rcpf(1.0f + __builtin_amdgcn_exp2f(-1.4426950408889634f * v)); }
;     __device__ __forceinline__ void operator()(const f32x4 (&acc)[2][2][4][2], const Unit& u, int wr, int wc, int fr_in, int fq_in) const {
;     ...
;             for (int m = 0; m < 4; ++m) { bf16_t* rowp = H + ((size_t)kt * mrows + (row0 + ai * HALF + m * 16)) * 64 + cin;
;                 float h[8];
; #pragma unroll
;                 for (int n = 0; n < 2; ++n) { f32x4 g = acc[ai][0][m][n], uu = acc[ai][1][m][n];
;                     if constexpr (LN) { g = ln_fix(g, rst.mu[ai][m], rst.rs[ai][m], csv[0][n], cbv[0][n]); uu = ln_fix(uu, rst.mu[ai][m], rst.rs[ai][m], csv[1][n], cbv[1][n]); }
; #pragma unroll
;                     for (int j = 0; j < 4; ++j) h[4 * n + j] = g[j] * fast_sigmoid(g[j]) * uu[j]; }
;                 u32x4 w; w.x = cvt_pk_bf16(h[0], h[1]); w.y = cvt_pk_bf16(h[2], h[3]); w.z = cvt_pk_bf16(h[4], h[5]); w.w = cvt_pk_bf16(h[6], h[7]);
;                 *(u32x4*)rowp = w; }
	v_mul_f32_e32 v80, v86, v84
	v_lshl_add_u64 v[96:97], s[10:11], 0, v[96:97]
	v_mul_f32_e32 v86, v82, v80
	v_mul_f32_e32 v80, v87, v85
	v_mul_f32_e32 v83, v83, v80
	v_lshl_add_u64 v[84:85], v[96:97], 0, v[112:113]
	v_cvt_pk_bf16_f32 v82, v92, v93
	v_cvt_pk_bf16_f32 v80, v88, v89
	v_cvt_pk_bf16_f32 v81, v90, v91
	v_cvt_pk_bf16_f32 v83, v86, v83
	global_store_dwordx4 v[84:85], v[80:83], off sc1
	s_nop 1
	v_mul_f32_e32 v82, 0xbfb8aa3b, v76
	v_exp_f32_e32 v82, v82
	v_mul_f32_e32 v83, 0xbfb8aa3b, v77
	v_exp_f32_e32 v83, v83
	v_add_u32_e32 v80, 48, v144
	v_add_f32_e32 v82, 1.0, v82
	v_rcp_f32_e32 v82, v82
	v_add_f32_e32 v83, 1.0, v83
	v_rcp_f32_e32 v83, v83
	v_ashrrev_i32_e32 v81, 31, v80
	v_mul_f32_e32 v76, v76, v82
	v_mul_f32_e32 v72, v72, v76
	v_mul_f32_e32 v76, v77, v83
	v_mul_f32_e32 v77, 0xbfb8aa3b, v78
	v_exp_f32_e32 v77, v77
	v_mul_f32_e32 v82, 0xbfb8aa3b, v79
	v_exp_f32_e32 v82, v82
	v_mul_f32_e32 v73, v73, v76
	v_add_f32_e32 v76, 1.0, v77
	v_rcp_f32_e32 v76, v76
	v_add_f32_e32 v77, 1.0, v82
	v_mul_f32_e32 v82, 0xbfb8aa3b, v68
	v_rcp_f32_e32 v77, v77
	v_exp_f32_e32 v82, v82
	v_mul_f32_e32 v76, v78, v76
	v_mul_f32_e32 v74, v74, v76
	v_mul_f32_e32 v76, v79, v77
	v_add_f32_e32 v77, 1.0, v82
	v_rcp_f32_e32 v77, v77
	v_mul_f32_e32 v78, 0xbfb8aa3b, v69
	v_exp_f32_e32 v78, v78
	v_mul_f32_e32 v75, v75, v76
	v_mul_f32_e32 v68, v68, v77
	v_mul_f32_e32 v76, v64, v68
	v_mul_f32_e32 v68, 0xbfb8aa3b, v70
	v_add_f32_e32 v64, 1.0, v78
	v_exp_f32_e32 v68, v68
	v_mul_f32_e32 v77, 0xbfb8aa3b, v71
	v_rcp_f32_e32 v64, v64
	v_exp_f32_e32 v77, v77
	v_add_f32_e32 v68, 1.0, v68
	v_rcp_f32_e32 v68, v68
	v_mul_f32_e32 v64, v69, v64
	v_add_f32_e32 v69, 1.0, v77
	v_rcp_f32_e32 v69, v69
	v_lshl_add_u64 v[80:81], s[24:25], 0, v[80:81]
	v_lshlrev_b64 v[80:81], 7, v[80:81]
	v_mul_f32_e32 v77, v65, v64
	v_mul_f32_e32 v64, v70, v68
	v_lshl_add_u64 v[80:81], s[10:11], 0, v[80:81]
	v_mul_f32_e32 v70, v66, v64
	v_mul_f32_e32 v64, v71, v69
	v_mul_f32_e32 v67, v67, v64
	v_lshl_add_u64 v[68:69], v[80:81], 0, v[112:113]
	v_cvt_pk_bf16_f32 v66, v76, v77
	v_cvt_pk_bf16_f32 v64, v72, v73
	v_cvt_pk_bf16_f32 v65, v74, v75
	v_cvt_pk_bf16_f32 v67, v70, v67
	global_store_dwordx4 v[68:69], v[64:67], off sc1
	s_nop 1
	v_mul_f32_e32 v66, 0xbfb8aa3b, v60
	v_exp_f32_e32 v66, v66
	v_mul_f32_e32 v67, 0xbfb8aa3b, v61
	v_exp_f32_e32 v67, v67
	v_add_u32_e32 v64, 0x80, v144
	v_add_f32_e32 v66, 1.0, v66
	v_rcp_f32_e32 v66, v66
	v_add_f32_e32 v67, 1.0, v67
	v_rcp_f32_e32 v67, v67
	v_ashrrev_i32_e32 v65, 31, v64
	v_mul_f32_e32 v60, v60, v66
	v_mul_f32_e32 v56, v56, v60
	v_mul_f32_e32 v60, v61, v67
	v_mul_f32_e32 v61, 0xbfb8aa3b, v62
	v_exp_f32_e32 v61, v61
	v_mul_f32_e32 v66, 0xbfb8aa3b, v63
	v_exp_f32_e32 v66, v66
	v_mul_f32_e32 v57, v57, v60
	v_add_f32_e32 v60, 1.0, v61
	v_rcp_f32_e32 v60, v60
	v_add_f32_e32 v61, 1.0, v66
	v_mul_f32_e32 v66, 0xbfb8aa3b, v52
	v_rcp_f32_e32 v61, v61
	v_exp_f32_e32 v66, v66
	v_mul_f32_e32 v60, v62, v60
	v_mul_f32_e32 v58, v58, v60
	v_mul_f32_e32 v60, v63, v61
	v_add_f32_e32 v61, 1.0, v66
	v_rcp_f32_e32 v61, v61
	v_mul_f32_e32 v62, 0xbfb8aa3b, v53
	v_exp_f32_e32 v62, v62
	v_mul_f32_e32 v59, v59, v60
	v_mul_f32_e32 v52, v52, v61
	v_mul_f32_e32 v60, v48, v52
	v_mul_f32_e32 v52, 0xbfb8aa3b, v54
	v_add_f32_e32 v48, 1.0, v62
	v_exp_f32_e32 v52, v52
	v_mul_f32_e32 v61, 0xbfb8aa3b, v55
	v_rcp_f32_e32 v48, v48
	v_exp_f32_e32 v61, v61
	v_add_f32_e32 v52, 1.0, v52
	v_rcp_f32_e32 v52, v52
	v_mul_f32_e32 v48, v53, v48
	v_add_f32_e32 v53, 1.0, v61
	v_rcp_f32_e32 v53, v53
	v_lshl_add_u64 v[64:65], s[24:25], 0, v[64:65]
	v_lshlrev_b64 v[64:65], 7, v[64:65]
	v_mul_f32_e32 v61, v49, v48
	v_mul_f32_e32 v48, v54, v52
	v_lshl_add_u64 v[64:65], s[10:11], 0, v[64:65]
	v_mul_f32_e32 v54, v50, v48
	v_mul_f32_e32 v48, v55, v53
	v_mul_f32_e32 v51, v51, v48
	v_lshl_add_u64 v[52:53], v[64:65], 0, v[112:113]
	v_cvt_pk_bf16_f32 v50, v60, v61
	v_cvt_pk_bf16_f32 v48, v56, v57
	v_cvt_pk_bf16_f32 v49, v58, v59
	v_cvt_pk_bf16_f32 v51, v54, v51
	global_store_dwordx4 v[52:53], v[48:51], off sc1
	s_nop 1
	v_mul_f32_e32 v50, 0xbfb8aa3b, v44
	v_exp_f32_e32 v50, v50
	v_mul_f32_e32 v51, 0xbfb8aa3b, v45
	v_exp_f32_e32 v51, v51
	v_add_u32_e32 v48, 0x90, v144
	v_add_f32_e32 v50, 1.0, v50
	v_rcp_f32_e32 v50, v50
	v_add_f32_e32 v51, 1.0, v51
	v_rcp_f32_e32 v51, v51
	v_ashrrev_i32_e32 v49, 31, v48
	v_mul_f32_e32 v44, v44, v50
	v_mul_f32_e32 v40, v40, v44
	v_mul_f32_e32 v44, v45, v51
	v_mul_f32_e32 v45, 0xbfb8aa3b, v46
	v_exp_f32_e32 v45, v45
	v_mul_f32_e32 v50, 0xbfb8aa3b, v47
	v_exp_f32_e32 v50, v50
	v_mul_f32_e32 v41, v41, v44
	v_add_f32_e32 v44, 1.0, v45
	v_rcp_f32_e32 v44, v44
	v_add_f32_e32 v45, 1.0, v50
	v_mul_f32_e32 v50, 0xbfb8aa3b, v36
	v_rcp_f32_e32 v45, v45
	v_exp_f32_e32 v50, v50
	v_mul_f32_e32 v44, v46, v44
; __device__ __forceinline__ unsigned cvt_pk_bf16(float lo, float hi) { unsigned r; asm("v_cvt_pk_bf16_f32 %0, %1, %2" : "=v"(r) : "v"(lo), "v"(hi)); return r; }
; __device__ __forceinline__ f32x4 ln_fix(const f32x4& a, float mu, float rs, const f32x4& cs, const f32x4& cb) { return (a - cs * mu) * rs + cb; }
; __device__ __forceinline__ float fast_sigmoid(float v) { return __builtin_amdgcn_rcpf(1.0f + __builtin_amdgcn_exp2f(-1.4426950408889634f * v)); }
;     __device__ __forceinline__ void operator()(const f32x4 (&acc)[2][2][4][2], const Unit& u, int wr, int wc, int fr_in, int fq_in) const {
;     ...
;             for (int m = 0; m < 4; ++m) { bf16_t* rowp = H + ((size_t)kt * mrows + (row0 + ai * HALF + m * 16)) * 64 + cin;
;                 float h[8];
; #pragma unroll
;                 for (int n = 0; n < 2; ++n) { f32x4 g = acc[ai][0][m][n], uu = acc[ai][1][m][n];
;                     if constexpr (LN) { g = ln_fix(g, rst.mu[ai][m], rst.rs[ai][m], csv[0][n], cbv[0][n]); uu = ln_fix(uu, rst.mu[ai][m], rst.rs[ai][m], csv[1][n], cbv[1][n]); }
; #pragma unroll
;                     for (int j = 0; j < 4; ++j) h[4 * n + j] = g[j] * fast_sigmoid(g[j]) * uu[j]; }
;                 u32x4 w; w.x = cvt_pk_bf16(h[0], h[1]); w.y = cvt_pk_bf16(h[2], h[3]); w.z = cvt_pk_bf16(h[4], h[5]); w.w = cvt_pk_bf16(h[6], h[7]);
;                 *(u32x4*)rowp = w; }
	v_mul_f32_e32 v42, v42, v44
	v_mul_f32_e32 v44, v47, v45
	v_add_f32_e32 v45, 1.0, v50
	v_rcp_f32_e32 v45, v45
	v_mul_f32_e32 v46, 0xbfb8aa3b, v37
	v_exp_f32_e32 v46, v46
	v_mul_f32_e32 v43, v43, v44
	v_mul_f32_e32 v36, v36, v45
	v_mul_f32_e32 v44, v32, v36
	v_mul_f32_e32 v36, 0xbfb8aa3b, v38
	v_add_f32_e32 v32, 1.0, v46
	v_exp_f32_e32 v36, v36
	v_mul_f32_e32 v45, 0xbfb8aa3b, v39
	v_rcp_f32_e32 v32, v32
	v_exp_f32_e32 v45, v45
	v_add_f32_e32 v36, 1.0, v36
	v_rcp_f32_e32 v36, v36
	v_mul_f32_e32 v32, v37, v32
	v_add_f32_e32 v37, 1.0, v45
	v_rcp_f32_e32 v37, v37
	v_lshl_add_u64 v[48:49], s[24:25], 0, v[48:49]
	v_lshlrev_b64 v[48:49], 7, v[48:49]
	v_mul_f32_e32 v45, v33, v32
	v_mul_f32_e32 v32, v38, v36
	v_lshl_add_u64 v[48:49], s[10:11], 0, v[48:49]
	v_mul_f32_e32 v38, v34, v32
	v_mul_f32_e32 v32, v39, v37
	v_mul_f32_e32 v35, v35, v32
	v_lshl_add_u64 v[36:37], v[48:49], 0, v[112:113]
	v_cvt_pk_bf16_f32 v34, v44, v45
	v_cvt_pk_bf16_f32 v32, v40, v41
	v_cvt_pk_bf16_f32 v33, v42, v43
	v_cvt_pk_bf16_f32 v35, v38, v35
	global_store_dwordx4 v[36:37], v[32:35], off sc1
	s_nop 1
	v_mul_f32_e32 v34, 0xbfb8aa3b, v28
	v_exp_f32_e32 v34, v34
	v_mul_f32_e32 v35, 0xbfb8aa3b, v29
	v_exp_f32_e32 v35, v35
	v_add_u32_e32 v32, 0xa0, v144
	v_add_f32_e32 v34, 1.0, v34
	v_rcp_f32_e32 v34, v34
	v_add_f32_e32 v35, 1.0, v35
	v_rcp_f32_e32 v35, v35
	v_ashrrev_i32_e32 v33, 31, v32
	v_mul_f32_e32 v28, v28, v34
	v_mul_f32_e32 v24, v24, v28
	v_mul_f32_e32 v28, v29, v35
	v_mul_f32_e32 v29, 0xbfb8aa3b, v30
	v_exp_f32_e32 v29, v29
	v_mul_f32_e32 v34, 0xbfb8aa3b, v31
	v_exp_f32_e32 v34, v34
	v_mul_f32_e32 v25, v25, v28
	v_add_f32_e32 v28, 1.0, v29
	v_rcp_f32_e32 v28, v28
	v_add_f32_e32 v29, 1.0, v34
	v_mul_f32_e32 v34, 0xbfb8aa3b, v20
	v_rcp_f32_e32 v29, v29
	v_exp_f32_e32 v34, v34
	v_mul_f32_e32 v28, v30, v28
	v_mul_f32_e32 v26, v26, v28
	v_mul_f32_e32 v28, v31, v29
	v_add_f32_e32 v29, 1.0, v34
	v_rcp_f32_e32 v29, v29
	v_mul_f32_e32 v30, 0xbfb8aa3b, v21
	v_exp_f32_e32 v30, v30
	v_mul_f32_e32 v27, v27, v28
	v_mul_f32_e32 v20, v20, v29
	v_mul_f32_e32 v28, v16, v20
	v_mul_f32_e32 v20, 0xbfb8aa3b, v22
	v_add_f32_e32 v16, 1.0, v30
	v_exp_f32_e32 v20, v20
	v_mul_f32_e32 v29, 0xbfb8aa3b, v23
	v_rcp_f32_e32 v16, v16
	v_exp_f32_e32 v29, v29
	v_add_f32_e32 v20, 1.0, v20
	v_rcp_f32_e32 v20, v20
	v_mul_f32_e32 v16, v21, v16
	v_add_f32_e32 v21, 1.0, v29
	v_rcp_f32_e32 v21, v21
	v_lshl_add_u64 v[32:33], s[24:25], 0, v[32:33]
	v_lshlrev_b64 v[32:33], 7, v[32:33]
	v_mul_f32_e32 v29, v17, v16
	v_mul_f32_e32 v16, v22, v20
	v_lshl_add_u64 v[32:33], s[10:11], 0, v[32:33]
	v_mul_f32_e32 v22, v18, v16
	v_mul_f32_e32 v16, v23, v21
	v_mul_f32_e32 v19, v19, v16
	v_lshl_add_u64 v[20:21], v[32:33], 0, v[112:113]
	v_cvt_pk_bf16_f32 v18, v28, v29
	v_cvt_pk_bf16_f32 v16, v24, v25
	v_cvt_pk_bf16_f32 v17, v26, v27
	v_cvt_pk_bf16_f32 v19, v22, v19
	global_store_dwordx4 v[20:21], v[16:19], off sc1
	s_nop 1
	v_mul_f32_e32 v18, 0xbfb8aa3b, v12
	v_exp_f32_e32 v18, v18
	v_mul_f32_e32 v19, 0xbfb8aa3b, v13
	v_exp_f32_e32 v19, v19
	v_add_u32_e32 v16, 0xb0, v144
	v_add_f32_e32 v18, 1.0, v18
	v_rcp_f32_e32 v18, v18
	v_add_f32_e32 v19, 1.0, v19
	v_rcp_f32_e32 v19, v19
	v_ashrrev_i32_e32 v17, 31, v16
	v_mul_f32_e32 v12, v12, v18
	v_mul_f32_e32 v8, v8, v12
	v_mul_f32_e32 v12, v13, v19
	v_mul_f32_e32 v13, 0xbfb8aa3b, v14
	v_exp_f32_e32 v13, v13
	v_mul_f32_e32 v18, 0xbfb8aa3b, v15
	v_exp_f32_e32 v18, v18
	v_mul_f32_e32 v9, v9, v12
	v_add_f32_e32 v12, 1.0, v13
	v_rcp_f32_e32 v12, v12
	v_add_f32_e32 v13, 1.0, v18
	v_mul_f32_e32 v18, 0xbfb8aa3b, v4
	v_rcp_f32_e32 v13, v13
	v_exp_f32_e32 v18, v18
	v_mul_f32_e32 v12, v14, v12
	v_mul_f32_e32 v10, v10, v12
	v_mul_f32_e32 v12, v15, v13
	v_add_f32_e32 v13, 1.0, v18
	v_rcp_f32_e32 v13, v13
	v_mul_f32_e32 v14, 0xbfb8aa3b, v5
	v_exp_f32_e32 v14, v14
	v_mul_f32_e32 v11, v11, v12
	v_mul_f32_e32 v4, v4, v13
	v_mul_f32_e32 v12, v0, v4
	v_mul_f32_e32 v4, 0xbfb8aa3b, v6
	v_add_f32_e32 v0, 1.0, v14
	v_exp_f32_e32 v4, v4
	v_mul_f32_e32 v13, 0xbfb8aa3b, v7
	v_rcp_f32_e32 v0, v0
	v_exp_f32_e32 v13, v13
	v_add_f32_e32 v4, 1.0, v4
	v_rcp_f32_e32 v4, v4
	v_mul_f32_e32 v0, v5, v0
	v_add_f32_e32 v5, 1.0, v13
	v_rcp_f32_e32 v5, v5
	v_lshl_add_u64 v[16:17], s[24:25], 0, v[16:17]
	v_lshlrev_b64 v[16:17], 7, v[16:17]
	v_mul_f32_e32 v13, v1, v0
	v_mul_f32_e32 v0, v6, v4
	v_lshl_add_u64 v[16:17], s[10:11], 0, v[16:17]
	v_mul_f32_e32 v6, v2, v0
	v_mul_f32_e32 v0, v7, v5
	v_mul_f32_e32 v3, v3, v0
	v_lshl_add_u64 v[4:5], v[16:17], 0, v[112:113]
	v_cvt_pk_bf16_f32 v0, v8, v9
	v_cvt_pk_bf16_f32 v1, v10, v11
	v_cvt_pk_bf16_f32 v2, v12, v13
	v_cvt_pk_bf16_f32 v3, v6, v3
	global_store_dwordx4 v[4:5], v[0:3], off sc1
	s_cbranch_vccnz .LBB0_254
	s_andn2_b64 vcc, exec, s[8:9]
	s_cbranch_vccnz .LBB0_253
	s_barrier
	s_branch .LBB0_253

; __device__ __forceinline__ unsigned xb_add(unsigned* p, unsigned v) { return __hip_atomic_fetch_add(p, v, __ATOMIC_RELAXED, __HIP_MEMORY_SCOPE_AGENT); }
; __device__ __forceinline__ void xcd_barrier(const XcdBarrier& b) {
;     ...
;         const unsigned old = xb_add(&bar[XB_XSUB(b.x)], 1u);
;         const unsigned gen = old / nloc;
;         if (old + 1u == (gen + 1u) * nloc) {
;             __builtin_amdgcn_fence(__ATOMIC_RELEASE, "agent");
;             asm volatile("s_waitcnt vmcnt(0)" ::: "memory");
;             const unsigned og = xb_add(&bar[XB_TOP], 1u);
.LBB0_297:
	s_andn2_saveexec_b64 s[8:9], s[8:9]
	s_cbranch_execz .LBB0_315
	s_mov_b64 s[8:9], exec
	s_waitcnt lgkmcnt(0)
	s_waitcnt vmcnt(0)
	v_mbcnt_lo_u32_b32 v1, s8, 0
	v_mbcnt_hi_u32_b32 v1, s9, v1
	v_cmp_eq_u32_e32 vcc, 0, v1
	s_and_saveexec_b64 s[10:11], vcc
	s_cbranch_execz .LBB0_300
	s_bcnt1_i32_b64 s8, s[8:9]
	v_mov_b32_e32 v2, 0x3000
	v_mov_b32_e32 v3, s8
	global_atomic_add v2, v2, v3, s[92:93] offset:1024 sc0

; __device__ __forceinline__ unsigned cvt_pk_bf16(float lo, float hi) { unsigned r; asm("v_cvt_pk_bf16_f32 %0, %1, %2" : "=v"(r) : "v"(lo), "v"(hi)); return r; }
; __device__ __forceinline__ float bf_lo(unsigned w) { return __uint_as_float(w << 16); }
; __device__ __forceinline__ float bf_hi(unsigned w) { return __uint_as_float(w & 0xffff0000u); }
;     __device__ __forceinline__ void operator()(const f32x4 (&acc)[2][2][4][2], const Unit& u, int wr, int wc, int fr_in, int fq_in) const {
;     ...
;                 for (int m = 0; m < 4; ++m) { const size_t off = (size_t)(row0 + ai * HALF + m * 16) * 1024 + col0 + bj * HALF;
;                     if constexpr (BASE == 0) { pf[m][0] = *(const f32x4*)(basef + off); pf[m][1] = *(const f32x4*)(basef + off + 4); } else pb[m] = *(const u32x4*)(baseb + off); }
; #pragma unroll
;                 for (int m = 0; m < 4; ++m) { const size_t off = (size_t)(row0 + ai * HALF + m * 16) * 1024 + col0 + bj * HALF; f32x4 b[2];
;                     if constexpr (BASE == 0) { b[0] = pf[m][0]; b[1] = pf[m][1]; }
;                     else { const u32x4 pw = pb[m]; b[0] = (f32x4){bf_lo(pw.x), bf_hi(pw.x), bf_lo(pw.y), bf_hi(pw.y)}; b[1] = (f32x4){bf_lo(pw.z), bf_hi(pw.z), bf_lo(pw.w), bf_hi(pw.w)}; }
;                     f32x4 z[2];
; #pragma unroll
;                     for (int n = 0; n < 2; ++n) { if constexpr (BASE == 1) b[n] = (b[n] - rst.mu[ai][m]) * rst.rs[ai][m] * gv[n] + bv[n];
;                         z[n] = b[n] * al_ + acc[ai][bj][m][n] * s_; }
;                     u32x4 w; w.x = cvt_pk_bf16(z[0][0], z[0][1]); w.y = cvt_pk_bf16(z[0][2], z[0][3]); w.z = cvt_pk_bf16(z[1][0], z[1][1]); w.w = cvt_pk_bf16(z[1][2], z[1][3]);
;                     *(u32x4*)(zb + off) = w;
.LBB0_341:
	s_lshl_b32 s7, s40, 8
	v_mov_b32_e32 v173, v147
	v_mov_b32_e32 v174, v149
	s_add_i32 s8, s7, s53
	v_mov_b32_e32 v148, 0x3fb504f3
	v_add_u32_e32 v162, s8, v173
	s_lshl_b32 s8, s6, 8
	s_or_b32 s8, s8, s54
	v_lshl_add_u32 v164, v174, 3, s8
	v_ashrrev_i32_e32 v165, 31, v164
	v_ashrrev_i32_e32 v163, 31, v162
	v_add_u32_e32 v204, 16, v162
	v_lshl_add_u64 v[166:167], v[164:165], 2, s[4:5]
	v_lshlrev_b64 v[150:151], 12, v[162:163]
	v_ashrrev_i32_e32 v205, 31, v204
	v_add_u32_e32 v206, 32, v162
	v_mov_b32_e32 v146, 0.5
	v_lshl_add_u64 v[150:151], v[166:167], 0, v[150:151]
	v_lshlrev_b64 v[152:153], 12, v[204:205]
	v_ashrrev_i32_e32 v207, 31, v206
	v_add_u32_e32 v208, 48, v162
	global_load_dwordx4 v[158:161], v[150:151], off offset:16
	global_load_dwordx4 v[176:179], v[150:151], off
	v_lshl_add_u64 v[152:153], v[166:167], 0, v[152:153]
	v_lshlrev_b64 v[154:155], 12, v[206:207]
	v_ashrrev_i32_e32 v209, 31, v208
	global_load_dwordx4 v[180:183], v[152:153], off offset:16
	global_load_dwordx4 v[184:187], v[152:153], off
	v_lshl_add_u64 v[154:155], v[166:167], 0, v[154:155]
	v_lshlrev_b64 v[156:157], 12, v[208:209]
	global_load_dwordx4 v[188:191], v[154:155], off offset:16
	global_load_dwordx4 v[192:195], v[154:155], off
	v_lshl_add_u64 v[156:157], v[166:167], 0, v[156:157]
	global_load_dwordx4 v[196:199], v[156:157], off
	global_load_dwordx4 v[200:203], v[156:157], off offset:16
	v_pk_mul_f32 v[216:217], v[116:117], v[146:147] op_sel_hi:[1,0]
	v_lshlrev_b64 v[116:117], 11, v[162:163]
	v_pk_mul_f32 v[214:215], v[122:123], v[146:147] op_sel_hi:[1,0]
	v_pk_mul_f32 v[218:219], v[118:119], v[146:147] op_sel_hi:[1,0]
	v_lshlrev_b64 v[164:165], 1, v[164:165]
	v_lshl_add_u64 v[116:117], s[12:13], 0, v[116:117]
	v_lshlrev_b64 v[118:119], 11, v[204:205]
	v_lshlrev_b64 v[122:123], 11, v[206:207]
	v_pk_mul_f32 v[210:211], v[124:125], v[146:147] op_sel_hi:[1,0]
	v_pk_mul_f32 v[126:127], v[126:127], v[146:147] op_sel_hi:[1,0]
	v_pk_mul_f32 v[212:213], v[120:121], v[146:147] op_sel_hi:[1,0]
	v_lshl_add_u64 v[120:121], v[116:117], 0, v[164:165]
	v_lshl_add_u64 v[116:117], s[12:13], 0, v[118:119]
	v_lshl_add_u64 v[118:119], s[12:13], 0, v[122:123]
	v_lshl_add_u64 v[122:123], v[116:117], 0, v[164:165]
	v_lshl_add_u64 v[124:125], v[118:119], 0, v[164:165]
	s_waitcnt vmcnt(0)
	v_pk_fma_f32 v[158:159], v[158:159], v[148:149], v[212:213] op_sel_hi:[1,0,1]
	v_pk_fma_f32 v[118:119], v[178:179], v[148:149], v[126:127] op_sel_hi:[1,0,1]
	v_pk_fma_f32 v[116:117], v[176:177], v[148:149], v[210:211] op_sel_hi:[1,0,1]
	v_pk_fma_f32 v[126:127], v[160:161], v[148:149], v[214:215] op_sel_hi:[1,0,1]
	v_cvt_pk_bf16_f32 v116, v116, v117
	v_cvt_pk_bf16_f32 v117, v118, v119
	v_cvt_pk_bf16_f32 v118, v158, v159
	v_pk_fma_f32 v[158:159], v[148:149], v[184:185], v[216:217] op_sel_hi:[0,1,1]
	v_pk_mul_f32 v[184:185], v[148:149], v[188:189] op_sel_hi:[0,1]
	v_cvt_pk_bf16_f32 v119, v126, v127
	v_pk_fma_f32 v[126:127], v[148:149], v[186:187], v[218:219] op_sel_hi:[0,1,1]
	v_pk_mul_f32 v[160:161], v[148:149], v[182:183] op_sel_hi:[0,1]
	v_pk_mul_f32 v[176:177], v[148:149], v[180:181] op_sel_hi:[0,1]
	v_pk_mul_f32 v[182:183], v[148:149], v[190:191] op_sel_hi:[0,1]
	v_pk_mul_f32 v[186:187], v[148:149], v[198:199] op_sel_hi:[0,1]
	v_pk_fma_f32 v[104:105], v[104:105], v[146:147], v[184:185] op_sel_hi:[1,0,1]
	v_pk_mul_f32 v[190:191], v[148:149], v[202:203] op_sel_hi:[0,1]
	v_pk_fma_f32 v[160:161], v[114:115], v[146:147], v[160:161] op_sel_hi:[1,0,1]
	v_pk_fma_f32 v[114:115], v[112:113], v[146:147], v[176:177] op_sel_hi:[1,0,1]
	v_cvt_pk_bf16_f32 v113, v126, v127
	v_pk_fma_f32 v[106:107], v[106:107], v[146:147], v[182:183] op_sel_hi:[1,0,1]
	v_pk_fma_f32 v[126:127], v[102:103], v[146:147], v[186:187] op_sel_hi:[1,0,1]
	v_cvt_pk_bf16_f32 v102, v104, v105
	v_pk_mul_f32 v[104:105], v[148:149], v[200:201] op_sel_hi:[0,1]
	v_pk_mul_f32 v[178:179], v[148:149], v[194:195] op_sel_hi:[0,1]
	v_cvt_pk_bf16_f32 v103, v106, v107
	v_pk_fma_f32 v[106:107], v[98:99], v[146:147], v[190:191] op_sel_hi:[1,0,1]
	v_pk_fma_f32 v[98:99], v[96:97], v[146:147], v[104:105] op_sel_hi:[1,0,1]
	v_lshlrev_b64 v[104:105], 11, v[208:209]
	v_pk_mul_f32 v[188:189], v[148:149], v[196:197] op_sel_hi:[0,1]
	v_pk_fma_f32 v[110:111], v[110:111], v[146:147], v[178:179] op_sel_hi:[1,0,1]
	v_lshl_add_u64 v[104:105], s[12:13], 0, v[104:105]
	v_cvt_pk_bf16_f32 v112, v158, v159
	v_pk_fma_f32 v[158:159], v[100:101], v[146:147], v[188:189] op_sel_hi:[1,0,1]
	v_cvt_pk_bf16_f32 v101, v110, v111
	v_lshl_add_u64 v[110:111], v[104:105], 0, v[164:165]
	v_add_u32_e32 v104, 0x80, v162
	v_ashrrev_i32_e32 v105, 31, v104
	v_cvt_pk_bf16_f32 v98, v98, v99
	v_cvt_pk_bf16_f32 v99, v106, v107
	v_lshlrev_b64 v[106:107], 12, v[104:105]
	v_pk_mul_f32 v[180:181], v[148:149], v[192:193] op_sel_hi:[0,1]
	v_cvt_pk_bf16_f32 v97, v126, v127
	v_lshl_add_u64 v[126:127], v[166:167], 0, v[106:107]
	v_add_u32_e32 v106, 0x90, v162
	v_pk_fma_f32 v[108:109], v[108:109], v[146:147], v[180:181] op_sel_hi:[1,0,1]
	v_ashrrev_i32_e32 v107, 31, v106
	v_cvt_pk_bf16_f32 v100, v108, v109
	v_lshlrev_b64 v[108:109], 12, v[106:107]
	v_cvt_pk_bf16_f32 v114, v114, v115
	v_cvt_pk_bf16_f32 v115, v160, v161
	v_cvt_pk_bf16_f32 v96, v158, v159
	v_lshl_add_u64 v[158:159], v[166:167], 0, v[108:109]
	v_add_u32_e32 v108, 0xa0, v162
	global_store_dwordx4 v[120:121], v[116:119], off sc1
	global_store_dwordx4 v[122:123], v[112:115], off sc1
	global_store_dwordx4 v[124:125], v[100:103], off sc1
	global_store_dwordx4 v[110:111], v[96:99], off sc1
	v_ashrrev_i32_e32 v109, 31, v108
	v_lshlrev_b64 v[160:161], 12, v[108:109]
	v_add_u32_e32 v208, 0xb0, v162
	global_load_dwordx4 v[176:179], v[126:127], off offset:16
	global_load_dwordx4 v[180:183], v[126:127], off
	global_load_dwordx4 v[184:187], v[158:159], off offset:16
	global_load_dwordx4 v[188:191], v[158:159], off
	v_lshl_add_u64 v[160:161], v[166:167], 0, v[160:161]
	v_ashrrev_i32_e32 v209, 31, v208
	global_load_dwordx4 v[192:195], v[160:161], off offset:16
	global_load_dwordx4 v[196:199], v[160:161], off
	v_lshlrev_b64 v[162:163], 12, v[208:209]
	v_lshl_add_u64 v[162:163], v[166:167], 0, v[162:163]
	global_load_dwordx4 v[200:203], v[162:163], off
	global_load_dwordx4 v[204:207], v[162:163], off offset:16
	v_lshlrev_b64 v[104:105], 11, v[104:105]
	v_lshlrev_b64 v[106:107], 11, v[106:107]
	v_lshlrev_b64 v[108:109], 11, v[108:109]
	v_lshl_add_u64 v[104:105], s[12:13], 0, v[104:105]
	v_lshl_add_u64 v[106:107], s[12:13], 0, v[106:107]
	v_lshl_add_u64 v[108:109], s[12:13], 0, v[108:109]
	v_lshl_add_u64 v[104:105], v[104:105], 0, v[164:165]
	v_lshl_add_u64 v[106:107], v[106:107], 0, v[164:165]
	v_lshl_add_u64 v[108:109], v[108:109], 0, v[164:165]
	s_waitcnt vmcnt(0)
; __device__ __forceinline__ unsigned cvt_pk_bf16(float lo, float hi) { unsigned r; asm("v_cvt_pk_bf16_f32 %0, %1, %2" : "=v"(r) : "v"(lo), "v"(hi)); return r; }
; __device__ __forceinline__ float bf_lo(unsigned w) { return __uint_as_float(w << 16); }
; __device__ __forceinline__ float bf_hi(unsigned w) { return __uint_as_float(w & 0xffff0000u); }
;     __device__ __forceinline__ void operator()(const f32x4 (&acc)[2][2][4][2], const Unit& u, int wr, int wc, int fr_in, int fq_in) const {
;     ...
;                 for (int m = 0; m < 4; ++m) { const size_t off = (size_t)(row0 + ai * HALF + m * 16) * 1024 + col0 + bj * HALF;
;                     if constexpr (BASE == 0) { pf[m][0] = *(const f32x4*)(basef + off); pf[m][1] = *(const f32x4*)(basef + off + 4); } else pb[m] = *(const u32x4*)(baseb + off); }
; #pragma unroll
;                 for (int m = 0; m < 4; ++m) { const size_t off = (size_t)(row0 + ai * HALF + m * 16) * 1024 + col0 + bj * HALF; f32x4 b[2];
;                     if constexpr (BASE == 0) { b[0] = pf[m][0]; b[1] = pf[m][1]; }
;                     else { const u32x4 pw = pb[m]; b[0] = (f32x4){bf_lo(pw.x), bf_hi(pw.x), bf_lo(pw.y), bf_hi(pw.y)}; b[1] = (f32x4){bf_lo(pw.z), bf_hi(pw.z), bf_lo(pw.w), bf_hi(pw.w)}; }
;                     f32x4 z[2];
; #pragma unroll
;                     for (int n = 0; n < 2; ++n) { if constexpr (BASE == 1) b[n] = (b[n] - rst.mu[ai][m]) * rst.rs[ai][m] * gv[n] + bv[n];
;                         z[n] = b[n] * al_ + acc[ai][bj][m][n] * s_; }
;                     u32x4 w; w.x = cvt_pk_bf16(z[0][0], z[0][1]); w.y = cvt_pk_bf16(z[0][2], z[0][3]); w.z = cvt_pk_bf16(z[1][0], z[1][1]); w.w = cvt_pk_bf16(z[1][2], z[1][3]);
;                     *(u32x4*)(zb + off) = w;
	v_pk_mul_f32 v[178:179], v[148:149], v[178:179] op_sel_hi:[0,1]
	v_pk_mul_f32 v[166:167], v[148:149], v[182:183] op_sel_hi:[0,1]
	v_pk_mul_f32 v[188:189], v[148:149], v[188:189] op_sel_hi:[0,1]
	v_pk_mul_f32 v[180:181], v[148:149], v[180:181] op_sel_hi:[0,1]
	v_pk_mul_f32 v[182:183], v[148:149], v[190:191] op_sel_hi:[0,1]
	v_pk_mul_f32 v[196:197], v[148:149], v[196:197] op_sel_hi:[0,1]
	v_pk_fma_f32 v[84:85], v[84:85], v[146:147], v[188:189] op_sel_hi:[1,0,1]
	v_pk_fma_f32 v[92:93], v[92:93], v[146:147], v[180:181] op_sel_hi:[1,0,1]
	v_pk_fma_f32 v[86:87], v[86:87], v[146:147], v[182:183] op_sel_hi:[1,0,1]
	v_pk_fma_f32 v[180:181], v[76:77], v[146:147], v[196:197] op_sel_hi:[1,0,1]
	v_cvt_pk_bf16_f32 v76, v84, v85
	v_pk_mul_f32 v[84:85], v[148:149], v[200:201] op_sel_hi:[0,1]
	v_cvt_pk_bf16_f32 v77, v86, v87
	v_pk_fma_f32 v[68:69], v[68:69], v[146:147], v[84:85] op_sel_hi:[1,0,1]
	v_pk_mul_f32 v[84:85], v[148:149], v[206:207] op_sel_hi:[0,1]
	v_pk_mul_f32 v[86:87], v[148:149], v[204:205] op_sel_hi:[0,1]
	v_pk_fma_f32 v[84:85], v[66:67], v[146:147], v[84:85] op_sel_hi:[1,0,1]
	v_pk_fma_f32 v[66:67], v[64:65], v[146:147], v[86:87] op_sel_hi:[1,0,1]
	v_cvt_pk_bf16_f32 v64, v68, v69
	v_lshlrev_b64 v[68:69], 11, v[208:209]
	v_pk_mul_f32 v[176:177], v[148:149], v[176:177] op_sel_hi:[0,1]
	v_pk_mul_f32 v[186:187], v[148:149], v[186:187] op_sel_hi:[0,1]
	v_pk_mul_f32 v[184:185], v[148:149], v[184:185] op_sel_hi:[0,1]
	v_pk_mul_f32 v[194:195], v[148:149], v[194:195] op_sel_hi:[0,1]
	v_pk_mul_f32 v[192:193], v[148:149], v[192:193] op_sel_hi:[0,1]
	v_lshl_add_u64 v[68:69], s[12:13], 0, v[68:69]
	v_pk_mul_f32 v[190:191], v[148:149], v[198:199] op_sel_hi:[0,1]
	v_pk_mul_f32 v[198:199], v[148:149], v[202:203] op_sel_hi:[0,1]
	v_pk_fma_f32 v[94:95], v[94:95], v[146:147], v[166:167] op_sel_hi:[1,0,1]
	v_pk_fma_f32 v[90:91], v[90:91], v[146:147], v[178:179] op_sel_hi:[1,0,1]
	v_pk_fma_f32 v[88:89], v[88:89], v[146:147], v[176:177] op_sel_hi:[1,0,1]
	v_pk_fma_f32 v[166:167], v[82:83], v[146:147], v[186:187] op_sel_hi:[1,0,1]
	v_pk_fma_f32 v[176:177], v[80:81], v[146:147], v[184:185] op_sel_hi:[1,0,1]
	v_pk_fma_f32 v[182:183], v[74:75], v[146:147], v[194:195] op_sel_hi:[1,0,1]
	v_pk_fma_f32 v[74:75], v[72:73], v[146:147], v[192:193] op_sel_hi:[1,0,1]
	v_cvt_pk_bf16_f32 v80, v92, v93
	v_cvt_pk_bf16_f32 v81, v94, v95
	v_cvt_pk_bf16_f32 v82, v88, v89
	v_cvt_pk_bf16_f32 v83, v90, v91
	v_lshl_add_u64 v[68:69], v[68:69], 0, v[164:165]
	v_pk_fma_f32 v[178:179], v[78:79], v[146:147], v[190:191] op_sel_hi:[1,0,1]
	v_cvt_pk_bf16_f32 v78, v176, v177
	v_cvt_pk_bf16_f32 v79, v166, v167
	v_cvt_pk_bf16_f32 v72, v180, v181
	v_cvt_pk_bf16_f32 v74, v74, v75
	v_cvt_pk_bf16_f32 v75, v182, v183
	s_nop 0
	v_cvt_pk_bf16_f32 v73, v178, v179
	global_store_dwordx4 v[104:105], v[80:83], off sc1
	global_store_dwordx4 v[106:107], v[76:79], off sc1
	global_store_dwordx4 v[108:109], v[72:75], off sc1
	v_pk_fma_f32 v[70:71], v[70:71], v[146:147], v[198:199] op_sel_hi:[1,0,1]
	v_cvt_pk_bf16_f32 v66, v66, v67
	v_cvt_pk_bf16_f32 v67, v84, v85
	s_nop 0
	v_cvt_pk_bf16_f32 v65, v70, v71
	global_store_dwordx4 v[68:69], v[64:67], off sc1
	global_load_dwordx4 v[84:87], v[150:151], off offset:512
	global_load_dwordx4 v[88:91], v[150:151], off offset:528
	global_load_dwordx4 v[92:95], v[152:153], off offset:512
	s_nop 0
	global_load_dwordx4 v[150:153], v[152:153], off offset:528
	s_nop 0
	global_load_dwordx4 v[164:167], v[154:155], off offset:512
	global_load_dwordx4 v[176:179], v[154:155], off offset:528
	global_load_dwordx4 v[180:183], v[156:157], off offset:512
	s_nop 0
	global_load_dwordx4 v[154:157], v[156:157], off offset:528
	s_waitcnt vmcnt(0)
	v_pk_mul_f32 v[70:71], v[148:149], v[86:87] op_sel_hi:[0,1]
	v_pk_mul_f32 v[84:85], v[148:149], v[84:85] op_sel_hi:[0,1]
	v_pk_mul_f32 v[86:87], v[148:149], v[90:91] op_sel_hi:[0,1]
	v_pk_mul_f32 v[88:89], v[148:149], v[88:89] op_sel_hi:[0,1]
	v_pk_mul_f32 v[90:91], v[148:149], v[94:95] op_sel_hi:[0,1]
	v_pk_mul_f32 v[94:95], v[148:149], v[152:153] op_sel_hi:[0,1]
	v_pk_mul_f32 v[150:151], v[148:149], v[150:151] op_sel_hi:[0,1]
	v_pk_mul_f32 v[152:153], v[148:149], v[166:167] op_sel_hi:[0,1]
	v_pk_mul_f32 v[156:157], v[148:149], v[156:157] op_sel_hi:[0,1]
	v_pk_mul_f32 v[154:155], v[148:149], v[154:155] op_sel_hi:[0,1]
	v_pk_mul_f32 v[92:93], v[148:149], v[92:93] op_sel_hi:[0,1]
	v_pk_mul_f32 v[164:165], v[148:149], v[164:165] op_sel_hi:[0,1]
	v_pk_mul_f32 v[166:167], v[148:149], v[178:179] op_sel_hi:[0,1]
	v_pk_mul_f32 v[176:177], v[148:149], v[176:177] op_sel_hi:[0,1]
	v_pk_mul_f32 v[178:179], v[148:149], v[182:183] op_sel_hi:[0,1]
	v_pk_mul_f32 v[180:181], v[148:149], v[180:181] op_sel_hi:[0,1]
	v_pk_fma_f32 v[62:63], v[62:63], v[146:147], v[70:71] op_sel_hi:[1,0,1]
	v_pk_fma_f32 v[60:61], v[60:61], v[146:147], v[84:85] op_sel_hi:[1,0,1]
	v_pk_fma_f32 v[58:59], v[58:59], v[146:147], v[86:87] op_sel_hi:[1,0,1]
	v_pk_fma_f32 v[56:57], v[56:57], v[146:147], v[88:89] op_sel_hi:[1,0,1]
	v_pk_fma_f32 v[50:51], v[50:51], v[146:147], v[94:95] op_sel_hi:[1,0,1]
	v_pk_fma_f32 v[70:71], v[48:49], v[146:147], v[150:151] op_sel_hi:[1,0,1]
	v_pk_fma_f32 v[84:85], v[46:47], v[146:147], v[152:153] op_sel_hi:[1,0,1]
	v_pk_fma_f32 v[94:95], v[34:35], v[146:147], v[156:157] op_sel_hi:[1,0,1]
	v_pk_fma_f32 v[34:35], v[32:33], v[146:147], v[154:155] op_sel_hi:[1,0,1]
	v_cvt_pk_bf16_f32 v46, v60, v61
	v_cvt_pk_bf16_f32 v47, v62, v63
	v_cvt_pk_bf16_f32 v48, v56, v57
	v_cvt_pk_bf16_f32 v49, v58, v59
	v_pk_fma_f32 v[54:55], v[54:55], v[146:147], v[90:91] op_sel_hi:[1,0,1]
	v_pk_fma_f32 v[52:53], v[52:53], v[146:147], v[92:93] op_sel_hi:[1,0,1]
; __device__ __forceinline__ unsigned cvt_pk_bf16(float lo, float hi) { unsigned r; asm("v_cvt_pk_bf16_f32 %0, %1, %2" : "=v"(r) : "v"(lo), "v"(hi)); return r; }
; __device__ __forceinline__ float bf_lo(unsigned w) { return __uint_as_float(w << 16); }
; __device__ __forceinline__ float bf_hi(unsigned w) { return __uint_as_float(w & 0xffff0000u); }
;     __device__ __forceinline__ void operator()(const f32x4 (&acc)[2][2][4][2], const Unit& u, int wr, int wc, int fr_in, int fq_in) const {
;     ...
;                 for (int m = 0; m < 4; ++m) { const size_t off = (size_t)(row0 + ai * HALF + m * 16) * 1024 + col0 + bj * HALF; f32x4 b[2];
;                     if constexpr (BASE == 0) { b[0] = pf[m][0]; b[1] = pf[m][1]; }
;                     else { const u32x4 pw = pb[m]; b[0] = (f32x4){bf_lo(pw.x), bf_hi(pw.x), bf_lo(pw.y), bf_hi(pw.y)}; b[1] = (f32x4){bf_lo(pw.z), bf_hi(pw.z), bf_lo(pw.w), bf_hi(pw.w)}; }
;                     f32x4 z[2];
; #pragma unroll
;                     for (int n = 0; n < 2; ++n) { if constexpr (BASE == 1) b[n] = (b[n] - rst.mu[ai][m]) * rst.rs[ai][m] * gv[n] + bv[n];
;                         z[n] = b[n] * al_ + acc[ai][bj][m][n] * s_; }
;                     u32x4 w; w.x = cvt_pk_bf16(z[0][0], z[0][1]); w.y = cvt_pk_bf16(z[0][2], z[0][3]); w.z = cvt_pk_bf16(z[1][0], z[1][1]); w.w = cvt_pk_bf16(z[1][2], z[1][3]);
;                     *(u32x4*)(zb + off) = w;
;                     const float r0 = bf_lo(w.x), r1 = bf_hi(w.x), r2 = bf_lo(w.y), r3 = bf_hi(w.y), r4 = bf_lo(w.z), r5 = bf_hi(w.z), r6 = bf_lo(w.w), r7 = bf_hi(w.w);
;                     s1[ai][m] += ((r0 + r1) + (r2 + r3)) + ((r4 + r5) + (r6 + r7)); s2[ai][m] += ((r0 * r0 + r1 * r1) + (r2 * r2 + r3 * r3)) + ((r4 * r4 + r5 * r5) + (r6 * r6 + r7 * r7)); }
	v_pk_fma_f32 v[44:45], v[44:45], v[146:147], v[164:165] op_sel_hi:[1,0,1]
	v_pk_fma_f32 v[86:87], v[42:43], v[146:147], v[166:167] op_sel_hi:[1,0,1]
	v_pk_fma_f32 v[88:89], v[40:41], v[146:147], v[176:177] op_sel_hi:[1,0,1]
	v_pk_fma_f32 v[90:91], v[38:39], v[146:147], v[178:179] op_sel_hi:[1,0,1]
	v_pk_fma_f32 v[92:93], v[36:37], v[146:147], v[180:181] op_sel_hi:[1,0,1]
	v_cvt_pk_bf16_f32 v40, v52, v53
	v_cvt_pk_bf16_f32 v41, v54, v55
	v_cvt_pk_bf16_f32 v42, v70, v71
	v_cvt_pk_bf16_f32 v43, v50, v51
	v_cvt_pk_bf16_f32 v36, v44, v45
	v_cvt_pk_bf16_f32 v37, v84, v85
	v_cvt_pk_bf16_f32 v38, v88, v89
	v_cvt_pk_bf16_f32 v39, v86, v87
	s_nop 0
	v_cvt_pk_bf16_f32 v32, v92, v93
	v_cvt_pk_bf16_f32 v33, v90, v91
	v_cvt_pk_bf16_f32 v34, v34, v35
	v_cvt_pk_bf16_f32 v35, v94, v95
	global_store_dwordx4 v[120:121], v[46:49], off offset:256 sc1
	global_store_dwordx4 v[122:123], v[40:43], off offset:256 sc1
	global_store_dwordx4 v[124:125], v[36:39], off offset:256 sc1
	global_store_dwordx4 v[110:111], v[32:35], off offset:256 sc1
	global_load_dwordx4 v[50:53], v[126:127], off offset:512
	global_load_dwordx4 v[54:57], v[126:127], off offset:528
	global_load_dwordx4 v[58:61], v[158:159], off offset:512
	global_load_dwordx4 v[84:87], v[158:159], off offset:528
	global_load_dwordx4 v[88:91], v[160:161], off offset:512
	global_load_dwordx4 v[92:95], v[160:161], off offset:528
	global_load_dwordx4 v[120:123], v[162:163], off offset:512
	global_load_dwordx4 v[124:127], v[162:163], off offset:528
	v_lshlrev_b32_e32 v70, 16, v117
	v_and_b32_e32 v152, 0xffff0000, v117
	v_lshlrev_b32_e32 v117, 16, v46
	v_and_b32_e32 v62, 0xffff0000, v116
	v_lshlrev_b32_e32 v116, 16, v116
	v_and_b32_e32 v153, 0xffff0000, v46
	v_mov_b32_e32 v63, v117
	v_pk_mul_f32 v[160:161], v[116:117], v[116:117]
	v_mov_b32_e32 v71, v153
	v_pk_mul_f32 v[166:167], v[62:63], v[62:63]
	v_lshlrev_b32_e32 v154, 16, v118
	v_lshlrev_b32_e32 v155, 16, v47
	v_and_b32_e32 v47, 0xffff0000, v47
	v_pk_mul_f32 v[162:163], v[152:153], v[152:153]
	v_pk_mul_f32 v[176:177], v[70:71], v[70:71]
	v_and_b32_e32 v46, 0xffff0000, v119
	v_and_b32_e32 v110, 0xffff0000, v118
	v_mov_b32_e32 v111, v155
	v_lshlrev_b32_e32 v150, 16, v119
	v_lshlrev_b32_e32 v156, 16, v48
	v_and_b32_e32 v48, 0xffff0000, v48
	v_pk_mul_f32 v[164:165], v[154:155], v[154:155]
	v_pk_mul_f32 v[178:179], v[110:111], v[110:111]
	v_mov_b32_e32 v151, v47
	v_lshlrev_b32_e32 v157, 16, v49
	v_and_b32_e32 v49, 0xffff0000, v49
	v_pk_mul_f32 v[158:159], v[48:49], v[48:49]
	v_and_b32_e32 v45, 64, v172
	v_pk_fma_f32 v[158:159], v[156:157], v[156:157], v[158:159]
	v_xor_b32_e32 v44, 16, v172
	v_add_u32_e32 v45, 64, v45
	v_pk_add_f32 v[158:159], v[158:159], v[158:159] op_sel_hi:[0,1]
	v_cmp_lt_i32_e32 vcc, v44, v45
	v_mov_b32_e32 v137, v159
	s_waitcnt vmcnt(0)
; __device__ __forceinline__ unsigned cvt_pk_bf16(float lo, float hi) { unsigned r; asm("v_cvt_pk_bf16_f32 %0, %1, %2" : "=v"(r) : "v"(lo), "v"(hi)); return r; }
; __device__ __forceinline__ float bf_lo(unsigned w) { return __uint_as_float(w << 16); }
; __device__ __forceinline__ float bf_hi(unsigned w) { return __uint_as_float(w & 0xffff0000u); }
; __device__ __forceinline__ void emit_row_stats(float (&s1)[2][4], float (&s2)[2][4], float* sp_new, const Unit& u, int wr, int wc, int fr, int fq, PG8_LAS unsigned char* xl) {
;     ...
;         for (int m = 0; m < 4; ++m) { float a = s1[ai][m], b = s2[ai][m]; a += __shfl_xor(a, 16); b += __shfl_xor(b, 16); a += __shfl_xor(a, 32); b += __shfl_xor(b, 32);
;             if (fq == 0) P[(ai * HALF + wr * 64 + m * 16 + fr) * 4 + wc] = (f32x2v){a, b}; }
;     __device__ __forceinline__ void operator()(const f32x4 (&acc)[2][2][4][2], const Unit& u, int wr, int wc, int fr_in, int fq_in) const {
;     ...
;                 for (int m = 0; m < 4; ++m) { const size_t off = (size_t)(row0 + ai * HALF + m * 16) * 1024 + col0 + bj * HALF; f32x4 b[2];
;                     if constexpr (BASE == 0) { b[0] = pf[m][0]; b[1] = pf[m][1]; }
;                     else { const u32x4 pw = pb[m]; b[0] = (f32x4){bf_lo(pw.x), bf_hi(pw.x), bf_lo(pw.y), bf_hi(pw.y)}; b[1] = (f32x4){bf_lo(pw.z), bf_hi(pw.z), bf_lo(pw.w), bf_hi(pw.w)}; }
;                     f32x4 z[2];
; #pragma unroll
;                     for (int n = 0; n < 2; ++n) { if constexpr (BASE == 1) b[n] = (b[n] - rst.mu[ai][m]) * rst.rs[ai][m] * gv[n] + bv[n];
;                         z[n] = b[n] * al_ + acc[ai][bj][m][n] * s_; }
;                     u32x4 w; w.x = cvt_pk_bf16(z[0][0], z[0][1]); w.y = cvt_pk_bf16(z[0][2], z[0][3]); w.z = cvt_pk_bf16(z[1][0], z[1][1]); w.w = cvt_pk_bf16(z[1][2], z[1][3]);
;                     *(u32x4*)(zb + off) = w;
;                     const float r0 = bf_lo(w.x), r1 = bf_hi(w.x), r2 = bf_lo(w.y), r3 = bf_hi(w.y), r4 = bf_lo(w.z), r5 = bf_hi(w.z), r6 = bf_lo(w.w), r7 = bf_hi(w.w);
;                     s1[ai][m] += ((r0 + r1) + (r2 + r3)) + ((r4 + r5) + (r6 + r7)); s2[ai][m] += ((r0 * r0 + r1 * r1) + (r2 * r2 + r3 * r3)) + ((r4 * r4 + r5 * r5) + (r6 * r6 + r7 * r7)); }
	v_pk_mul_f32 v[50:51], v[148:149], v[50:51] op_sel_hi:[0,1]
	v_pk_mul_f32 v[56:57], v[148:149], v[56:57] op_sel_hi:[0,1]
	v_pk_mul_f32 v[60:61], v[148:149], v[60:61] op_sel_hi:[0,1]
	v_pk_mul_f32 v[58:59], v[148:149], v[58:59] op_sel_hi:[0,1]
	v_pk_mul_f32 v[54:55], v[148:149], v[54:55] op_sel_hi:[0,1]
	v_pk_mul_f32 v[92:93], v[148:149], v[92:93] op_sel_hi:[0,1]
	v_pk_fma_f32 v[22:23], v[22:23], v[146:147], v[60:61] op_sel_hi:[1,0,1]
	v_pk_fma_f32 v[20:21], v[20:21], v[146:147], v[58:59] op_sel_hi:[1,0,1]
	v_pk_mul_f32 v[90:91], v[148:149], v[90:91] op_sel_hi:[0,1]
	v_pk_fma_f32 v[26:27], v[26:27], v[146:147], v[56:57] op_sel_hi:[1,0,1]
	v_pk_fma_f32 v[24:25], v[24:25], v[146:147], v[54:55] op_sel_hi:[1,0,1]
	v_pk_fma_f32 v[56:57], v[8:9], v[146:147], v[92:93] op_sel_hi:[1,0,1]
	v_cvt_pk_bf16_f32 v8, v20, v21
	v_cvt_pk_bf16_f32 v9, v22, v23
	v_pk_mov_b32 v[20:21], v[116:117], v[160:161] op_sel:[1,0]
	v_pk_mov_b32 v[22:23], v[152:153], v[166:167] op_sel:[1,0]
	v_pk_mul_f32 v[86:87], v[148:149], v[86:87] op_sel_hi:[0,1]
	v_pk_mul_f32 v[84:85], v[148:149], v[84:85] op_sel_hi:[0,1]
	v_pk_fma_f32 v[28:29], v[28:29], v[146:147], v[50:51] op_sel_hi:[1,0,1]
	v_pk_fma_f32 v[50:51], v[14:15], v[146:147], v[90:91] op_sel_hi:[1,0,1]
	v_cvt_pk_bf16_f32 v14, v24, v25
	v_pk_add_f32 v[20:21], v[20:21], v[22:23]
	v_pk_mov_b32 v[22:23], v[154:155], v[176:177] op_sel:[1,0]
	v_pk_mov_b32 v[24:25], v[46:47], v[162:163] op_sel:[1,0]
	v_pk_mul_f32 v[94:95], v[148:149], v[94:95] op_sel_hi:[0,1]
	v_pk_fma_f32 v[18:19], v[18:19], v[146:147], v[86:87] op_sel_hi:[1,0,1]
	v_pk_fma_f32 v[16:17], v[16:17], v[146:147], v[84:85] op_sel_hi:[1,0,1]
	v_pk_add_f32 v[22:23], v[22:23], v[24:25]
	v_pk_fma_f32 v[54:55], v[10:11], v[146:147], v[94:95] op_sel_hi:[1,0,1]
	v_cvt_pk_bf16_f32 v10, v16, v17
	v_cvt_pk_bf16_f32 v11, v18, v19
	v_pk_mul_f32 v[16:17], v[150:151], v[150:151]
	v_pk_mul_f32 v[18:19], v[46:47], v[46:47]
	v_pk_add_f32 v[20:21], v[20:21], v[22:23]
	v_mov_b32_e32 v22, v156
	v_mov_b32_e32 v23, v164
	v_mov_b32_e32 v24, v48
	v_mov_b32_e32 v25, v178
	v_pk_add_f32 v[22:23], v[22:23], v[24:25]
	v_pk_mov_b32 v[16:17], v[156:157], v[16:17] op_sel:[1,0]
	v_pk_mov_b32 v[24:25], v[48:49], v[18:19] op_sel:[1,0]
	v_cndmask_b32_e32 v44, v172, v44, vcc
	v_pk_add_f32 v[16:17], v[16:17], v[24:25]
	v_pk_add_f32 v[24:25], v[46:47], v[150:151]
	v_pk_add_f32 v[16:17], v[22:23], v[16:17]
	v_pk_add_f32 v[22:23], v[152:153], v[70:71]
	v_pk_add_f32 v[16:17], v[20:21], v[16:17]
	v_pk_add_f32 v[20:21], v[116:117], v[62:63]
	v_mov_b32_e32 v23, v163
	v_mov_b32_e32 v21, v161
	v_pk_add_f32 v[20:21], v[20:21], v[22:23]
	v_pk_add_f32 v[22:23], v[154:155], v[110:111]
	v_mov_b32_e32 v25, v19
	v_mov_b32_e32 v23, v165
	v_pk_add_f32 v[18:19], v[22:23], v[24:25]
	v_lshlrev_b32_e32 v44, 2, v44
	v_pk_add_f32 v[18:19], v[20:21], v[18:19]
	v_xor_b32_e32 v20, 32, v172
	v_pk_add_f32 v[18:19], v[18:19], v[136:137]
	v_cmp_lt_i32_e32 vcc, v20, v45
	v_pk_add_f32 v[16:17], v[16:17], v[18:19]
	ds_bpermute_b32 v18, v44, v16
	ds_bpermute_b32 v19, v44, v17
	v_cndmask_b32_e32 v20, v172, v20, vcc
	v_pk_mul_f32 v[52:53], v[148:149], v[52:53] op_sel_hi:[0,1]
	v_pk_mul_f32 v[88:89], v[148:149], v[88:89] op_sel_hi:[0,1]
	v_pk_mul_f32 v[126:127], v[148:149], v[126:127] op_sel_hi:[0,1]
	v_pk_mul_f32 v[124:125], v[148:149], v[124:125] op_sel_hi:[0,1]
	v_lshlrev_b32_e32 v21, 2, v20
	s_waitcnt lgkmcnt(0)
	v_pk_add_f32 v[16:17], v[16:17], v[18:19]
	v_pk_mul_f32 v[122:123], v[148:149], v[122:123] op_sel_hi:[0,1]
	v_pk_mul_f32 v[120:121], v[148:149], v[120:121] op_sel_hi:[0,1]
	v_pk_fma_f32 v[30:31], v[30:31], v[146:147], v[52:53] op_sel_hi:[1,0,1]
	v_pk_fma_f32 v[52:53], v[12:13], v[146:147], v[88:89] op_sel_hi:[1,0,1]
	v_pk_fma_f32 v[84:85], v[2:3], v[146:147], v[126:127] op_sel_hi:[1,0,1]
	v_pk_fma_f32 v[2:3], v[0:1], v[146:147], v[124:125] op_sel_hi:[1,0,1]
	v_cvt_pk_bf16_f32 v12, v28, v29
	v_cvt_pk_bf16_f32 v13, v30, v31
	v_cvt_pk_bf16_f32 v15, v26, v27
	ds_bpermute_b32 v18, v21, v16
	ds_bpermute_b32 v19, v21, v17
	v_pk_fma_f32 v[58:59], v[6:7], v[146:147], v[122:123] op_sel_hi:[1,0,1]
	v_pk_fma_f32 v[60:61], v[4:5], v[146:147], v[120:121] op_sel_hi:[1,0,1]
	v_cvt_pk_bf16_f32 v4, v52, v53
	v_cvt_pk_bf16_f32 v5, v50, v51
	v_cvt_pk_bf16_f32 v6, v56, v57
	v_cvt_pk_bf16_f32 v7, v54, v55
	v_cvt_pk_bf16_f32 v1, v58, v59
	s_nop 0
	v_cvt_pk_bf16_f32 v0, v60, v61
	v_cvt_pk_bf16_f32 v2, v2, v3
	v_cvt_pk_bf16_f32 v3, v84, v85
	global_store_dwordx4 v[104:105], v[12:15], off offset:256 sc1
	global_store_dwordx4 v[106:107], v[8:11], off offset:256 sc1
	global_store_dwordx4 v[108:109], v[4:7], off offset:256 sc1
	global_store_dwordx4 v[68:69], v[0:3], off offset:256 sc1
	v_cmp_eq_u32_e32 vcc, 0, v174
	v_lshl_add_u32 v20, v173, 5, s61
	s_and_saveexec_b64 s[8:9], vcc
	s_cbranch_execz .LBB0_343
	s_waitcnt lgkmcnt(0)
	v_pk_add_f32 v[16:17], v[16:17], v[18:19]
	ds_write_b64 v20, v[16:17]

; __device__ __forceinline__ void emit_row_stats(float (&s1)[2][4], float (&s2)[2][4], float* sp_new, const Unit& u, int wr, int wc, int fr, int fq, PG8_LAS unsigned char* xl) {
;     ...
;     asm volatile("s_waitcnt lgkmcnt(0)" ::: "memory"); __builtin_amdgcn_s_barrier(); asm volatile("" ::: "memory");
;     const int tid = (wr * 4 + wc) * 64 + fq * 16 + fr;
;     if (tid < 256) { const f32x2v a = P[tid * 4 + 0], b = P[tid * 4 + 1], c = P[tid * 4 + 2], d = P[tid * 4 + 3];
;         f32x2v o; o.x = (a.x + b.x) + (c.x + d.x); o.y = (a.y + b.y) + (c.y + d.y);
;         *(f32x2v*)(sp_new + ((size_t)(u.pm * BM + tid) * 4 + u.pn) * 2) = o; }
.LBB0_357:
	s_or_b64 exec, exec, s[8:9]
	s_waitcnt lgkmcnt(0)
	s_barrier
	v_lshlrev_b32_e32 v0, 4, v174
	v_add3_u32 v0, s58, v173, v0
	s_movk_i32 s8, 0x100
	v_cmp_gt_i32_e32 vcc, s8, v0
	s_and_saveexec_b64 s[40:41], vcc
	s_cbranch_execz .LBB0_359
	v_lshl_add_u32 v1, v0, 5, 0
	v_add_u32_e32 v1, 0x20400, v1
	s_waitcnt lgkmcnt(0)
	ds_read_b128 v[2:5], v1
	ds_read_b128 v[6:9], v1 offset:16
	v_add_u32_e32 v0, s7, v0
	v_ashrrev_i32_e32 v1, 31, v0
	v_lshlrev_b64 v[0:1], 5, v[0:1]
	s_waitcnt lgkmcnt(1)
	v_pk_add_f32 v[2:3], v[2:3], v[4:5]
	s_waitcnt lgkmcnt(0)
	v_pk_add_f32 v[4:5], v[6:7], v[8:9]
	s_ashr_i32 s7, s6, 31
	v_lshl_add_u64 v[0:1], s[22:23], 0, v[0:1]
	v_pk_add_f32 v[2:3], v[2:3], v[4:5]
	v_lshl_add_u64 v[0:1], s[6:7], 3, v[0:1]
	global_store_dwordx2 v[0:1], v[2:3], off sc1

; __device__ __forceinline__ unsigned xb_add(unsigned* p, unsigned v) { return __hip_atomic_fetch_add(p, v, __ATOMIC_RELAXED, __HIP_MEMORY_SCOPE_AGENT); }
; __device__ __forceinline__ void xcd_barrier(const XcdBarrier& b) {
;     ...
;         const unsigned old = xb_add(&bar[XB_XSUB(b.x)], 1u);
;         const unsigned gen = old / nloc;
;         if (old + 1u == (gen + 1u) * nloc) {
;             __builtin_amdgcn_fence(__ATOMIC_RELEASE, "agent");
;             asm volatile("s_waitcnt vmcnt(0)" ::: "memory");
;             const unsigned og = xb_add(&bar[XB_TOP], 1u);
.LBB0_393:
	s_andn2_saveexec_b64 s[6:7], s[6:7]
	s_cbranch_execz .LBB0_411
	s_mov_b64 s[6:7], exec
	s_waitcnt lgkmcnt(0)
	s_waitcnt vmcnt(0)
	v_mbcnt_lo_u32_b32 v1, s6, 0
	v_mbcnt_hi_u32_b32 v1, s7, v1
	v_cmp_eq_u32_e32 vcc, 0, v1
	s_and_saveexec_b64 s[10:11], vcc
	s_cbranch_execz .LBB0_396
	s_bcnt1_i32_b64 s3, s[6:7]
	v_readlane_b32 s6, v255, 48
	v_mov_b32_e32 v2, 0
	v_mov_b32_e32 v3, s3
	v_readlane_b32 s7, v255, 49
	s_nop 4
	global_atomic_add v2, v2, v3, s[6:7] sc0

; __device__ __forceinline__ unsigned cvt_pk_bf16(float lo, float hi) { unsigned r; asm("v_cvt_pk_bf16_f32 %0, %1, %2" : "=v"(r) : "v"(lo), "v"(hi)); return r; }
; __device__ __forceinline__ float bf_lo(unsigned w) { return __uint_as_float(w << 16); }
; __device__ __forceinline__ float bf_hi(unsigned w) { return __uint_as_float(w & 0xffff0000u); }
; __device__ __forceinline__ void load_row_stats(const float* sp, int row0, RowStats& r) {
;     ...
;         for (int m = 0; m < 4; ++m) { const float* p = sp + (size_t)(row0 + ai * HALF + m * 16) * 8; const f32x4 a = *(const f32x4*)p, b = *(const f32x4*)(p + 4);
;             const float s1 = (a[0] + a[2]) + (b[0] + b[2]), s2 = (a[1] + a[3]) + (b[1] + b[3]); const float mu = s1 * (1.f / 1024.f); const float var = s2 * (1.f / 1024.f) - mu * mu;
;             r.mu[ai][m] = mu; r.rs[ai][m] = __builtin_amdgcn_rsqf(__builtin_fmaxf(var, 0.f) + 1e-5f); } }
;     __device__ __forceinline__ void operator()(const f32x4 (&acc)[2][2][4][2], const Unit& u, int wr, int wc, int fr_in, int fq_in) const {
;     ...
;                 for (int m = 0; m < 4; ++m) { const size_t off = (size_t)(row0 + ai * HALF + m * 16) * 1024 + col0 + bj * HALF; f32x4 b[2];
;                     if constexpr (BASE == 0) { b[0] = pf[m][0]; b[1] = pf[m][1]; }
;                     else { const u32x4 pw = pb[m]; b[0] = (f32x4){bf_lo(pw.x), bf_hi(pw.x), bf_lo(pw.y), bf_hi(pw.y)}; b[1] = (f32x4){bf_lo(pw.z), bf_hi(pw.z), bf_lo(pw.w), bf_hi(pw.w)}; }
;                     f32x4 z[2];
; #pragma unroll
;                     for (int n = 0; n < 2; ++n) { if constexpr (BASE == 1) b[n] = (b[n] - rst.mu[ai][m]) * rst.rs[ai][m] * gv[n] + bv[n];
;                         z[n] = b[n] * al_ + acc[ai][bj][m][n] * s_; }
;                     u32x4 w; w.x = cvt_pk_bf16(z[0][0], z[0][1]); w.y = cvt_pk_bf16(z[0][2], z[0][3]); w.z = cvt_pk_bf16(z[1][0], z[1][1]); w.w = cvt_pk_bf16(z[1][2], z[1][3]);
;                     *(u32x4*)(zb + off) = w;
.Lrs1_skip:
	s_waitcnt vmcnt(0) lgkmcnt(0)
	s_barrier
	ds_read_b64 v[208:209], v181
	ds_read_b64 v[204:205], v181 offset:128
	ds_read_b64 v[200:201], v181 offset:256
	ds_read_b64 v[196:197], v181 offset:384
	ds_read_b64 v[192:193], v181 offset:1024
	ds_read_b64 v[188:189], v181 offset:1152
	ds_read_b64 v[184:185], v181 offset:1280
	ds_read_b64 v[180:181], v181 offset:1408
	s_waitcnt lgkmcnt(0)
	v_fma_f32 v209, -v208, v208, v209
	v_max_f32_e32 v209, 0, v209
	v_add_f32_e32 v209, 0x3727c5ac, v209
	v_rsq_f32_e32 v206, v209
	v_fma_f32 v205, -v204, v204, v205
	v_max_f32_e32 v205, 0, v205
	v_add_f32_e32 v205, 0x3727c5ac, v205
	v_rsq_f32_e32 v202, v205
	v_fma_f32 v201, -v200, v200, v201
	v_max_f32_e32 v201, 0, v201
	v_add_f32_e32 v201, 0x3727c5ac, v201
	v_rsq_f32_e32 v198, v201
	v_fma_f32 v197, -v196, v196, v197
	v_max_f32_e32 v197, 0, v197
	v_add_f32_e32 v197, 0x3727c5ac, v197
	v_rsq_f32_e32 v194, v197
	v_fma_f32 v193, -v192, v192, v193
	v_max_f32_e32 v193, 0, v193
	v_add_f32_e32 v193, 0x3727c5ac, v193
	v_rsq_f32_e32 v190, v193
	v_fma_f32 v189, -v188, v188, v189
	v_max_f32_e32 v189, 0, v189
	v_add_f32_e32 v189, 0x3727c5ac, v189
	v_rsq_f32_e32 v186, v189
	v_fma_f32 v185, -v184, v184, v185
	v_max_f32_e32 v185, 0, v185
	v_add_f32_e32 v185, 0x3727c5ac, v185
	v_rsq_f32_e32 v182, v185
	v_fma_f32 v181, -v180, v180, v181
	v_max_f32_e32 v181, 0, v181
	v_add_f32_e32 v181, 0x3727c5ac, v181
	v_rsq_f32_e32 v178, v181
	s_waitcnt vmcnt(0)
	v_lshlrev_b32_e32 v165, 16, v152
	v_and_b32_e32 v181, 0xffff0000, v152
	v_lshlrev_b32_e32 v152, 16, v153
	v_and_b32_e32 v153, 0xffff0000, v153
	v_lshlrev_b32_e32 v185, 16, v154
	v_and_b32_e32 v189, 0xffff0000, v154
	v_lshlrev_b32_e32 v193, 16, v155
	v_and_b32_e32 v197, 0xffff0000, v155
	v_sub_f32_e32 v153, v153, v208
	v_sub_f32_e32 v152, v152, v208
	v_sub_f32_e32 v155, v181, v208
	v_sub_f32_e32 v154, v165, v208
	v_pk_mul_f32 v[154:155], v[206:207], v[154:155] op_sel_hi:[0,1]
	v_pk_mul_f32 v[152:153], v[206:207], v[152:153] op_sel_hi:[0,1]
	v_pk_fma_f32 v[152:153], v[138:139], v[152:153], v[142:143]
	v_pk_fma_f32 v[154:155], v[136:137], v[154:155], v[140:141]
	v_pk_mul_f32 v[152:153], v[176:177], v[152:153] op_sel_hi:[0,1]
	v_pk_mul_f32 v[154:155], v[176:177], v[154:155] op_sel_hi:[0,1]
	v_pk_fma_f32 v[126:127], v[126:127], v[174:175], v[152:153] op_sel_hi:[1,0,1]
	v_pk_fma_f32 v[124:125], v[124:125], v[174:175], v[154:155] op_sel_hi:[1,0,1]
	v_sub_f32_e32 v153, v197, v208
	v_sub_f32_e32 v152, v193, v208
	v_sub_f32_e32 v155, v189, v208
	v_sub_f32_e32 v154, v185, v208
	v_pk_mul_f32 v[154:155], v[206:207], v[154:155] op_sel_hi:[0,1]
	v_pk_mul_f32 v[152:153], v[206:207], v[152:153] op_sel_hi:[0,1]
	v_pk_fma_f32 v[152:153], v[130:131], v[152:153], v[134:135]
	v_pk_fma_f32 v[154:155], v[128:129], v[154:155], v[132:133]
	v_pk_mul_f32 v[152:153], v[176:177], v[152:153] op_sel_hi:[0,1]
	v_pk_mul_f32 v[154:155], v[176:177], v[154:155] op_sel_hi:[0,1]
	v_pk_fma_f32 v[152:153], v[122:123], v[174:175], v[152:153] op_sel_hi:[1,0,1]
	v_pk_fma_f32 v[122:123], v[120:121], v[174:175], v[154:155] op_sel_hi:[1,0,1]
	v_cvt_pk_bf16_f32 v120, v124, v125
	v_lshl_add_u64 v[124:125], s[22:23], 0, v[232:233]
	v_cvt_pk_bf16_f32 v121, v126, v127
	v_lshl_add_u64 v[232:233], v[124:125], 0, v[220:221]
	v_lshlrev_b32_e32 v125, 16, v144
	v_and_b32_e32 v127, 0xffff0000, v144
	v_lshlrev_b32_e32 v144, 16, v145
	v_and_b32_e32 v145, 0xffff0000, v145
	v_cvt_pk_bf16_f32 v122, v122, v123
	v_cvt_pk_bf16_f32 v123, v152, v153
	v_lshlrev_b32_e32 v153, 16, v146
	v_and_b32_e32 v155, 0xffff0000, v146
	v_lshlrev_b32_e32 v165, 16, v147
	v_and_b32_e32 v181, 0xffff0000, v147
	v_sub_f32_e32 v145, v145, v204
	v_sub_f32_e32 v144, v144, v204
	v_sub_f32_e32 v147, v127, v204
	v_sub_f32_e32 v146, v125, v204
	v_pk_mul_f32 v[146:147], v[202:203], v[146:147] op_sel_hi:[0,1]
	v_pk_mul_f32 v[144:145], v[202:203], v[144:145] op_sel_hi:[0,1]
	v_pk_fma_f32 v[144:145], v[138:139], v[144:145], v[142:143]
	v_pk_fma_f32 v[146:147], v[136:137], v[146:147], v[140:141]
	v_pk_mul_f32 v[144:145], v[176:177], v[144:145] op_sel_hi:[0,1]
	v_pk_mul_f32 v[146:147], v[176:177], v[146:147] op_sel_hi:[0,1]
	v_pk_fma_f32 v[118:119], v[118:119], v[174:175], v[144:145] op_sel_hi:[1,0,1]
	v_pk_fma_f32 v[116:117], v[116:117], v[174:175], v[146:147] op_sel_hi:[1,0,1]
	v_sub_f32_e32 v145, v181, v204
	v_sub_f32_e32 v144, v165, v204
	v_sub_f32_e32 v147, v155, v204
	v_sub_f32_e32 v146, v153, v204
	v_pk_mul_f32 v[146:147], v[202:203], v[146:147] op_sel_hi:[0,1]
	v_pk_mul_f32 v[144:145], v[202:203], v[144:145] op_sel_hi:[0,1]
	v_pk_fma_f32 v[144:145], v[130:131], v[144:145], v[134:135]
	v_pk_fma_f32 v[146:147], v[128:129], v[146:147], v[132:133]
	v_pk_mul_f32 v[144:145], v[176:177], v[144:145] op_sel_hi:[0,1]
	v_pk_mul_f32 v[146:147], v[176:177], v[146:147] op_sel_hi:[0,1]
	v_pk_fma_f32 v[144:145], v[114:115], v[174:175], v[144:145] op_sel_hi:[1,0,1]
	v_pk_fma_f32 v[114:115], v[112:113], v[174:175], v[146:147] op_sel_hi:[1,0,1]
	v_cvt_pk_bf16_f32 v113, v118, v119
	v_lshlrev_b32_e32 v125, 16, v242
	v_and_b32_e32 v127, 0xffff0000, v242
	v_lshlrev_b32_e32 v118, 16, v243
	v_and_b32_e32 v119, 0xffff0000, v243
	v_cvt_pk_bf16_f32 v114, v114, v115
	v_cvt_pk_bf16_f32 v115, v144, v145
	v_sub_f32_e32 v119, v119, v200
	v_sub_f32_e32 v118, v118, v200
	v_sub_f32_e32 v145, v127, v200
	v_sub_f32_e32 v144, v125, v200
	v_pk_mul_f32 v[144:145], v[198:199], v[144:145] op_sel_hi:[0,1]
	v_pk_mul_f32 v[118:119], v[198:199], v[118:119] op_sel_hi:[0,1]
	v_pk_fma_f32 v[118:119], v[138:139], v[118:119], v[142:143]
	v_pk_fma_f32 v[144:145], v[136:137], v[144:145], v[140:141]
	v_lshlrev_b32_e32 v146, 16, v244
	v_and_b32_e32 v147, 0xffff0000, v244
; __device__ __forceinline__ unsigned cvt_pk_bf16(float lo, float hi) { unsigned r; asm("v_cvt_pk_bf16_f32 %0, %1, %2" : "=v"(r) : "v"(lo), "v"(hi)); return r; }
; __device__ __forceinline__ float bf_lo(unsigned w) { return __uint_as_float(w << 16); }
; __device__ __forceinline__ float bf_hi(unsigned w) { return __uint_as_float(w & 0xffff0000u); }
;     __device__ __forceinline__ void operator()(const f32x4 (&acc)[2][2][4][2], const Unit& u, int wr, int wc, int fr_in, int fq_in) const {
;     ...
;                 for (int m = 0; m < 4; ++m) { const size_t off = (size_t)(row0 + ai * HALF + m * 16) * 1024 + col0 + bj * HALF;
;                     if constexpr (BASE == 0) { pf[m][0] = *(const f32x4*)(basef + off); pf[m][1] = *(const f32x4*)(basef + off + 4); } else pb[m] = *(const u32x4*)(baseb + off); }
; #pragma unroll
;                 for (int m = 0; m < 4; ++m) { const size_t off = (size_t)(row0 + ai * HALF + m * 16) * 1024 + col0 + bj * HALF; f32x4 b[2];
;                     if constexpr (BASE == 0) { b[0] = pf[m][0]; b[1] = pf[m][1]; }
;                     else { const u32x4 pw = pb[m]; b[0] = (f32x4){bf_lo(pw.x), bf_hi(pw.x), bf_lo(pw.y), bf_hi(pw.y)}; b[1] = (f32x4){bf_lo(pw.z), bf_hi(pw.z), bf_lo(pw.w), bf_hi(pw.w)}; }
;                     f32x4 z[2];
; #pragma unroll
;                     for (int n = 0; n < 2; ++n) { if constexpr (BASE == 1) b[n] = (b[n] - rst.mu[ai][m]) * rst.rs[ai][m] * gv[n] + bv[n];
;                         z[n] = b[n] * al_ + acc[ai][bj][m][n] * s_; }
;                     u32x4 w; w.x = cvt_pk_bf16(z[0][0], z[0][1]); w.y = cvt_pk_bf16(z[0][2], z[0][3]); w.z = cvt_pk_bf16(z[1][0], z[1][1]); w.w = cvt_pk_bf16(z[1][2], z[1][3]);
;                     *(u32x4*)(zb + off) = w;
	v_lshlrev_b32_e32 v153, 16, v245
	v_and_b32_e32 v155, 0xffff0000, v245
	v_pk_mul_f32 v[144:145], v[176:177], v[144:145] op_sel_hi:[0,1]
	v_pk_mul_f32 v[118:119], v[176:177], v[118:119] op_sel_hi:[0,1]
	v_pk_fma_f32 v[110:111], v[110:111], v[174:175], v[118:119] op_sel_hi:[1,0,1]
	v_pk_fma_f32 v[108:109], v[108:109], v[174:175], v[144:145] op_sel_hi:[1,0,1]
	v_sub_f32_e32 v119, v155, v200
	v_sub_f32_e32 v118, v153, v200
	v_sub_f32_e32 v145, v147, v200
	v_sub_f32_e32 v144, v146, v200
	v_pk_mul_f32 v[144:145], v[198:199], v[144:145] op_sel_hi:[0,1]
	v_pk_mul_f32 v[118:119], v[198:199], v[118:119] op_sel_hi:[0,1]
	v_pk_fma_f32 v[118:119], v[130:131], v[118:119], v[134:135]
	v_pk_fma_f32 v[144:145], v[128:129], v[144:145], v[132:133]
	v_pk_mul_f32 v[118:119], v[176:177], v[118:119] op_sel_hi:[0,1]
	v_pk_mul_f32 v[144:145], v[176:177], v[144:145] op_sel_hi:[0,1]
	v_pk_fma_f32 v[118:119], v[106:107], v[174:175], v[118:119] op_sel_hi:[1,0,1]
	v_pk_fma_f32 v[106:107], v[104:105], v[174:175], v[144:145] op_sel_hi:[1,0,1]
	v_cvt_pk_bf16_f32 v105, v110, v111
	v_lshlrev_b32_e32 v110, 16, v149
	v_cvt_pk_bf16_f32 v106, v106, v107
	v_cvt_pk_bf16_f32 v107, v118, v119
	v_lshlrev_b32_e32 v118, 16, v148
	v_and_b32_e32 v119, 0xffff0000, v148
	v_and_b32_e32 v111, 0xffff0000, v149
	v_sub_f32_e32 v111, v111, v196
	v_sub_f32_e32 v110, v110, v196
	v_sub_f32_e32 v119, v119, v196
	v_sub_f32_e32 v118, v118, v196
	v_pk_mul_f32 v[118:119], v[194:195], v[118:119] op_sel_hi:[0,1]
	v_pk_mul_f32 v[110:111], v[194:195], v[110:111] op_sel_hi:[0,1]
	v_pk_fma_f32 v[110:111], v[138:139], v[110:111], v[142:143]
	v_pk_fma_f32 v[118:119], v[136:137], v[118:119], v[140:141]
	v_lshlrev_b32_e32 v125, 16, v150
	v_and_b32_e32 v127, 0xffff0000, v150
	v_lshlrev_b32_e32 v144, 16, v151
	v_and_b32_e32 v145, 0xffff0000, v151
	v_pk_mul_f32 v[118:119], v[176:177], v[118:119] op_sel_hi:[0,1]
	v_pk_mul_f32 v[110:111], v[176:177], v[110:111] op_sel_hi:[0,1]
	v_pk_fma_f32 v[102:103], v[102:103], v[174:175], v[110:111] op_sel_hi:[1,0,1]
	v_pk_fma_f32 v[100:101], v[100:101], v[174:175], v[118:119] op_sel_hi:[1,0,1]
	v_sub_f32_e32 v111, v145, v196
	v_sub_f32_e32 v110, v144, v196
	v_sub_f32_e32 v119, v127, v196
	v_sub_f32_e32 v118, v125, v196
	v_pk_mul_f32 v[118:119], v[194:195], v[118:119] op_sel_hi:[0,1]
	v_pk_mul_f32 v[110:111], v[194:195], v[110:111] op_sel_hi:[0,1]
	v_pk_fma_f32 v[110:111], v[130:131], v[110:111], v[134:135]
	v_pk_fma_f32 v[118:119], v[128:129], v[118:119], v[132:133]
	v_pk_mul_f32 v[110:111], v[176:177], v[110:111] op_sel_hi:[0,1]
	v_pk_mul_f32 v[118:119], v[176:177], v[118:119] op_sel_hi:[0,1]
	v_cvt_pk_bf16_f32 v112, v116, v117
	v_lshl_add_u64 v[116:117], s[22:23], 0, v[236:237]
	v_cvt_pk_bf16_f32 v104, v108, v109
	v_lshl_add_u64 v[108:109], s[22:23], 0, v[240:241]
	v_pk_fma_f32 v[110:111], v[98:99], v[174:175], v[110:111] op_sel_hi:[1,0,1]
	v_pk_fma_f32 v[98:99], v[96:97], v[174:175], v[118:119] op_sel_hi:[1,0,1]
	v_cvt_pk_bf16_f32 v96, v100, v101
	v_lshl_add_u64 v[100:101], s[22:23], 0, v[238:239]
	v_lshl_add_u64 v[116:117], v[116:117], 0, v[220:221]
	v_lshl_add_u64 v[108:109], v[108:109], 0, v[220:221]
	v_lshl_add_u64 v[100:101], v[100:101], 0, v[220:221]
	global_store_dwordx4 v[232:233], v[120:123], off sc1
	global_store_dwordx4 v[116:117], v[112:115], off sc1
	global_store_dwordx4 v[108:109], v[104:107], off sc1
	v_cvt_pk_bf16_f32 v97, v102, v103
	v_cvt_pk_bf16_f32 v98, v98, v99
	v_cvt_pk_bf16_f32 v99, v110, v111
	global_store_dwordx4 v[100:101], v[96:99], off sc1
	v_lshlrev_b64 v[144:145], 11, v[222:223]
	v_lshl_add_u64 v[102:103], v[234:235], 0, v[144:145]
	global_load_dwordx4 v[236:239], v[102:103], off
	v_lshlrev_b64 v[146:147], 11, v[226:227]
	v_lshl_add_u64 v[110:111], v[234:235], 0, v[146:147]
	global_load_dwordx4 v[240:243], v[110:111], off
	v_lshlrev_b64 v[150:151], 11, v[210:211]
	v_lshl_add_u64 v[148:149], v[234:235], 0, v[150:151]
	global_load_dwordx4 v[244:247], v[148:149], off
	v_lshlrev_b64 v[210:211], 11, v[212:213]
	v_lshl_add_u64 v[118:119], v[234:235], 0, v[210:211]
	global_load_dwordx4 v[248:251], v[118:119], off
	v_and_b32_e32 v154, 0xffff0000, v120
	v_lshlrev_b32_e32 v152, 16, v121
	v_and_b32_e32 v126, 0xffff0000, v122
	v_lshlrev_b32_e32 v124, 16, v123
	s_waitcnt vmcnt(0)
; __device__ __forceinline__ unsigned cvt_pk_bf16(float lo, float hi) { unsigned r; asm("v_cvt_pk_bf16_f32 %0, %1, %2" : "=v"(r) : "v"(lo), "v"(hi)); return r; }
; __device__ __forceinline__ float bf_lo(unsigned w) { return __uint_as_float(w << 16); }
; __device__ __forceinline__ float bf_hi(unsigned w) { return __uint_as_float(w & 0xffff0000u); }
;     __device__ __forceinline__ void operator()(const f32x4 (&acc)[2][2][4][2], const Unit& u, int wr, int wc, int fr_in, int fq_in) const {
;     ...
;                 for (int m = 0; m < 4; ++m) { const size_t off = (size_t)(row0 + ai * HALF + m * 16) * 1024 + col0 + bj * HALF; f32x4 b[2];
;                     if constexpr (BASE == 0) { b[0] = pf[m][0]; b[1] = pf[m][1]; }
;                     else { const u32x4 pw = pb[m]; b[0] = (f32x4){bf_lo(pw.x), bf_hi(pw.x), bf_lo(pw.y), bf_hi(pw.y)}; b[1] = (f32x4){bf_lo(pw.z), bf_hi(pw.z), bf_lo(pw.w), bf_hi(pw.w)}; }
;                     f32x4 z[2];
; #pragma unroll
;                     for (int n = 0; n < 2; ++n) { if constexpr (BASE == 1) b[n] = (b[n] - rst.mu[ai][m]) * rst.rs[ai][m] * gv[n] + bv[n];
;                         z[n] = b[n] * al_ + acc[ai][bj][m][n] * s_; }
;                     u32x4 w; w.x = cvt_pk_bf16(z[0][0], z[0][1]); w.y = cvt_pk_bf16(z[0][2], z[0][3]); w.z = cvt_pk_bf16(z[1][0], z[1][1]); w.w = cvt_pk_bf16(z[1][2], z[1][3]);
;                     *(u32x4*)(zb + off) = w;
	v_lshlrev_b32_e32 v125, 16, v236
	v_and_b32_e32 v127, 0xffff0000, v236
	v_lshlrev_b32_e32 v153, 16, v237
	v_and_b32_e32 v155, 0xffff0000, v237
	v_sub_f32_e32 v213, v155, v192
	v_sub_f32_e32 v212, v153, v192
	v_sub_f32_e32 v223, v127, v192
	v_sub_f32_e32 v222, v125, v192
	v_pk_mul_f32 v[222:223], v[190:191], v[222:223] op_sel_hi:[0,1]
	v_pk_mul_f32 v[212:213], v[190:191], v[212:213] op_sel_hi:[0,1]
	v_pk_fma_f32 v[212:213], v[138:139], v[212:213], v[142:143]
	v_pk_fma_f32 v[222:223], v[136:137], v[222:223], v[140:141]
	v_lshlrev_b32_e32 v165, 16, v238
	v_and_b32_e32 v181, 0xffff0000, v238
	v_lshlrev_b32_e32 v185, 16, v239
	v_and_b32_e32 v189, 0xffff0000, v239
	v_pk_mul_f32 v[222:223], v[176:177], v[222:223] op_sel_hi:[0,1]
	v_pk_mul_f32 v[212:213], v[176:177], v[212:213] op_sel_hi:[0,1]
	v_pk_fma_f32 v[94:95], v[94:95], v[174:175], v[212:213] op_sel_hi:[1,0,1]
	v_pk_fma_f32 v[92:93], v[92:93], v[174:175], v[222:223] op_sel_hi:[1,0,1]
	v_sub_f32_e32 v213, v189, v192
	v_sub_f32_e32 v212, v185, v192
	v_sub_f32_e32 v223, v181, v192
	v_sub_f32_e32 v222, v165, v192
	v_pk_mul_f32 v[222:223], v[190:191], v[222:223] op_sel_hi:[0,1]
	v_pk_mul_f32 v[212:213], v[190:191], v[212:213] op_sel_hi:[0,1]
	v_pk_fma_f32 v[212:213], v[130:131], v[212:213], v[134:135]
	v_pk_fma_f32 v[222:223], v[128:129], v[222:223], v[132:133]
	v_pk_mul_f32 v[212:213], v[176:177], v[212:213] op_sel_hi:[0,1]
	v_pk_mul_f32 v[222:223], v[176:177], v[222:223] op_sel_hi:[0,1]
	v_pk_fma_f32 v[212:213], v[90:91], v[174:175], v[212:213] op_sel_hi:[1,0,1]
	v_pk_fma_f32 v[90:91], v[88:89], v[174:175], v[222:223] op_sel_hi:[1,0,1]
	v_cvt_pk_bf16_f32 v88, v92, v93
	v_lshl_add_u64 v[92:93], s[22:23], 0, v[144:145]
	v_cvt_pk_bf16_f32 v89, v94, v95
	v_lshl_add_u64 v[144:145], v[92:93], 0, v[220:221]
	v_lshlrev_b32_e32 v94, 16, v240
	v_and_b32_e32 v95, 0xffff0000, v240
	v_lshlrev_b32_e32 v92, 16, v241
	v_and_b32_e32 v93, 0xffff0000, v241
	v_sub_f32_e32 v93, v93, v188
	v_sub_f32_e32 v92, v92, v188
	v_sub_f32_e32 v95, v95, v188
	v_sub_f32_e32 v94, v94, v188
	v_pk_mul_f32 v[94:95], v[186:187], v[94:95] op_sel_hi:[0,1]
	v_pk_mul_f32 v[92:93], v[186:187], v[92:93] op_sel_hi:[0,1]
	v_pk_fma_f32 v[92:93], v[138:139], v[92:93], v[142:143]
	v_pk_fma_f32 v[94:95], v[136:137], v[94:95], v[140:141]
	v_lshlrev_b32_e32 v125, 16, v242
	v_and_b32_e32 v127, 0xffff0000, v242
	v_lshlrev_b32_e32 v153, 16, v243
	v_and_b32_e32 v155, 0xffff0000, v243
	v_pk_mul_f32 v[94:95], v[176:177], v[94:95] op_sel_hi:[0,1]
	v_pk_mul_f32 v[92:93], v[176:177], v[92:93] op_sel_hi:[0,1]
	v_pk_fma_f32 v[86:87], v[86:87], v[174:175], v[92:93] op_sel_hi:[1,0,1]
	v_pk_fma_f32 v[84:85], v[84:85], v[174:175], v[94:95] op_sel_hi:[1,0,1]
	v_sub_f32_e32 v93, v155, v188
	v_sub_f32_e32 v92, v153, v188
	v_sub_f32_e32 v95, v127, v188
	v_sub_f32_e32 v94, v125, v188
	v_pk_mul_f32 v[94:95], v[186:187], v[94:95] op_sel_hi:[0,1]
	v_pk_mul_f32 v[92:93], v[186:187], v[92:93] op_sel_hi:[0,1]
	v_pk_fma_f32 v[92:93], v[130:131], v[92:93], v[134:135]
	v_pk_fma_f32 v[94:95], v[128:129], v[94:95], v[132:133]
	v_pk_mul_f32 v[92:93], v[176:177], v[92:93] op_sel_hi:[0,1]
	v_pk_mul_f32 v[94:95], v[176:177], v[94:95] op_sel_hi:[0,1]
	v_pk_fma_f32 v[92:93], v[82:83], v[174:175], v[92:93] op_sel_hi:[1,0,1]
	v_pk_fma_f32 v[82:83], v[80:81], v[174:175], v[94:95] op_sel_hi:[1,0,1]
	v_cvt_pk_bf16_f32 v80, v84, v85
	v_lshl_add_u64 v[84:85], s[22:23], 0, v[146:147]
	v_cvt_pk_bf16_f32 v81, v86, v87
	v_lshl_add_u64 v[146:147], v[84:85], 0, v[220:221]
	v_lshlrev_b32_e32 v86, 16, v244
	v_and_b32_e32 v87, 0xffff0000, v244
	v_lshlrev_b32_e32 v84, 16, v245
	v_and_b32_e32 v85, 0xffff0000, v245
	v_sub_f32_e32 v85, v85, v184
	v_sub_f32_e32 v84, v84, v184
	v_sub_f32_e32 v87, v87, v184
	v_sub_f32_e32 v86, v86, v184
	v_pk_mul_f32 v[86:87], v[182:183], v[86:87] op_sel_hi:[0,1]
	v_pk_mul_f32 v[84:85], v[182:183], v[84:85] op_sel_hi:[0,1]
	v_pk_fma_f32 v[84:85], v[138:139], v[84:85], v[142:143]
	v_pk_fma_f32 v[86:87], v[136:137], v[86:87], v[140:141]
	v_cvt_pk_bf16_f32 v82, v82, v83
	v_cvt_pk_bf16_f32 v83, v92, v93
	v_lshlrev_b32_e32 v92, 16, v246
	v_and_b32_e32 v93, 0xffff0000, v246
	v_lshlrev_b32_e32 v94, 16, v247
	v_and_b32_e32 v95, 0xffff0000, v247
	v_pk_mul_f32 v[86:87], v[176:177], v[86:87] op_sel_hi:[0,1]
	v_pk_mul_f32 v[84:85], v[176:177], v[84:85] op_sel_hi:[0,1]
	v_pk_fma_f32 v[78:79], v[78:79], v[174:175], v[84:85] op_sel_hi:[1,0,1]
	v_pk_fma_f32 v[76:77], v[76:77], v[174:175], v[86:87] op_sel_hi:[1,0,1]
	v_sub_f32_e32 v85, v95, v184
	v_sub_f32_e32 v84, v94, v184
	v_sub_f32_e32 v87, v93, v184
	v_sub_f32_e32 v86, v92, v184
	v_pk_mul_f32 v[86:87], v[182:183], v[86:87] op_sel_hi:[0,1]
	v_pk_mul_f32 v[84:85], v[182:183], v[84:85] op_sel_hi:[0,1]
	v_pk_fma_f32 v[84:85], v[130:131], v[84:85], v[134:135]
	v_pk_fma_f32 v[86:87], v[128:129], v[86:87], v[132:133]
	v_pk_mul_f32 v[84:85], v[176:177], v[84:85] op_sel_hi:[0,1]
	v_pk_mul_f32 v[86:87], v[176:177], v[86:87] op_sel_hi:[0,1]
	v_pk_fma_f32 v[84:85], v[74:75], v[174:175], v[84:85] op_sel_hi:[1,0,1]
	v_pk_fma_f32 v[74:75], v[72:73], v[174:175], v[86:87] op_sel_hi:[1,0,1]
	v_cvt_pk_bf16_f32 v72, v76, v77
	v_lshl_add_u64 v[76:77], s[22:23], 0, v[150:151]
	v_cvt_pk_bf16_f32 v73, v78, v79
	v_lshl_add_u64 v[150:151], v[76:77], 0, v[220:221]
	v_lshlrev_b32_e32 v78, 16, v248
	v_and_b32_e32 v79, 0xffff0000, v248
	v_lshlrev_b32_e32 v76, 16, v249
	v_and_b32_e32 v77, 0xffff0000, v249
	v_sub_f32_e32 v77, v77, v180
	v_sub_f32_e32 v76, v76, v180
	v_sub_f32_e32 v79, v79, v180
	v_sub_f32_e32 v78, v78, v180
	v_pk_mul_f32 v[78:79], v[178:179], v[78:79] op_sel_hi:[0,1]
	v_pk_mul_f32 v[76:77], v[178:179], v[76:77] op_sel_hi:[0,1]
; __device__ __forceinline__ unsigned cvt_pk_bf16(float lo, float hi) { unsigned r; asm("v_cvt_pk_bf16_f32 %0, %1, %2" : "=v"(r) : "v"(lo), "v"(hi)); return r; }
; __device__ __forceinline__ float bf_lo(unsigned w) { return __uint_as_float(w << 16); }
; __device__ __forceinline__ float bf_hi(unsigned w) { return __uint_as_float(w & 0xffff0000u); }
;     __device__ __forceinline__ void operator()(const f32x4 (&acc)[2][2][4][2], const Unit& u, int wr, int wc, int fr_in, int fq_in) const {
;     ...
;                 for (int n = 0; n < 2; ++n) { gv[n] = *(const f32x4*)(lg + col0 + bj * HALF + 4 * n); bv[n] = *(const f32x4*)(lb + col0 + bj * HALF + 4 * n); } }
; #pragma unroll
;             for (int ai = 0; ai < 2; ++ai) {
;                 f32x4 pf[4][2]; u32x4 pb[4];
; #pragma unroll
;                 for (int m = 0; m < 4; ++m) { const size_t off = (size_t)(row0 + ai * HALF + m * 16) * 1024 + col0 + bj * HALF;
;                     if constexpr (BASE == 0) { pf[m][0] = *(const f32x4*)(basef + off); pf[m][1] = *(const f32x4*)(basef + off + 4); } else pb[m] = *(const u32x4*)(baseb + off); }
; #pragma unroll
;                 for (int m = 0; m < 4; ++m) { const size_t off = (size_t)(row0 + ai * HALF + m * 16) * 1024 + col0 + bj * HALF; f32x4 b[2];
;                     if constexpr (BASE == 0) { b[0] = pf[m][0]; b[1] = pf[m][1]; }
;                     else { const u32x4 pw = pb[m]; b[0] = (f32x4){bf_lo(pw.x), bf_hi(pw.x), bf_lo(pw.y), bf_hi(pw.y)}; b[1] = (f32x4){bf_lo(pw.z), bf_hi(pw.z), bf_lo(pw.w), bf_hi(pw.w)}; }
;                     f32x4 z[2];
; #pragma unroll
;                     for (int n = 0; n < 2; ++n) { if constexpr (BASE == 1) b[n] = (b[n] - rst.mu[ai][m]) * rst.rs[ai][m] * gv[n] + bv[n];
;                         z[n] = b[n] * al_ + acc[ai][bj][m][n] * s_; }
;                     u32x4 w; w.x = cvt_pk_bf16(z[0][0], z[0][1]); w.y = cvt_pk_bf16(z[0][2], z[0][3]); w.z = cvt_pk_bf16(z[1][0], z[1][1]); w.w = cvt_pk_bf16(z[1][2], z[1][3]);
;                     *(u32x4*)(zb + off) = w;
;                     const float r0 = bf_lo(w.x), r1 = bf_hi(w.x), r2 = bf_lo(w.y), r3 = bf_hi(w.y), r4 = bf_lo(w.z), r5 = bf_hi(w.z), r6 = bf_lo(w.w), r7 = bf_hi(w.w);
;                     s1[ai][m] += ((r0 + r1) + (r2 + r3)) + ((r4 + r5) + (r6 + r7)); s2[ai][m] += ((r0 * r0 + r1 * r1) + (r2 * r2 + r3 * r3)) + ((r4 * r4 + r5 * r5) + (r6 * r6 + r7 * r7)); }
	v_pk_fma_f32 v[76:77], v[138:139], v[76:77], v[142:143]
	v_pk_fma_f32 v[78:79], v[136:137], v[78:79], v[140:141]
	v_cvt_pk_bf16_f32 v74, v74, v75
	v_cvt_pk_bf16_f32 v75, v84, v85
	v_lshlrev_b32_e32 v84, 16, v250
	v_and_b32_e32 v85, 0xffff0000, v250
	v_lshlrev_b32_e32 v86, 16, v251
	v_and_b32_e32 v87, 0xffff0000, v251
	v_pk_mul_f32 v[78:79], v[176:177], v[78:79] op_sel_hi:[0,1]
	v_pk_mul_f32 v[76:77], v[176:177], v[76:77] op_sel_hi:[0,1]
	v_pk_fma_f32 v[70:71], v[70:71], v[174:175], v[76:77] op_sel_hi:[1,0,1]
	v_pk_fma_f32 v[68:69], v[68:69], v[174:175], v[78:79] op_sel_hi:[1,0,1]
	v_sub_f32_e32 v77, v87, v180
	v_sub_f32_e32 v76, v86, v180
	v_sub_f32_e32 v79, v85, v180
	v_sub_f32_e32 v78, v84, v180
	v_pk_mul_f32 v[78:79], v[178:179], v[78:79] op_sel_hi:[0,1]
	v_pk_mul_f32 v[76:77], v[178:179], v[76:77] op_sel_hi:[0,1]
	v_pk_fma_f32 v[76:77], v[130:131], v[76:77], v[134:135]
	v_pk_fma_f32 v[78:79], v[128:129], v[78:79], v[132:133]
	v_pk_mul_f32 v[76:77], v[176:177], v[76:77] op_sel_hi:[0,1]
	v_pk_mul_f32 v[78:79], v[176:177], v[78:79] op_sel_hi:[0,1]
	v_pk_fma_f32 v[76:77], v[66:67], v[174:175], v[76:77] op_sel_hi:[1,0,1]
	v_pk_fma_f32 v[66:67], v[64:65], v[174:175], v[78:79] op_sel_hi:[1,0,1]
	v_cvt_pk_bf16_f32 v64, v68, v69
	v_lshl_add_u64 v[68:69], s[22:23], 0, v[210:211]
	v_lshl_add_u64 v[128:129], v[68:69], 0, v[220:221]
	v_cvt_pk_bf16_f32 v90, v90, v91
	v_cvt_pk_bf16_f32 v91, v212, v213
	global_store_dwordx4 v[144:145], v[88:91], off sc1
	global_store_dwordx4 v[146:147], v[80:83], off sc1
	global_store_dwordx4 v[150:151], v[72:75], off sc1
	v_cvt_pk_bf16_f32 v65, v70, v71
	v_cvt_pk_bf16_f32 v66, v66, v67
	v_cvt_pk_bf16_f32 v67, v76, v77
	global_store_dwordx4 v[128:129], v[64:67], off sc1
	global_load_dwordx4 v[68:71], v[216:217], off offset:528
	global_load_dwordx4 v[84:87], v[216:217], off offset:512
	global_load_dwordx4 v[76:79], v[214:215], off offset:528
	global_load_dwordx4 v[92:95], v[214:215], off offset:512
	global_load_dwordx4 v[130:133], v[218:219], off offset:256
	global_load_dwordx4 v[134:137], v[224:225], off offset:256
	global_load_dwordx4 v[138:141], v[228:229], off offset:256
	global_load_dwordx4 v[210:213], v[230:231], off offset:256
	s_waitcnt vmcnt(0)
	v_lshlrev_b32_e32 v125, 16, v130
	v_and_b32_e32 v127, 0xffff0000, v130
	v_lshlrev_b32_e32 v130, 16, v131
	v_and_b32_e32 v131, 0xffff0000, v131
	v_lshlrev_b32_e32 v142, 16, v132
	v_and_b32_e32 v143, 0xffff0000, v132
	v_lshlrev_b32_e32 v153, 16, v133
	v_and_b32_e32 v155, 0xffff0000, v133
	v_sub_f32_e32 v131, v131, v208
	v_sub_f32_e32 v130, v130, v208
	v_sub_f32_e32 v133, v127, v208
	v_sub_f32_e32 v132, v125, v208
	v_pk_mul_f32 v[132:133], v[206:207], v[132:133] op_sel_hi:[0,1]
	v_pk_mul_f32 v[130:131], v[206:207], v[130:131] op_sel_hi:[0,1]
	v_pk_fma_f32 v[130:131], v[86:87], v[130:131], v[94:95]
	v_pk_fma_f32 v[132:133], v[84:85], v[132:133], v[92:93]
	v_pk_mul_f32 v[130:131], v[176:177], v[130:131] op_sel_hi:[0,1]
	v_pk_mul_f32 v[132:133], v[176:177], v[132:133] op_sel_hi:[0,1]
	v_pk_fma_f32 v[62:63], v[62:63], v[174:175], v[130:131] op_sel_hi:[1,0,1]
	v_pk_fma_f32 v[60:61], v[60:61], v[174:175], v[132:133] op_sel_hi:[1,0,1]
	v_sub_f32_e32 v131, v155, v208
	v_sub_f32_e32 v130, v153, v208
	v_sub_f32_e32 v133, v143, v208
	v_sub_f32_e32 v132, v142, v208
	v_pk_mul_f32 v[132:133], v[206:207], v[132:133] op_sel_hi:[0,1]
	v_pk_mul_f32 v[130:131], v[206:207], v[130:131] op_sel_hi:[0,1]
	v_pk_fma_f32 v[130:131], v[70:71], v[130:131], v[78:79]
	v_pk_fma_f32 v[132:133], v[68:69], v[132:133], v[76:77]
	v_pk_mul_f32 v[130:131], v[176:177], v[130:131] op_sel_hi:[0,1]
	v_pk_mul_f32 v[132:133], v[176:177], v[132:133] op_sel_hi:[0,1]
	v_pk_fma_f32 v[130:131], v[58:59], v[174:175], v[130:131] op_sel_hi:[1,0,1]
	v_pk_fma_f32 v[58:59], v[56:57], v[174:175], v[132:133] op_sel_hi:[1,0,1]
	v_cvt_pk_bf16_f32 v57, v62, v63
	v_cvt_pk_bf16_f32 v56, v60, v61
	v_and_b32_e32 v125, 0xffff0000, v134
	v_cvt_pk_bf16_f32 v58, v58, v59
	v_cvt_pk_bf16_f32 v59, v130, v131
	global_store_dwordx4 v[232:233], v[56:59], off offset:256 sc1
	v_and_b32_e32 v63, 0xffff0000, v59
	v_and_b32_e32 v62, 0xffff0000, v58
	v_lshlrev_b32_e32 v61, 16, v59
	v_lshlrev_b32_e32 v60, 16, v58
	v_pk_mul_f32 v[58:59], v[62:63], v[62:63]
	v_lshlrev_b32_e32 v127, 16, v135
	v_pk_fma_f32 v[58:59], v[60:61], v[60:61], v[58:59]
	v_and_b32_e32 v130, 0xffff0000, v135
	v_pk_add_f32 v[58:59], v[58:59], v[58:59] op_sel_hi:[0,1]
	v_lshlrev_b32_e32 v58, 16, v134
	v_sub_f32_e32 v131, v130, v204
	v_sub_f32_e32 v130, v127, v204
	v_sub_f32_e32 v133, v125, v204
	v_sub_f32_e32 v132, v58, v204
	v_pk_mul_f32 v[132:133], v[202:203], v[132:133] op_sel_hi:[0,1]
	v_pk_mul_f32 v[130:131], v[202:203], v[130:131] op_sel_hi:[0,1]
	v_pk_fma_f32 v[130:131], v[86:87], v[130:131], v[94:95]
	v_pk_fma_f32 v[132:133], v[84:85], v[132:133], v[92:93]
	v_lshlrev_b32_e32 v134, 16, v136
	v_and_b32_e32 v135, 0xffff0000, v136
	v_lshlrev_b32_e32 v136, 16, v137
	v_and_b32_e32 v137, 0xffff0000, v137
	v_pk_mul_f32 v[132:133], v[176:177], v[132:133] op_sel_hi:[0,1]
	v_pk_mul_f32 v[130:131], v[176:177], v[130:131] op_sel_hi:[0,1]
	v_pk_fma_f32 v[54:55], v[54:55], v[174:175], v[130:131] op_sel_hi:[1,0,1]
	v_pk_fma_f32 v[52:53], v[52:53], v[174:175], v[132:133] op_sel_hi:[1,0,1]
	v_sub_f32_e32 v131, v137, v204
	v_sub_f32_e32 v130, v136, v204
	v_sub_f32_e32 v133, v135, v204
	v_sub_f32_e32 v132, v134, v204
	v_pk_mul_f32 v[132:133], v[202:203], v[132:133] op_sel_hi:[0,1]
	v_pk_mul_f32 v[130:131], v[202:203], v[130:131] op_sel_hi:[0,1]
	v_pk_fma_f32 v[130:131], v[70:71], v[130:131], v[78:79]
	v_pk_fma_f32 v[132:133], v[68:69], v[132:133], v[76:77]
	v_pk_mul_f32 v[130:131], v[176:177], v[130:131] op_sel_hi:[0,1]
; __device__ __forceinline__ unsigned cvt_pk_bf16(float lo, float hi) { unsigned r; asm("v_cvt_pk_bf16_f32 %0, %1, %2" : "=v"(r) : "v"(lo), "v"(hi)); return r; }
; __device__ __forceinline__ float bf_lo(unsigned w) { return __uint_as_float(w << 16); }
; __device__ __forceinline__ float bf_hi(unsigned w) { return __uint_as_float(w & 0xffff0000u); }
;     __device__ __forceinline__ void operator()(const f32x4 (&acc)[2][2][4][2], const Unit& u, int wr, int wc, int fr_in, int fq_in) const {
;     ...
;                 for (int m = 0; m < 4; ++m) { const size_t off = (size_t)(row0 + ai * HALF + m * 16) * 1024 + col0 + bj * HALF; f32x4 b[2];
;                     if constexpr (BASE == 0) { b[0] = pf[m][0]; b[1] = pf[m][1]; }
;                     else { const u32x4 pw = pb[m]; b[0] = (f32x4){bf_lo(pw.x), bf_hi(pw.x), bf_lo(pw.y), bf_hi(pw.y)}; b[1] = (f32x4){bf_lo(pw.z), bf_hi(pw.z), bf_lo(pw.w), bf_hi(pw.w)}; }
;                     f32x4 z[2];
; #pragma unroll
;                     for (int n = 0; n < 2; ++n) { if constexpr (BASE == 1) b[n] = (b[n] - rst.mu[ai][m]) * rst.rs[ai][m] * gv[n] + bv[n];
;                         z[n] = b[n] * al_ + acc[ai][bj][m][n] * s_; }
;                     u32x4 w; w.x = cvt_pk_bf16(z[0][0], z[0][1]); w.y = cvt_pk_bf16(z[0][2], z[0][3]); w.z = cvt_pk_bf16(z[1][0], z[1][1]); w.w = cvt_pk_bf16(z[1][2], z[1][3]);
;                     *(u32x4*)(zb + off) = w;
	v_pk_mul_f32 v[132:133], v[176:177], v[132:133] op_sel_hi:[0,1]
	v_pk_fma_f32 v[130:131], v[50:51], v[174:175], v[130:131] op_sel_hi:[1,0,1]
	v_pk_fma_f32 v[50:51], v[48:49], v[174:175], v[132:133] op_sel_hi:[1,0,1]
	v_cvt_pk_bf16_f32 v48, v52, v53
	v_cvt_pk_bf16_f32 v49, v54, v55
	v_lshlrev_b32_e32 v54, 16, v138
	v_and_b32_e32 v55, 0xffff0000, v138
	v_lshlrev_b32_e32 v52, 16, v139
	v_and_b32_e32 v53, 0xffff0000, v139
	v_sub_f32_e32 v53, v53, v200
	v_sub_f32_e32 v52, v52, v200
	v_sub_f32_e32 v55, v55, v200
	v_sub_f32_e32 v54, v54, v200
	v_pk_mul_f32 v[54:55], v[198:199], v[54:55] op_sel_hi:[0,1]
	v_pk_mul_f32 v[52:53], v[198:199], v[52:53] op_sel_hi:[0,1]
	v_pk_fma_f32 v[52:53], v[86:87], v[52:53], v[94:95]
	v_pk_fma_f32 v[54:55], v[84:85], v[54:55], v[92:93]
	v_cvt_pk_bf16_f32 v50, v50, v51
	v_cvt_pk_bf16_f32 v51, v130, v131
	global_store_dwordx4 v[116:117], v[48:51], off offset:256 sc1
	v_lshlrev_b32_e32 v58, 16, v140
	v_and_b32_e32 v116, 0xffff0000, v140
	v_lshlrev_b32_e32 v117, 16, v141
	v_and_b32_e32 v125, 0xffff0000, v141
	v_pk_mul_f32 v[54:55], v[176:177], v[54:55] op_sel_hi:[0,1]
	v_pk_mul_f32 v[52:53], v[176:177], v[52:53] op_sel_hi:[0,1]
	v_pk_fma_f32 v[46:47], v[46:47], v[174:175], v[52:53] op_sel_hi:[1,0,1]
	v_pk_fma_f32 v[44:45], v[44:45], v[174:175], v[54:55] op_sel_hi:[1,0,1]
	v_sub_f32_e32 v53, v125, v200
	v_sub_f32_e32 v52, v117, v200
	v_sub_f32_e32 v55, v116, v200
	v_sub_f32_e32 v54, v58, v200
	v_pk_mul_f32 v[54:55], v[198:199], v[54:55] op_sel_hi:[0,1]
	v_pk_mul_f32 v[52:53], v[198:199], v[52:53] op_sel_hi:[0,1]
	v_pk_fma_f32 v[52:53], v[70:71], v[52:53], v[78:79]
	v_pk_fma_f32 v[54:55], v[68:69], v[54:55], v[76:77]
	v_pk_mul_f32 v[52:53], v[176:177], v[52:53] op_sel_hi:[0,1]
	v_pk_mul_f32 v[54:55], v[176:177], v[54:55] op_sel_hi:[0,1]
	v_pk_fma_f32 v[52:53], v[42:43], v[174:175], v[52:53] op_sel_hi:[1,0,1]
	v_pk_fma_f32 v[42:43], v[40:41], v[174:175], v[54:55] op_sel_hi:[1,0,1]
	v_cvt_pk_bf16_f32 v40, v44, v45
	v_cvt_pk_bf16_f32 v41, v46, v47
	v_lshlrev_b32_e32 v46, 16, v210
	v_and_b32_e32 v47, 0xffff0000, v210
	v_lshlrev_b32_e32 v44, 16, v211
	v_and_b32_e32 v45, 0xffff0000, v211
	v_sub_f32_e32 v45, v45, v196
	v_sub_f32_e32 v44, v44, v196
	v_sub_f32_e32 v47, v47, v196
	v_sub_f32_e32 v46, v46, v196
	v_pk_mul_f32 v[46:47], v[194:195], v[46:47] op_sel_hi:[0,1]
	v_pk_mul_f32 v[44:45], v[194:195], v[44:45] op_sel_hi:[0,1]
	v_pk_fma_f32 v[44:45], v[86:87], v[44:45], v[94:95]
	v_pk_fma_f32 v[46:47], v[84:85], v[46:47], v[92:93]
	v_cvt_pk_bf16_f32 v42, v42, v43
	v_cvt_pk_bf16_f32 v43, v52, v53
	v_lshlrev_b32_e32 v52, 16, v212
	v_and_b32_e32 v53, 0xffff0000, v212
	v_lshlrev_b32_e32 v54, 16, v213
	v_and_b32_e32 v55, 0xffff0000, v213
	v_pk_mul_f32 v[46:47], v[176:177], v[46:47] op_sel_hi:[0,1]
	v_pk_mul_f32 v[44:45], v[176:177], v[44:45] op_sel_hi:[0,1]
	v_pk_fma_f32 v[38:39], v[38:39], v[174:175], v[44:45] op_sel_hi:[1,0,1]
	v_pk_fma_f32 v[36:37], v[36:37], v[174:175], v[46:47] op_sel_hi:[1,0,1]
	v_sub_f32_e32 v45, v55, v196
	v_sub_f32_e32 v44, v54, v196
	v_sub_f32_e32 v47, v53, v196
	v_sub_f32_e32 v46, v52, v196
	v_pk_mul_f32 v[46:47], v[194:195], v[46:47] op_sel_hi:[0,1]
	v_pk_mul_f32 v[44:45], v[194:195], v[44:45] op_sel_hi:[0,1]
	v_pk_fma_f32 v[44:45], v[70:71], v[44:45], v[78:79]
	v_pk_fma_f32 v[46:47], v[68:69], v[46:47], v[76:77]
	v_pk_mul_f32 v[44:45], v[176:177], v[44:45] op_sel_hi:[0,1]
	v_pk_mul_f32 v[46:47], v[176:177], v[46:47] op_sel_hi:[0,1]
	v_pk_fma_f32 v[44:45], v[34:35], v[174:175], v[44:45] op_sel_hi:[1,0,1]
	v_pk_fma_f32 v[34:35], v[32:33], v[174:175], v[46:47] op_sel_hi:[1,0,1]
	global_store_dwordx4 v[108:109], v[40:43], off offset:256 sc1
	v_cvt_pk_bf16_f32 v32, v36, v37
	v_cvt_pk_bf16_f32 v33, v38, v39
	v_cvt_pk_bf16_f32 v34, v34, v35
	v_cvt_pk_bf16_f32 v35, v44, v45
	global_store_dwordx4 v[100:101], v[32:35], off offset:256 sc1
	global_load_dwordx4 v[36:39], v[102:103], off offset:256
	global_load_dwordx4 v[44:47], v[110:111], off offset:256
	global_load_dwordx4 v[52:55], v[148:149], off offset:256
	s_nop 0
	global_load_dwordx4 v[100:103], v[118:119], off offset:256
	v_mov_b32_e32 v165, v59
	s_waitcnt vmcnt(0)
	v_lshlrev_b32_e32 v58, 16, v36
	v_and_b32_e32 v108, 0xffff0000, v36
	v_lshlrev_b32_e32 v36, 16, v37
	v_and_b32_e32 v37, 0xffff0000, v37
	v_lshlrev_b32_e32 v109, 16, v38
	v_and_b32_e32 v110, 0xffff0000, v38
	v_lshlrev_b32_e32 v111, 16, v39
	v_and_b32_e32 v116, 0xffff0000, v39
	v_sub_f32_e32 v37, v37, v192
	v_sub_f32_e32 v36, v36, v192
	v_sub_f32_e32 v39, v108, v192
	v_sub_f32_e32 v38, v58, v192
	v_pk_mul_f32 v[38:39], v[190:191], v[38:39] op_sel_hi:[0,1]
	v_pk_mul_f32 v[36:37], v[190:191], v[36:37] op_sel_hi:[0,1]
	v_pk_fma_f32 v[36:37], v[86:87], v[36:37], v[94:95]
	v_pk_fma_f32 v[38:39], v[84:85], v[38:39], v[92:93]
	v_pk_mul_f32 v[36:37], v[176:177], v[36:37] op_sel_hi:[0,1]
	v_pk_mul_f32 v[38:39], v[176:177], v[38:39] op_sel_hi:[0,1]
	v_pk_fma_f32 v[30:31], v[30:31], v[174:175], v[36:37] op_sel_hi:[1,0,1]
	v_pk_fma_f32 v[28:29], v[28:29], v[174:175], v[38:39] op_sel_hi:[1,0,1]
	v_sub_f32_e32 v37, v116, v192
	v_sub_f32_e32 v36, v111, v192
	v_sub_f32_e32 v39, v110, v192
	v_sub_f32_e32 v38, v109, v192
	v_pk_mul_f32 v[38:39], v[190:191], v[38:39] op_sel_hi:[0,1]
	v_pk_mul_f32 v[36:37], v[190:191], v[36:37] op_sel_hi:[0,1]
	v_pk_fma_f32 v[36:37], v[70:71], v[36:37], v[78:79]
	v_pk_fma_f32 v[38:39], v[68:69], v[38:39], v[76:77]
	v_pk_mul_f32 v[36:37], v[176:177], v[36:37] op_sel_hi:[0,1]
	v_pk_mul_f32 v[38:39], v[176:177], v[38:39] op_sel_hi:[0,1]
	v_pk_fma_f32 v[36:37], v[26:27], v[174:175], v[36:37] op_sel_hi:[1,0,1]
	v_pk_fma_f32 v[26:27], v[24:25], v[174:175], v[38:39] op_sel_hi:[1,0,1]
; __device__ __forceinline__ unsigned cvt_pk_bf16(float lo, float hi) { unsigned r; asm("v_cvt_pk_bf16_f32 %0, %1, %2" : "=v"(r) : "v"(lo), "v"(hi)); return r; }
; __device__ __forceinline__ float bf_lo(unsigned w) { return __uint_as_float(w << 16); }
; __device__ __forceinline__ float bf_hi(unsigned w) { return __uint_as_float(w & 0xffff0000u); }
;     __device__ __forceinline__ void operator()(const f32x4 (&acc)[2][2][4][2], const Unit& u, int wr, int wc, int fr_in, int fq_in) const {
;     ...
;                 for (int m = 0; m < 4; ++m) { const size_t off = (size_t)(row0 + ai * HALF + m * 16) * 1024 + col0 + bj * HALF; f32x4 b[2];
;                     if constexpr (BASE == 0) { b[0] = pf[m][0]; b[1] = pf[m][1]; }
;                     else { const u32x4 pw = pb[m]; b[0] = (f32x4){bf_lo(pw.x), bf_hi(pw.x), bf_lo(pw.y), bf_hi(pw.y)}; b[1] = (f32x4){bf_lo(pw.z), bf_hi(pw.z), bf_lo(pw.w), bf_hi(pw.w)}; }
;                     f32x4 z[2];
; #pragma unroll
;                     for (int n = 0; n < 2; ++n) { if constexpr (BASE == 1) b[n] = (b[n] - rst.mu[ai][m]) * rst.rs[ai][m] * gv[n] + bv[n];
;                         z[n] = b[n] * al_ + acc[ai][bj][m][n] * s_; }
;                     u32x4 w; w.x = cvt_pk_bf16(z[0][0], z[0][1]); w.y = cvt_pk_bf16(z[0][2], z[0][3]); w.z = cvt_pk_bf16(z[1][0], z[1][1]); w.w = cvt_pk_bf16(z[1][2], z[1][3]);
;                     *(u32x4*)(zb + off) = w;
	v_cvt_pk_bf16_f32 v24, v28, v29
	v_cvt_pk_bf16_f32 v25, v30, v31
	v_lshlrev_b32_e32 v30, 16, v44
	v_and_b32_e32 v31, 0xffff0000, v44
	v_lshlrev_b32_e32 v28, 16, v45
	v_and_b32_e32 v29, 0xffff0000, v45
	v_sub_f32_e32 v29, v29, v188
	v_sub_f32_e32 v28, v28, v188
	v_sub_f32_e32 v31, v31, v188
	v_sub_f32_e32 v30, v30, v188
	v_pk_mul_f32 v[30:31], v[186:187], v[30:31] op_sel_hi:[0,1]
	v_pk_mul_f32 v[28:29], v[186:187], v[28:29] op_sel_hi:[0,1]
	v_pk_fma_f32 v[28:29], v[86:87], v[28:29], v[94:95]
	v_pk_fma_f32 v[30:31], v[84:85], v[30:31], v[92:93]
	v_cvt_pk_bf16_f32 v26, v26, v27
	v_cvt_pk_bf16_f32 v27, v36, v37
	v_lshlrev_b32_e32 v36, 16, v46
	v_and_b32_e32 v37, 0xffff0000, v46
	v_lshlrev_b32_e32 v38, 16, v47
	v_and_b32_e32 v39, 0xffff0000, v47
	v_pk_mul_f32 v[30:31], v[176:177], v[30:31] op_sel_hi:[0,1]
	v_pk_mul_f32 v[28:29], v[176:177], v[28:29] op_sel_hi:[0,1]
	v_pk_fma_f32 v[22:23], v[22:23], v[174:175], v[28:29] op_sel_hi:[1,0,1]
	v_pk_fma_f32 v[20:21], v[20:21], v[174:175], v[30:31] op_sel_hi:[1,0,1]
	v_sub_f32_e32 v29, v39, v188
	v_sub_f32_e32 v28, v38, v188
	v_sub_f32_e32 v31, v37, v188
	v_sub_f32_e32 v30, v36, v188
	v_pk_mul_f32 v[30:31], v[186:187], v[30:31] op_sel_hi:[0,1]
	v_pk_mul_f32 v[28:29], v[186:187], v[28:29] op_sel_hi:[0,1]
	v_pk_fma_f32 v[28:29], v[70:71], v[28:29], v[78:79]
	v_pk_fma_f32 v[30:31], v[68:69], v[30:31], v[76:77]
	v_pk_mul_f32 v[28:29], v[176:177], v[28:29] op_sel_hi:[0,1]
	v_pk_mul_f32 v[30:31], v[176:177], v[30:31] op_sel_hi:[0,1]
	v_pk_fma_f32 v[28:29], v[18:19], v[174:175], v[28:29] op_sel_hi:[1,0,1]
	v_pk_fma_f32 v[18:19], v[16:17], v[174:175], v[30:31] op_sel_hi:[1,0,1]
	v_cvt_pk_bf16_f32 v16, v20, v21
	v_cvt_pk_bf16_f32 v17, v22, v23
	v_lshlrev_b32_e32 v22, 16, v52
	v_and_b32_e32 v23, 0xffff0000, v52
	v_lshlrev_b32_e32 v20, 16, v53
	v_and_b32_e32 v21, 0xffff0000, v53
	v_sub_f32_e32 v21, v21, v184
	v_sub_f32_e32 v20, v20, v184
	v_sub_f32_e32 v23, v23, v184
	v_sub_f32_e32 v22, v22, v184
	v_pk_mul_f32 v[22:23], v[182:183], v[22:23] op_sel_hi:[0,1]
	v_pk_mul_f32 v[20:21], v[182:183], v[20:21] op_sel_hi:[0,1]
	v_pk_fma_f32 v[20:21], v[86:87], v[20:21], v[94:95]
	v_pk_fma_f32 v[22:23], v[84:85], v[22:23], v[92:93]
	v_cvt_pk_bf16_f32 v18, v18, v19
	v_cvt_pk_bf16_f32 v19, v28, v29
	v_lshlrev_b32_e32 v28, 16, v54
	v_and_b32_e32 v29, 0xffff0000, v54
	v_lshlrev_b32_e32 v30, 16, v55
	v_and_b32_e32 v31, 0xffff0000, v55
	v_pk_mul_f32 v[22:23], v[176:177], v[22:23] op_sel_hi:[0,1]
	v_pk_mul_f32 v[20:21], v[176:177], v[20:21] op_sel_hi:[0,1]
	v_pk_fma_f32 v[14:15], v[14:15], v[174:175], v[20:21] op_sel_hi:[1,0,1]
	v_pk_fma_f32 v[12:13], v[12:13], v[174:175], v[22:23] op_sel_hi:[1,0,1]
	v_sub_f32_e32 v21, v31, v184
	v_sub_f32_e32 v20, v30, v184
	v_sub_f32_e32 v23, v29, v184
	v_sub_f32_e32 v22, v28, v184
	v_pk_mul_f32 v[22:23], v[182:183], v[22:23] op_sel_hi:[0,1]
	v_pk_mul_f32 v[20:21], v[182:183], v[20:21] op_sel_hi:[0,1]
	v_pk_fma_f32 v[20:21], v[70:71], v[20:21], v[78:79]
	v_pk_fma_f32 v[22:23], v[68:69], v[22:23], v[76:77]
	v_pk_mul_f32 v[20:21], v[176:177], v[20:21] op_sel_hi:[0,1]
	v_pk_mul_f32 v[22:23], v[176:177], v[22:23] op_sel_hi:[0,1]
	v_pk_fma_f32 v[20:21], v[10:11], v[174:175], v[20:21] op_sel_hi:[1,0,1]
	v_pk_fma_f32 v[10:11], v[8:9], v[174:175], v[22:23] op_sel_hi:[1,0,1]
	v_cvt_pk_bf16_f32 v8, v12, v13
	v_cvt_pk_bf16_f32 v9, v14, v15
	v_lshlrev_b32_e32 v14, 16, v100
	v_and_b32_e32 v15, 0xffff0000, v100
	v_lshlrev_b32_e32 v12, 16, v101
	v_and_b32_e32 v13, 0xffff0000, v101
	v_sub_f32_e32 v13, v13, v180
	v_sub_f32_e32 v12, v12, v180
	v_sub_f32_e32 v15, v15, v180
	v_sub_f32_e32 v14, v14, v180
	v_pk_mul_f32 v[14:15], v[178:179], v[14:15] op_sel_hi:[0,1]
	v_pk_mul_f32 v[12:13], v[178:179], v[12:13] op_sel_hi:[0,1]
	v_pk_fma_f32 v[12:13], v[86:87], v[12:13], v[94:95]
	v_pk_fma_f32 v[14:15], v[84:85], v[14:15], v[92:93]
	v_cvt_pk_bf16_f32 v10, v10, v11
	v_cvt_pk_bf16_f32 v11, v20, v21
	v_lshlrev_b32_e32 v20, 16, v102
; __device__ __forceinline__ unsigned cvt_pk_bf16(float lo, float hi) { unsigned r; asm("v_cvt_pk_bf16_f32 %0, %1, %2" : "=v"(r) : "v"(lo), "v"(hi)); return r; }
; __device__ __forceinline__ float bf_lo(unsigned w) { return __uint_as_float(w << 16); }
; __device__ __forceinline__ float bf_hi(unsigned w) { return __uint_as_float(w & 0xffff0000u); }
; __device__ __forceinline__ void emit_row_stats(float (&s1)[2][4], float (&s2)[2][4], float* sp_new, const Unit& u, int wr, int wc, int fr, int fq, PG8_LAS unsigned char* xl) {
;     ...
;         for (int m = 0; m < 4; ++m) { float a = s1[ai][m], b = s2[ai][m]; a += __shfl_xor(a, 16); b += __shfl_xor(b, 16); a += __shfl_xor(a, 32); b += __shfl_xor(b, 32);
;             if (fq == 0) P[(ai * HALF + wr * 64 + m * 16 + fr) * 4 + wc] = (f32x2v){a, b}; }
;     __device__ __forceinline__ void operator()(const f32x4 (&acc)[2][2][4][2], const Unit& u, int wr, int wc, int fr_in, int fq_in) const {
;     ...
;                     for (int n = 0; n < 2; ++n) { if constexpr (BASE == 1) b[n] = (b[n] - rst.mu[ai][m]) * rst.rs[ai][m] * gv[n] + bv[n];
;                         z[n] = b[n] * al_ + acc[ai][bj][m][n] * s_; }
;                     u32x4 w; w.x = cvt_pk_bf16(z[0][0], z[0][1]); w.y = cvt_pk_bf16(z[0][2], z[0][3]); w.z = cvt_pk_bf16(z[1][0], z[1][1]); w.w = cvt_pk_bf16(z[1][2], z[1][3]);
;                     *(u32x4*)(zb + off) = w;
;                     const float r0 = bf_lo(w.x), r1 = bf_hi(w.x), r2 = bf_lo(w.y), r3 = bf_hi(w.y), r4 = bf_lo(w.z), r5 = bf_hi(w.z), r6 = bf_lo(w.w), r7 = bf_hi(w.w);
;                     s1[ai][m] += ((r0 + r1) + (r2 + r3)) + ((r4 + r5) + (r6 + r7)); s2[ai][m] += ((r0 * r0 + r1 * r1) + (r2 * r2 + r3 * r3)) + ((r4 * r4 + r5 * r5) + (r6 * r6 + r7 * r7)); }
	v_and_b32_e32 v21, 0xffff0000, v102
	v_lshlrev_b32_e32 v22, 16, v103
	v_and_b32_e32 v23, 0xffff0000, v103
	v_pk_mul_f32 v[14:15], v[176:177], v[14:15] op_sel_hi:[0,1]
	v_pk_mul_f32 v[12:13], v[176:177], v[12:13] op_sel_hi:[0,1]
	v_pk_fma_f32 v[6:7], v[6:7], v[174:175], v[12:13] op_sel_hi:[1,0,1]
	v_pk_fma_f32 v[4:5], v[4:5], v[174:175], v[14:15] op_sel_hi:[1,0,1]
	v_sub_f32_e32 v13, v23, v180
	v_sub_f32_e32 v12, v22, v180
	v_sub_f32_e32 v15, v21, v180
	v_sub_f32_e32 v14, v20, v180
	v_pk_mul_f32 v[14:15], v[178:179], v[14:15] op_sel_hi:[0,1]
	v_pk_mul_f32 v[12:13], v[178:179], v[12:13] op_sel_hi:[0,1]
	v_pk_fma_f32 v[12:13], v[70:71], v[12:13], v[78:79]
	v_pk_fma_f32 v[14:15], v[68:69], v[14:15], v[76:77]
	v_pk_mul_f32 v[12:13], v[176:177], v[12:13] op_sel_hi:[0,1]
	v_pk_mul_f32 v[14:15], v[176:177], v[14:15] op_sel_hi:[0,1]
	v_pk_fma_f32 v[12:13], v[2:3], v[174:175], v[12:13] op_sel_hi:[1,0,1]
	v_pk_fma_f32 v[2:3], v[0:1], v[174:175], v[14:15] op_sel_hi:[1,0,1]
	v_cvt_pk_bf16_f32 v0, v4, v5
	v_and_b32_e32 v5, 64, v195
	v_xor_b32_e32 v4, 16, v195
	v_add_u32_e32 v5, 64, v5
	v_cmp_lt_i32_e32 vcc, v4, v5
	v_cvt_pk_bf16_f32 v2, v2, v3
	v_cvt_pk_bf16_f32 v3, v12, v13
	v_cvt_pk_bf16_f32 v1, v6, v7
	v_and_b32_e32 v21, 0xffff0000, v56
	v_and_b32_e32 v20, 0xffff0000, v121
	v_cndmask_b32_e32 v4, v195, v4, vcc
	v_lshlrev_b32_e32 v13, 2, v4
	v_xor_b32_e32 v4, 32, v195
	v_cmp_lt_i32_e32 vcc, v4, v5
	v_lshlrev_b32_e32 v5, 16, v56
	v_mov_b32_e32 v155, v5
	v_cndmask_b32_e32 v4, v195, v4, vcc
	v_lshlrev_b32_e32 v12, 2, v4
	v_lshlrev_b32_e32 v4, 16, v120
	v_pk_mul_f32 v[6:7], v[4:5], v[4:5]
	v_pk_mul_f32 v[14:15], v[154:155], v[154:155]
	v_mov_b32_e32 v153, v21
	v_pk_mov_b32 v[54:55], v[4:5], v[6:7] op_sel:[1,0]
	v_pk_add_f32 v[4:5], v[4:5], v[154:155]
	v_pk_mul_f32 v[22:23], v[152:153], v[152:153]
	v_pk_mul_f32 v[28:29], v[20:21], v[20:21]
	v_lshlrev_b32_e32 v30, 16, v122
	v_lshlrev_b32_e32 v31, 16, v57
	v_and_b32_e32 v45, 0xffff0000, v57
	v_and_b32_e32 v44, 0xffff0000, v123
	v_pk_mov_b32 v[14:15], v[20:21], v[14:15] op_sel:[1,0]
	v_mov_b32_e32 v5, v7
	v_pk_add_f32 v[6:7], v[20:21], v[152:153]
	v_mov_b32_e32 v127, v31
	v_mov_b32_e32 v125, v45
	v_pk_add_f32 v[14:15], v[54:55], v[14:15]
	v_pk_mov_b32 v[22:23], v[30:31], v[22:23] op_sel:[1,0]
	v_pk_mov_b32 v[54:55], v[44:45], v[28:29] op_sel:[1,0]
	v_mov_b32_e32 v7, v29
	v_pk_mul_f32 v[36:37], v[30:31], v[30:31]
	v_pk_mul_f32 v[38:39], v[126:127], v[126:127]
	v_pk_mul_f32 v[46:47], v[124:125], v[124:125]
	v_pk_mul_f32 v[52:53], v[44:45], v[44:45]
	v_pk_add_f32 v[22:23], v[22:23], v[54:55]
	v_pk_add_f32 v[4:5], v[4:5], v[6:7]
	v_pk_add_f32 v[6:7], v[30:31], v[126:127]
	v_pk_add_f32 v[20:21], v[44:45], v[124:125]
	v_pk_add_f32 v[14:15], v[14:15], v[22:23]
	v_mov_b32_e32 v22, v60
	v_mov_b32_e32 v23, v36
	v_mov_b32_e32 v54, v62
	v_mov_b32_e32 v55, v38
	v_pk_mov_b32 v[38:39], v[60:61], v[46:47] op_sel:[1,0]
	v_pk_mov_b32 v[46:47], v[62:63], v[52:53] op_sel:[1,0]
	v_mov_b32_e32 v7, v37
	v_mov_b32_e32 v21, v53
	v_pk_add_f32 v[22:23], v[22:23], v[54:55]
	v_pk_add_f32 v[38:39], v[38:39], v[46:47]
	v_pk_add_f32 v[6:7], v[6:7], v[20:21]
	v_pk_add_f32 v[22:23], v[22:23], v[38:39]
	v_pk_add_f32 v[4:5], v[4:5], v[6:7]
	v_pk_add_f32 v[14:15], v[14:15], v[22:23]
	v_pk_add_f32 v[4:5], v[4:5], v[164:165]
	global_store_dwordx4 v[144:145], v[24:27], off offset:256 sc1
	v_pk_add_f32 v[4:5], v[14:15], v[4:5]
	ds_bpermute_b32 v6, v13, v4
	ds_bpermute_b32 v7, v13, v5
	global_store_dwordx4 v[146:147], v[16:19], off offset:256 sc1
	global_store_dwordx4 v[150:151], v[8:11], off offset:256 sc1
	global_store_dwordx4 v[128:129], v[0:3], off offset:256 sc1
	s_waitcnt lgkmcnt(0)
	v_pk_add_f32 v[4:5], v[4:5], v[6:7]
	ds_bpermute_b32 v6, v12, v4
	ds_bpermute_b32 v7, v12, v5
	v_cmp_eq_u32_e32 vcc, 0, v203
	v_lshl_add_u32 v14, v199, 5, s66
	s_and_saveexec_b64 s[8:9], vcc
	s_cbranch_execz .LBB0_1177
	s_waitcnt lgkmcnt(0)
	v_pk_add_f32 v[4:5], v[4:5], v[6:7]
	ds_write_b64 v14, v[4:5]

; __device__ __forceinline__ void emit_row_stats(float (&s1)[2][4], float (&s2)[2][4], float* sp_new, const Unit& u, int wr, int wc, int fr, int fq, PG8_LAS unsigned char* xl) {
;     ...
;     asm volatile("s_waitcnt lgkmcnt(0)" ::: "memory"); __builtin_amdgcn_s_barrier(); asm volatile("" ::: "memory");
;     const int tid = (wr * 4 + wc) * 64 + fq * 16 + fr;
;     if (tid < 256) { const f32x2v a = P[tid * 4 + 0], b = P[tid * 4 + 1], c = P[tid * 4 + 2], d = P[tid * 4 + 3];
;         f32x2v o; o.x = (a.x + b.x) + (c.x + d.x); o.y = (a.y + b.y) + (c.y + d.y);
;         *(f32x2v*)(sp_new + ((size_t)(u.pm * BM + tid) * 4 + u.pn) * 2) = o; }
.LBB0_1191:
	s_or_b64 exec, exec, s[8:9]
	s_waitcnt lgkmcnt(0)
	s_barrier
	v_lshlrev_b32_e32 v0, 4, v203
	v_add3_u32 v0, s21, v199, v0
	s_movk_i32 s8, 0x100
	v_cmp_gt_i32_e32 vcc, s8, v0
	s_and_saveexec_b64 s[48:49], vcc
	s_cbranch_execz .LBB0_1193
	v_lshl_add_u32 v1, v0, 5, 0
	v_add_u32_e32 v1, 0x20400, v1
	s_waitcnt lgkmcnt(0)
	ds_read_b128 v[2:5], v1
	ds_read_b128 v[6:9], v1 offset:16
	v_add_u32_e32 v0, s11, v0
	v_ashrrev_i32_e32 v1, 31, v0
	v_lshlrev_b64 v[0:1], 5, v[0:1]
	s_waitcnt lgkmcnt(1)
	v_pk_add_f32 v[2:3], v[2:3], v[4:5]
	s_waitcnt lgkmcnt(0)
	v_pk_add_f32 v[4:5], v[6:7], v[8:9]
	s_ashr_i32 s11, s10, 31
	v_lshl_add_u64 v[0:1], s[26:27], 0, v[0:1]
	v_pk_add_f32 v[2:3], v[2:3], v[4:5]
	v_lshl_add_u64 v[0:1], s[10:11], 3, v[0:1]
	global_store_dwordx2 v[0:1], v[2:3], off sc1

; __device__ __forceinline__ unsigned xb_add(unsigned* p, unsigned v) { return __hip_atomic_fetch_add(p, v, __ATOMIC_RELAXED, __HIP_MEMORY_SCOPE_AGENT); }
; __device__ __forceinline__ void xcd_barrier(const XcdBarrier& b) {
;     ...
;         const unsigned old = xb_add(&bar[XB_XSUB(b.x)], 1u);
;         const unsigned gen = old / nloc;
;         if (old + 1u == (gen + 1u) * nloc) {
;             __builtin_amdgcn_fence(__ATOMIC_RELEASE, "agent");
;             asm volatile("s_waitcnt vmcnt(0)" ::: "memory");
;             const unsigned og = xb_add(&bar[XB_TOP], 1u);
.LBB0_1227:
	s_andn2_saveexec_b64 s[6:7], s[6:7]
	s_cbranch_execz .LBB0_1245
	s_mov_b64 s[6:7], exec
	s_waitcnt lgkmcnt(0)
	s_waitcnt vmcnt(0)
	v_mbcnt_lo_u32_b32 v1, s6, 0
	v_mbcnt_hi_u32_b32 v1, s7, v1
	v_cmp_eq_u32_e32 vcc, 0, v1
	s_and_saveexec_b64 s[8:9], vcc
	s_cbranch_execz .LBB0_1230
	s_bcnt1_i32_b64 s3, s[6:7]
	v_readlane_b32 s6, v255, 48
	v_mov_b32_e32 v2, 0
	v_mov_b32_e32 v3, s3
	v_readlane_b32 s7, v255, 49
	s_nop 4
	global_atomic_add v2, v2, v3, s[6:7] sc0

; __device__ __forceinline__ float fast_sigmoid(float v) { return __builtin_amdgcn_rcpf(1.0f + __builtin_amdgcn_exp2f(-1.4426950408889634f * v)); }
; __device__ __forceinline__ f32x4 ln_fix(const f32x4& a, float mu, float rs, const f32x4& cs, const f32x4& cb) { return (a - cs * mu) * rs + cb; }
; __device__ __forceinline__ void load_row_stats(const float* sp, int row0, RowStats& r) {
;     ...
;         for (int m = 0; m < 4; ++m) { const float* p = sp + (size_t)(row0 + ai * HALF + m * 16) * 8; const f32x4 a = *(const f32x4*)p, b = *(const f32x4*)(p + 4);
;             const float s1 = (a[0] + a[2]) + (b[0] + b[2]), s2 = (a[1] + a[3]) + (b[1] + b[3]); const float mu = s1 * (1.f / 1024.f); const float var = s2 * (1.f / 1024.f) - mu * mu;
;             r.mu[ai][m] = mu; r.rs[ai][m] = __builtin_amdgcn_rsqf(__builtin_fmaxf(var, 0.f) + 1e-5f); } }
;     __device__ __forceinline__ void operator()(const f32x4 (&acc)[2][2][4][2], const Unit& u, int wr, int wc, int fr_in, int fq_in) const {
;     ...
;         const int row0 = u.pm * BM + wr * 64 + fr, n0 = u.pn * BM + wc * 32 + 8 * fq; const int kt = u.pn * 2 + (wc >> 1), cin = (wc & 1) * 32 + 8 * fq;
;         RowStats rst; f32x4 csv[2][2], cbv[2][2];
;         if constexpr (LN) { load_row_stats(sp, row0, rst);
; #pragma unroll
;             for (int bj = 0; bj < 2; ++bj)
; #pragma unroll
;                 for (int n = 0; n < 2; ++n) { csv[bj][n] = *(const f32x4*)(cs + n0 + bj * HALF + 4 * n); cbv[bj][n] = *(const f32x4*)(cb + n0 + bj * HALF + 4 * n); } }
; #pragma unroll
;         for (int ai = 0; ai < 2; ++ai)
; #pragma unroll
;             for (int m = 0; m < 4; ++m) { bf16_t* rowp = H + ((size_t)kt * mrows + (row0 + ai * HALF + m * 16)) * 64 + cin;
;                 float h[8];
; #pragma unroll
;                 for (int n = 0; n < 2; ++n) { f32x4 g = acc[ai][0][m][n], uu = acc[ai][1][m][n];
;                     if constexpr (LN) { g = ln_fix(g, rst.mu[ai][m], rst.rs[ai][m], csv[0][n], cbv[0][n]); uu = ln_fix(uu, rst.mu[ai][m], rst.rs[ai][m], csv[1][n], cbv[1][n]); }
; #pragma unroll
;                     for (int j = 0; j < 4; ++j) h[4 * n + j] = g[j] * fast_sigmoid(g[j]) * uu[j]; }
.Lrs2_skip:
	s_waitcnt vmcnt(0) lgkmcnt(0)
	s_barrier
	v_and_b32_e32 v116, 0xff, v192
	v_lshlrev_b32_e32 v116, 3, v116
	v_add_u32_e32 v116, 0x22400, v116
	ds_read_b64 v[226:227], v116
	ds_read_b64 v[220:221], v116 offset:128
	ds_read_b64 v[214:215], v116 offset:256
	ds_read_b64 v[200:201], v116 offset:384
	ds_read_b64 v[194:195], v116 offset:1024
	ds_read_b64 v[186:187], v116 offset:1152
	ds_read_b64 v[180:181], v116 offset:1280
	ds_read_b64 v[176:177], v116 offset:1408
	s_cmp_lg_u32 s99, 0
	s_waitcnt lgkmcnt(0)
	v_add_u32_e32 v224, 16, v192
	v_ashrrev_i32_e32 v225, 31, v224
	v_add_u32_e32 v218, 32, v192
	v_ashrrev_i32_e32 v219, 31, v218
	v_add_u32_e32 v212, 48, v192
	v_ashrrev_i32_e32 v213, 31, v212
	v_add_u32_e32 v204, 0x80, v192
	v_ashrrev_i32_e32 v205, 31, v204
	v_add_u32_e32 v196, 0x90, v192
	v_ashrrev_i32_e32 v197, 31, v196
	v_add_u32_e32 v188, 0xa0, v192
	v_ashrrev_i32_e32 v189, 31, v188
	v_add_u32_e32 v182, 0xb0, v192
	v_ashrrev_i32_e32 v183, 31, v182
	s_lshl_b32 s35, s45, 8
	s_or_b32 s35, s35, s55
	v_lshlrev_b32_e32 v206, 3, v112
	v_add_u32_e32 v112, s35, v206
	s_lshl_b32 s35, s45, 1
	s_or_b32 s44, s35, s59
	s_ashr_i32 s45, s44, 31
	s_lshl_b64 s[44:45], s[44:45], 15
	v_lshl_add_u64 v[192:193], s[44:45], 0, v[192:193]
	v_lshlrev_b64 v[192:193], 7, v[192:193]
	v_add_u32_e32 v230, s60, v206
	v_lshl_add_u64 v[232:233], s[6:7], 0, v[192:193]
	v_mov_b32_e32 v192, v144
	v_mov_b32_e32 v193, v140
	v_mov_b32_e32 v140, v145
	v_ashrrev_i32_e32 v231, 31, v230
	v_fma_f32 v113, -v226, v226, v227
	v_max_f32_e32 v113, 0, v113
	v_add_f32_e32 v113, 0x3727c5ac, v113
	v_rsq_f32_e32 v228, v113
	v_fma_f32 v113, -v220, v220, v221
	v_max_f32_e32 v113, 0, v113
	v_add_f32_e32 v113, 0x3727c5ac, v113
	v_rsq_f32_e32 v222, v113
	v_fma_f32 v113, -v214, v214, v215
	v_max_f32_e32 v113, 0, v113
	v_add_f32_e32 v113, 0x3727c5ac, v113
	v_rsq_f32_e32 v216, v113
	v_fma_f32 v113, -v200, v200, v201
	v_max_f32_e32 v113, 0, v113
	v_add_f32_e32 v113, 0x3727c5ac, v113
	v_rsq_f32_e32 v202, v113
	v_fma_f32 v113, -v194, v194, v195
	v_max_f32_e32 v113, 0, v113
	v_add_f32_e32 v113, 0x3727c5ac, v113
	v_rsq_f32_e32 v198, v113
	v_fma_f32 v113, -v186, v186, v187
	v_max_f32_e32 v113, 0, v113
	v_add_f32_e32 v113, 0x3727c5ac, v113
	v_rsq_f32_e32 v190, v113
	v_fma_f32 v113, -v180, v180, v181
	v_max_f32_e32 v113, 0, v113
	v_add_f32_e32 v113, 0x3727c5ac, v113
	v_rsq_f32_e32 v184, v113
	s_nop 0
	v_fma_f32 v113, -v176, v176, v177
	v_max_f32_e32 v113, 0, v113
	v_add_f32_e32 v113, 0x3727c5ac, v113
	v_rsq_f32_e32 v178, v113
	v_ashrrev_i32_e32 v113, 31, v112
	v_lshlrev_b64 v[112:113], 2, v[112:113]
	v_lshl_add_u64 v[136:137], s[12:13], 0, v[112:113]
	v_lshl_add_u64 v[156:157], s[22:23], 0, v[112:113]
	global_load_dwordx4 v[112:115], v[136:137], off offset:16
	global_load_dwordx4 v[128:131], v[136:137], off
	global_load_dwordx4 v[116:119], v[156:157], off offset:16
	global_load_dwordx4 v[132:135], v[156:157], off
	global_load_dwordx4 v[148:151], v[136:137], off offset:528
	s_nop 0
	global_load_dwordx4 v[136:139], v[136:137], off offset:512
	s_nop 0
	global_load_dwordx4 v[152:155], v[156:157], off offset:528
	s_nop 0
	global_load_dwordx4 v[156:159], v[156:157], off offset:512
	s_waitcnt vmcnt(0)
	v_mov_b32_e32 v207, v128
	v_mov_b32_e32 v211, v131
	v_mov_b32_e32 v206, v136
	v_pk_fma_f32 v[208:209], v[226:227], v[206:207], v[192:193] op_sel_hi:[0,1,1] neg_lo:[1,0,0] neg_hi:[1,0,0]
	v_mov_b32_e32 v192, v156
	v_mov_b32_e32 v193, v132
	v_pk_fma_f32 v[208:209], v[228:229], v[208:209], v[192:193] op_sel_hi:[0,1,1]
	v_mul_f32_e32 v132, 0xbfb8aa3b, v209
	v_exp_f32_e32 v132, v132
	v_mov_b32_e32 v156, v138
	v_mov_b32_e32 v210, v139
	v_add_f32_e32 v132, 1.0, v132
	v_rcp_f32_e32 v132, v132
	s_nop 0
	v_mul_f32_e32 v132, v209, v132
	v_mul_f32_e32 v223, v208, v132
	v_mov_b32_e32 v208, v137
	v_mov_b32_e32 v209, v129
	v_pk_fma_f32 v[140:141], v[226:227], v[208:209], v[140:141] op_sel_hi:[0,1,1] neg_lo:[1,0,0] neg_hi:[1,0,0]
	v_mov_b32_e32 v132, v157
	v_pk_fma_f32 v[140:141], v[228:229], v[140:141], v[132:133] op_sel_hi:[0,1,1]
	v_mul_f32_e32 v144, 0xbfb8aa3b, v141
	v_exp_f32_e32 v144, v144
	v_mov_b32_e32 v157, v130
	v_add_f32_e32 v144, 1.0, v144
	v_rcp_f32_e32 v144, v144
	s_nop 0
	v_mul_f32_e32 v141, v141, v144
	v_mul_f32_e32 v229, v140, v141
	v_mov_b32_e32 v140, v146
	v_mov_b32_e32 v141, v142
	v_pk_fma_f32 v[144:145], v[226:227], v[156:157], v[140:141] op_sel_hi:[0,1,1] neg_lo:[1,0,0] neg_hi:[1,0,0]
	v_mov_b32_e32 v140, v158
	v_mov_b32_e32 v141, v134
	v_pk_fma_f32 v[144:145], v[228:229], v[144:145], v[140:141] op_sel_hi:[0,1,1]
	v_mul_f32_e32 v134, 0xbfb8aa3b, v145
	v_exp_f32_e32 v134, v134
	v_mov_b32_e32 v142, v147
	v_pk_fma_f32 v[142:143], v[226:227], v[210:211], v[142:143] op_sel_hi:[0,1,1] neg_lo:[1,0,0] neg_hi:[1,0,0]
	v_add_f32_e32 v134, 1.0, v134
	v_rcp_f32_e32 v134, v134
	s_nop 0
	v_mul_f32_e32 v134, v145, v134
	v_mul_f32_e32 v158, v144, v134
	v_mov_b32_e32 v134, v159
	v_pk_fma_f32 v[142:143], v[228:229], v[142:143], v[134:135] op_sel_hi:[0,1,1]
	v_mul_f32_e32 v144, 0xbfb8aa3b, v143
	v_exp_f32_e32 v144, v144
	v_mov_b32_e32 v145, v120
	v_mov_b32_e32 v120, v125
	v_mov_b32_e32 v125, v122
	v_add_f32_e32 v144, 1.0, v144
	v_rcp_f32_e32 v144, v144
	v_mov_b32_e32 v122, v127
	v_mul_f32_e32 v143, v143, v144
	v_mul_f32_e32 v159, v142, v143
	v_mov_b32_e32 v142, v148
	v_mov_b32_e32 v143, v112
	v_mov_b32_e32 v144, v124
	v_pk_fma_f32 v[146:147], v[226:227], v[142:143], v[144:145] op_sel_hi:[0,1,1] neg_lo:[1,0,0] neg_hi:[1,0,0]
	v_mov_b32_e32 v144, v152
	v_mov_b32_e32 v145, v116
	v_pk_fma_f32 v[146:147], v[228:229], v[146:147], v[144:145] op_sel_hi:[0,1,1]
	v_mul_f32_e32 v112, 0xbfb8aa3b, v147
	v_exp_f32_e32 v112, v112
; __device__ __forceinline__ unsigned cvt_pk_bf16(float lo, float hi) { unsigned r; asm("v_cvt_pk_bf16_f32 %0, %1, %2" : "=v"(r) : "v"(lo), "v"(hi)); return r; }
; __device__ __forceinline__ float fast_sigmoid(float v) { return __builtin_amdgcn_rcpf(1.0f + __builtin_amdgcn_exp2f(-1.4426950408889634f * v)); }
; __device__ __forceinline__ f32x4 ln_fix(const f32x4& a, float mu, float rs, const f32x4& cs, const f32x4& cb) { return (a - cs * mu) * rs + cb; }
;     __device__ __forceinline__ void operator()(const f32x4 (&acc)[2][2][4][2], const Unit& u, int wr, int wc, int fr_in, int fq_in) const {
;     ...
;             for (int m = 0; m < 4; ++m) { bf16_t* rowp = H + ((size_t)kt * mrows + (row0 + ai * HALF + m * 16)) * 64 + cin;
;                 float h[8];
; #pragma unroll
;                 for (int n = 0; n < 2; ++n) { f32x4 g = acc[ai][0][m][n], uu = acc[ai][1][m][n];
;                     if constexpr (LN) { g = ln_fix(g, rst.mu[ai][m], rst.rs[ai][m], csv[0][n], cbv[0][n]); uu = ln_fix(uu, rst.mu[ai][m], rst.rs[ai][m], csv[1][n], cbv[1][n]); }
; #pragma unroll
;                     for (int j = 0; j < 4; ++j) h[4 * n + j] = g[j] * fast_sigmoid(g[j]) * uu[j]; }
;                 u32x4 w; w.x = cvt_pk_bf16(h[0], h[1]); w.y = cvt_pk_bf16(h[2], h[3]); w.z = cvt_pk_bf16(h[4], h[5]); w.w = cvt_pk_bf16(h[6], h[7]);
;                 *(u32x4*)rowp = w; }
	v_mov_b32_e32 v116, v153
	v_add_f32_e32 v112, 1.0, v112
	v_rcp_f32_e32 v112, v112
	s_nop 0
	v_mul_f32_e32 v112, v147, v112
	v_mul_f32_e32 v148, v146, v112
	v_mov_b32_e32 v112, v149
	v_pk_fma_f32 v[120:121], v[226:227], v[112:113], v[120:121] op_sel_hi:[0,1,1] neg_lo:[1,0,0] neg_hi:[1,0,0]
	v_pk_fma_f32 v[120:121], v[228:229], v[120:121], v[116:117] op_sel_hi:[0,1,1]
	v_mul_f32_e32 v124, 0xbfb8aa3b, v121
	v_exp_f32_e32 v124, v124
	s_nop 0
	v_add_f32_e32 v124, 1.0, v124
	v_rcp_f32_e32 v124, v124
	s_nop 0
	v_mul_f32_e32 v121, v121, v124
	v_mul_f32_e32 v149, v120, v121
	v_mov_b32_e32 v120, v150
	v_mov_b32_e32 v121, v114
	v_mov_b32_e32 v124, v126
	v_pk_fma_f32 v[146:147], v[226:227], v[120:121], v[124:125] op_sel_hi:[0,1,1] neg_lo:[1,0,0] neg_hi:[1,0,0]
	v_mov_b32_e32 v124, v154
	v_mov_b32_e32 v125, v118
	v_pk_fma_f32 v[146:147], v[228:229], v[146:147], v[124:125] op_sel_hi:[0,1,1]
	v_mul_f32_e32 v114, 0xbfb8aa3b, v147
	v_exp_f32_e32 v114, v114
	v_mov_b32_e32 v118, v155
	v_cvt_pk_bf16_f32 v148, v148, v149
	v_add_f32_e32 v114, 1.0, v114
	v_rcp_f32_e32 v114, v114
	s_nop 0
	v_mul_f32_e32 v114, v147, v114
	v_mul_f32_e32 v150, v146, v114
	v_mov_b32_e32 v114, v151
	v_pk_fma_f32 v[122:123], v[226:227], v[114:115], v[122:123] op_sel_hi:[0,1,1] neg_lo:[1,0,0] neg_hi:[1,0,0]
	v_pk_fma_f32 v[122:123], v[228:229], v[122:123], v[118:119] op_sel_hi:[0,1,1]
	v_mul_f32_e32 v126, 0xbfb8aa3b, v123
	v_exp_f32_e32 v126, v126
	v_cvt_pk_bf16_f32 v146, v223, v229
	v_cvt_pk_bf16_f32 v147, v158, v159
	s_nop 0
	v_add_f32_e32 v126, 1.0, v126
	v_rcp_f32_e32 v126, v126
	s_nop 0
	v_mul_f32_e32 v123, v123, v126
	v_mul_f32_e32 v151, v122, v123
	v_lshlrev_b64 v[122:123], 1, v[230:231]
	v_lshl_add_u64 v[126:127], v[232:233], 0, v[122:123]
	v_cvt_pk_bf16_f32 v149, v150, v151
	global_store_dwordx4 v[126:127], v[146:149], off sc1
	v_lshl_add_u64 v[126:127], s[44:45], 0, v[224:225]
	v_lshlrev_b64 v[126:127], 7, v[126:127]
	v_mov_b32_e32 v146, v108
	v_mov_b32_e32 v147, v104
	v_pk_fma_f32 v[146:147], v[220:221], v[206:207], v[146:147] op_sel_hi:[0,1,1] neg_lo:[1,0,0] neg_hi:[1,0,0]
	v_pk_fma_f32 v[146:147], v[222:223], v[146:147], v[192:193] op_sel_hi:[0,1,1]
	v_mul_f32_e32 v104, 0xbfb8aa3b, v147
	v_exp_f32_e32 v104, v104
	v_lshl_add_u64 v[126:127], s[6:7], 0, v[126:127]
	v_add_f32_e32 v104, 1.0, v104
	v_rcp_f32_e32 v104, v104
	s_nop 0
	v_mul_f32_e32 v104, v147, v104
	v_mul_f32_e32 v108, v146, v104
	v_mov_b32_e32 v104, v109
	v_pk_fma_f32 v[104:105], v[220:221], v[208:209], v[104:105] op_sel_hi:[0,1,1] neg_lo:[1,0,0] neg_hi:[1,0,0]
	v_pk_fma_f32 v[104:105], v[222:223], v[104:105], v[132:133] op_sel_hi:[0,1,1]
	v_mul_f32_e32 v109, 0xbfb8aa3b, v105
	v_exp_f32_e32 v109, v109
	s_nop 0
	v_add_f32_e32 v109, 1.0, v109
	v_rcp_f32_e32 v109, v109
	s_nop 0
	v_mul_f32_e32 v105, v105, v109
	v_mul_f32_e32 v109, v104, v105
	v_mov_b32_e32 v104, v110
	v_mov_b32_e32 v105, v106
	v_pk_fma_f32 v[104:105], v[220:221], v[156:157], v[104:105] op_sel_hi:[0,1,1] neg_lo:[1,0,0] neg_hi:[1,0,0]
	v_pk_fma_f32 v[104:105], v[222:223], v[104:105], v[140:141] op_sel_hi:[0,1,1]
	v_mul_f32_e32 v106, 0xbfb8aa3b, v105
	v_exp_f32_e32 v106, v106
	s_nop 0
	v_add_f32_e32 v106, 1.0, v106
	v_rcp_f32_e32 v106, v106
	s_nop 0
	v_mul_f32_e32 v105, v105, v106
	v_mov_b32_e32 v106, v111
	v_mul_f32_e32 v110, v104, v105
	v_pk_fma_f32 v[104:105], v[220:221], v[210:211], v[106:107] op_sel_hi:[0,1,1] neg_lo:[1,0,0] neg_hi:[1,0,0]
	v_pk_fma_f32 v[104:105], v[222:223], v[104:105], v[134:135] op_sel_hi:[0,1,1]
	v_mul_f32_e32 v106, 0xbfb8aa3b, v105
	v_exp_f32_e32 v106, v106
	s_nop 0
	v_add_f32_e32 v106, 1.0, v106
	v_rcp_f32_e32 v106, v106
	s_nop 0
	v_mul_f32_e32 v105, v105, v106
	v_mul_f32_e32 v106, v104, v105
	v_mov_b32_e32 v104, v100
	v_mov_b32_e32 v105, v96
	v_pk_fma_f32 v[104:105], v[220:221], v[142:143], v[104:105] op_sel_hi:[0,1,1] neg_lo:[1,0,0] neg_hi:[1,0,0]
	v_pk_fma_f32 v[104:105], v[222:223], v[104:105], v[144:145] op_sel_hi:[0,1,1]
	v_mul_f32_e32 v96, 0xbfb8aa3b, v105
	v_exp_f32_e32 v96, v96
	s_nop 0
	v_add_f32_e32 v96, 1.0, v96
	v_rcp_f32_e32 v96, v96
	s_nop 0
	v_mul_f32_e32 v96, v105, v96
	v_mul_f32_e32 v104, v104, v96
	v_mov_b32_e32 v96, v101
	v_pk_fma_f32 v[96:97], v[220:221], v[112:113], v[96:97] op_sel_hi:[0,1,1] neg_lo:[1,0,0] neg_hi:[1,0,0]
	v_pk_fma_f32 v[96:97], v[222:223], v[96:97], v[116:117] op_sel_hi:[0,1,1]
	v_mul_f32_e32 v100, 0xbfb8aa3b, v97
	v_exp_f32_e32 v100, v100
	s_nop 0
	v_add_f32_e32 v100, 1.0, v100
	v_rcp_f32_e32 v100, v100
	s_nop 0
	v_mul_f32_e32 v97, v97, v100
	v_mul_f32_e32 v105, v96, v97
	v_mov_b32_e32 v96, v102
	v_mov_b32_e32 v97, v98
	v_pk_fma_f32 v[96:97], v[220:221], v[120:121], v[96:97] op_sel_hi:[0,1,1] neg_lo:[1,0,0] neg_hi:[1,0,0]
	v_pk_fma_f32 v[96:97], v[222:223], v[96:97], v[124:125] op_sel_hi:[0,1,1]
	v_mul_f32_e32 v98, 0xbfb8aa3b, v97
	v_exp_f32_e32 v98, v98
	v_lshl_add_u64 v[100:101], v[126:127], 0, v[122:123]
	v_add_f32_e32 v98, 1.0, v98
	v_rcp_f32_e32 v98, v98
	s_nop 0
	v_mul_f32_e32 v97, v97, v98
	v_mov_b32_e32 v98, v103
	v_mul_f32_e32 v102, v96, v97
	v_pk_fma_f32 v[96:97], v[220:221], v[114:115], v[98:99] op_sel_hi:[0,1,1] neg_lo:[1,0,0] neg_hi:[1,0,0]
	v_pk_fma_f32 v[96:97], v[222:223], v[96:97], v[118:119] op_sel_hi:[0,1,1]
	v_mul_f32_e32 v98, 0xbfb8aa3b, v97
	v_exp_f32_e32 v98, v98
	s_nop 0
	v_add_f32_e32 v98, 1.0, v98
	v_rcp_f32_e32 v98, v98
	s_nop 0
	v_mul_f32_e32 v97, v97, v98
	v_mul_f32_e32 v99, v96, v97
	v_cvt_pk_bf16_f32 v98, v104, v105
	v_cvt_pk_bf16_f32 v99, v102, v99
	v_cvt_pk_bf16_f32 v96, v108, v109
	v_cvt_pk_bf16_f32 v97, v110, v106
	global_store_dwordx4 v[100:101], v[96:99], off sc1
	s_nop 1
	v_mov_b32_e32 v98, v92
	v_mov_b32_e32 v99, v88
; __device__ __forceinline__ unsigned cvt_pk_bf16(float lo, float hi) { unsigned r; asm("v_cvt_pk_bf16_f32 %0, %1, %2" : "=v"(r) : "v"(lo), "v"(hi)); return r; }
; __device__ __forceinline__ float fast_sigmoid(float v) { return __builtin_amdgcn_rcpf(1.0f + __builtin_amdgcn_exp2f(-1.4426950408889634f * v)); }
; __device__ __forceinline__ f32x4 ln_fix(const f32x4& a, float mu, float rs, const f32x4& cs, const f32x4& cb) { return (a - cs * mu) * rs + cb; }
;     __device__ __forceinline__ void operator()(const f32x4 (&acc)[2][2][4][2], const Unit& u, int wr, int wc, int fr_in, int fq_in) const {
;     ...
;             for (int m = 0; m < 4; ++m) { bf16_t* rowp = H + ((size_t)kt * mrows + (row0 + ai * HALF + m * 16)) * 64 + cin;
;                 float h[8];
; #pragma unroll
;                 for (int n = 0; n < 2; ++n) { f32x4 g = acc[ai][0][m][n], uu = acc[ai][1][m][n];
;                     if constexpr (LN) { g = ln_fix(g, rst.mu[ai][m], rst.rs[ai][m], csv[0][n], cbv[0][n]); uu = ln_fix(uu, rst.mu[ai][m], rst.rs[ai][m], csv[1][n], cbv[1][n]); }
; #pragma unroll
;                     for (int j = 0; j < 4; ++j) h[4 * n + j] = g[j] * fast_sigmoid(g[j]) * uu[j]; }
;                 u32x4 w; w.x = cvt_pk_bf16(h[0], h[1]); w.y = cvt_pk_bf16(h[2], h[3]); w.z = cvt_pk_bf16(h[4], h[5]); w.w = cvt_pk_bf16(h[6], h[7]);
;                 *(u32x4*)rowp = w; }
	v_pk_fma_f32 v[98:99], v[214:215], v[206:207], v[98:99] op_sel_hi:[0,1,1] neg_lo:[1,0,0] neg_hi:[1,0,0]
	v_pk_fma_f32 v[98:99], v[216:217], v[98:99], v[192:193] op_sel_hi:[0,1,1]
	v_mul_f32_e32 v88, 0xbfb8aa3b, v99
	v_exp_f32_e32 v88, v88
	v_lshl_add_u64 v[96:97], s[44:45], 0, v[218:219]
	v_lshlrev_b64 v[96:97], 7, v[96:97]
	v_lshl_add_u64 v[96:97], s[6:7], 0, v[96:97]
	v_add_f32_e32 v88, 1.0, v88
	v_rcp_f32_e32 v88, v88
	s_nop 0
	v_mul_f32_e32 v88, v99, v88
	v_mul_f32_e32 v92, v98, v88
	v_mov_b32_e32 v88, v93
	v_pk_fma_f32 v[88:89], v[214:215], v[208:209], v[88:89] op_sel_hi:[0,1,1] neg_lo:[1,0,0] neg_hi:[1,0,0]
	v_pk_fma_f32 v[88:89], v[216:217], v[88:89], v[132:133] op_sel_hi:[0,1,1]
	v_mul_f32_e32 v93, 0xbfb8aa3b, v89
	v_exp_f32_e32 v93, v93
	s_nop 0
	v_add_f32_e32 v93, 1.0, v93
	v_rcp_f32_e32 v93, v93
	s_nop 0
	v_mul_f32_e32 v89, v89, v93
	v_mul_f32_e32 v93, v88, v89
	v_mov_b32_e32 v88, v94
	v_mov_b32_e32 v89, v90
	v_pk_fma_f32 v[88:89], v[214:215], v[156:157], v[88:89] op_sel_hi:[0,1,1] neg_lo:[1,0,0] neg_hi:[1,0,0]
	v_pk_fma_f32 v[88:89], v[216:217], v[88:89], v[140:141] op_sel_hi:[0,1,1]
	v_mul_f32_e32 v90, 0xbfb8aa3b, v89
	v_exp_f32_e32 v90, v90
	s_nop 0
	v_add_f32_e32 v90, 1.0, v90
	v_rcp_f32_e32 v90, v90
	s_nop 0
	v_mul_f32_e32 v89, v89, v90
	v_mov_b32_e32 v90, v95
	v_mul_f32_e32 v94, v88, v89
	v_pk_fma_f32 v[88:89], v[214:215], v[210:211], v[90:91] op_sel_hi:[0,1,1] neg_lo:[1,0,0] neg_hi:[1,0,0]
	v_pk_fma_f32 v[88:89], v[216:217], v[88:89], v[134:135] op_sel_hi:[0,1,1]
	v_mul_f32_e32 v90, 0xbfb8aa3b, v89
	v_exp_f32_e32 v90, v90
	s_nop 0
	v_add_f32_e32 v90, 1.0, v90
	v_rcp_f32_e32 v90, v90
	s_nop 0
	v_mul_f32_e32 v89, v89, v90
	v_mul_f32_e32 v90, v88, v89
	v_mov_b32_e32 v88, v84
	v_mov_b32_e32 v89, v80
	v_pk_fma_f32 v[88:89], v[214:215], v[142:143], v[88:89] op_sel_hi:[0,1,1] neg_lo:[1,0,0] neg_hi:[1,0,0]
	v_pk_fma_f32 v[88:89], v[216:217], v[88:89], v[144:145] op_sel_hi:[0,1,1]
	v_mul_f32_e32 v80, 0xbfb8aa3b, v89
	v_exp_f32_e32 v80, v80
	s_nop 0
	v_add_f32_e32 v80, 1.0, v80
	v_rcp_f32_e32 v80, v80
	s_nop 0
	v_mul_f32_e32 v80, v89, v80
	v_mul_f32_e32 v88, v88, v80
	v_mov_b32_e32 v80, v85
	v_pk_fma_f32 v[80:81], v[214:215], v[112:113], v[80:81] op_sel_hi:[0,1,1] neg_lo:[1,0,0] neg_hi:[1,0,0]
	v_pk_fma_f32 v[80:81], v[216:217], v[80:81], v[116:117] op_sel_hi:[0,1,1]
	v_mul_f32_e32 v84, 0xbfb8aa3b, v81
	v_exp_f32_e32 v84, v84
	s_nop 0
	v_add_f32_e32 v84, 1.0, v84
	v_rcp_f32_e32 v84, v84
	s_nop 0
	v_mul_f32_e32 v81, v81, v84
	v_mul_f32_e32 v89, v80, v81
	v_mov_b32_e32 v80, v86
	v_mov_b32_e32 v81, v82
	v_pk_fma_f32 v[80:81], v[214:215], v[120:121], v[80:81] op_sel_hi:[0,1,1] neg_lo:[1,0,0] neg_hi:[1,0,0]
	v_pk_fma_f32 v[80:81], v[216:217], v[80:81], v[124:125] op_sel_hi:[0,1,1]
	v_mul_f32_e32 v82, 0xbfb8aa3b, v81
	v_exp_f32_e32 v82, v82
	v_lshl_add_u64 v[84:85], v[96:97], 0, v[122:123]
	v_add_f32_e32 v82, 1.0, v82
	v_rcp_f32_e32 v82, v82
	s_nop 0
	v_mul_f32_e32 v81, v81, v82
	v_mov_b32_e32 v82, v87
	v_mul_f32_e32 v86, v80, v81
	v_pk_fma_f32 v[80:81], v[214:215], v[114:115], v[82:83] op_sel_hi:[0,1,1] neg_lo:[1,0,0] neg_hi:[1,0,0]
	v_pk_fma_f32 v[80:81], v[216:217], v[80:81], v[118:119] op_sel_hi:[0,1,1]
	v_mul_f32_e32 v82, 0xbfb8aa3b, v81
	v_exp_f32_e32 v82, v82
	s_nop 0
	v_add_f32_e32 v82, 1.0, v82
	v_rcp_f32_e32 v82, v82
	s_nop 0
	v_mul_f32_e32 v81, v81, v82
	v_mul_f32_e32 v83, v80, v81
	v_cvt_pk_bf16_f32 v82, v88, v89
	v_cvt_pk_bf16_f32 v83, v86, v83
	v_cvt_pk_bf16_f32 v80, v92, v93
	v_cvt_pk_bf16_f32 v81, v94, v90
	global_store_dwordx4 v[84:85], v[80:83], off sc1
	s_nop 1
	v_mov_b32_e32 v82, v76
	v_mov_b32_e32 v83, v72
	v_pk_fma_f32 v[82:83], v[200:201], v[206:207], v[82:83] op_sel_hi:[0,1,1] neg_lo:[1,0,0] neg_hi:[1,0,0]
	v_pk_fma_f32 v[82:83], v[202:203], v[82:83], v[192:193] op_sel_hi:[0,1,1]
	v_mul_f32_e32 v72, 0xbfb8aa3b, v83
	v_exp_f32_e32 v72, v72
	v_lshl_add_u64 v[80:81], s[44:45], 0, v[212:213]
	v_lshlrev_b64 v[80:81], 7, v[80:81]
	v_lshl_add_u64 v[80:81], s[6:7], 0, v[80:81]
	v_add_f32_e32 v72, 1.0, v72
	v_rcp_f32_e32 v72, v72
	s_nop 0
	v_mul_f32_e32 v72, v83, v72
	v_mul_f32_e32 v76, v82, v72
	v_mov_b32_e32 v72, v77
	v_pk_fma_f32 v[72:73], v[200:201], v[208:209], v[72:73] op_sel_hi:[0,1,1] neg_lo:[1,0,0] neg_hi:[1,0,0]
	v_pk_fma_f32 v[72:73], v[202:203], v[72:73], v[132:133] op_sel_hi:[0,1,1]
	v_mul_f32_e32 v77, 0xbfb8aa3b, v73
	v_exp_f32_e32 v77, v77
	s_nop 0
	v_add_f32_e32 v77, 1.0, v77
	v_rcp_f32_e32 v77, v77
	s_nop 0
	v_mul_f32_e32 v73, v73, v77
	v_mul_f32_e32 v77, v72, v73
	v_mov_b32_e32 v72, v78
	v_mov_b32_e32 v73, v74
	v_pk_fma_f32 v[72:73], v[200:201], v[156:157], v[72:73] op_sel_hi:[0,1,1] neg_lo:[1,0,0] neg_hi:[1,0,0]
	v_pk_fma_f32 v[72:73], v[202:203], v[72:73], v[140:141] op_sel_hi:[0,1,1]
	v_mul_f32_e32 v74, 0xbfb8aa3b, v73
	v_exp_f32_e32 v74, v74
	s_nop 0
	v_add_f32_e32 v74, 1.0, v74
	v_rcp_f32_e32 v74, v74
	s_nop 0
	v_mul_f32_e32 v73, v73, v74
	v_mov_b32_e32 v74, v79
	v_mul_f32_e32 v78, v72, v73
	v_pk_fma_f32 v[72:73], v[200:201], v[210:211], v[74:75] op_sel_hi:[0,1,1] neg_lo:[1,0,0] neg_hi:[1,0,0]
	v_pk_fma_f32 v[72:73], v[202:203], v[72:73], v[134:135] op_sel_hi:[0,1,1]
	v_mul_f32_e32 v74, 0xbfb8aa3b, v73
	v_exp_f32_e32 v74, v74
	s_nop 0
	v_add_f32_e32 v74, 1.0, v74
	v_rcp_f32_e32 v74, v74
	s_nop 0
	v_mul_f32_e32 v73, v73, v74
	v_mul_f32_e32 v74, v72, v73
	v_mov_b32_e32 v72, v68
	v_mov_b32_e32 v73, v64
	v_pk_fma_f32 v[72:73], v[200:201], v[142:143], v[72:73] op_sel_hi:[0,1,1] neg_lo:[1,0,0] neg_hi:[1,0,0]
	v_pk_fma_f32 v[72:73], v[202:203], v[72:73], v[144:145] op_sel_hi:[0,1,1]
	v_mul_f32_e32 v64, 0xbfb8aa3b, v73
	v_exp_f32_e32 v64, v64
	s_nop 0
	v_add_f32_e32 v64, 1.0, v64
	v_rcp_f32_e32 v64, v64
; __device__ __forceinline__ unsigned cvt_pk_bf16(float lo, float hi) { unsigned r; asm("v_cvt_pk_bf16_f32 %0, %1, %2" : "=v"(r) : "v"(lo), "v"(hi)); return r; }
; __device__ __forceinline__ float fast_sigmoid(float v) { return __builtin_amdgcn_rcpf(1.0f + __builtin_amdgcn_exp2f(-1.4426950408889634f * v)); }
; __device__ __forceinline__ f32x4 ln_fix(const f32x4& a, float mu, float rs, const f32x4& cs, const f32x4& cb) { return (a - cs * mu) * rs + cb; }
;     __device__ __forceinline__ void operator()(const f32x4 (&acc)[2][2][4][2], const Unit& u, int wr, int wc, int fr_in, int fq_in) const {
;     ...
;             for (int m = 0; m < 4; ++m) { bf16_t* rowp = H + ((size_t)kt * mrows + (row0 + ai * HALF + m * 16)) * 64 + cin;
;                 float h[8];
; #pragma unroll
;                 for (int n = 0; n < 2; ++n) { f32x4 g = acc[ai][0][m][n], uu = acc[ai][1][m][n];
;                     if constexpr (LN) { g = ln_fix(g, rst.mu[ai][m], rst.rs[ai][m], csv[0][n], cbv[0][n]); uu = ln_fix(uu, rst.mu[ai][m], rst.rs[ai][m], csv[1][n], cbv[1][n]); }
; #pragma unroll
;                     for (int j = 0; j < 4; ++j) h[4 * n + j] = g[j] * fast_sigmoid(g[j]) * uu[j]; }
;                 u32x4 w; w.x = cvt_pk_bf16(h[0], h[1]); w.y = cvt_pk_bf16(h[2], h[3]); w.z = cvt_pk_bf16(h[4], h[5]); w.w = cvt_pk_bf16(h[6], h[7]);
;                 *(u32x4*)rowp = w; }
	s_nop 0
	v_mul_f32_e32 v64, v73, v64
	v_mul_f32_e32 v72, v72, v64
	v_mov_b32_e32 v64, v69
	v_pk_fma_f32 v[64:65], v[200:201], v[112:113], v[64:65] op_sel_hi:[0,1,1] neg_lo:[1,0,0] neg_hi:[1,0,0]
	v_pk_fma_f32 v[64:65], v[202:203], v[64:65], v[116:117] op_sel_hi:[0,1,1]
	v_mul_f32_e32 v68, 0xbfb8aa3b, v65
	v_exp_f32_e32 v68, v68
	s_nop 0
	v_add_f32_e32 v68, 1.0, v68
	v_rcp_f32_e32 v68, v68
	s_nop 0
	v_mul_f32_e32 v65, v65, v68
	v_mul_f32_e32 v73, v64, v65
	v_mov_b32_e32 v64, v70
	v_mov_b32_e32 v65, v66
	v_pk_fma_f32 v[64:65], v[200:201], v[120:121], v[64:65] op_sel_hi:[0,1,1] neg_lo:[1,0,0] neg_hi:[1,0,0]
	v_pk_fma_f32 v[64:65], v[202:203], v[64:65], v[124:125] op_sel_hi:[0,1,1]
	v_mul_f32_e32 v66, 0xbfb8aa3b, v65
	v_exp_f32_e32 v66, v66
	v_lshl_add_u64 v[68:69], v[80:81], 0, v[122:123]
	v_add_f32_e32 v66, 1.0, v66
	v_rcp_f32_e32 v66, v66
	s_nop 0
	v_mul_f32_e32 v65, v65, v66
	v_mov_b32_e32 v66, v71
	v_mul_f32_e32 v70, v64, v65
	v_pk_fma_f32 v[64:65], v[200:201], v[114:115], v[66:67] op_sel_hi:[0,1,1] neg_lo:[1,0,0] neg_hi:[1,0,0]
	v_pk_fma_f32 v[64:65], v[202:203], v[64:65], v[118:119] op_sel_hi:[0,1,1]
	v_mul_f32_e32 v66, 0xbfb8aa3b, v65
	v_exp_f32_e32 v66, v66
	s_nop 0
	v_add_f32_e32 v66, 1.0, v66
	v_rcp_f32_e32 v66, v66
	s_nop 0
	v_mul_f32_e32 v65, v65, v66
	v_mul_f32_e32 v67, v64, v65
	v_cvt_pk_bf16_f32 v66, v72, v73
	v_cvt_pk_bf16_f32 v67, v70, v67
	v_cvt_pk_bf16_f32 v64, v76, v77
	v_cvt_pk_bf16_f32 v65, v78, v74
	global_store_dwordx4 v[68:69], v[64:67], off sc1
	s_nop 1
	v_mov_b32_e32 v66, v60
	v_mov_b32_e32 v67, v56
	v_pk_fma_f32 v[66:67], v[194:195], v[206:207], v[66:67] op_sel_hi:[0,1,1] neg_lo:[1,0,0] neg_hi:[1,0,0]
	v_pk_fma_f32 v[66:67], v[198:199], v[66:67], v[192:193] op_sel_hi:[0,1,1]
	v_mul_f32_e32 v56, 0xbfb8aa3b, v67
	v_exp_f32_e32 v56, v56
	v_lshl_add_u64 v[64:65], s[44:45], 0, v[204:205]
	v_lshlrev_b64 v[64:65], 7, v[64:65]
	v_lshl_add_u64 v[64:65], s[6:7], 0, v[64:65]
	v_add_f32_e32 v56, 1.0, v56
	v_rcp_f32_e32 v56, v56
	s_nop 0
	v_mul_f32_e32 v56, v67, v56
	v_mul_f32_e32 v60, v66, v56
	v_mov_b32_e32 v56, v61
	v_pk_fma_f32 v[56:57], v[194:195], v[208:209], v[56:57] op_sel_hi:[0,1,1] neg_lo:[1,0,0] neg_hi:[1,0,0]
	v_pk_fma_f32 v[56:57], v[198:199], v[56:57], v[132:133] op_sel_hi:[0,1,1]
	v_mul_f32_e32 v61, 0xbfb8aa3b, v57
	v_exp_f32_e32 v61, v61
	s_nop 0
	v_add_f32_e32 v61, 1.0, v61
	v_rcp_f32_e32 v61, v61
	s_nop 0
	v_mul_f32_e32 v57, v57, v61
	v_mul_f32_e32 v61, v56, v57
	v_mov_b32_e32 v56, v62
	v_mov_b32_e32 v57, v58
	v_pk_fma_f32 v[56:57], v[194:195], v[156:157], v[56:57] op_sel_hi:[0,1,1] neg_lo:[1,0,0] neg_hi:[1,0,0]
	v_pk_fma_f32 v[56:57], v[198:199], v[56:57], v[140:141] op_sel_hi:[0,1,1]
	v_mul_f32_e32 v58, 0xbfb8aa3b, v57
	v_exp_f32_e32 v58, v58
	s_nop 0
	v_add_f32_e32 v58, 1.0, v58
	v_rcp_f32_e32 v58, v58
	s_nop 0
	v_mul_f32_e32 v57, v57, v58
	v_mov_b32_e32 v58, v63
	v_mul_f32_e32 v62, v56, v57
	v_pk_fma_f32 v[56:57], v[194:195], v[210:211], v[58:59] op_sel_hi:[0,1,1] neg_lo:[1,0,0] neg_hi:[1,0,0]
	v_pk_fma_f32 v[56:57], v[198:199], v[56:57], v[134:135] op_sel_hi:[0,1,1]
	v_mul_f32_e32 v58, 0xbfb8aa3b, v57
	v_exp_f32_e32 v58, v58
	s_nop 0
	v_add_f32_e32 v58, 1.0, v58
	v_rcp_f32_e32 v58, v58
	s_nop 0
	v_mul_f32_e32 v57, v57, v58
	v_mul_f32_e32 v58, v56, v57
	v_mov_b32_e32 v56, v52
	v_mov_b32_e32 v57, v48
	v_pk_fma_f32 v[56:57], v[194:195], v[142:143], v[56:57] op_sel_hi:[0,1,1] neg_lo:[1,0,0] neg_hi:[1,0,0]
	v_pk_fma_f32 v[56:57], v[198:199], v[56:57], v[144:145] op_sel_hi:[0,1,1]
	v_mul_f32_e32 v48, 0xbfb8aa3b, v57
	v_exp_f32_e32 v48, v48
	s_nop 0
	v_add_f32_e32 v48, 1.0, v48
	v_rcp_f32_e32 v48, v48
	s_nop 0
	v_mul_f32_e32 v48, v57, v48
	v_mul_f32_e32 v56, v56, v48
	v_mov_b32_e32 v48, v53
	v_pk_fma_f32 v[48:49], v[194:195], v[112:113], v[48:49] op_sel_hi:[0,1,1] neg_lo:[1,0,0] neg_hi:[1,0,0]
	v_pk_fma_f32 v[48:49], v[198:199], v[48:49], v[116:117] op_sel_hi:[0,1,1]
	v_mul_f32_e32 v52, 0xbfb8aa3b, v49
	v_exp_f32_e32 v52, v52
	s_nop 0
	v_add_f32_e32 v52, 1.0, v52
	v_rcp_f32_e32 v52, v52
	s_nop 0
	v_mul_f32_e32 v49, v49, v52
	v_mul_f32_e32 v57, v48, v49
	v_mov_b32_e32 v48, v54
	v_mov_b32_e32 v49, v50
	v_pk_fma_f32 v[48:49], v[194:195], v[120:121], v[48:49] op_sel_hi:[0,1,1] neg_lo:[1,0,0] neg_hi:[1,0,0]
	v_pk_fma_f32 v[48:49], v[198:199], v[48:49], v[124:125] op_sel_hi:[0,1,1]
	v_mul_f32_e32 v50, 0xbfb8aa3b, v49
	v_exp_f32_e32 v50, v50
	v_lshl_add_u64 v[52:53], v[64:65], 0, v[122:123]
	v_add_f32_e32 v50, 1.0, v50
	v_rcp_f32_e32 v50, v50
	s_nop 0
	v_mul_f32_e32 v49, v49, v50
	v_mov_b32_e32 v50, v55
	v_mul_f32_e32 v54, v48, v49
	v_pk_fma_f32 v[48:49], v[194:195], v[114:115], v[50:51] op_sel_hi:[0,1,1] neg_lo:[1,0,0] neg_hi:[1,0,0]
	v_pk_fma_f32 v[48:49], v[198:199], v[48:49], v[118:119] op_sel_hi:[0,1,1]
	v_mul_f32_e32 v50, 0xbfb8aa3b, v49
	v_exp_f32_e32 v50, v50
	s_nop 0
	v_add_f32_e32 v50, 1.0, v50
	v_rcp_f32_e32 v50, v50
	s_nop 0
	v_mul_f32_e32 v49, v49, v50
	v_mul_f32_e32 v51, v48, v49
	v_cvt_pk_bf16_f32 v50, v56, v57
	v_cvt_pk_bf16_f32 v51, v54, v51
	v_cvt_pk_bf16_f32 v48, v60, v61
	v_cvt_pk_bf16_f32 v49, v62, v58
	global_store_dwordx4 v[52:53], v[48:51], off sc1
	s_nop 1
	v_mov_b32_e32 v50, v44
	v_mov_b32_e32 v51, v40
	v_pk_fma_f32 v[50:51], v[186:187], v[206:207], v[50:51] op_sel_hi:[0,1,1] neg_lo:[1,0,0] neg_hi:[1,0,0]
	v_pk_fma_f32 v[50:51], v[190:191], v[50:51], v[192:193] op_sel_hi:[0,1,1]
	v_mul_f32_e32 v40, 0xbfb8aa3b, v51
	v_exp_f32_e32 v40, v40
	v_lshl_add_u64 v[48:49], s[44:45], 0, v[196:197]
	v_lshlrev_b64 v[48:49], 7, v[48:49]
	v_lshl_add_u64 v[48:49], s[6:7], 0, v[48:49]
	v_add_f32_e32 v40, 1.0, v40
	v_rcp_f32_e32 v40, v40
	s_nop 0
	v_mul_f32_e32 v40, v51, v40
	v_mul_f32_e32 v44, v50, v40
; __device__ __forceinline__ unsigned cvt_pk_bf16(float lo, float hi) { unsigned r; asm("v_cvt_pk_bf16_f32 %0, %1, %2" : "=v"(r) : "v"(lo), "v"(hi)); return r; }
; __device__ __forceinline__ float fast_sigmoid(float v) { return __builtin_amdgcn_rcpf(1.0f + __builtin_amdgcn_exp2f(-1.4426950408889634f * v)); }
; __device__ __forceinline__ f32x4 ln_fix(const f32x4& a, float mu, float rs, const f32x4& cs, const f32x4& cb) { return (a - cs * mu) * rs + cb; }
;     __device__ __forceinline__ void operator()(const f32x4 (&acc)[2][2][4][2], const Unit& u, int wr, int wc, int fr_in, int fq_in) const {
;     ...
;             for (int m = 0; m < 4; ++m) { bf16_t* rowp = H + ((size_t)kt * mrows + (row0 + ai * HALF + m * 16)) * 64 + cin;
;                 float h[8];
; #pragma unroll
;                 for (int n = 0; n < 2; ++n) { f32x4 g = acc[ai][0][m][n], uu = acc[ai][1][m][n];
;                     if constexpr (LN) { g = ln_fix(g, rst.mu[ai][m], rst.rs[ai][m], csv[0][n], cbv[0][n]); uu = ln_fix(uu, rst.mu[ai][m], rst.rs[ai][m], csv[1][n], cbv[1][n]); }
; #pragma unroll
;                     for (int j = 0; j < 4; ++j) h[4 * n + j] = g[j] * fast_sigmoid(g[j]) * uu[j]; }
;                 u32x4 w; w.x = cvt_pk_bf16(h[0], h[1]); w.y = cvt_pk_bf16(h[2], h[3]); w.z = cvt_pk_bf16(h[4], h[5]); w.w = cvt_pk_bf16(h[6], h[7]);
;                 *(u32x4*)rowp = w; }
	v_mov_b32_e32 v40, v45
	v_pk_fma_f32 v[40:41], v[186:187], v[208:209], v[40:41] op_sel_hi:[0,1,1] neg_lo:[1,0,0] neg_hi:[1,0,0]
	v_pk_fma_f32 v[40:41], v[190:191], v[40:41], v[132:133] op_sel_hi:[0,1,1]
	v_mul_f32_e32 v45, 0xbfb8aa3b, v41
	v_exp_f32_e32 v45, v45
	s_nop 0
	v_add_f32_e32 v45, 1.0, v45
	v_rcp_f32_e32 v45, v45
	s_nop 0
	v_mul_f32_e32 v41, v41, v45
	v_mul_f32_e32 v45, v40, v41
	v_mov_b32_e32 v40, v46
	v_mov_b32_e32 v41, v42
	v_pk_fma_f32 v[40:41], v[186:187], v[156:157], v[40:41] op_sel_hi:[0,1,1] neg_lo:[1,0,0] neg_hi:[1,0,0]
	v_pk_fma_f32 v[40:41], v[190:191], v[40:41], v[140:141] op_sel_hi:[0,1,1]
	v_mul_f32_e32 v42, 0xbfb8aa3b, v41
	v_exp_f32_e32 v42, v42
	s_nop 0
	v_add_f32_e32 v42, 1.0, v42
	v_rcp_f32_e32 v42, v42
	s_nop 0
	v_mul_f32_e32 v41, v41, v42
	v_mov_b32_e32 v42, v47
	v_mul_f32_e32 v46, v40, v41
	v_pk_fma_f32 v[40:41], v[186:187], v[210:211], v[42:43] op_sel_hi:[0,1,1] neg_lo:[1,0,0] neg_hi:[1,0,0]
	v_pk_fma_f32 v[40:41], v[190:191], v[40:41], v[134:135] op_sel_hi:[0,1,1]
	v_mul_f32_e32 v42, 0xbfb8aa3b, v41
	v_exp_f32_e32 v42, v42
	s_nop 0
	v_add_f32_e32 v42, 1.0, v42
	v_rcp_f32_e32 v42, v42
	s_nop 0
	v_mul_f32_e32 v41, v41, v42
	v_mul_f32_e32 v42, v40, v41
	v_mov_b32_e32 v40, v36
	v_mov_b32_e32 v41, v32
	v_pk_fma_f32 v[40:41], v[186:187], v[142:143], v[40:41] op_sel_hi:[0,1,1] neg_lo:[1,0,0] neg_hi:[1,0,0]
	v_pk_fma_f32 v[40:41], v[190:191], v[40:41], v[144:145] op_sel_hi:[0,1,1]
	v_mul_f32_e32 v32, 0xbfb8aa3b, v41
	v_exp_f32_e32 v32, v32
	s_nop 0
	v_add_f32_e32 v32, 1.0, v32
	v_rcp_f32_e32 v32, v32
	s_nop 0
	v_mul_f32_e32 v32, v41, v32
	v_mul_f32_e32 v40, v40, v32
	v_mov_b32_e32 v32, v37
	v_pk_fma_f32 v[32:33], v[186:187], v[112:113], v[32:33] op_sel_hi:[0,1,1] neg_lo:[1,0,0] neg_hi:[1,0,0]
	v_pk_fma_f32 v[32:33], v[190:191], v[32:33], v[116:117] op_sel_hi:[0,1,1]
	v_mul_f32_e32 v36, 0xbfb8aa3b, v33
	v_exp_f32_e32 v36, v36
	s_nop 0
	v_add_f32_e32 v36, 1.0, v36
	v_rcp_f32_e32 v36, v36
	s_nop 0
	v_mul_f32_e32 v33, v33, v36
	v_mul_f32_e32 v41, v32, v33
	v_mov_b32_e32 v32, v38
	v_mov_b32_e32 v33, v34
	v_pk_fma_f32 v[32:33], v[186:187], v[120:121], v[32:33] op_sel_hi:[0,1,1] neg_lo:[1,0,0] neg_hi:[1,0,0]
	v_pk_fma_f32 v[32:33], v[190:191], v[32:33], v[124:125] op_sel_hi:[0,1,1]
	v_mul_f32_e32 v34, 0xbfb8aa3b, v33
	v_exp_f32_e32 v34, v34
	v_lshl_add_u64 v[36:37], v[48:49], 0, v[122:123]
	v_add_f32_e32 v34, 1.0, v34
	v_rcp_f32_e32 v34, v34
	s_nop 0
	v_mul_f32_e32 v33, v33, v34
	v_mov_b32_e32 v34, v39
	v_mul_f32_e32 v38, v32, v33
	v_pk_fma_f32 v[32:33], v[186:187], v[114:115], v[34:35] op_sel_hi:[0,1,1] neg_lo:[1,0,0] neg_hi:[1,0,0]
	v_pk_fma_f32 v[32:33], v[190:191], v[32:33], v[118:119] op_sel_hi:[0,1,1]
	v_mul_f32_e32 v34, 0xbfb8aa3b, v33
	v_exp_f32_e32 v34, v34
	s_nop 0
	v_add_f32_e32 v34, 1.0, v34
	v_rcp_f32_e32 v34, v34
	s_nop 0
	v_mul_f32_e32 v33, v33, v34
	v_mul_f32_e32 v35, v32, v33
	v_cvt_pk_bf16_f32 v34, v40, v41
	v_cvt_pk_bf16_f32 v35, v38, v35
	v_cvt_pk_bf16_f32 v32, v44, v45
	v_cvt_pk_bf16_f32 v33, v46, v42
	global_store_dwordx4 v[36:37], v[32:35], off sc1
	s_nop 1
	v_mov_b32_e32 v34, v28
	v_mov_b32_e32 v35, v24
	v_pk_fma_f32 v[34:35], v[180:181], v[206:207], v[34:35] op_sel_hi:[0,1,1] neg_lo:[1,0,0] neg_hi:[1,0,0]
	v_pk_fma_f32 v[34:35], v[184:185], v[34:35], v[192:193] op_sel_hi:[0,1,1]
	v_mul_f32_e32 v24, 0xbfb8aa3b, v35
	v_exp_f32_e32 v24, v24
	v_lshl_add_u64 v[32:33], s[44:45], 0, v[188:189]
	v_lshlrev_b64 v[32:33], 7, v[32:33]
	v_lshl_add_u64 v[32:33], s[6:7], 0, v[32:33]
	v_add_f32_e32 v24, 1.0, v24
	v_rcp_f32_e32 v24, v24
	s_nop 0
	v_mul_f32_e32 v24, v35, v24
	v_mul_f32_e32 v28, v34, v24
	v_mov_b32_e32 v24, v29
	v_pk_fma_f32 v[24:25], v[180:181], v[208:209], v[24:25] op_sel_hi:[0,1,1] neg_lo:[1,0,0] neg_hi:[1,0,0]
	v_pk_fma_f32 v[24:25], v[184:185], v[24:25], v[132:133] op_sel_hi:[0,1,1]
	v_mul_f32_e32 v29, 0xbfb8aa3b, v25
	v_exp_f32_e32 v29, v29
	s_nop 0
	v_add_f32_e32 v29, 1.0, v29
	v_rcp_f32_e32 v29, v29
	s_nop 0
	v_mul_f32_e32 v25, v25, v29
	v_mul_f32_e32 v29, v24, v25
	v_mov_b32_e32 v24, v30
	v_mov_b32_e32 v25, v26
	v_pk_fma_f32 v[24:25], v[180:181], v[156:157], v[24:25] op_sel_hi:[0,1,1] neg_lo:[1,0,0] neg_hi:[1,0,0]
	v_pk_fma_f32 v[24:25], v[184:185], v[24:25], v[140:141] op_sel_hi:[0,1,1]
	v_mul_f32_e32 v26, 0xbfb8aa3b, v25
	v_exp_f32_e32 v26, v26
	s_nop 0
	v_add_f32_e32 v26, 1.0, v26
	v_rcp_f32_e32 v26, v26
	s_nop 0
	v_mul_f32_e32 v25, v25, v26
	v_mov_b32_e32 v26, v31
	v_mul_f32_e32 v30, v24, v25
	v_pk_fma_f32 v[24:25], v[180:181], v[210:211], v[26:27] op_sel_hi:[0,1,1] neg_lo:[1,0,0] neg_hi:[1,0,0]
	v_pk_fma_f32 v[24:25], v[184:185], v[24:25], v[134:135] op_sel_hi:[0,1,1]
	v_mul_f32_e32 v26, 0xbfb8aa3b, v25
	v_exp_f32_e32 v26, v26
	s_nop 0
	v_add_f32_e32 v26, 1.0, v26
	v_rcp_f32_e32 v26, v26
	s_nop 0
	v_mul_f32_e32 v25, v25, v26
	v_mul_f32_e32 v26, v24, v25
	v_mov_b32_e32 v24, v20
	v_mov_b32_e32 v25, v16
	v_pk_fma_f32 v[24:25], v[180:181], v[142:143], v[24:25] op_sel_hi:[0,1,1] neg_lo:[1,0,0] neg_hi:[1,0,0]
	v_pk_fma_f32 v[24:25], v[184:185], v[24:25], v[144:145] op_sel_hi:[0,1,1]
	v_mul_f32_e32 v16, 0xbfb8aa3b, v25
	v_exp_f32_e32 v16, v16
	s_nop 0
	v_add_f32_e32 v16, 1.0, v16
	v_rcp_f32_e32 v16, v16
	s_nop 0
	v_mul_f32_e32 v16, v25, v16
	v_mul_f32_e32 v24, v24, v16
	v_mov_b32_e32 v16, v21
; __device__ __forceinline__ unsigned cvt_pk_bf16(float lo, float hi) { unsigned r; asm("v_cvt_pk_bf16_f32 %0, %1, %2" : "=v"(r) : "v"(lo), "v"(hi)); return r; }
; __device__ __forceinline__ float fast_sigmoid(float v) { return __builtin_amdgcn_rcpf(1.0f + __builtin_amdgcn_exp2f(-1.4426950408889634f * v)); }
; __device__ __forceinline__ f32x4 ln_fix(const f32x4& a, float mu, float rs, const f32x4& cs, const f32x4& cb) { return (a - cs * mu) * rs + cb; }
;     __device__ __forceinline__ void operator()(const f32x4 (&acc)[2][2][4][2], const Unit& u, int wr, int wc, int fr_in, int fq_in) const {
;     ...
;             for (int m = 0; m < 4; ++m) { bf16_t* rowp = H + ((size_t)kt * mrows + (row0 + ai * HALF + m * 16)) * 64 + cin;
;                 float h[8];
; #pragma unroll
;                 for (int n = 0; n < 2; ++n) { f32x4 g = acc[ai][0][m][n], uu = acc[ai][1][m][n];
;                     if constexpr (LN) { g = ln_fix(g, rst.mu[ai][m], rst.rs[ai][m], csv[0][n], cbv[0][n]); uu = ln_fix(uu, rst.mu[ai][m], rst.rs[ai][m], csv[1][n], cbv[1][n]); }
; #pragma unroll
;                     for (int j = 0; j < 4; ++j) h[4 * n + j] = g[j] * fast_sigmoid(g[j]) * uu[j]; }
;                 u32x4 w; w.x = cvt_pk_bf16(h[0], h[1]); w.y = cvt_pk_bf16(h[2], h[3]); w.z = cvt_pk_bf16(h[4], h[5]); w.w = cvt_pk_bf16(h[6], h[7]);
;                 *(u32x4*)rowp = w; }
	v_pk_fma_f32 v[16:17], v[180:181], v[112:113], v[16:17] op_sel_hi:[0,1,1] neg_lo:[1,0,0] neg_hi:[1,0,0]
	v_pk_fma_f32 v[16:17], v[184:185], v[16:17], v[116:117] op_sel_hi:[0,1,1]
	v_mul_f32_e32 v20, 0xbfb8aa3b, v17
	v_exp_f32_e32 v20, v20
	s_nop 0
	v_add_f32_e32 v20, 1.0, v20
	v_rcp_f32_e32 v20, v20
	s_nop 0
	v_mul_f32_e32 v17, v17, v20
	v_mul_f32_e32 v25, v16, v17
	v_mov_b32_e32 v16, v22
	v_mov_b32_e32 v17, v18
	v_pk_fma_f32 v[16:17], v[180:181], v[120:121], v[16:17] op_sel_hi:[0,1,1] neg_lo:[1,0,0] neg_hi:[1,0,0]
	v_pk_fma_f32 v[16:17], v[184:185], v[16:17], v[124:125] op_sel_hi:[0,1,1]
	v_mul_f32_e32 v18, 0xbfb8aa3b, v17
	v_exp_f32_e32 v18, v18
	v_lshl_add_u64 v[20:21], v[32:33], 0, v[122:123]
	v_add_f32_e32 v18, 1.0, v18
	v_rcp_f32_e32 v18, v18
	s_nop 0
	v_mul_f32_e32 v17, v17, v18
	v_mov_b32_e32 v18, v23
	v_mul_f32_e32 v22, v16, v17
	v_pk_fma_f32 v[16:17], v[180:181], v[114:115], v[18:19] op_sel_hi:[0,1,1] neg_lo:[1,0,0] neg_hi:[1,0,0]
	v_pk_fma_f32 v[16:17], v[184:185], v[16:17], v[118:119] op_sel_hi:[0,1,1]
	v_mul_f32_e32 v18, 0xbfb8aa3b, v17
	v_exp_f32_e32 v18, v18
	v_mov_b32_e32 v23, v8
	v_add_f32_e32 v18, 1.0, v18
	v_rcp_f32_e32 v18, v18
	s_nop 0
	v_mul_f32_e32 v17, v17, v18
	v_mul_f32_e32 v19, v16, v17
	v_cvt_pk_bf16_f32 v18, v24, v25
	v_cvt_pk_bf16_f32 v19, v22, v19
	v_cvt_pk_bf16_f32 v16, v28, v29
	v_cvt_pk_bf16_f32 v17, v30, v26
	global_store_dwordx4 v[20:21], v[16:19], off sc1
	v_mov_b32_e32 v20, v136
	v_mov_b32_e32 v21, v176
	v_mov_b32_e32 v18, v176
	v_mov_b32_e32 v19, v128
	v_mov_b32_e32 v22, v12
	v_pk_fma_f32 v[18:19], v[18:19], v[20:21], v[22:23] neg_lo:[1,0,0] neg_hi:[1,0,0]
	v_mov_b32_e32 v128, v176
	v_pk_fma_f32 v[18:19], v[18:19], v[178:179], v[192:193] op_sel_hi:[1,0,1]
	v_lshl_add_u64 v[16:17], s[44:45], 0, v[182:183]
	v_mul_f32_e32 v8, 0xbfb8aa3b, v19
	v_exp_f32_e32 v8, v8
	v_lshlrev_b64 v[16:17], 7, v[16:17]
	v_lshl_add_u64 v[16:17], s[6:7], 0, v[16:17]
	s_mov_b64 s[44:45], -1
	v_add_f32_e32 v8, 1.0, v8
	v_rcp_f32_e32 v8, v8
	s_nop 0
	v_mul_f32_e32 v8, v19, v8
	v_mul_f32_e32 v20, v18, v8
	v_pk_mov_b32 v[18:19], v[136:137], v[176:177] op_sel:[1,0]
	v_mov_b32_e32 v8, v13
	v_pk_fma_f32 v[8:9], v[128:129], v[18:19], v[8:9] neg_lo:[1,0,0] neg_hi:[1,0,0]
	v_mov_b32_e32 v13, v176
	v_pk_fma_f32 v[8:9], v[8:9], v[178:179], v[132:133] op_sel_hi:[1,0,1]
	v_mov_b32_e32 v18, v14
	v_mul_f32_e32 v12, 0xbfb8aa3b, v9
	v_exp_f32_e32 v12, v12
	v_mov_b32_e32 v19, v10
	v_add_f32_e32 v12, 1.0, v12
	v_rcp_f32_e32 v12, v12
	s_nop 0
	v_mul_f32_e32 v9, v9, v12
	v_mul_f32_e32 v21, v8, v9
	v_mov_b32_e32 v8, v176
	v_mov_b32_e32 v9, v130
	v_mov_b32_e32 v12, v138
	v_pk_fma_f32 v[8:9], v[8:9], v[12:13], v[18:19] neg_lo:[1,0,0] neg_hi:[1,0,0]
	v_mov_b32_e32 v130, v176
	v_pk_fma_f32 v[8:9], v[8:9], v[178:179], v[140:141] op_sel_hi:[1,0,1]
	s_nop 0
	v_mul_f32_e32 v10, 0xbfb8aa3b, v9
	v_exp_f32_e32 v10, v10
	s_nop 0
	v_add_f32_e32 v10, 1.0, v10
	v_rcp_f32_e32 v10, v10
	s_nop 0
	v_mul_f32_e32 v9, v9, v10
	v_mul_f32_e32 v12, v8, v9
	v_pk_mov_b32 v[8:9], v[138:139], v[176:177] op_sel:[1,0]
	v_mov_b32_e32 v10, v15
	v_pk_fma_f32 v[8:9], v[130:131], v[8:9], v[10:11] neg_lo:[1,0,0] neg_hi:[1,0,0]
	s_nop 0
	v_pk_fma_f32 v[8:9], v[8:9], v[178:179], v[134:135] op_sel_hi:[1,0,1]
	s_nop 0
	v_mul_f32_e32 v10, 0xbfb8aa3b, v9
	v_exp_f32_e32 v10, v10
	s_nop 0
	v_add_f32_e32 v10, 1.0, v10
	v_rcp_f32_e32 v10, v10
	s_nop 0
	v_mul_f32_e32 v9, v9, v10
	v_mul_f32_e32 v10, v8, v9
	v_mov_b32_e32 v8, v0
	v_mov_b32_e32 v9, v4
	v_pk_fma_f32 v[8:9], v[176:177], v[142:143], v[8:9] op_sel_hi:[0,1,1] neg_lo:[1,0,0] neg_hi:[1,0,0]
	v_pk_fma_f32 v[8:9], v[178:179], v[8:9], v[144:145] op_sel_hi:[0,1,1]
	v_mul_f32_e32 v0, 0xbfb8aa3b, v9
	v_exp_f32_e32 v0, v0
	v_mov_b32_e32 v4, v1
	v_add_f32_e32 v0, 1.0, v0
	v_rcp_f32_e32 v0, v0
	s_nop 0
	v_mul_f32_e32 v0, v9, v0
	v_mul_f32_e32 v8, v8, v0
	v_pk_fma_f32 v[0:1], v[176:177], v[112:113], v[4:5] op_sel_hi:[0,1,1] neg_lo:[1,0,0] neg_hi:[1,0,0]
	v_pk_fma_f32 v[0:1], v[178:179], v[0:1], v[116:117] op_sel_hi:[0,1,1]
	v_mul_f32_e32 v4, 0xbfb8aa3b, v1
	v_exp_f32_e32 v4, v4
	s_nop 0
	v_add_f32_e32 v4, 1.0, v4
	v_rcp_f32_e32 v4, v4
	s_nop 0
	v_mul_f32_e32 v1, v1, v4
	v_mul_f32_e32 v9, v0, v1
	v_mov_b32_e32 v0, v2
	v_mov_b32_e32 v1, v6
	v_pk_fma_f32 v[0:1], v[176:177], v[120:121], v[0:1] op_sel_hi:[0,1,1] neg_lo:[1,0,0] neg_hi:[1,0,0]
	v_pk_fma_f32 v[0:1], v[178:179], v[0:1], v[124:125] op_sel_hi:[0,1,1]
	v_mul_f32_e32 v2, 0xbfb8aa3b, v1
	v_exp_f32_e32 v2, v2
	v_mov_b32_e32 v6, v3
	v_lshl_add_u64 v[4:5], v[16:17], 0, v[122:123]
	v_add_f32_e32 v2, 1.0, v2
	v_rcp_f32_e32 v2, v2
	s_nop 0
	v_mul_f32_e32 v1, v1, v2
	v_mul_f32_e32 v11, v0, v1
	v_pk_fma_f32 v[0:1], v[176:177], v[114:115], v[6:7] op_sel_hi:[0,1,1] neg_lo:[1,0,0] neg_hi:[1,0,0]
	v_pk_fma_f32 v[0:1], v[178:179], v[0:1], v[118:119] op_sel_hi:[0,1,1]
	v_mul_f32_e32 v2, 0xbfb8aa3b, v1
	v_exp_f32_e32 v2, v2
	s_nop 0
	v_add_f32_e32 v2, 1.0, v2
	v_rcp_f32_e32 v2, v2
	s_nop 0
	v_mul_f32_e32 v1, v1, v2
	v_mul_f32_e32 v3, v0, v1
	v_cvt_pk_bf16_f32 v0, v20, v21
	v_cvt_pk_bf16_f32 v1, v12, v10
	v_cvt_pk_bf16_f32 v2, v8, v9
	v_cvt_pk_bf16_f32 v3, v11, v3
	global_store_dwordx4 v[4:5], v[0:3], off sc1
	s_cbranch_vccnz .LBB0_1252
	s_andn2_b64 vcc, exec, s[4:5]
	s_cbranch_vccnz .LBB0_1251
	s_barrier
	s_branch .LBB0_1251

; __device__ __forceinline__ unsigned cvt_pk_bf16(float lo, float hi) { unsigned r; asm("v_cvt_pk_bf16_f32 %0, %1, %2" : "=v"(r) : "v"(lo), "v"(hi)); return r; }
;     __device__ __forceinline__ void operator()(const f32x4 (&acc)[2][2][4][2], const Unit& u, int wr, int wc, int fr_in, int fq_in) const {
;     ...
;             for (int m = 0; m < 4; ++m) { bf16_t* rowp = base + (size_t)(row0 + ai * HALF + m * 16) * ldc + col0;
; #pragma unroll
;                 for (int bj = 0; bj < 2; ++bj) { f32x4 v0 = acc[ai][bj][m][0] + bv[bj][0], v1 = acc[ai][bj][m][1] + bv[bj][1];
;                     if (ACT == 1) { f32x2 a = gelu_pk((f32x2){v0[0], v0[1]}), b = gelu_pk((f32x2){v0[2], v0[3]}), c = gelu_pk((f32x2){v1[0], v1[1]}), d = gelu_pk((f32x2){v1[2], v1[3]});
;                         v0 = (f32x4){a.x, a.y, b.x, b.y}; v1 = (f32x4){c.x, c.y, d.x, d.y}; }
;                     v0 = v0 * sc; v1 = v1 * sc; u32x4 w; w.x = cvt_pk_bf16(v0[0], v0[1]); w.y = cvt_pk_bf16(v0[2], v0[3]); w.z = cvt_pk_bf16(v1[0], v1[1]); w.w = cvt_pk_bf16(v1[2], v1[3]);
;                     *(u32x4*)(rowp + bj * HALF) = w; } }
.LBB0_1337:
	v_mov_b32_e32 v16, v152
	v_mov_b32_e32 v17, v153
	s_lshl_b32 s8, s8, 8
	s_lshl_b32 s9, s34, 8
	s_add_i32 s9, s9, s54
	s_or_b32 s8, s8, s55
	v_add_u32_e32 v16, s9, v16
	v_lshl_add_u32 v18, v17, 3, s8
	v_ashrrev_i32_e32 v19, 31, v18
	v_ashrrev_i32_e32 v17, 31, v16
	v_lshl_add_u64 v[18:19], v[18:19], 1, s[22:23]
	v_lshlrev_b64 v[16:17], 11, v[16:17]
	v_lshl_add_u64 v[24:25], v[18:19], 0, v[16:17]
	v_cvt_pk_bf16_f32 v17, v126, v127
	s_mov_b64 s[8:9], 0x8000
	v_cvt_pk_bf16_f32 v16, v124, v125
	v_cvt_pk_bf16_f32 v18, v120, v121
	v_cvt_pk_bf16_f32 v19, v122, v123
	global_store_dwordx4 v[24:25], v[16:19], off sc1
	v_lshl_add_u64 v[26:27], v[24:25], 0, s[8:9]
	s_mov_b32 s8, 0x8000
	v_cvt_pk_bf16_f32 v17, v144, v145
	v_cvt_pk_bf16_f32 v16, v146, v147
	v_cvt_pk_bf16_f32 v18, v150, v151
	v_cvt_pk_bf16_f32 v19, v148, v149
	global_store_dwordx4 v[24:25], v[16:19], off offset:256 sc1
	v_cvt_pk_bf16_f32 v4, v4, v5
	v_cvt_pk_bf16_f32 v5, v6, v7
	v_cvt_pk_bf16_f32 v6, v0, v1
	v_cvt_pk_bf16_f32 v7, v2, v3
	s_nop 1
	v_cvt_pk_bf16_f32 v17, v100, v101
	v_add_co_u32_e32 v100, vcc, s8, v24
	v_cvt_pk_bf16_f32 v16, v102, v103
	v_cvt_pk_bf16_f32 v18, v110, v111
	v_cvt_pk_bf16_f32 v19, v108, v109
	s_mov_b64 s[8:9], 0x10000
	s_nop 0
	v_addc_co_u32_e32 v101, vcc, 0, v25, vcc
	global_store_dwordx4 v[100:101], v[16:19], off sc1
	s_nop 1
	v_cvt_pk_bf16_f32 v16, v114, v115
	v_cvt_pk_bf16_f32 v17, v112, v113
	v_cvt_pk_bf16_f32 v18, v118, v119
	v_cvt_pk_bf16_f32 v19, v116, v117
	global_store_dwordx4 v[26:27], v[16:19], off offset:256 sc1
	v_lshl_add_u64 v[26:27], v[24:25], 0, s[8:9]
	s_mov_b32 s8, 0x10000
	v_cvt_pk_bf16_f32 v17, v84, v85
	v_add_co_u32_e32 v84, vcc, s8, v24
	v_cvt_pk_bf16_f32 v16, v86, v87
	v_cvt_pk_bf16_f32 v18, v94, v95
	v_cvt_pk_bf16_f32 v19, v92, v93
	s_mov_b64 s[8:9], 0x18000
	s_nop 0
	v_addc_co_u32_e32 v85, vcc, 0, v25, vcc
	global_store_dwordx4 v[84:85], v[16:19], off sc1
	s_nop 1
	v_cvt_pk_bf16_f32 v16, v98, v99
	v_cvt_pk_bf16_f32 v17, v96, v97
	v_cvt_pk_bf16_f32 v18, v106, v107
	v_cvt_pk_bf16_f32 v19, v104, v105
	global_store_dwordx4 v[26:27], v[16:19], off offset:256 sc1
	v_lshl_add_u64 v[26:27], v[24:25], 0, s[8:9]
	s_mov_b32 s8, 0x18000
	v_cvt_pk_bf16_f32 v17, v72, v73
	v_add_co_u32_e32 v72, vcc, s8, v24
	v_cvt_pk_bf16_f32 v16, v74, v75
	v_cvt_pk_bf16_f32 v18, v78, v79
	v_cvt_pk_bf16_f32 v19, v76, v77
	s_mov_b64 s[8:9], 0x40000
	s_nop 0
	v_addc_co_u32_e32 v73, vcc, 0, v25, vcc
	global_store_dwordx4 v[72:73], v[16:19], off sc1
	s_nop 1
	v_cvt_pk_bf16_f32 v16, v68, v69
	v_cvt_pk_bf16_f32 v17, v70, v71
	v_cvt_pk_bf16_f32 v18, v64, v65
	v_cvt_pk_bf16_f32 v19, v66, v67
	global_store_dwordx4 v[26:27], v[16:19], off offset:256 sc1
	v_lshl_add_u64 v[26:27], v[24:25], 0, s[8:9]
	s_mov_b32 s8, 0x40000
	v_cvt_pk_bf16_f32 v18, v56, v57
	v_add_co_u32_e32 v56, vcc, s8, v24
	v_cvt_pk_bf16_f32 v16, v60, v61
	v_cvt_pk_bf16_f32 v17, v62, v63
	v_cvt_pk_bf16_f32 v19, v58, v59
	s_mov_b64 s[8:9], 0x48000
	s_nop 0
	v_addc_co_u32_e32 v57, vcc, 0, v25, vcc
	global_store_dwordx4 v[56:57], v[16:19], off sc1
	s_nop 1
	v_cvt_pk_bf16_f32 v16, v82, v83
	v_cvt_pk_bf16_f32 v17, v80, v81
	v_cvt_pk_bf16_f32 v18, v90, v91
	v_cvt_pk_bf16_f32 v19, v88, v89
	global_store_dwordx4 v[26:27], v[16:19], off offset:256 sc1
	v_lshl_add_u64 v[26:27], v[24:25], 0, s[8:9]
	s_mov_b32 s8, 0x48000
	v_cvt_pk_bf16_f32 v17, v36, v37
	v_add_co_u32_e32 v36, vcc, s8, v24
	v_cvt_pk_bf16_f32 v16, v38, v39
	v_cvt_pk_bf16_f32 v18, v46, v47
	v_cvt_pk_bf16_f32 v19, v44, v45
	s_mov_b64 s[8:9], 0x50000
	s_nop 0
	v_addc_co_u32_e32 v37, vcc, 0, v25, vcc
	global_store_dwordx4 v[36:37], v[16:19], off sc1
	s_nop 1
	v_cvt_pk_bf16_f32 v16, v50, v51
	v_cvt_pk_bf16_f32 v17, v48, v49
	v_cvt_pk_bf16_f32 v18, v54, v55
	v_cvt_pk_bf16_f32 v19, v52, v53
	global_store_dwordx4 v[26:27], v[16:19], off offset:256 sc1
	v_lshl_add_u64 v[26:27], v[24:25], 0, s[8:9]
	s_mov_b32 s8, 0x50000
	v_cvt_pk_bf16_f32 v17, v20, v21
	v_add_co_u32_e32 v20, vcc, s8, v24
	v_cvt_pk_bf16_f32 v16, v22, v23
	v_cvt_pk_bf16_f32 v18, v30, v31
	v_cvt_pk_bf16_f32 v19, v28, v29
	s_mov_b64 s[8:9], 0x58000
	s_nop 0
	v_addc_co_u32_e32 v21, vcc, 0, v25, vcc
	global_store_dwordx4 v[20:21], v[16:19], off sc1
	v_lshl_add_u64 v[20:21], v[24:25], 0, s[8:9]
	s_mov_b64 s[8:9], -1
	v_cvt_pk_bf16_f32 v17, v32, v33
	v_cvt_pk_bf16_f32 v16, v34, v35
	v_cvt_pk_bf16_f32 v18, v42, v43
	v_cvt_pk_bf16_f32 v19, v40, v41
	global_store_dwordx4 v[26:27], v[16:19], off offset:256 sc1
	global_store_dwordx4 v[20:21], v[4:7], off offset:256 sc1
	s_nop 0
	v_cvt_pk_bf16_f32 v17, v8, v9
	v_add_co_u32_e32 v8, vcc, 0x58000, v24
	v_cvt_pk_bf16_f32 v16, v10, v11
	v_cvt_pk_bf16_f32 v18, v14, v15
	v_cvt_pk_bf16_f32 v19, v12, v13
	s_nop 1
	v_addc_co_u32_e32 v9, vcc, 0, v25, vcc
	s_andn2_b64 vcc, exec, s[38:39]
	global_store_dwordx4 v[8:9], v[16:19], off sc1
	s_cbranch_vccnz .LBB0_1324
	s_andn2_b64 vcc, exec, s[12:13]
	s_cbranch_vccnz .LBB0_1323
	s_barrier
	s_branch .LBB0_1323

; __device__ __forceinline__ unsigned cvt_pk_bf16(float lo, float hi) { unsigned r; asm("v_cvt_pk_bf16_f32 %0, %1, %2" : "=v"(r) : "v"(lo), "v"(hi)); return r; }
; __device__ __forceinline__ float bf_lo(unsigned w) { return __uint_as_float(w << 16); }
; __device__ __forceinline__ float bf_hi(unsigned w) { return __uint_as_float(w & 0xffff0000u); }
; __device__ __forceinline__ void load_row_stats(const float* sp, int row0, RowStats& r) {
;     ...
;         for (int m = 0; m < 4; ++m) { const float* p = sp + (size_t)(row0 + ai * HALF + m * 16) * 8; const f32x4 a = *(const f32x4*)p, b = *(const f32x4*)(p + 4);
;             const float s1 = (a[0] + a[2]) + (b[0] + b[2]), s2 = (a[1] + a[3]) + (b[1] + b[3]); const float mu = s1 * (1.f / 1024.f); const float var = s2 * (1.f / 1024.f) - mu * mu;
;             r.mu[ai][m] = mu; r.rs[ai][m] = __builtin_amdgcn_rsqf(__builtin_fmaxf(var, 0.f) + 1e-5f); } }
;     __device__ __forceinline__ void operator()(const f32x4 (&acc)[2][2][4][2], const Unit& u, int wr, int wc, int fr_in, int fq_in) const {
;     ...
;                 for (int m = 0; m < 4; ++m) { const size_t off = (size_t)(row0 + ai * HALF + m * 16) * 1024 + col0 + bj * HALF; f32x4 b[2];
;                     if constexpr (BASE == 0) { b[0] = pf[m][0]; b[1] = pf[m][1]; }
;                     else { const u32x4 pw = pb[m]; b[0] = (f32x4){bf_lo(pw.x), bf_hi(pw.x), bf_lo(pw.y), bf_hi(pw.y)}; b[1] = (f32x4){bf_lo(pw.z), bf_hi(pw.z), bf_lo(pw.w), bf_hi(pw.w)}; }
;                     f32x4 z[2];
; #pragma unroll
;                     for (int n = 0; n < 2; ++n) { if constexpr (BASE == 1) b[n] = (b[n] - rst.mu[ai][m]) * rst.rs[ai][m] * gv[n] + bv[n];
;                         z[n] = b[n] * al_ + acc[ai][bj][m][n] * s_; }
;                     u32x4 w; w.x = cvt_pk_bf16(z[0][0], z[0][1]); w.y = cvt_pk_bf16(z[0][2], z[0][3]); w.z = cvt_pk_bf16(z[1][0], z[1][1]); w.w = cvt_pk_bf16(z[1][2], z[1][3]);
;                     *(u32x4*)(zb + off) = w;
.Lrs3_skip:
	s_waitcnt vmcnt(0) lgkmcnt(0)
	s_barrier
	ds_read_b64 v[208:209], v181
	ds_read_b64 v[204:205], v181 offset:128
	ds_read_b64 v[200:201], v181 offset:256
	ds_read_b64 v[196:197], v181 offset:384
	ds_read_b64 v[192:193], v181 offset:1024
	ds_read_b64 v[188:189], v181 offset:1152
	ds_read_b64 v[184:185], v181 offset:1280
	ds_read_b64 v[180:181], v181 offset:1408
	s_waitcnt lgkmcnt(0)
	v_fma_f32 v209, -v208, v208, v209
	v_max_f32_e32 v209, 0, v209
	v_add_f32_e32 v209, 0x3727c5ac, v209
	v_rsq_f32_e32 v206, v209
	v_fma_f32 v205, -v204, v204, v205
	v_max_f32_e32 v205, 0, v205
	v_add_f32_e32 v205, 0x3727c5ac, v205
	v_rsq_f32_e32 v202, v205
	v_fma_f32 v201, -v200, v200, v201
	v_max_f32_e32 v201, 0, v201
	v_add_f32_e32 v201, 0x3727c5ac, v201
	v_rsq_f32_e32 v198, v201
	v_fma_f32 v197, -v196, v196, v197
	v_max_f32_e32 v197, 0, v197
	v_add_f32_e32 v197, 0x3727c5ac, v197
	v_rsq_f32_e32 v194, v197
	v_fma_f32 v193, -v192, v192, v193
	v_max_f32_e32 v193, 0, v193
	v_add_f32_e32 v193, 0x3727c5ac, v193
	v_rsq_f32_e32 v190, v193
	v_fma_f32 v189, -v188, v188, v189
	v_max_f32_e32 v189, 0, v189
	v_add_f32_e32 v189, 0x3727c5ac, v189
	v_rsq_f32_e32 v186, v189
	v_fma_f32 v185, -v184, v184, v185
	v_max_f32_e32 v185, 0, v185
	v_add_f32_e32 v185, 0x3727c5ac, v185
	v_rsq_f32_e32 v182, v185
	v_fma_f32 v181, -v180, v180, v181
	v_max_f32_e32 v181, 0, v181
	v_add_f32_e32 v181, 0x3727c5ac, v181
	v_rsq_f32_e32 v178, v181
	s_waitcnt vmcnt(0)
	v_lshlrev_b32_e32 v165, 16, v152
	v_and_b32_e32 v181, 0xffff0000, v152
	v_lshlrev_b32_e32 v152, 16, v153
	v_and_b32_e32 v153, 0xffff0000, v153
	v_lshlrev_b32_e32 v185, 16, v154
	v_and_b32_e32 v189, 0xffff0000, v154
	v_lshlrev_b32_e32 v193, 16, v155
	v_and_b32_e32 v197, 0xffff0000, v155
	v_sub_f32_e32 v153, v153, v208
	v_sub_f32_e32 v152, v152, v208
	v_sub_f32_e32 v155, v181, v208
	v_sub_f32_e32 v154, v165, v208
	v_pk_mul_f32 v[154:155], v[206:207], v[154:155] op_sel_hi:[0,1]
	v_pk_mul_f32 v[152:153], v[206:207], v[152:153] op_sel_hi:[0,1]
	v_pk_fma_f32 v[152:153], v[138:139], v[152:153], v[142:143]
	v_pk_fma_f32 v[154:155], v[136:137], v[154:155], v[140:141]
	v_pk_mul_f32 v[152:153], v[176:177], v[152:153] op_sel_hi:[0,1]
	v_pk_mul_f32 v[154:155], v[176:177], v[154:155] op_sel_hi:[0,1]
	v_pk_fma_f32 v[126:127], v[126:127], v[174:175], v[152:153] op_sel_hi:[1,0,1]
	v_pk_fma_f32 v[124:125], v[124:125], v[174:175], v[154:155] op_sel_hi:[1,0,1]
	v_sub_f32_e32 v153, v197, v208
	v_sub_f32_e32 v152, v193, v208
	v_sub_f32_e32 v155, v189, v208
	v_sub_f32_e32 v154, v185, v208
	v_pk_mul_f32 v[154:155], v[206:207], v[154:155] op_sel_hi:[0,1]
	v_pk_mul_f32 v[152:153], v[206:207], v[152:153] op_sel_hi:[0,1]
	v_pk_fma_f32 v[152:153], v[130:131], v[152:153], v[134:135]
	v_pk_fma_f32 v[154:155], v[128:129], v[154:155], v[132:133]
	v_pk_mul_f32 v[152:153], v[176:177], v[152:153] op_sel_hi:[0,1]
	v_pk_mul_f32 v[154:155], v[176:177], v[154:155] op_sel_hi:[0,1]
	v_pk_fma_f32 v[152:153], v[122:123], v[174:175], v[152:153] op_sel_hi:[1,0,1]
	v_pk_fma_f32 v[122:123], v[120:121], v[174:175], v[154:155] op_sel_hi:[1,0,1]
	v_cvt_pk_bf16_f32 v120, v124, v125
	v_lshl_add_u64 v[124:125], s[26:27], 0, v[232:233]
	v_cvt_pk_bf16_f32 v121, v126, v127
	v_lshl_add_u64 v[232:233], v[124:125], 0, v[220:221]
	v_lshlrev_b32_e32 v125, 16, v144
	v_and_b32_e32 v127, 0xffff0000, v144
	v_lshlrev_b32_e32 v144, 16, v145
	v_and_b32_e32 v145, 0xffff0000, v145
	v_cvt_pk_bf16_f32 v122, v122, v123
	v_cvt_pk_bf16_f32 v123, v152, v153
	v_lshlrev_b32_e32 v153, 16, v146
	v_and_b32_e32 v155, 0xffff0000, v146
	v_lshlrev_b32_e32 v165, 16, v147
	v_and_b32_e32 v181, 0xffff0000, v147
	v_sub_f32_e32 v145, v145, v204
	v_sub_f32_e32 v144, v144, v204
	v_sub_f32_e32 v147, v127, v204
	v_sub_f32_e32 v146, v125, v204
	v_pk_mul_f32 v[146:147], v[202:203], v[146:147] op_sel_hi:[0,1]
	v_pk_mul_f32 v[144:145], v[202:203], v[144:145] op_sel_hi:[0,1]
	v_pk_fma_f32 v[144:145], v[138:139], v[144:145], v[142:143]
	v_pk_fma_f32 v[146:147], v[136:137], v[146:147], v[140:141]
	v_pk_mul_f32 v[144:145], v[176:177], v[144:145] op_sel_hi:[0,1]
	v_pk_mul_f32 v[146:147], v[176:177], v[146:147] op_sel_hi:[0,1]
	v_pk_fma_f32 v[118:119], v[118:119], v[174:175], v[144:145] op_sel_hi:[1,0,1]
	v_pk_fma_f32 v[116:117], v[116:117], v[174:175], v[146:147] op_sel_hi:[1,0,1]
	v_sub_f32_e32 v145, v181, v204
	v_sub_f32_e32 v144, v165, v204
	v_sub_f32_e32 v147, v155, v204
	v_sub_f32_e32 v146, v153, v204
	v_pk_mul_f32 v[146:147], v[202:203], v[146:147] op_sel_hi:[0,1]
	v_pk_mul_f32 v[144:145], v[202:203], v[144:145] op_sel_hi:[0,1]
	v_pk_fma_f32 v[144:145], v[130:131], v[144:145], v[134:135]
	v_pk_fma_f32 v[146:147], v[128:129], v[146:147], v[132:133]
	v_pk_mul_f32 v[144:145], v[176:177], v[144:145] op_sel_hi:[0,1]
	v_pk_mul_f32 v[146:147], v[176:177], v[146:147] op_sel_hi:[0,1]
	v_pk_fma_f32 v[144:145], v[114:115], v[174:175], v[144:145] op_sel_hi:[1,0,1]
	v_pk_fma_f32 v[114:115], v[112:113], v[174:175], v[146:147] op_sel_hi:[1,0,1]
	v_cvt_pk_bf16_f32 v113, v118, v119
	v_lshlrev_b32_e32 v125, 16, v242
	v_and_b32_e32 v127, 0xffff0000, v242
	v_lshlrev_b32_e32 v118, 16, v243
	v_and_b32_e32 v119, 0xffff0000, v243
	v_cvt_pk_bf16_f32 v114, v114, v115
	v_cvt_pk_bf16_f32 v115, v144, v145
	v_sub_f32_e32 v119, v119, v200
	v_sub_f32_e32 v118, v118, v200
	v_sub_f32_e32 v145, v127, v200
	v_sub_f32_e32 v144, v125, v200
	v_pk_mul_f32 v[144:145], v[198:199], v[144:145] op_sel_hi:[0,1]
	v_pk_mul_f32 v[118:119], v[198:199], v[118:119] op_sel_hi:[0,1]
	v_pk_fma_f32 v[118:119], v[138:139], v[118:119], v[142:143]
	v_pk_fma_f32 v[144:145], v[136:137], v[144:145], v[140:141]
	v_lshlrev_b32_e32 v146, 16, v244
	v_and_b32_e32 v147, 0xffff0000, v244
; __device__ __forceinline__ unsigned cvt_pk_bf16(float lo, float hi) { unsigned r; asm("v_cvt_pk_bf16_f32 %0, %1, %2" : "=v"(r) : "v"(lo), "v"(hi)); return r; }
; __device__ __forceinline__ float bf_lo(unsigned w) { return __uint_as_float(w << 16); }
; __device__ __forceinline__ float bf_hi(unsigned w) { return __uint_as_float(w & 0xffff0000u); }
;     __device__ __forceinline__ void operator()(const f32x4 (&acc)[2][2][4][2], const Unit& u, int wr, int wc, int fr_in, int fq_in) const {
;     ...
;                 for (int m = 0; m < 4; ++m) { const size_t off = (size_t)(row0 + ai * HALF + m * 16) * 1024 + col0 + bj * HALF; f32x4 b[2];
;                     if constexpr (BASE == 0) { b[0] = pf[m][0]; b[1] = pf[m][1]; }
;                     else { const u32x4 pw = pb[m]; b[0] = (f32x4){bf_lo(pw.x), bf_hi(pw.x), bf_lo(pw.y), bf_hi(pw.y)}; b[1] = (f32x4){bf_lo(pw.z), bf_hi(pw.z), bf_lo(pw.w), bf_hi(pw.w)}; }
;                     f32x4 z[2];
; #pragma unroll
;                     for (int n = 0; n < 2; ++n) { if constexpr (BASE == 1) b[n] = (b[n] - rst.mu[ai][m]) * rst.rs[ai][m] * gv[n] + bv[n];
;                         z[n] = b[n] * al_ + acc[ai][bj][m][n] * s_; }
;                     u32x4 w; w.x = cvt_pk_bf16(z[0][0], z[0][1]); w.y = cvt_pk_bf16(z[0][2], z[0][3]); w.z = cvt_pk_bf16(z[1][0], z[1][1]); w.w = cvt_pk_bf16(z[1][2], z[1][3]);
;                     *(u32x4*)(zb + off) = w;
;                     const float r0 = bf_lo(w.x), r1 = bf_hi(w.x), r2 = bf_lo(w.y), r3 = bf_hi(w.y), r4 = bf_lo(w.z), r5 = bf_hi(w.z), r6 = bf_lo(w.w), r7 = bf_hi(w.w);
	v_lshlrev_b32_e32 v153, 16, v245
	v_and_b32_e32 v155, 0xffff0000, v245
	v_pk_mul_f32 v[144:145], v[176:177], v[144:145] op_sel_hi:[0,1]
	v_pk_mul_f32 v[118:119], v[176:177], v[118:119] op_sel_hi:[0,1]
	v_pk_fma_f32 v[110:111], v[110:111], v[174:175], v[118:119] op_sel_hi:[1,0,1]
	v_pk_fma_f32 v[108:109], v[108:109], v[174:175], v[144:145] op_sel_hi:[1,0,1]
	v_sub_f32_e32 v119, v155, v200
	v_sub_f32_e32 v118, v153, v200
	v_sub_f32_e32 v145, v147, v200
	v_sub_f32_e32 v144, v146, v200
	v_pk_mul_f32 v[144:145], v[198:199], v[144:145] op_sel_hi:[0,1]
	v_pk_mul_f32 v[118:119], v[198:199], v[118:119] op_sel_hi:[0,1]
	v_pk_fma_f32 v[118:119], v[130:131], v[118:119], v[134:135]
	v_pk_fma_f32 v[144:145], v[128:129], v[144:145], v[132:133]
	v_pk_mul_f32 v[118:119], v[176:177], v[118:119] op_sel_hi:[0,1]
	v_pk_mul_f32 v[144:145], v[176:177], v[144:145] op_sel_hi:[0,1]
	v_pk_fma_f32 v[118:119], v[106:107], v[174:175], v[118:119] op_sel_hi:[1,0,1]
	v_pk_fma_f32 v[106:107], v[104:105], v[174:175], v[144:145] op_sel_hi:[1,0,1]
	v_cvt_pk_bf16_f32 v105, v110, v111
	v_lshlrev_b32_e32 v110, 16, v149
	v_cvt_pk_bf16_f32 v106, v106, v107
	v_cvt_pk_bf16_f32 v107, v118, v119
	v_lshlrev_b32_e32 v118, 16, v148
	v_and_b32_e32 v119, 0xffff0000, v148
	v_and_b32_e32 v111, 0xffff0000, v149
	v_sub_f32_e32 v111, v111, v196
	v_sub_f32_e32 v110, v110, v196
	v_sub_f32_e32 v119, v119, v196
	v_sub_f32_e32 v118, v118, v196
	v_pk_mul_f32 v[118:119], v[194:195], v[118:119] op_sel_hi:[0,1]
	v_pk_mul_f32 v[110:111], v[194:195], v[110:111] op_sel_hi:[0,1]
	v_pk_fma_f32 v[110:111], v[138:139], v[110:111], v[142:143]
	v_pk_fma_f32 v[118:119], v[136:137], v[118:119], v[140:141]
	v_lshlrev_b32_e32 v125, 16, v150
	v_and_b32_e32 v127, 0xffff0000, v150
	v_lshlrev_b32_e32 v144, 16, v151
	v_and_b32_e32 v145, 0xffff0000, v151
	v_pk_mul_f32 v[118:119], v[176:177], v[118:119] op_sel_hi:[0,1]
	v_pk_mul_f32 v[110:111], v[176:177], v[110:111] op_sel_hi:[0,1]
	v_pk_fma_f32 v[102:103], v[102:103], v[174:175], v[110:111] op_sel_hi:[1,0,1]
	v_pk_fma_f32 v[100:101], v[100:101], v[174:175], v[118:119] op_sel_hi:[1,0,1]
	v_sub_f32_e32 v111, v145, v196
	v_sub_f32_e32 v110, v144, v196
	v_sub_f32_e32 v119, v127, v196
	v_sub_f32_e32 v118, v125, v196
	v_pk_mul_f32 v[118:119], v[194:195], v[118:119] op_sel_hi:[0,1]
	v_pk_mul_f32 v[110:111], v[194:195], v[110:111] op_sel_hi:[0,1]
	v_pk_fma_f32 v[110:111], v[130:131], v[110:111], v[134:135]
	v_pk_fma_f32 v[118:119], v[128:129], v[118:119], v[132:133]
	v_pk_mul_f32 v[110:111], v[176:177], v[110:111] op_sel_hi:[0,1]
	v_pk_mul_f32 v[118:119], v[176:177], v[118:119] op_sel_hi:[0,1]
	v_cvt_pk_bf16_f32 v112, v116, v117
	v_lshl_add_u64 v[116:117], s[26:27], 0, v[236:237]
	v_cvt_pk_bf16_f32 v104, v108, v109
	v_lshl_add_u64 v[108:109], s[26:27], 0, v[240:241]
	v_pk_fma_f32 v[110:111], v[98:99], v[174:175], v[110:111] op_sel_hi:[1,0,1]
	v_pk_fma_f32 v[98:99], v[96:97], v[174:175], v[118:119] op_sel_hi:[1,0,1]
	v_cvt_pk_bf16_f32 v96, v100, v101
	v_lshl_add_u64 v[100:101], s[26:27], 0, v[238:239]
	v_lshl_add_u64 v[116:117], v[116:117], 0, v[220:221]
	v_lshl_add_u64 v[108:109], v[108:109], 0, v[220:221]
	v_lshl_add_u64 v[100:101], v[100:101], 0, v[220:221]
	global_store_dwordx4 v[232:233], v[120:123], off sc1
	global_store_dwordx4 v[116:117], v[112:115], off sc1
	global_store_dwordx4 v[108:109], v[104:107], off sc1
	v_cvt_pk_bf16_f32 v97, v102, v103
	v_cvt_pk_bf16_f32 v98, v98, v99
	v_cvt_pk_bf16_f32 v99, v110, v111
	global_store_dwordx4 v[100:101], v[96:99], off sc1
	v_lshlrev_b64 v[144:145], 11, v[222:223]
	v_lshl_add_u64 v[102:103], v[234:235], 0, v[144:145]
	global_load_dwordx4 v[236:239], v[102:103], off
	v_lshlrev_b64 v[146:147], 11, v[226:227]
	v_lshl_add_u64 v[110:111], v[234:235], 0, v[146:147]
	global_load_dwordx4 v[240:243], v[110:111], off
	v_lshlrev_b64 v[150:151], 11, v[210:211]
	v_lshl_add_u64 v[148:149], v[234:235], 0, v[150:151]
	global_load_dwordx4 v[244:247], v[148:149], off
	v_lshlrev_b64 v[210:211], 11, v[212:213]
	v_lshl_add_u64 v[118:119], v[234:235], 0, v[210:211]
	global_load_dwordx4 v[248:251], v[118:119], off
	v_and_b32_e32 v154, 0xffff0000, v120
	v_lshlrev_b32_e32 v152, 16, v121
	v_and_b32_e32 v126, 0xffff0000, v122
	v_lshlrev_b32_e32 v124, 16, v123
	s_waitcnt vmcnt(0)
; __device__ __forceinline__ unsigned cvt_pk_bf16(float lo, float hi) { unsigned r; asm("v_cvt_pk_bf16_f32 %0, %1, %2" : "=v"(r) : "v"(lo), "v"(hi)); return r; }
; __device__ __forceinline__ float bf_lo(unsigned w) { return __uint_as_float(w << 16); }
; __device__ __forceinline__ float bf_hi(unsigned w) { return __uint_as_float(w & 0xffff0000u); }
;     __device__ __forceinline__ void operator()(const f32x4 (&acc)[2][2][4][2], const Unit& u, int wr, int wc, int fr_in, int fq_in) const {
;     ...
;                 for (int m = 0; m < 4; ++m) { const size_t off = (size_t)(row0 + ai * HALF + m * 16) * 1024 + col0 + bj * HALF; f32x4 b[2];
;                     if constexpr (BASE == 0) { b[0] = pf[m][0]; b[1] = pf[m][1]; }
;                     else { const u32x4 pw = pb[m]; b[0] = (f32x4){bf_lo(pw.x), bf_hi(pw.x), bf_lo(pw.y), bf_hi(pw.y)}; b[1] = (f32x4){bf_lo(pw.z), bf_hi(pw.z), bf_lo(pw.w), bf_hi(pw.w)}; }
;                     f32x4 z[2];
; #pragma unroll
;                     for (int n = 0; n < 2; ++n) { if constexpr (BASE == 1) b[n] = (b[n] - rst.mu[ai][m]) * rst.rs[ai][m] * gv[n] + bv[n];
;                         z[n] = b[n] * al_ + acc[ai][bj][m][n] * s_; }
;                     u32x4 w; w.x = cvt_pk_bf16(z[0][0], z[0][1]); w.y = cvt_pk_bf16(z[0][2], z[0][3]); w.z = cvt_pk_bf16(z[1][0], z[1][1]); w.w = cvt_pk_bf16(z[1][2], z[1][3]);
;                     *(u32x4*)(zb + off) = w;
	v_lshlrev_b32_e32 v125, 16, v236
	v_and_b32_e32 v127, 0xffff0000, v236
	v_lshlrev_b32_e32 v153, 16, v237
	v_and_b32_e32 v155, 0xffff0000, v237
	v_sub_f32_e32 v213, v155, v192
	v_sub_f32_e32 v212, v153, v192
	v_sub_f32_e32 v223, v127, v192
	v_sub_f32_e32 v222, v125, v192
	v_pk_mul_f32 v[222:223], v[190:191], v[222:223] op_sel_hi:[0,1]
	v_pk_mul_f32 v[212:213], v[190:191], v[212:213] op_sel_hi:[0,1]
	v_pk_fma_f32 v[212:213], v[138:139], v[212:213], v[142:143]
	v_pk_fma_f32 v[222:223], v[136:137], v[222:223], v[140:141]
	v_lshlrev_b32_e32 v165, 16, v238
	v_and_b32_e32 v181, 0xffff0000, v238
	v_lshlrev_b32_e32 v185, 16, v239
	v_and_b32_e32 v189, 0xffff0000, v239
	v_pk_mul_f32 v[222:223], v[176:177], v[222:223] op_sel_hi:[0,1]
	v_pk_mul_f32 v[212:213], v[176:177], v[212:213] op_sel_hi:[0,1]
	v_pk_fma_f32 v[94:95], v[94:95], v[174:175], v[212:213] op_sel_hi:[1,0,1]
	v_pk_fma_f32 v[92:93], v[92:93], v[174:175], v[222:223] op_sel_hi:[1,0,1]
	v_sub_f32_e32 v213, v189, v192
	v_sub_f32_e32 v212, v185, v192
	v_sub_f32_e32 v223, v181, v192
	v_sub_f32_e32 v222, v165, v192
	v_pk_mul_f32 v[222:223], v[190:191], v[222:223] op_sel_hi:[0,1]
	v_pk_mul_f32 v[212:213], v[190:191], v[212:213] op_sel_hi:[0,1]
	v_pk_fma_f32 v[212:213], v[130:131], v[212:213], v[134:135]
	v_pk_fma_f32 v[222:223], v[128:129], v[222:223], v[132:133]
	v_pk_mul_f32 v[212:213], v[176:177], v[212:213] op_sel_hi:[0,1]
	v_pk_mul_f32 v[222:223], v[176:177], v[222:223] op_sel_hi:[0,1]
	v_pk_fma_f32 v[212:213], v[90:91], v[174:175], v[212:213] op_sel_hi:[1,0,1]
	v_pk_fma_f32 v[90:91], v[88:89], v[174:175], v[222:223] op_sel_hi:[1,0,1]
	v_cvt_pk_bf16_f32 v88, v92, v93
	v_lshl_add_u64 v[92:93], s[26:27], 0, v[144:145]
	v_cvt_pk_bf16_f32 v89, v94, v95
	v_lshl_add_u64 v[144:145], v[92:93], 0, v[220:221]
	v_lshlrev_b32_e32 v94, 16, v240
	v_and_b32_e32 v95, 0xffff0000, v240
	v_lshlrev_b32_e32 v92, 16, v241
	v_and_b32_e32 v93, 0xffff0000, v241
	v_sub_f32_e32 v93, v93, v188
	v_sub_f32_e32 v92, v92, v188
	v_sub_f32_e32 v95, v95, v188
	v_sub_f32_e32 v94, v94, v188
	v_pk_mul_f32 v[94:95], v[186:187], v[94:95] op_sel_hi:[0,1]
	v_pk_mul_f32 v[92:93], v[186:187], v[92:93] op_sel_hi:[0,1]
	v_pk_fma_f32 v[92:93], v[138:139], v[92:93], v[142:143]
	v_pk_fma_f32 v[94:95], v[136:137], v[94:95], v[140:141]
	v_lshlrev_b32_e32 v125, 16, v242
	v_and_b32_e32 v127, 0xffff0000, v242
	v_lshlrev_b32_e32 v153, 16, v243
	v_and_b32_e32 v155, 0xffff0000, v243
	v_pk_mul_f32 v[94:95], v[176:177], v[94:95] op_sel_hi:[0,1]
	v_pk_mul_f32 v[92:93], v[176:177], v[92:93] op_sel_hi:[0,1]
	v_pk_fma_f32 v[86:87], v[86:87], v[174:175], v[92:93] op_sel_hi:[1,0,1]
	v_pk_fma_f32 v[84:85], v[84:85], v[174:175], v[94:95] op_sel_hi:[1,0,1]
	v_sub_f32_e32 v93, v155, v188
	v_sub_f32_e32 v92, v153, v188
	v_sub_f32_e32 v95, v127, v188
	v_sub_f32_e32 v94, v125, v188
	v_pk_mul_f32 v[94:95], v[186:187], v[94:95] op_sel_hi:[0,1]
	v_pk_mul_f32 v[92:93], v[186:187], v[92:93] op_sel_hi:[0,1]
	v_pk_fma_f32 v[92:93], v[130:131], v[92:93], v[134:135]
	v_pk_fma_f32 v[94:95], v[128:129], v[94:95], v[132:133]
	v_pk_mul_f32 v[92:93], v[176:177], v[92:93] op_sel_hi:[0,1]
	v_pk_mul_f32 v[94:95], v[176:177], v[94:95] op_sel_hi:[0,1]
	v_pk_fma_f32 v[92:93], v[82:83], v[174:175], v[92:93] op_sel_hi:[1,0,1]
	v_pk_fma_f32 v[82:83], v[80:81], v[174:175], v[94:95] op_sel_hi:[1,0,1]
	v_cvt_pk_bf16_f32 v80, v84, v85
	v_lshl_add_u64 v[84:85], s[26:27], 0, v[146:147]
	v_cvt_pk_bf16_f32 v81, v86, v87
	v_lshl_add_u64 v[146:147], v[84:85], 0, v[220:221]
	v_lshlrev_b32_e32 v86, 16, v244
	v_and_b32_e32 v87, 0xffff0000, v244
	v_lshlrev_b32_e32 v84, 16, v245
	v_and_b32_e32 v85, 0xffff0000, v245
	v_sub_f32_e32 v85, v85, v184
	v_sub_f32_e32 v84, v84, v184
	v_sub_f32_e32 v87, v87, v184
	v_sub_f32_e32 v86, v86, v184
	v_pk_mul_f32 v[86:87], v[182:183], v[86:87] op_sel_hi:[0,1]
	v_pk_mul_f32 v[84:85], v[182:183], v[84:85] op_sel_hi:[0,1]
	v_pk_fma_f32 v[84:85], v[138:139], v[84:85], v[142:143]
	v_pk_fma_f32 v[86:87], v[136:137], v[86:87], v[140:141]
	v_cvt_pk_bf16_f32 v82, v82, v83
	v_cvt_pk_bf16_f32 v83, v92, v93
	v_lshlrev_b32_e32 v92, 16, v246
	v_and_b32_e32 v93, 0xffff0000, v246
	v_lshlrev_b32_e32 v94, 16, v247
	v_and_b32_e32 v95, 0xffff0000, v247
	v_pk_mul_f32 v[86:87], v[176:177], v[86:87] op_sel_hi:[0,1]
	v_pk_mul_f32 v[84:85], v[176:177], v[84:85] op_sel_hi:[0,1]
	v_pk_fma_f32 v[78:79], v[78:79], v[174:175], v[84:85] op_sel_hi:[1,0,1]
	v_pk_fma_f32 v[76:77], v[76:77], v[174:175], v[86:87] op_sel_hi:[1,0,1]
	v_sub_f32_e32 v85, v95, v184
	v_sub_f32_e32 v84, v94, v184
	v_sub_f32_e32 v87, v93, v184
	v_sub_f32_e32 v86, v92, v184
	v_pk_mul_f32 v[86:87], v[182:183], v[86:87] op_sel_hi:[0,1]
	v_pk_mul_f32 v[84:85], v[182:183], v[84:85] op_sel_hi:[0,1]
	v_pk_fma_f32 v[84:85], v[130:131], v[84:85], v[134:135]
	v_pk_fma_f32 v[86:87], v[128:129], v[86:87], v[132:133]
	v_pk_mul_f32 v[84:85], v[176:177], v[84:85] op_sel_hi:[0,1]
	v_pk_mul_f32 v[86:87], v[176:177], v[86:87] op_sel_hi:[0,1]
	v_pk_fma_f32 v[84:85], v[74:75], v[174:175], v[84:85] op_sel_hi:[1,0,1]
	v_pk_fma_f32 v[74:75], v[72:73], v[174:175], v[86:87] op_sel_hi:[1,0,1]
	v_cvt_pk_bf16_f32 v72, v76, v77
	v_lshl_add_u64 v[76:77], s[26:27], 0, v[150:151]
	v_cvt_pk_bf16_f32 v73, v78, v79
	v_lshl_add_u64 v[150:151], v[76:77], 0, v[220:221]
	v_lshlrev_b32_e32 v78, 16, v248
	v_and_b32_e32 v79, 0xffff0000, v248
	v_lshlrev_b32_e32 v76, 16, v249
	v_and_b32_e32 v77, 0xffff0000, v249
	v_sub_f32_e32 v77, v77, v180
	v_sub_f32_e32 v76, v76, v180
	v_sub_f32_e32 v79, v79, v180
	v_sub_f32_e32 v78, v78, v180
	v_pk_mul_f32 v[78:79], v[178:179], v[78:79] op_sel_hi:[0,1]
	v_pk_mul_f32 v[76:77], v[178:179], v[76:77] op_sel_hi:[0,1]
; __device__ __forceinline__ unsigned cvt_pk_bf16(float lo, float hi) { unsigned r; asm("v_cvt_pk_bf16_f32 %0, %1, %2" : "=v"(r) : "v"(lo), "v"(hi)); return r; }
; __device__ __forceinline__ float bf_lo(unsigned w) { return __uint_as_float(w << 16); }
; __device__ __forceinline__ float bf_hi(unsigned w) { return __uint_as_float(w & 0xffff0000u); }
;     __device__ __forceinline__ void operator()(const f32x4 (&acc)[2][2][4][2], const Unit& u, int wr, int wc, int fr_in, int fq_in) const {
;     ...
;                 for (int m = 0; m < 4; ++m) { const size_t off = (size_t)(row0 + ai * HALF + m * 16) * 1024 + col0 + bj * HALF; f32x4 b[2];
;                     if constexpr (BASE == 0) { b[0] = pf[m][0]; b[1] = pf[m][1]; }
;                     else { const u32x4 pw = pb[m]; b[0] = (f32x4){bf_lo(pw.x), bf_hi(pw.x), bf_lo(pw.y), bf_hi(pw.y)}; b[1] = (f32x4){bf_lo(pw.z), bf_hi(pw.z), bf_lo(pw.w), bf_hi(pw.w)}; }
;                     f32x4 z[2];
; #pragma unroll
;                     for (int n = 0; n < 2; ++n) { if constexpr (BASE == 1) b[n] = (b[n] - rst.mu[ai][m]) * rst.rs[ai][m] * gv[n] + bv[n];
;                         z[n] = b[n] * al_ + acc[ai][bj][m][n] * s_; }
;                     u32x4 w; w.x = cvt_pk_bf16(z[0][0], z[0][1]); w.y = cvt_pk_bf16(z[0][2], z[0][3]); w.z = cvt_pk_bf16(z[1][0], z[1][1]); w.w = cvt_pk_bf16(z[1][2], z[1][3]);
;                     *(u32x4*)(zb + off) = w;
;                     const float r0 = bf_lo(w.x), r1 = bf_hi(w.x), r2 = bf_lo(w.y), r3 = bf_hi(w.y), r4 = bf_lo(w.z), r5 = bf_hi(w.z), r6 = bf_lo(w.w), r7 = bf_hi(w.w);
;                     s1[ai][m] += ((r0 + r1) + (r2 + r3)) + ((r4 + r5) + (r6 + r7)); s2[ai][m] += ((r0 * r0 + r1 * r1) + (r2 * r2 + r3 * r3)) + ((r4 * r4 + r5 * r5) + (r6 * r6 + r7 * r7)); }
	v_pk_fma_f32 v[76:77], v[138:139], v[76:77], v[142:143]
	v_pk_fma_f32 v[78:79], v[136:137], v[78:79], v[140:141]
	v_cvt_pk_bf16_f32 v74, v74, v75
	v_cvt_pk_bf16_f32 v75, v84, v85
	v_lshlrev_b32_e32 v84, 16, v250
	v_and_b32_e32 v85, 0xffff0000, v250
	v_lshlrev_b32_e32 v86, 16, v251
	v_and_b32_e32 v87, 0xffff0000, v251
	v_pk_mul_f32 v[78:79], v[176:177], v[78:79] op_sel_hi:[0,1]
	v_pk_mul_f32 v[76:77], v[176:177], v[76:77] op_sel_hi:[0,1]
	v_pk_fma_f32 v[70:71], v[70:71], v[174:175], v[76:77] op_sel_hi:[1,0,1]
	v_pk_fma_f32 v[68:69], v[68:69], v[174:175], v[78:79] op_sel_hi:[1,0,1]
	v_sub_f32_e32 v77, v87, v180
	v_sub_f32_e32 v76, v86, v180
	v_sub_f32_e32 v79, v85, v180
	v_sub_f32_e32 v78, v84, v180
	v_pk_mul_f32 v[78:79], v[178:179], v[78:79] op_sel_hi:[0,1]
	v_pk_mul_f32 v[76:77], v[178:179], v[76:77] op_sel_hi:[0,1]
	v_pk_fma_f32 v[76:77], v[130:131], v[76:77], v[134:135]
	v_pk_fma_f32 v[78:79], v[128:129], v[78:79], v[132:133]
	v_pk_mul_f32 v[76:77], v[176:177], v[76:77] op_sel_hi:[0,1]
	v_pk_mul_f32 v[78:79], v[176:177], v[78:79] op_sel_hi:[0,1]
	v_pk_fma_f32 v[76:77], v[66:67], v[174:175], v[76:77] op_sel_hi:[1,0,1]
	v_pk_fma_f32 v[66:67], v[64:65], v[174:175], v[78:79] op_sel_hi:[1,0,1]
	v_cvt_pk_bf16_f32 v64, v68, v69
	v_lshl_add_u64 v[68:69], s[26:27], 0, v[210:211]
	v_lshl_add_u64 v[128:129], v[68:69], 0, v[220:221]
	v_cvt_pk_bf16_f32 v90, v90, v91
	v_cvt_pk_bf16_f32 v91, v212, v213
	global_store_dwordx4 v[144:145], v[88:91], off sc1
	global_store_dwordx4 v[146:147], v[80:83], off sc1
	global_store_dwordx4 v[150:151], v[72:75], off sc1
	v_cvt_pk_bf16_f32 v65, v70, v71
	v_cvt_pk_bf16_f32 v66, v66, v67
	v_cvt_pk_bf16_f32 v67, v76, v77
	global_store_dwordx4 v[128:129], v[64:67], off sc1
	global_load_dwordx4 v[68:71], v[216:217], off offset:528
	global_load_dwordx4 v[84:87], v[216:217], off offset:512
	global_load_dwordx4 v[76:79], v[214:215], off offset:528
	global_load_dwordx4 v[92:95], v[214:215], off offset:512
	global_load_dwordx4 v[130:133], v[218:219], off offset:256
	global_load_dwordx4 v[134:137], v[224:225], off offset:256
	global_load_dwordx4 v[138:141], v[228:229], off offset:256
	global_load_dwordx4 v[210:213], v[230:231], off offset:256
	s_waitcnt vmcnt(0)
	v_lshlrev_b32_e32 v125, 16, v130
	v_and_b32_e32 v127, 0xffff0000, v130
	v_lshlrev_b32_e32 v130, 16, v131
	v_and_b32_e32 v131, 0xffff0000, v131
	v_lshlrev_b32_e32 v142, 16, v132
	v_and_b32_e32 v143, 0xffff0000, v132
	v_lshlrev_b32_e32 v153, 16, v133
	v_and_b32_e32 v155, 0xffff0000, v133
	v_sub_f32_e32 v131, v131, v208
	v_sub_f32_e32 v130, v130, v208
	v_sub_f32_e32 v133, v127, v208
	v_sub_f32_e32 v132, v125, v208
	v_pk_mul_f32 v[132:133], v[206:207], v[132:133] op_sel_hi:[0,1]
	v_pk_mul_f32 v[130:131], v[206:207], v[130:131] op_sel_hi:[0,1]
	v_pk_fma_f32 v[130:131], v[86:87], v[130:131], v[94:95]
	v_pk_fma_f32 v[132:133], v[84:85], v[132:133], v[92:93]
	v_pk_mul_f32 v[130:131], v[176:177], v[130:131] op_sel_hi:[0,1]
	v_pk_mul_f32 v[132:133], v[176:177], v[132:133] op_sel_hi:[0,1]
	v_pk_fma_f32 v[62:63], v[62:63], v[174:175], v[130:131] op_sel_hi:[1,0,1]
	v_pk_fma_f32 v[60:61], v[60:61], v[174:175], v[132:133] op_sel_hi:[1,0,1]
	v_sub_f32_e32 v131, v155, v208
	v_sub_f32_e32 v130, v153, v208
	v_sub_f32_e32 v133, v143, v208
	v_sub_f32_e32 v132, v142, v208
	v_pk_mul_f32 v[132:133], v[206:207], v[132:133] op_sel_hi:[0,1]
	v_pk_mul_f32 v[130:131], v[206:207], v[130:131] op_sel_hi:[0,1]
	v_pk_fma_f32 v[130:131], v[70:71], v[130:131], v[78:79]
	v_pk_fma_f32 v[132:133], v[68:69], v[132:133], v[76:77]
	v_pk_mul_f32 v[130:131], v[176:177], v[130:131] op_sel_hi:[0,1]
	v_pk_mul_f32 v[132:133], v[176:177], v[132:133] op_sel_hi:[0,1]
	v_pk_fma_f32 v[130:131], v[58:59], v[174:175], v[130:131] op_sel_hi:[1,0,1]
	v_pk_fma_f32 v[58:59], v[56:57], v[174:175], v[132:133] op_sel_hi:[1,0,1]
	v_cvt_pk_bf16_f32 v57, v62, v63
	v_cvt_pk_bf16_f32 v56, v60, v61
	v_and_b32_e32 v125, 0xffff0000, v134
	v_cvt_pk_bf16_f32 v58, v58, v59
	v_cvt_pk_bf16_f32 v59, v130, v131
	global_store_dwordx4 v[232:233], v[56:59], off offset:256 sc1
	v_and_b32_e32 v63, 0xffff0000, v59
	v_and_b32_e32 v62, 0xffff0000, v58
	v_lshlrev_b32_e32 v61, 16, v59
	v_lshlrev_b32_e32 v60, 16, v58
	v_pk_mul_f32 v[58:59], v[62:63], v[62:63]
	v_lshlrev_b32_e32 v127, 16, v135
	v_pk_fma_f32 v[58:59], v[60:61], v[60:61], v[58:59]
	v_and_b32_e32 v130, 0xffff0000, v135
	v_pk_add_f32 v[58:59], v[58:59], v[58:59] op_sel_hi:[0,1]
	v_lshlrev_b32_e32 v58, 16, v134
	v_sub_f32_e32 v131, v130, v204
	v_sub_f32_e32 v130, v127, v204
	v_sub_f32_e32 v133, v125, v204
	v_sub_f32_e32 v132, v58, v204
	v_pk_mul_f32 v[132:133], v[202:203], v[132:133] op_sel_hi:[0,1]
	v_pk_mul_f32 v[130:131], v[202:203], v[130:131] op_sel_hi:[0,1]
	v_pk_fma_f32 v[130:131], v[86:87], v[130:131], v[94:95]
	v_pk_fma_f32 v[132:133], v[84:85], v[132:133], v[92:93]
	v_lshlrev_b32_e32 v134, 16, v136
	v_and_b32_e32 v135, 0xffff0000, v136
	v_lshlrev_b32_e32 v136, 16, v137
	v_and_b32_e32 v137, 0xffff0000, v137
	v_pk_mul_f32 v[132:133], v[176:177], v[132:133] op_sel_hi:[0,1]
	v_pk_mul_f32 v[130:131], v[176:177], v[130:131] op_sel_hi:[0,1]
	v_pk_fma_f32 v[54:55], v[54:55], v[174:175], v[130:131] op_sel_hi:[1,0,1]
	v_pk_fma_f32 v[52:53], v[52:53], v[174:175], v[132:133] op_sel_hi:[1,0,1]
	v_sub_f32_e32 v131, v137, v204
	v_sub_f32_e32 v130, v136, v204
	v_sub_f32_e32 v133, v135, v204
	v_sub_f32_e32 v132, v134, v204
	v_pk_mul_f32 v[132:133], v[202:203], v[132:133] op_sel_hi:[0,1]
	v_pk_mul_f32 v[130:131], v[202:203], v[130:131] op_sel_hi:[0,1]
	v_pk_fma_f32 v[130:131], v[70:71], v[130:131], v[78:79]
	v_pk_fma_f32 v[132:133], v[68:69], v[132:133], v[76:77]
	v_pk_mul_f32 v[130:131], v[176:177], v[130:131] op_sel_hi:[0,1]
; __device__ __forceinline__ unsigned cvt_pk_bf16(float lo, float hi) { unsigned r; asm("v_cvt_pk_bf16_f32 %0, %1, %2" : "=v"(r) : "v"(lo), "v"(hi)); return r; }
; __device__ __forceinline__ float bf_lo(unsigned w) { return __uint_as_float(w << 16); }
; __device__ __forceinline__ float bf_hi(unsigned w) { return __uint_as_float(w & 0xffff0000u); }
;     __device__ __forceinline__ void operator()(const f32x4 (&acc)[2][2][4][2], const Unit& u, int wr, int wc, int fr_in, int fq_in) const {
;     ...
;                 for (int m = 0; m < 4; ++m) { const size_t off = (size_t)(row0 + ai * HALF + m * 16) * 1024 + col0 + bj * HALF; f32x4 b[2];
;                     if constexpr (BASE == 0) { b[0] = pf[m][0]; b[1] = pf[m][1]; }
;                     else { const u32x4 pw = pb[m]; b[0] = (f32x4){bf_lo(pw.x), bf_hi(pw.x), bf_lo(pw.y), bf_hi(pw.y)}; b[1] = (f32x4){bf_lo(pw.z), bf_hi(pw.z), bf_lo(pw.w), bf_hi(pw.w)}; }
;                     f32x4 z[2];
; #pragma unroll
;                     for (int n = 0; n < 2; ++n) { if constexpr (BASE == 1) b[n] = (b[n] - rst.mu[ai][m]) * rst.rs[ai][m] * gv[n] + bv[n];
;                         z[n] = b[n] * al_ + acc[ai][bj][m][n] * s_; }
;                     u32x4 w; w.x = cvt_pk_bf16(z[0][0], z[0][1]); w.y = cvt_pk_bf16(z[0][2], z[0][3]); w.z = cvt_pk_bf16(z[1][0], z[1][1]); w.w = cvt_pk_bf16(z[1][2], z[1][3]);
;                     *(u32x4*)(zb + off) = w;
	v_pk_mul_f32 v[132:133], v[176:177], v[132:133] op_sel_hi:[0,1]
	v_pk_fma_f32 v[130:131], v[50:51], v[174:175], v[130:131] op_sel_hi:[1,0,1]
	v_pk_fma_f32 v[50:51], v[48:49], v[174:175], v[132:133] op_sel_hi:[1,0,1]
	v_cvt_pk_bf16_f32 v48, v52, v53
	v_cvt_pk_bf16_f32 v49, v54, v55
	v_lshlrev_b32_e32 v54, 16, v138
	v_and_b32_e32 v55, 0xffff0000, v138
	v_lshlrev_b32_e32 v52, 16, v139
	v_and_b32_e32 v53, 0xffff0000, v139
	v_sub_f32_e32 v53, v53, v200
	v_sub_f32_e32 v52, v52, v200
	v_sub_f32_e32 v55, v55, v200
	v_sub_f32_e32 v54, v54, v200
	v_pk_mul_f32 v[54:55], v[198:199], v[54:55] op_sel_hi:[0,1]
	v_pk_mul_f32 v[52:53], v[198:199], v[52:53] op_sel_hi:[0,1]
	v_pk_fma_f32 v[52:53], v[86:87], v[52:53], v[94:95]
	v_pk_fma_f32 v[54:55], v[84:85], v[54:55], v[92:93]
	v_cvt_pk_bf16_f32 v50, v50, v51
	v_cvt_pk_bf16_f32 v51, v130, v131
	global_store_dwordx4 v[116:117], v[48:51], off offset:256 sc1
	v_lshlrev_b32_e32 v58, 16, v140
	v_and_b32_e32 v116, 0xffff0000, v140
	v_lshlrev_b32_e32 v117, 16, v141
	v_and_b32_e32 v125, 0xffff0000, v141
	v_pk_mul_f32 v[54:55], v[176:177], v[54:55] op_sel_hi:[0,1]
	v_pk_mul_f32 v[52:53], v[176:177], v[52:53] op_sel_hi:[0,1]
	v_pk_fma_f32 v[46:47], v[46:47], v[174:175], v[52:53] op_sel_hi:[1,0,1]
	v_pk_fma_f32 v[44:45], v[44:45], v[174:175], v[54:55] op_sel_hi:[1,0,1]
	v_sub_f32_e32 v53, v125, v200
	v_sub_f32_e32 v52, v117, v200
	v_sub_f32_e32 v55, v116, v200
	v_sub_f32_e32 v54, v58, v200
	v_pk_mul_f32 v[54:55], v[198:199], v[54:55] op_sel_hi:[0,1]
	v_pk_mul_f32 v[52:53], v[198:199], v[52:53] op_sel_hi:[0,1]
	v_pk_fma_f32 v[52:53], v[70:71], v[52:53], v[78:79]
	v_pk_fma_f32 v[54:55], v[68:69], v[54:55], v[76:77]
	v_pk_mul_f32 v[52:53], v[176:177], v[52:53] op_sel_hi:[0,1]
	v_pk_mul_f32 v[54:55], v[176:177], v[54:55] op_sel_hi:[0,1]
	v_pk_fma_f32 v[52:53], v[42:43], v[174:175], v[52:53] op_sel_hi:[1,0,1]
	v_pk_fma_f32 v[42:43], v[40:41], v[174:175], v[54:55] op_sel_hi:[1,0,1]
	v_cvt_pk_bf16_f32 v40, v44, v45
	v_cvt_pk_bf16_f32 v41, v46, v47
	v_lshlrev_b32_e32 v46, 16, v210
	v_and_b32_e32 v47, 0xffff0000, v210
	v_lshlrev_b32_e32 v44, 16, v211
	v_and_b32_e32 v45, 0xffff0000, v211
	v_sub_f32_e32 v45, v45, v196
	v_sub_f32_e32 v44, v44, v196
	v_sub_f32_e32 v47, v47, v196
	v_sub_f32_e32 v46, v46, v196
	v_pk_mul_f32 v[46:47], v[194:195], v[46:47] op_sel_hi:[0,1]
	v_pk_mul_f32 v[44:45], v[194:195], v[44:45] op_sel_hi:[0,1]
	v_pk_fma_f32 v[44:45], v[86:87], v[44:45], v[94:95]
	v_pk_fma_f32 v[46:47], v[84:85], v[46:47], v[92:93]
	v_cvt_pk_bf16_f32 v42, v42, v43
	v_cvt_pk_bf16_f32 v43, v52, v53
	v_lshlrev_b32_e32 v52, 16, v212
	v_and_b32_e32 v53, 0xffff0000, v212
	v_lshlrev_b32_e32 v54, 16, v213
	v_and_b32_e32 v55, 0xffff0000, v213
	v_pk_mul_f32 v[46:47], v[176:177], v[46:47] op_sel_hi:[0,1]
	v_pk_mul_f32 v[44:45], v[176:177], v[44:45] op_sel_hi:[0,1]
	v_pk_fma_f32 v[38:39], v[38:39], v[174:175], v[44:45] op_sel_hi:[1,0,1]
	v_pk_fma_f32 v[36:37], v[36:37], v[174:175], v[46:47] op_sel_hi:[1,0,1]
	v_sub_f32_e32 v45, v55, v196
	v_sub_f32_e32 v44, v54, v196
	v_sub_f32_e32 v47, v53, v196
	v_sub_f32_e32 v46, v52, v196
	v_pk_mul_f32 v[46:47], v[194:195], v[46:47] op_sel_hi:[0,1]
	v_pk_mul_f32 v[44:45], v[194:195], v[44:45] op_sel_hi:[0,1]
	v_pk_fma_f32 v[44:45], v[70:71], v[44:45], v[78:79]
	v_pk_fma_f32 v[46:47], v[68:69], v[46:47], v[76:77]
	v_pk_mul_f32 v[44:45], v[176:177], v[44:45] op_sel_hi:[0,1]
	v_pk_mul_f32 v[46:47], v[176:177], v[46:47] op_sel_hi:[0,1]
	v_pk_fma_f32 v[44:45], v[34:35], v[174:175], v[44:45] op_sel_hi:[1,0,1]
	v_pk_fma_f32 v[34:35], v[32:33], v[174:175], v[46:47] op_sel_hi:[1,0,1]
	global_store_dwordx4 v[108:109], v[40:43], off offset:256 sc1
	v_cvt_pk_bf16_f32 v32, v36, v37
	v_cvt_pk_bf16_f32 v33, v38, v39
	v_cvt_pk_bf16_f32 v34, v34, v35
	v_cvt_pk_bf16_f32 v35, v44, v45
	global_store_dwordx4 v[100:101], v[32:35], off offset:256 sc1
	global_load_dwordx4 v[36:39], v[102:103], off offset:256
	global_load_dwordx4 v[44:47], v[110:111], off offset:256
	global_load_dwordx4 v[52:55], v[148:149], off offset:256
	s_nop 0
	global_load_dwordx4 v[100:103], v[118:119], off offset:256
	v_mov_b32_e32 v165, v59
	s_waitcnt vmcnt(0)
	v_lshlrev_b32_e32 v58, 16, v36
	v_and_b32_e32 v108, 0xffff0000, v36
	v_lshlrev_b32_e32 v36, 16, v37
	v_and_b32_e32 v37, 0xffff0000, v37
	v_lshlrev_b32_e32 v109, 16, v38
	v_and_b32_e32 v110, 0xffff0000, v38
	v_lshlrev_b32_e32 v111, 16, v39
	v_and_b32_e32 v116, 0xffff0000, v39
	v_sub_f32_e32 v37, v37, v192
	v_sub_f32_e32 v36, v36, v192
	v_sub_f32_e32 v39, v108, v192
	v_sub_f32_e32 v38, v58, v192
	v_pk_mul_f32 v[38:39], v[190:191], v[38:39] op_sel_hi:[0,1]
	v_pk_mul_f32 v[36:37], v[190:191], v[36:37] op_sel_hi:[0,1]
	v_pk_fma_f32 v[36:37], v[86:87], v[36:37], v[94:95]
	v_pk_fma_f32 v[38:39], v[84:85], v[38:39], v[92:93]
	v_pk_mul_f32 v[36:37], v[176:177], v[36:37] op_sel_hi:[0,1]
	v_pk_mul_f32 v[38:39], v[176:177], v[38:39] op_sel_hi:[0,1]
	v_pk_fma_f32 v[30:31], v[30:31], v[174:175], v[36:37] op_sel_hi:[1,0,1]
	v_pk_fma_f32 v[28:29], v[28:29], v[174:175], v[38:39] op_sel_hi:[1,0,1]
	v_sub_f32_e32 v37, v116, v192
	v_sub_f32_e32 v36, v111, v192
	v_sub_f32_e32 v39, v110, v192
	v_sub_f32_e32 v38, v109, v192
	v_pk_mul_f32 v[38:39], v[190:191], v[38:39] op_sel_hi:[0,1]
	v_pk_mul_f32 v[36:37], v[190:191], v[36:37] op_sel_hi:[0,1]
	v_pk_fma_f32 v[36:37], v[70:71], v[36:37], v[78:79]
	v_pk_fma_f32 v[38:39], v[68:69], v[38:39], v[76:77]
	v_pk_mul_f32 v[36:37], v[176:177], v[36:37] op_sel_hi:[0,1]
	v_pk_mul_f32 v[38:39], v[176:177], v[38:39] op_sel_hi:[0,1]
	v_pk_fma_f32 v[36:37], v[26:27], v[174:175], v[36:37] op_sel_hi:[1,0,1]
	v_pk_fma_f32 v[26:27], v[24:25], v[174:175], v[38:39] op_sel_hi:[1,0,1]
; __device__ __forceinline__ unsigned cvt_pk_bf16(float lo, float hi) { unsigned r; asm("v_cvt_pk_bf16_f32 %0, %1, %2" : "=v"(r) : "v"(lo), "v"(hi)); return r; }
; __device__ __forceinline__ float bf_lo(unsigned w) { return __uint_as_float(w << 16); }
; __device__ __forceinline__ float bf_hi(unsigned w) { return __uint_as_float(w & 0xffff0000u); }
;     __device__ __forceinline__ void operator()(const f32x4 (&acc)[2][2][4][2], const Unit& u, int wr, int wc, int fr_in, int fq_in) const {
;     ...
;                 for (int m = 0; m < 4; ++m) { const size_t off = (size_t)(row0 + ai * HALF + m * 16) * 1024 + col0 + bj * HALF; f32x4 b[2];
;                     if constexpr (BASE == 0) { b[0] = pf[m][0]; b[1] = pf[m][1]; }
;                     else { const u32x4 pw = pb[m]; b[0] = (f32x4){bf_lo(pw.x), bf_hi(pw.x), bf_lo(pw.y), bf_hi(pw.y)}; b[1] = (f32x4){bf_lo(pw.z), bf_hi(pw.z), bf_lo(pw.w), bf_hi(pw.w)}; }
;                     f32x4 z[2];
; #pragma unroll
;                     for (int n = 0; n < 2; ++n) { if constexpr (BASE == 1) b[n] = (b[n] - rst.mu[ai][m]) * rst.rs[ai][m] * gv[n] + bv[n];
;                         z[n] = b[n] * al_ + acc[ai][bj][m][n] * s_; }
;                     u32x4 w; w.x = cvt_pk_bf16(z[0][0], z[0][1]); w.y = cvt_pk_bf16(z[0][2], z[0][3]); w.z = cvt_pk_bf16(z[1][0], z[1][1]); w.w = cvt_pk_bf16(z[1][2], z[1][3]);
	v_cvt_pk_bf16_f32 v24, v28, v29
	v_cvt_pk_bf16_f32 v25, v30, v31
	v_lshlrev_b32_e32 v30, 16, v44
	v_and_b32_e32 v31, 0xffff0000, v44
	v_lshlrev_b32_e32 v28, 16, v45
	v_and_b32_e32 v29, 0xffff0000, v45
	v_sub_f32_e32 v29, v29, v188
	v_sub_f32_e32 v28, v28, v188
	v_sub_f32_e32 v31, v31, v188
	v_sub_f32_e32 v30, v30, v188
	v_pk_mul_f32 v[30:31], v[186:187], v[30:31] op_sel_hi:[0,1]
	v_pk_mul_f32 v[28:29], v[186:187], v[28:29] op_sel_hi:[0,1]
	v_pk_fma_f32 v[28:29], v[86:87], v[28:29], v[94:95]
	v_pk_fma_f32 v[30:31], v[84:85], v[30:31], v[92:93]
	v_cvt_pk_bf16_f32 v26, v26, v27
	v_cvt_pk_bf16_f32 v27, v36, v37
	v_lshlrev_b32_e32 v36, 16, v46
	v_and_b32_e32 v37, 0xffff0000, v46
	v_lshlrev_b32_e32 v38, 16, v47
	v_and_b32_e32 v39, 0xffff0000, v47
	v_pk_mul_f32 v[30:31], v[176:177], v[30:31] op_sel_hi:[0,1]
	v_pk_mul_f32 v[28:29], v[176:177], v[28:29] op_sel_hi:[0,1]
	v_pk_fma_f32 v[22:23], v[22:23], v[174:175], v[28:29] op_sel_hi:[1,0,1]
	v_pk_fma_f32 v[20:21], v[20:21], v[174:175], v[30:31] op_sel_hi:[1,0,1]
	v_sub_f32_e32 v29, v39, v188
	v_sub_f32_e32 v28, v38, v188
	v_sub_f32_e32 v31, v37, v188
	v_sub_f32_e32 v30, v36, v188
	v_pk_mul_f32 v[30:31], v[186:187], v[30:31] op_sel_hi:[0,1]
	v_pk_mul_f32 v[28:29], v[186:187], v[28:29] op_sel_hi:[0,1]
	v_pk_fma_f32 v[28:29], v[70:71], v[28:29], v[78:79]
	v_pk_fma_f32 v[30:31], v[68:69], v[30:31], v[76:77]
	v_pk_mul_f32 v[28:29], v[176:177], v[28:29] op_sel_hi:[0,1]
	v_pk_mul_f32 v[30:31], v[176:177], v[30:31] op_sel_hi:[0,1]
	v_pk_fma_f32 v[28:29], v[18:19], v[174:175], v[28:29] op_sel_hi:[1,0,1]
	v_pk_fma_f32 v[18:19], v[16:17], v[174:175], v[30:31] op_sel_hi:[1,0,1]
	v_cvt_pk_bf16_f32 v16, v20, v21
	v_cvt_pk_bf16_f32 v17, v22, v23
	v_lshlrev_b32_e32 v22, 16, v52
	v_and_b32_e32 v23, 0xffff0000, v52
	v_lshlrev_b32_e32 v20, 16, v53
	v_and_b32_e32 v21, 0xffff0000, v53
	v_sub_f32_e32 v21, v21, v184
	v_sub_f32_e32 v20, v20, v184
	v_sub_f32_e32 v23, v23, v184
	v_sub_f32_e32 v22, v22, v184
	v_pk_mul_f32 v[22:23], v[182:183], v[22:23] op_sel_hi:[0,1]
	v_pk_mul_f32 v[20:21], v[182:183], v[20:21] op_sel_hi:[0,1]
	v_pk_fma_f32 v[20:21], v[86:87], v[20:21], v[94:95]
	v_pk_fma_f32 v[22:23], v[84:85], v[22:23], v[92:93]
	v_cvt_pk_bf16_f32 v18, v18, v19
	v_cvt_pk_bf16_f32 v19, v28, v29
	v_lshlrev_b32_e32 v28, 16, v54
	v_and_b32_e32 v29, 0xffff0000, v54
	v_lshlrev_b32_e32 v30, 16, v55
	v_and_b32_e32 v31, 0xffff0000, v55
	v_pk_mul_f32 v[22:23], v[176:177], v[22:23] op_sel_hi:[0,1]
	v_pk_mul_f32 v[20:21], v[176:177], v[20:21] op_sel_hi:[0,1]
	v_pk_fma_f32 v[14:15], v[14:15], v[174:175], v[20:21] op_sel_hi:[1,0,1]
	v_pk_fma_f32 v[12:13], v[12:13], v[174:175], v[22:23] op_sel_hi:[1,0,1]
	v_sub_f32_e32 v21, v31, v184
	v_sub_f32_e32 v20, v30, v184
	v_sub_f32_e32 v23, v29, v184
	v_sub_f32_e32 v22, v28, v184
	v_pk_mul_f32 v[22:23], v[182:183], v[22:23] op_sel_hi:[0,1]
	v_pk_mul_f32 v[20:21], v[182:183], v[20:21] op_sel_hi:[0,1]
	v_pk_fma_f32 v[20:21], v[70:71], v[20:21], v[78:79]
	v_pk_fma_f32 v[22:23], v[68:69], v[22:23], v[76:77]
	v_pk_mul_f32 v[20:21], v[176:177], v[20:21] op_sel_hi:[0,1]
	v_pk_mul_f32 v[22:23], v[176:177], v[22:23] op_sel_hi:[0,1]
	v_pk_fma_f32 v[20:21], v[10:11], v[174:175], v[20:21] op_sel_hi:[1,0,1]
	v_pk_fma_f32 v[10:11], v[8:9], v[174:175], v[22:23] op_sel_hi:[1,0,1]
	v_cvt_pk_bf16_f32 v8, v12, v13
	v_cvt_pk_bf16_f32 v9, v14, v15
	v_lshlrev_b32_e32 v14, 16, v100
	v_and_b32_e32 v15, 0xffff0000, v100
	v_lshlrev_b32_e32 v12, 16, v101
	v_and_b32_e32 v13, 0xffff0000, v101
	v_sub_f32_e32 v13, v13, v180
	v_sub_f32_e32 v12, v12, v180
	v_sub_f32_e32 v15, v15, v180
	v_sub_f32_e32 v14, v14, v180
	v_pk_mul_f32 v[14:15], v[178:179], v[14:15] op_sel_hi:[0,1]
	v_pk_mul_f32 v[12:13], v[178:179], v[12:13] op_sel_hi:[0,1]
	v_pk_fma_f32 v[12:13], v[86:87], v[12:13], v[94:95]
	v_pk_fma_f32 v[14:15], v[84:85], v[14:15], v[92:93]
	v_cvt_pk_bf16_f32 v10, v10, v11
	v_cvt_pk_bf16_f32 v11, v20, v21
	v_lshlrev_b32_e32 v20, 16, v102
; __device__ __forceinline__ float bf_lo(unsigned w) { return __uint_as_float(w << 16); }
; __device__ __forceinline__ float bf_hi(unsigned w) { return __uint_as_float(w & 0xffff0000u); }
; __device__ __forceinline__ void emit_row_stats(float (&s1)[2][4], float (&s2)[2][4], float* sp_new, const Unit& u, int wr, int wc, int fr, int fq, PG8_LAS unsigned char* xl) {
;     ...
;         for (int m = 0; m < 4; ++m) { float a = s1[ai][m], b = s2[ai][m]; a += __shfl_xor(a, 16); b += __shfl_xor(b, 16); a += __shfl_xor(a, 32); b += __shfl_xor(b, 32);
;             if (fq == 0) P[(ai * HALF + wr * 64 + m * 16 + fr) * 4 + wc] = (f32x2v){a, b}; }
;     __device__ __forceinline__ void operator()(const f32x4 (&acc)[2][2][4][2], const Unit& u, int wr, int wc, int fr_in, int fq_in) const {
;     ...
;                     const float r0 = bf_lo(w.x), r1 = bf_hi(w.x), r2 = bf_lo(w.y), r3 = bf_hi(w.y), r4 = bf_lo(w.z), r5 = bf_hi(w.z), r6 = bf_lo(w.w), r7 = bf_hi(w.w);
;                     s1[ai][m] += ((r0 + r1) + (r2 + r3)) + ((r4 + r5) + (r6 + r7)); s2[ai][m] += ((r0 * r0 + r1 * r1) + (r2 * r2 + r3 * r3)) + ((r4 * r4 + r5 * r5) + (r6 * r6 + r7 * r7)); }
	v_and_b32_e32 v21, 0xffff0000, v102
	v_lshlrev_b32_e32 v22, 16, v103
	v_and_b32_e32 v23, 0xffff0000, v103
	v_pk_mul_f32 v[14:15], v[176:177], v[14:15] op_sel_hi:[0,1]
	v_pk_mul_f32 v[12:13], v[176:177], v[12:13] op_sel_hi:[0,1]
	v_pk_fma_f32 v[6:7], v[6:7], v[174:175], v[12:13] op_sel_hi:[1,0,1]
	v_pk_fma_f32 v[4:5], v[4:5], v[174:175], v[14:15] op_sel_hi:[1,0,1]
	v_sub_f32_e32 v13, v23, v180
	v_sub_f32_e32 v12, v22, v180
	v_sub_f32_e32 v15, v21, v180
	v_sub_f32_e32 v14, v20, v180
	v_pk_mul_f32 v[14:15], v[178:179], v[14:15] op_sel_hi:[0,1]
	v_pk_mul_f32 v[12:13], v[178:179], v[12:13] op_sel_hi:[0,1]
	v_pk_fma_f32 v[12:13], v[70:71], v[12:13], v[78:79]
	v_pk_fma_f32 v[14:15], v[68:69], v[14:15], v[76:77]
	v_pk_mul_f32 v[12:13], v[176:177], v[12:13] op_sel_hi:[0,1]
	v_pk_mul_f32 v[14:15], v[176:177], v[14:15] op_sel_hi:[0,1]
	v_pk_fma_f32 v[12:13], v[2:3], v[174:175], v[12:13] op_sel_hi:[1,0,1]
	v_pk_fma_f32 v[2:3], v[0:1], v[174:175], v[14:15] op_sel_hi:[1,0,1]
	v_cvt_pk_bf16_f32 v0, v4, v5
	v_and_b32_e32 v5, 64, v195
	v_xor_b32_e32 v4, 16, v195
	v_add_u32_e32 v5, 64, v5
	v_cmp_lt_i32_e32 vcc, v4, v5
	v_cvt_pk_bf16_f32 v2, v2, v3
	v_cvt_pk_bf16_f32 v3, v12, v13
	v_cvt_pk_bf16_f32 v1, v6, v7
	v_and_b32_e32 v21, 0xffff0000, v56
	v_and_b32_e32 v20, 0xffff0000, v121
	v_cndmask_b32_e32 v4, v195, v4, vcc
	v_lshlrev_b32_e32 v13, 2, v4
	v_xor_b32_e32 v4, 32, v195
	v_cmp_lt_i32_e32 vcc, v4, v5
	v_lshlrev_b32_e32 v5, 16, v56
	v_mov_b32_e32 v155, v5
	v_cndmask_b32_e32 v4, v195, v4, vcc
	v_lshlrev_b32_e32 v12, 2, v4
	v_lshlrev_b32_e32 v4, 16, v120
	v_pk_mul_f32 v[6:7], v[4:5], v[4:5]
	v_pk_mul_f32 v[14:15], v[154:155], v[154:155]
	v_mov_b32_e32 v153, v21
	v_pk_mov_b32 v[54:55], v[4:5], v[6:7] op_sel:[1,0]
	v_pk_add_f32 v[4:5], v[4:5], v[154:155]
	v_pk_mul_f32 v[22:23], v[152:153], v[152:153]
	v_pk_mul_f32 v[28:29], v[20:21], v[20:21]
	v_lshlrev_b32_e32 v30, 16, v122
	v_lshlrev_b32_e32 v31, 16, v57
	v_and_b32_e32 v45, 0xffff0000, v57
	v_and_b32_e32 v44, 0xffff0000, v123
	v_pk_mov_b32 v[14:15], v[20:21], v[14:15] op_sel:[1,0]
	v_mov_b32_e32 v5, v7
	v_pk_add_f32 v[6:7], v[20:21], v[152:153]
	v_mov_b32_e32 v127, v31
	v_mov_b32_e32 v125, v45
	v_pk_add_f32 v[14:15], v[54:55], v[14:15]
	v_pk_mov_b32 v[22:23], v[30:31], v[22:23] op_sel:[1,0]
	v_pk_mov_b32 v[54:55], v[44:45], v[28:29] op_sel:[1,0]
	v_mov_b32_e32 v7, v29
	v_pk_mul_f32 v[36:37], v[30:31], v[30:31]
	v_pk_mul_f32 v[38:39], v[126:127], v[126:127]
	v_pk_mul_f32 v[46:47], v[124:125], v[124:125]
	v_pk_mul_f32 v[52:53], v[44:45], v[44:45]
	v_pk_add_f32 v[22:23], v[22:23], v[54:55]
	v_pk_add_f32 v[4:5], v[4:5], v[6:7]
	v_pk_add_f32 v[6:7], v[30:31], v[126:127]
	v_pk_add_f32 v[20:21], v[44:45], v[124:125]
	v_pk_add_f32 v[14:15], v[14:15], v[22:23]
	v_mov_b32_e32 v22, v60
	v_mov_b32_e32 v23, v36
	v_mov_b32_e32 v54, v62
	v_mov_b32_e32 v55, v38
	v_pk_mov_b32 v[38:39], v[60:61], v[46:47] op_sel:[1,0]
	v_pk_mov_b32 v[46:47], v[62:63], v[52:53] op_sel:[1,0]
	v_mov_b32_e32 v7, v37
	v_mov_b32_e32 v21, v53
	v_pk_add_f32 v[22:23], v[22:23], v[54:55]
	v_pk_add_f32 v[38:39], v[38:39], v[46:47]
	v_pk_add_f32 v[6:7], v[6:7], v[20:21]
	v_pk_add_f32 v[22:23], v[22:23], v[38:39]
	v_pk_add_f32 v[4:5], v[4:5], v[6:7]
	v_pk_add_f32 v[14:15], v[14:15], v[22:23]
	v_pk_add_f32 v[4:5], v[4:5], v[164:165]
	global_store_dwordx4 v[144:145], v[24:27], off offset:256 sc1
	v_pk_add_f32 v[4:5], v[14:15], v[4:5]
	ds_bpermute_b32 v6, v13, v4
	ds_bpermute_b32 v7, v13, v5
	global_store_dwordx4 v[146:147], v[16:19], off offset:256 sc1
	global_store_dwordx4 v[150:151], v[8:11], off offset:256 sc1
	global_store_dwordx4 v[128:129], v[0:3], off offset:256 sc1
	s_waitcnt lgkmcnt(0)
	v_pk_add_f32 v[4:5], v[4:5], v[6:7]
	ds_bpermute_b32 v6, v12, v4
	ds_bpermute_b32 v7, v12, v5
	v_cmp_eq_u32_e32 vcc, 0, v203
	v_lshl_add_u32 v14, v199, 5, s66
	s_and_saveexec_b64 s[8:9], vcc
	s_cbranch_execz .LBB0_1367
	s_waitcnt lgkmcnt(0)
	v_pk_add_f32 v[4:5], v[4:5], v[6:7]
	ds_write_b64 v14, v[4:5]

; __device__ __forceinline__ void emit_row_stats(float (&s1)[2][4], float (&s2)[2][4], float* sp_new, const Unit& u, int wr, int wc, int fr, int fq, PG8_LAS unsigned char* xl) {
;     ...
;     asm volatile("s_waitcnt lgkmcnt(0)" ::: "memory"); __builtin_amdgcn_s_barrier(); asm volatile("" ::: "memory");
;     const int tid = (wr * 4 + wc) * 64 + fq * 16 + fr;
;     if (tid < 256) { const f32x2v a = P[tid * 4 + 0], b = P[tid * 4 + 1], c = P[tid * 4 + 2], d = P[tid * 4 + 3];
;         f32x2v o; o.x = (a.x + b.x) + (c.x + d.x); o.y = (a.y + b.y) + (c.y + d.y);
;         *(f32x2v*)(sp_new + ((size_t)(u.pm * BM + tid) * 4 + u.pn) * 2) = o; }
.LBB0_1381:
	s_or_b64 exec, exec, s[8:9]
	s_waitcnt lgkmcnt(0)
	s_barrier
	v_lshlrev_b32_e32 v0, 4, v203
	v_add3_u32 v0, s65, v199, v0
	s_movk_i32 s8, 0x100
	v_cmp_gt_i32_e32 vcc, s8, v0
	s_and_saveexec_b64 s[46:47], vcc
	s_cbranch_execz .LBB0_1383
	v_lshl_add_u32 v1, v0, 5, 0
	v_add_u32_e32 v1, 0x20400, v1
	s_waitcnt lgkmcnt(0)
	ds_read_b128 v[2:5], v1
	ds_read_b128 v[6:9], v1 offset:16
	v_add_u32_e32 v0, s11, v0
	v_ashrrev_i32_e32 v1, 31, v0
	v_lshlrev_b64 v[0:1], 5, v[0:1]
	s_waitcnt lgkmcnt(1)
	v_pk_add_f32 v[2:3], v[2:3], v[4:5]
	s_waitcnt lgkmcnt(0)
	v_pk_add_f32 v[4:5], v[6:7], v[8:9]
	s_ashr_i32 s11, s10, 31
	v_lshl_add_u64 v[0:1], s[24:25], 0, v[0:1]
	v_pk_add_f32 v[2:3], v[2:3], v[4:5]
	v_lshl_add_u64 v[0:1], s[10:11], 3, v[0:1]
	global_store_dwordx2 v[0:1], v[2:3], off sc1

; __device__ __forceinline__ float bf_lo(unsigned w) { return __uint_as_float(w << 16); }
; __device__ __forceinline__ void load_row_stats(const float* sp, int row0, RowStats& r) {
;     ...
;         for (int m = 0; m < 4; ++m) { const float* p = sp + (size_t)(row0 + ai * HALF + m * 16) * 8; const f32x4 a = *(const f32x4*)p, b = *(const f32x4*)(p + 4);
;             const float s1 = (a[0] + a[2]) + (b[0] + b[2]), s2 = (a[1] + a[3]) + (b[1] + b[3]); const float mu = s1 * (1.f / 1024.f); const float var = s2 * (1.f / 1024.f) - mu * mu;
;             r.mu[ai][m] = mu; r.rs[ai][m] = __builtin_amdgcn_rsqf(__builtin_fmaxf(var, 0.f) + 1e-5f); } }
;     __device__ __forceinline__ void operator()(const f32x4 (&acc)[2][2][4][2], const Unit& u, int wr, int wc, int fr_in, int fq_in) const {
;     ...
;         RowStats rst; load_row_stats(sp, row0, rst);
; #pragma unroll
;         for (int bj = 0; bj < 2; ++bj) { f32x4 csv[2], cbv[2], gv[2], bv[2];
; #pragma unroll
;             for (int n = 0; n < 2; ++n) { csv[n] = *(const f32x4*)(cs + col0 + bj * HALF + 4 * n); cbv[n] = *(const f32x4*)(cb + col0 + bj * HALF + 4 * n); gv[n] = *(const f32x4*)(lg + col0 + bj * HALF + 4 * n); bv[n] = *(const f32x4*)(lb + col0 + bj * HALF + 4 * n); }
; #pragma unroll
;             for (int am = 0; am < (FINAL ? 8 : 4); ++am) { constexpr int GR = FINAL ? 1 : 2; const int ai = (am * GR) >> 2; u32x4 ppw[4], pzw[4];
; #pragma unroll
;                 for (int m = (am * GR) & 3; m < ((am * GR) & 3) + GR; ++m) { const size_t off = (size_t)(row0 + ai * HALF + m * 16) * 1024 + col0 + bj * HALF; ppw[m] = *(const u32x4*)(pexb + off); pzw[m] = *(const u32x4*)(zb + off); }
;                 asm volatile("" ::: "memory");
; #pragma unroll
;                 for (int m = (am * GR) & 3; m < ((am * GR) & 3) + GR; ++m) { const size_t off = (size_t)(row0 + ai * HALF + m * 16) * 1024 + col0 + bj * HALF; const float mu = rst.mu[ai][m], rs = rst.rs[ai][m];
;                     const u32x4 pw = ppw[m]; const u32x4 zw = pzw[m];
;                     const f32x4 x0 = ((f32x4){bf_lo(zw.x), bf_hi(zw.x), bf_lo(zw.y), bf_hi(zw.y)} - mu) * rs * gv[0] + bv[0], x1 = ((f32x4){bf_lo(zw.z), bf_hi(zw.z), bf_lo(zw.w), bf_hi(zw.w)} - mu) * rs * gv[1] + bv[1];
;                     const f32x4 a0 = ln_fix(acc[ai][bj][m][0], mu, rs, csv[0], cbv[0]), a1 = ln_fix(acc[ai][bj][m][1], mu, rs, csv[1], cbv[1]); f32x4 o0, o1;
.Lrs4_skip:
	s_waitcnt vmcnt(0) lgkmcnt(0)
	s_barrier
	v_and_b32_e32 v106, 0xff, v244
	v_lshlrev_b32_e32 v106, 3, v106
	v_add_u32_e32 v106, 0x22400, v106
	ds_read_b64 v[212:213], v106
	ds_read_b64 v[208:209], v106 offset:128
	ds_read_b64 v[204:205], v106 offset:256
	ds_read_b64 v[200:201], v106 offset:384
	ds_read_b64 v[196:197], v106 offset:1024
	ds_read_b64 v[192:193], v106 offset:1152
	ds_read_b64 v[188:189], v106 offset:1280
	ds_read_b64 v[184:185], v106 offset:1408
	s_cmp_lg_u32 s99, 0
	s_waitcnt lgkmcnt(0)
	v_add_u32_e32 v242, 16, v244
	v_ashrrev_i32_e32 v243, 31, v242
	v_add_u32_e32 v240, 32, v244
	v_ashrrev_i32_e32 v241, 31, v240
	v_add_u32_e32 v238, 48, v244
	v_ashrrev_i32_e32 v239, 31, v238
	v_add_u32_e32 v236, 0x80, v244
	v_ashrrev_i32_e32 v237, 31, v236
	v_add_u32_e32 v234, 0x90, v244
	v_ashrrev_i32_e32 v235, 31, v234
	v_add_u32_e32 v220, 0xa0, v244
	v_ashrrev_i32_e32 v221, 31, v220
	v_add_u32_e32 v218, 0xb0, v244
	v_ashrrev_i32_e32 v219, 31, v218
	v_ashrrev_i32_e32 v217, 31, v216
	v_lshlrev_b64 v[230:231], 10, v[244:245]
	v_lshl_add_u64 v[160:161], v[230:231], 0, v[216:217]
	v_lshlrev_b64 v[160:161], 1, v[160:161]
	v_lshl_add_u64 v[162:163], s[44:45], 0, v[160:161]
	v_lshl_add_u64 v[160:161], s[40:41], 0, v[160:161]
	v_lshlrev_b64 v[232:233], 10, v[242:243]
	s_mov_b64 s[10:11], -1
	s_nop 0
	v_fma_f32 v104, -v212, v212, v213
	v_max_f32_e32 v104, 0, v104
	v_add_f32_e32 v104, 0x3727c5ac, v104
	v_rsq_f32_e32 v214, v104
	s_nop 0
	v_fma_f32 v104, -v208, v208, v209
	v_max_f32_e32 v104, 0, v104
	v_add_f32_e32 v104, 0x3727c5ac, v104
	v_rsq_f32_e32 v210, v104
	s_nop 0
	v_fma_f32 v104, -v204, v204, v205
	v_max_f32_e32 v104, 0, v104
	v_add_f32_e32 v104, 0x3727c5ac, v104
	v_rsq_f32_e32 v206, v104
	s_nop 0
	v_fma_f32 v104, -v200, v200, v201
	v_max_f32_e32 v104, 0, v104
	v_add_f32_e32 v104, 0x3727c5ac, v104
	v_rsq_f32_e32 v202, v104
	s_nop 0
	v_fma_f32 v104, -v196, v196, v197
	v_max_f32_e32 v104, 0, v104
	v_add_f32_e32 v104, 0x3727c5ac, v104
	v_rsq_f32_e32 v198, v104
	s_nop 0
	v_fma_f32 v104, -v192, v192, v193
	v_max_f32_e32 v104, 0, v104
	v_add_f32_e32 v104, 0x3727c5ac, v104
	v_rsq_f32_e32 v194, v104
	s_nop 0
	v_fma_f32 v104, -v188, v188, v189
	v_max_f32_e32 v104, 0, v104
	v_add_f32_e32 v104, 0x3727c5ac, v104
	v_rsq_f32_e32 v190, v104
	s_nop 0
	v_fma_f32 v104, -v184, v184, v185
	v_max_f32_e32 v104, 0, v104
	v_add_f32_e32 v104, 0x3727c5ac, v104
	v_rsq_f32_e32 v186, v104
	v_lshlrev_b64 v[104:105], 2, v[216:217]
	v_lshl_add_u64 v[228:229], s[48:49], 0, v[104:105]
	v_lshl_add_u64 v[226:227], s[50:51], 0, v[104:105]
	v_lshl_add_u64 v[224:225], s[4:5], 0, v[104:105]
	v_lshl_add_u64 v[222:223], s[6:7], 0, v[104:105]
	global_load_dwordx4 v[108:111], v[228:229], off offset:16
	global_load_dwordx4 v[116:119], v[228:229], off
	global_load_dwordx4 v[104:107], v[226:227], off offset:16
	global_load_dwordx4 v[112:115], v[226:227], off
	global_load_dwordx4 v[120:123], v[224:225], off offset:16
	global_load_dwordx4 v[136:139], v[224:225], off
	global_load_dwordx4 v[124:127], v[222:223], off offset:16
	global_load_dwordx4 v[140:143], v[222:223], off
	global_load_dwordx4 v[168:171], v[162:163], off
	global_load_dwordx4 v[248:251], v[160:161], off
	v_lshl_add_u64 v[160:161], v[232:233], 0, v[216:217]
	v_lshlrev_b64 v[164:165], 1, v[160:161]
	v_lshl_add_u64 v[160:161], s[44:45], 0, v[164:165]
	v_lshl_add_u64 v[164:165], s[40:41], 0, v[164:165]
	global_load_dwordx4 v[160:163], v[160:161], off
	s_waitcnt vmcnt(0)
	v_pk_fma_f32 v[152:153], v[212:213], v[108:109], v[152:153] op_sel_hi:[0,1,1] neg_lo:[1,0,0] neg_hi:[1,0,0]
	global_load_dwordx4 v[164:167], v[164:165], off
	v_pk_fma_f32 v[156:157], v[212:213], v[116:117], v[156:157] op_sel_hi:[0,1,1] neg_lo:[1,0,0] neg_hi:[1,0,0]
	v_pk_fma_f32 v[158:159], v[212:213], v[118:119], v[158:159] op_sel_hi:[0,1,1] neg_lo:[1,0,0] neg_hi:[1,0,0]
	v_pk_fma_f32 v[154:155], v[212:213], v[110:111], v[154:155] op_sel_hi:[0,1,1] neg_lo:[1,0,0] neg_hi:[1,0,0]
	v_pk_fma_f32 v[148:149], v[208:209], v[116:117], v[148:149] op_sel_hi:[0,1,1] neg_lo:[1,0,0] neg_hi:[1,0,0]
	v_pk_fma_f32 v[150:151], v[208:209], v[118:119], v[150:151] op_sel_hi:[0,1,1] neg_lo:[1,0,0] neg_hi:[1,0,0]
	v_pk_fma_f32 v[132:133], v[204:205], v[116:117], v[132:133] op_sel_hi:[0,1,1] neg_lo:[1,0,0] neg_hi:[1,0,0]
	v_lshlrev_b32_e32 v211, 16, v248
	v_and_b32_e32 v215, 0xffff0000, v248
	v_lshlrev_b32_e32 v246, 16, v249
	v_and_b32_e32 v247, 0xffff0000, v249
	v_sub_f32_e32 v247, v247, v212
	v_sub_f32_e32 v246, v246, v212
	v_sub_f32_e32 v249, v215, v212
	v_sub_f32_e32 v248, v211, v212
	v_pk_mul_f32 v[248:249], v[214:215], v[248:249] op_sel_hi:[0,1]
	v_pk_mul_f32 v[246:247], v[214:215], v[246:247] op_sel_hi:[0,1]
	v_and_b32_e32 v215, 0xffff0000, v250
	v_pk_fma_f32 v[156:157], v[214:215], v[156:157], v[112:113] op_sel_hi:[0,1,1]
	v_mul_f32_e32 v157, 0xbfb8aa3b, v157
	v_exp_f32_e32 v157, v157
	v_lshlrev_b32_e32 v211, 16, v250
	v_pk_fma_f32 v[248:249], v[136:137], v[248:249], v[140:141]
	v_sub_f32_e32 v252, v211, v212
	v_add_f32_e32 v157, 1.0, v157
	v_rcp_f32_e32 v157, v157
	v_pk_fma_f32 v[158:159], v[214:215], v[158:159], v[114:115] op_sel_hi:[0,1,1]
	v_lshlrev_b32_e32 v211, 16, v168
	v_and_b32_e32 v168, 0xffff0000, v168
	v_fmac_f32_e32 v249, v157, v168
	v_mul_f32_e32 v157, 0xbfb8aa3b, v158
	v_exp_f32_e32 v157, v157
	v_pk_fma_f32 v[246:247], v[138:139], v[246:247], v[142:143]
	v_lshlrev_b32_e32 v158, 16, v169
	v_pk_fma_f32 v[152:153], v[214:215], v[152:153], v[104:105] op_sel_hi:[0,1,1]
	v_add_f32_e32 v157, 1.0, v157
	v_rcp_f32_e32 v157, v157
	v_mul_f32_e32 v152, 0xbfb8aa3b, v152
	v_exp_f32_e32 v152, v152
	v_sub_f32_e32 v253, v215, v212
	v_fma_f32 v157, v157, v158, v246
; __device__ __forceinline__ unsigned cvt_pk_bf16(float lo, float hi) { unsigned r; asm("v_cvt_pk_bf16_f32 %0, %1, %2" : "=v"(r) : "v"(lo), "v"(hi)); return r; }
; __device__ __forceinline__ float fast_sigmoid(float v) { return __builtin_amdgcn_rcpf(1.0f + __builtin_amdgcn_exp2f(-1.4426950408889634f * v)); }
; __device__ __forceinline__ f32x4 ln_fix(const f32x4& a, float mu, float rs, const f32x4& cs, const f32x4& cb) { return (a - cs * mu) * rs + cb; }
; __device__ __forceinline__ float bf_lo(unsigned w) { return __uint_as_float(w << 16); }
; __device__ __forceinline__ float bf_hi(unsigned w) { return __uint_as_float(w & 0xffff0000u); }
;     __device__ __forceinline__ void operator()(const f32x4 (&acc)[2][2][4][2], const Unit& u, int wr, int wc, int fr_in, int fq_in) const {
;     ...
;                 for (int m = (am * GR) & 3; m < ((am * GR) & 3) + GR; ++m) { const size_t off = (size_t)(row0 + ai * HALF + m * 16) * 1024 + col0 + bj * HALF; const float mu = rst.mu[ai][m], rs = rst.rs[ai][m];
;                     const u32x4 pw = ppw[m]; const u32x4 zw = pzw[m];
;                     const f32x4 x0 = ((f32x4){bf_lo(zw.x), bf_hi(zw.x), bf_lo(zw.y), bf_hi(zw.y)} - mu) * rs * gv[0] + bv[0], x1 = ((f32x4){bf_lo(zw.z), bf_hi(zw.z), bf_lo(zw.w), bf_hi(zw.w)} - mu) * rs * gv[1] + bv[1];
;                     const f32x4 a0 = ln_fix(acc[ai][bj][m][0], mu, rs, csv[0], cbv[0]), a1 = ln_fix(acc[ai][bj][m][1], mu, rs, csv[1], cbv[1]); f32x4 o0, o1;
;                     o0[0] = x0[0] + fast_sigmoid(a0[0]) * bf_lo(pw.x); o0[1] = x0[1] + fast_sigmoid(a0[1]) * bf_hi(pw.x);
;                     o0[2] = x0[2] + fast_sigmoid(a0[2]) * bf_lo(pw.y); o0[3] = x0[3] + fast_sigmoid(a0[3]) * bf_hi(pw.y);
;                     o1[0] = x1[0] + fast_sigmoid(a1[0]) * bf_lo(pw.z); o1[1] = x1[1] + fast_sigmoid(a1[1]) * bf_hi(pw.z);
;                     o1[2] = x1[2] + fast_sigmoid(a1[2]) * bf_lo(pw.w); o1[3] = x1[3] + fast_sigmoid(a1[3]) * bf_hi(pw.w);
;                     if constexpr (FINAL) { *(f32x4*)(outf + off) = o0; *(f32x4*)(outf + off + 4) = o1; }
;                     else { u32x4 w; w.x = cvt_pk_bf16(o0[0], o0[1]); w.y = cvt_pk_bf16(o0[2], o0[3]); w.z = cvt_pk_bf16(o1[0], o1[1]); w.w = cvt_pk_bf16(o1[2], o1[3]); *(u32x4*)(pexb + off) = w; } } } }
	v_mul_f32_e32 v158, 0xbfb8aa3b, v159
	v_exp_f32_e32 v158, v158
	v_add_f32_e32 v152, 1.0, v152
	v_rcp_f32_e32 v152, v152
	v_pk_mul_f32 v[252:253], v[214:215], v[252:253] op_sel_hi:[0,1]
	v_add_f32_e32 v158, 1.0, v158
	v_rcp_f32_e32 v158, v158
	v_and_b32_e32 v159, 0xffff0000, v169
	v_pk_fma_f32 v[252:253], v[120:121], v[252:253], v[124:125]
	v_pk_fma_f32 v[154:155], v[214:215], v[154:155], v[106:107] op_sel_hi:[0,1,1]
	v_fmac_f32_e32 v247, v158, v159
	v_lshlrev_b32_e32 v158, 16, v170
	v_fma_f32 v158, v152, v158, v252
	v_mul_f32_e32 v152, 0xbfb8aa3b, v153
	v_exp_f32_e32 v152, v152
	v_and_b32_e32 v153, 0xffff0000, v170
	v_lshlrev_b32_e32 v250, 16, v251
	v_and_b32_e32 v251, 0xffff0000, v251
	v_add_f32_e32 v152, 1.0, v152
	v_rcp_f32_e32 v152, v152
	v_sub_f32_e32 v251, v251, v212
	v_sub_f32_e32 v250, v250, v212
	v_pk_mul_f32 v[250:251], v[214:215], v[250:251] op_sel_hi:[0,1]
	v_fmac_f32_e32 v253, v152, v153
	v_mul_f32_e32 v152, 0xbfb8aa3b, v154
	v_exp_f32_e32 v152, v152
	v_pk_fma_f32 v[250:251], v[122:123], v[250:251], v[126:127]
	v_mul_f32_e32 v156, 0xbfb8aa3b, v156
	v_lshlrev_b32_e32 v153, 16, v171
	v_add_f32_e32 v152, 1.0, v152
	v_rcp_f32_e32 v152, v152
	v_exp_f32_e32 v156, v156
	v_pk_fma_f32 v[148:149], v[210:211], v[148:149], v[112:113] op_sel_hi:[0,1,1]
	v_mul_f32_e32 v148, 0xbfb8aa3b, v148
	v_fma_f32 v159, v152, v153, v250
	v_mul_f32_e32 v152, 0xbfb8aa3b, v155
	v_exp_f32_e32 v152, v152
	v_add_f32_e32 v156, 1.0, v156
	v_rcp_f32_e32 v156, v156
	v_exp_f32_e32 v148, v148
	v_add_f32_e32 v152, 1.0, v152
	v_rcp_f32_e32 v152, v152
	v_mul_f32_e32 v149, 0xbfb8aa3b, v149
	v_fma_f32 v156, v156, v211, v248
	v_and_b32_e32 v153, 0xffff0000, v171
	v_exp_f32_e32 v149, v149
	v_fmac_f32_e32 v251, v152, v153
	v_cvt_pk_bf16_f32 v152, v156, v249
	v_cvt_pk_bf16_f32 v153, v157, v247
	v_lshlrev_b64 v[156:157], 11, v[244:245]
	v_lshl_add_u64 v[156:157], s[44:45], 0, v[156:157]
	v_lshlrev_b64 v[168:169], 1, v[216:217]
	v_cvt_pk_bf16_f32 v154, v158, v253
	v_cvt_pk_bf16_f32 v155, v159, v251
	v_lshl_add_u64 v[156:157], v[156:157], 0, v[168:169]
	v_add_f32_e32 v148, 1.0, v148
	global_store_dwordx4 v[156:157], v[152:155], off sc1
	v_rcp_f32_e32 v148, v148
	v_add_f32_e32 v149, 1.0, v149
	s_waitcnt vmcnt(0)
	v_lshlrev_b32_e32 v154, 16, v164
	v_and_b32_e32 v155, 0xffff0000, v164
	v_sub_f32_e32 v155, v155, v208
	v_sub_f32_e32 v154, v154, v208
	v_rcp_f32_e32 v149, v149
	v_lshlrev_b32_e32 v152, 16, v165
	v_and_b32_e32 v153, 0xffff0000, v165
	v_pk_mul_f32 v[154:155], v[210:211], v[154:155] op_sel_hi:[0,1]
	v_lshlrev_b32_e32 v164, 16, v166
	v_and_b32_e32 v165, 0xffff0000, v166
	v_lshlrev_b32_e32 v158, 16, v167
	v_and_b32_e32 v159, 0xffff0000, v167
	v_pk_fma_f32 v[166:167], v[208:209], v[108:109], v[144:145] op_sel_hi:[0,1,1] neg_lo:[1,0,0] neg_hi:[1,0,0]
	v_pk_fma_f32 v[154:155], v[136:137], v[154:155], v[140:141]
	v_pk_fma_f32 v[144:145], v[208:209], v[110:111], v[146:147] op_sel_hi:[0,1,1] neg_lo:[1,0,0] neg_hi:[1,0,0]
	v_pk_fma_f32 v[146:147], v[210:211], v[166:167], v[104:105] op_sel_hi:[0,1,1]
	v_lshlrev_b32_e32 v166, 16, v160
	v_pk_fma_f32 v[150:151], v[210:211], v[150:151], v[114:115] op_sel_hi:[0,1,1]
	v_fma_f32 v148, v148, v166, v154
	v_and_b32_e32 v154, 0xffff0000, v160
	v_fmac_f32_e32 v155, v149, v154
	v_mul_f32_e32 v149, 0xbfb8aa3b, v150
	v_exp_f32_e32 v149, v149
	v_sub_f32_e32 v153, v153, v208
	v_sub_f32_e32 v152, v152, v208
	v_pk_mul_f32 v[152:153], v[210:211], v[152:153] op_sel_hi:[0,1]
	v_add_f32_e32 v149, 1.0, v149
	v_rcp_f32_e32 v149, v149
	v_pk_fma_f32 v[152:153], v[138:139], v[152:153], v[142:143]
	v_lshlrev_b32_e32 v150, 16, v161
	v_mul_f32_e32 v146, 0xbfb8aa3b, v146
	v_fma_f32 v149, v149, v150, v152
	v_mul_f32_e32 v150, 0xbfb8aa3b, v151
	v_exp_f32_e32 v150, v150
	v_pk_fma_f32 v[144:145], v[210:211], v[144:145], v[106:107] op_sel_hi:[0,1,1]
	v_exp_f32_e32 v146, v146
	v_mul_f32_e32 v147, 0xbfb8aa3b, v147
	v_exp_f32_e32 v147, v147
	v_mul_f32_e32 v144, 0xbfb8aa3b, v144
	v_exp_f32_e32 v144, v144
	v_add_f32_e32 v150, 1.0, v150
	v_rcp_f32_e32 v150, v150
	v_add_f32_e32 v146, 1.0, v146
	v_rcp_f32_e32 v146, v146
	v_add_f32_e32 v147, 1.0, v147
	v_sub_f32_e32 v165, v165, v208
	v_sub_f32_e32 v164, v164, v208
	v_rcp_f32_e32 v147, v147
	v_add_f32_e32 v144, 1.0, v144
	v_pk_mul_f32 v[164:165], v[210:211], v[164:165] op_sel_hi:[0,1]
	v_and_b32_e32 v151, 0xffff0000, v161
	v_rcp_f32_e32 v144, v144
	v_sub_f32_e32 v159, v159, v208
	v_sub_f32_e32 v158, v158, v208
	v_pk_fma_f32 v[164:165], v[120:121], v[164:165], v[124:125]
	v_fmac_f32_e32 v153, v150, v151
	v_lshlrev_b32_e32 v150, 16, v162
	v_pk_mul_f32 v[158:159], v[210:211], v[158:159] op_sel_hi:[0,1]
	v_fma_f32 v146, v146, v150, v164
	v_and_b32_e32 v150, 0xffff0000, v162
	v_pk_fma_f32 v[158:159], v[122:123], v[158:159], v[126:127]
	v_fmac_f32_e32 v165, v147, v150
	v_lshlrev_b32_e32 v147, 16, v163
	v_fma_f32 v147, v144, v147, v158
	v_mul_f32_e32 v144, 0xbfb8aa3b, v145
	v_exp_f32_e32 v144, v144
	v_and_b32_e32 v145, 0xffff0000, v163
	v_lshlrev_b64 v[160:161], 10, v[240:241]
	v_cvt_pk_bf16_f32 v146, v146, v165
	v_add_f32_e32 v144, 1.0, v144
	v_rcp_f32_e32 v144, v144
	v_lshlrev_b64 v[162:163], 10, v[238:239]
	v_pk_fma_f32 v[132:133], v[206:207], v[132:133], v[112:113] op_sel_hi:[0,1,1]
	v_mul_f32_e32 v133, 0xbfb8aa3b, v133
	v_fmac_f32_e32 v159, v144, v145
	v_cvt_pk_bf16_f32 v144, v148, v155
	v_cvt_pk_bf16_f32 v145, v149, v153
	v_lshlrev_b64 v[148:149], 11, v[242:243]
	v_lshl_add_u64 v[148:149], s[44:45], 0, v[148:149]
	v_cvt_pk_bf16_f32 v147, v147, v159
	v_lshl_add_u64 v[158:159], v[148:149], 0, v[168:169]
	global_store_dwordx4 v[158:159], v[144:147], off sc1
	v_exp_f32_e32 v133, v133
; __device__ __forceinline__ float fast_sigmoid(float v) { return __builtin_amdgcn_rcpf(1.0f + __builtin_amdgcn_exp2f(-1.4426950408889634f * v)); }
; __device__ __forceinline__ f32x4 ln_fix(const f32x4& a, float mu, float rs, const f32x4& cs, const f32x4& cb) { return (a - cs * mu) * rs + cb; }
; __device__ __forceinline__ float bf_lo(unsigned w) { return __uint_as_float(w << 16); }
; __device__ __forceinline__ float bf_hi(unsigned w) { return __uint_as_float(w & 0xffff0000u); }
;     __device__ __forceinline__ void operator()(const f32x4 (&acc)[2][2][4][2], const Unit& u, int wr, int wc, int fr_in, int fq_in) const {
;     ...
;                 for (int m = (am * GR) & 3; m < ((am * GR) & 3) + GR; ++m) { const size_t off = (size_t)(row0 + ai * HALF + m * 16) * 1024 + col0 + bj * HALF; const float mu = rst.mu[ai][m], rs = rst.rs[ai][m];
;                     const u32x4 pw = ppw[m]; const u32x4 zw = pzw[m];
;                     const f32x4 x0 = ((f32x4){bf_lo(zw.x), bf_hi(zw.x), bf_lo(zw.y), bf_hi(zw.y)} - mu) * rs * gv[0] + bv[0], x1 = ((f32x4){bf_lo(zw.z), bf_hi(zw.z), bf_lo(zw.w), bf_hi(zw.w)} - mu) * rs * gv[1] + bv[1];
;                     const f32x4 a0 = ln_fix(acc[ai][bj][m][0], mu, rs, csv[0], cbv[0]), a1 = ln_fix(acc[ai][bj][m][1], mu, rs, csv[1], cbv[1]); f32x4 o0, o1;
;                     o0[0] = x0[0] + fast_sigmoid(a0[0]) * bf_lo(pw.x); o0[1] = x0[1] + fast_sigmoid(a0[1]) * bf_hi(pw.x);
;                     o0[2] = x0[2] + fast_sigmoid(a0[2]) * bf_lo(pw.y); o0[3] = x0[3] + fast_sigmoid(a0[3]) * bf_hi(pw.y);
;                     o1[0] = x1[0] + fast_sigmoid(a1[0]) * bf_lo(pw.z); o1[1] = x1[1] + fast_sigmoid(a1[1]) * bf_hi(pw.z);
;                     o1[2] = x1[2] + fast_sigmoid(a1[2]) * bf_lo(pw.w); o1[3] = x1[3] + fast_sigmoid(a1[3]) * bf_hi(pw.w);
	v_pk_fma_f32 v[134:135], v[204:205], v[118:119], v[134:135] op_sel_hi:[0,1,1] neg_lo:[1,0,0] neg_hi:[1,0,0]
	v_lshl_add_u64 v[144:145], v[160:161], 0, v[216:217]
	v_lshlrev_b64 v[144:145], 1, v[144:145]
	v_lshl_add_u64 v[146:147], s[44:45], 0, v[144:145]
	v_lshl_add_u64 v[144:145], s[40:41], 0, v[144:145]
	global_load_dwordx4 v[152:155], v[146:147], off
	global_load_dwordx4 v[242:245], v[144:145], off
	v_lshl_add_u64 v[144:145], v[162:163], 0, v[216:217]
	v_lshlrev_b64 v[148:149], 1, v[144:145]
	v_lshl_add_u64 v[144:145], s[44:45], 0, v[148:149]
	v_lshl_add_u64 v[148:149], s[40:41], 0, v[148:149]
	global_load_dwordx4 v[144:147], v[144:145], off
	v_add_f32_e32 v133, 1.0, v133
	global_load_dwordx4 v[148:151], v[148:149], off
	v_rcp_f32_e32 v133, v133
	v_pk_fma_f32 v[134:135], v[206:207], v[134:135], v[114:115] op_sel_hi:[0,1,1]
	v_pk_fma_f32 v[128:129], v[204:205], v[108:109], v[128:129] op_sel_hi:[0,1,1] neg_lo:[1,0,0] neg_hi:[1,0,0]
	v_pk_fma_f32 v[128:129], v[206:207], v[128:129], v[104:105] op_sel_hi:[0,1,1]
	v_mul_f32_e32 v128, 0xbfb8aa3b, v128
	v_exp_f32_e32 v128, v128
	v_pk_fma_f32 v[130:131], v[204:205], v[110:111], v[130:131] op_sel_hi:[0,1,1] neg_lo:[1,0,0] neg_hi:[1,0,0]
	v_pk_fma_f32 v[130:131], v[206:207], v[130:131], v[106:107] op_sel_hi:[0,1,1]
	v_mul_f32_e32 v132, 0xbfb8aa3b, v132
	v_add_f32_e32 v128, 1.0, v128
	v_rcp_f32_e32 v128, v128
	v_exp_f32_e32 v132, v132
	v_pk_fma_f32 v[100:101], v[200:201], v[116:117], v[100:101] op_sel_hi:[0,1,1] neg_lo:[1,0,0] neg_hi:[1,0,0]
	v_pk_fma_f32 v[100:101], v[202:203], v[100:101], v[112:113] op_sel_hi:[0,1,1]
	v_mul_f32_e32 v100, 0xbfb8aa3b, v100
	v_add_f32_e32 v132, 1.0, v132
	v_rcp_f32_e32 v132, v132
	v_exp_f32_e32 v100, v100
	v_mul_f32_e32 v101, 0xbfb8aa3b, v101
	v_exp_f32_e32 v101, v101
	v_add_f32_e32 v100, 1.0, v100
	v_rcp_f32_e32 v100, v100
	v_add_f32_e32 v101, 1.0, v101
	v_rcp_f32_e32 v101, v101
	v_pk_fma_f32 v[102:103], v[200:201], v[118:119], v[102:103] op_sel_hi:[0,1,1] neg_lo:[1,0,0] neg_hi:[1,0,0]
	v_pk_fma_f32 v[102:103], v[202:203], v[102:103], v[114:115] op_sel_hi:[0,1,1]
	v_pk_fma_f32 v[96:97], v[200:201], v[108:109], v[96:97] op_sel_hi:[0,1,1] neg_lo:[1,0,0] neg_hi:[1,0,0]
	v_pk_fma_f32 v[96:97], v[202:203], v[96:97], v[104:105] op_sel_hi:[0,1,1]
	v_mul_f32_e32 v96, 0xbfb8aa3b, v96
	v_exp_f32_e32 v96, v96
	v_pk_fma_f32 v[98:99], v[200:201], v[110:111], v[98:99] op_sel_hi:[0,1,1] neg_lo:[1,0,0] neg_hi:[1,0,0]
	v_pk_fma_f32 v[98:99], v[202:203], v[98:99], v[106:107] op_sel_hi:[0,1,1]
	v_pk_fma_f32 v[92:93], v[196:197], v[116:117], v[92:93] op_sel_hi:[0,1,1] neg_lo:[1,0,0] neg_hi:[1,0,0]
	v_add_f32_e32 v96, 1.0, v96
	v_rcp_f32_e32 v96, v96
	v_pk_fma_f32 v[92:93], v[92:93], v[198:199], v[112:113] op_sel_hi:[1,0,1]
	v_pk_fma_f32 v[94:95], v[196:197], v[118:119], v[94:95] op_sel_hi:[0,1,1] neg_lo:[1,0,0] neg_hi:[1,0,0]
	v_mul_f32_e32 v93, 0xbfb8aa3b, v93
	v_exp_f32_e32 v93, v93
	v_pk_fma_f32 v[94:95], v[94:95], v[198:199], v[114:115] op_sel_hi:[1,0,1]
	v_pk_fma_f32 v[88:89], v[196:197], v[108:109], v[88:89] op_sel_hi:[0,1,1] neg_lo:[1,0,0] neg_hi:[1,0,0]
	v_pk_fma_f32 v[88:89], v[198:199], v[88:89], v[104:105] op_sel_hi:[0,1,1]
	v_add_f32_e32 v93, 1.0, v93
	v_rcp_f32_e32 v93, v93
	v_mul_f32_e32 v88, 0xbfb8aa3b, v88
	v_exp_f32_e32 v88, v88
	v_pk_fma_f32 v[90:91], v[196:197], v[110:111], v[90:91] op_sel_hi:[0,1,1] neg_lo:[1,0,0] neg_hi:[1,0,0]
	v_pk_fma_f32 v[90:91], v[198:199], v[90:91], v[106:107] op_sel_hi:[0,1,1]
	v_mul_f32_e32 v92, 0xbfb8aa3b, v92
	v_add_f32_e32 v88, 1.0, v88
	v_rcp_f32_e32 v88, v88
	v_exp_f32_e32 v92, v92
	v_pk_fma_f32 v[84:85], v[116:117], v[192:193], v[84:85] op_sel_hi:[1,0,1] neg_lo:[1,0,0] neg_hi:[1,0,0]
	v_pk_fma_f32 v[80:81], v[192:193], v[108:109], v[80:81] op_sel_hi:[0,1,1] neg_lo:[1,0,0] neg_hi:[1,0,0]
	v_pk_fma_f32 v[84:85], v[84:85], v[194:195], v[112:113] op_sel_hi:[1,0,1]
	v_add_f32_e32 v92, 1.0, v92
	v_rcp_f32_e32 v92, v92
	v_mul_f32_e32 v84, 0xbfb8aa3b, v84
	v_exp_f32_e32 v84, v84
	v_mul_f32_e32 v85, 0xbfb8aa3b, v85
	v_exp_f32_e32 v85, v85
	v_pk_fma_f32 v[80:81], v[194:195], v[80:81], v[104:105] op_sel_hi:[0,1,1]
	v_add_f32_e32 v84, 1.0, v84
	v_rcp_f32_e32 v84, v84
	v_add_f32_e32 v85, 1.0, v85
	v_rcp_f32_e32 v85, v85
	v_mul_f32_e32 v80, 0xbfb8aa3b, v80
	v_exp_f32_e32 v80, v80
	v_pk_fma_f32 v[82:83], v[192:193], v[110:111], v[82:83] op_sel_hi:[0,1,1] neg_lo:[1,0,0] neg_hi:[1,0,0]
	v_pk_fma_f32 v[82:83], v[194:195], v[82:83], v[106:107] op_sel_hi:[0,1,1]
	v_pk_fma_f32 v[76:77], v[116:117], v[188:189], v[76:77] op_sel_hi:[1,0,1] neg_lo:[1,0,0] neg_hi:[1,0,0]
	s_waitcnt vmcnt(0)
; __device__ __forceinline__ unsigned cvt_pk_bf16(float lo, float hi) { unsigned r; asm("v_cvt_pk_bf16_f32 %0, %1, %2" : "=v"(r) : "v"(lo), "v"(hi)); return r; }
; __device__ __forceinline__ float fast_sigmoid(float v) { return __builtin_amdgcn_rcpf(1.0f + __builtin_amdgcn_exp2f(-1.4426950408889634f * v)); }
; __device__ __forceinline__ f32x4 ln_fix(const f32x4& a, float mu, float rs, const f32x4& cs, const f32x4& cb) { return (a - cs * mu) * rs + cb; }
; __device__ __forceinline__ float bf_lo(unsigned w) { return __uint_as_float(w << 16); }
; __device__ __forceinline__ float bf_hi(unsigned w) { return __uint_as_float(w & 0xffff0000u); }
;     __device__ __forceinline__ void operator()(const f32x4 (&acc)[2][2][4][2], const Unit& u, int wr, int wc, int fr_in, int fq_in) const {
;     ...
;                 for (int m = (am * GR) & 3; m < ((am * GR) & 3) + GR; ++m) { const size_t off = (size_t)(row0 + ai * HALF + m * 16) * 1024 + col0 + bj * HALF; const float mu = rst.mu[ai][m], rs = rst.rs[ai][m];
;                     const u32x4 pw = ppw[m]; const u32x4 zw = pzw[m];
;                     const f32x4 x0 = ((f32x4){bf_lo(zw.x), bf_hi(zw.x), bf_lo(zw.y), bf_hi(zw.y)} - mu) * rs * gv[0] + bv[0], x1 = ((f32x4){bf_lo(zw.z), bf_hi(zw.z), bf_lo(zw.w), bf_hi(zw.w)} - mu) * rs * gv[1] + bv[1];
;                     const f32x4 a0 = ln_fix(acc[ai][bj][m][0], mu, rs, csv[0], cbv[0]), a1 = ln_fix(acc[ai][bj][m][1], mu, rs, csv[1], cbv[1]); f32x4 o0, o1;
;                     o0[0] = x0[0] + fast_sigmoid(a0[0]) * bf_lo(pw.x); o0[1] = x0[1] + fast_sigmoid(a0[1]) * bf_hi(pw.x);
;                     o0[2] = x0[2] + fast_sigmoid(a0[2]) * bf_lo(pw.y); o0[3] = x0[3] + fast_sigmoid(a0[3]) * bf_hi(pw.y);
;                     o1[0] = x1[0] + fast_sigmoid(a1[0]) * bf_lo(pw.z); o1[1] = x1[1] + fast_sigmoid(a1[1]) * bf_hi(pw.z);
;                     o1[2] = x1[2] + fast_sigmoid(a1[2]) * bf_lo(pw.w); o1[3] = x1[3] + fast_sigmoid(a1[3]) * bf_hi(pw.w);
;                     if constexpr (FINAL) { *(f32x4*)(outf + off) = o0; *(f32x4*)(outf + off + 4) = o1; }
;                     else { u32x4 w; w.x = cvt_pk_bf16(o0[0], o0[1]); w.y = cvt_pk_bf16(o0[2], o0[3]); w.z = cvt_pk_bf16(o1[0], o1[1]); w.w = cvt_pk_bf16(o1[2], o1[3]); *(u32x4*)(pexb + off) = w; } } } }
	v_lshlrev_b32_e32 v166, 16, v242
	v_and_b32_e32 v167, 0xffff0000, v242
	v_sub_f32_e32 v167, v167, v204
	v_sub_f32_e32 v166, v166, v204
	v_pk_mul_f32 v[166:167], v[206:207], v[166:167] op_sel_hi:[0,1]
	v_lshlrev_b32_e32 v211, 16, v244
	v_pk_fma_f32 v[166:167], v[136:137], v[166:167], v[140:141]
	v_sub_f32_e32 v242, v211, v204
	v_lshlrev_b32_e32 v211, 16, v152
	v_and_b32_e32 v152, 0xffff0000, v152
	v_fmac_f32_e32 v167, v133, v152
	v_mul_f32_e32 v133, 0xbfb8aa3b, v134
	v_exp_f32_e32 v133, v133
	v_lshlrev_b32_e32 v164, 16, v243
	v_and_b32_e32 v165, 0xffff0000, v243
	v_sub_f32_e32 v165, v165, v204
	v_add_f32_e32 v133, 1.0, v133
	v_rcp_f32_e32 v133, v133
	v_sub_f32_e32 v164, v164, v204
	v_pk_mul_f32 v[164:165], v[206:207], v[164:165] op_sel_hi:[0,1]
	v_pk_fma_f32 v[164:165], v[138:139], v[164:165], v[142:143]
	v_lshlrev_b32_e32 v134, 16, v153
	v_fma_f32 v133, v133, v134, v164
	v_mul_f32_e32 v134, 0xbfb8aa3b, v135
	v_exp_f32_e32 v134, v134
	v_and_b32_e32 v215, 0xffff0000, v244
	v_sub_f32_e32 v243, v215, v204
	v_pk_mul_f32 v[242:243], v[206:207], v[242:243] op_sel_hi:[0,1]
	v_add_f32_e32 v134, 1.0, v134
	v_rcp_f32_e32 v134, v134
	v_and_b32_e32 v135, 0xffff0000, v153
	v_pk_fma_f32 v[242:243], v[120:121], v[242:243], v[124:125]
	v_lshlrev_b32_e32 v170, 16, v245
	v_fmac_f32_e32 v165, v134, v135
	v_lshlrev_b32_e32 v134, 16, v154
	v_fma_f32 v134, v128, v134, v242
	v_mul_f32_e32 v128, 0xbfb8aa3b, v129
	v_exp_f32_e32 v128, v128
	v_and_b32_e32 v129, 0xffff0000, v154
	v_and_b32_e32 v171, 0xffff0000, v245
	v_sub_f32_e32 v171, v171, v204
	v_add_f32_e32 v128, 1.0, v128
	v_rcp_f32_e32 v128, v128
	v_sub_f32_e32 v170, v170, v204
	v_pk_mul_f32 v[170:171], v[206:207], v[170:171] op_sel_hi:[0,1]
	v_pk_fma_f32 v[170:171], v[122:123], v[170:171], v[126:127]
	v_fmac_f32_e32 v243, v128, v129
	v_mul_f32_e32 v128, 0xbfb8aa3b, v130
	v_exp_f32_e32 v128, v128
	v_lshlrev_b32_e32 v129, 16, v155
	v_fma_f32 v132, v132, v211, v166
	v_cvt_pk_bf16_f32 v130, v134, v243
	v_add_f32_e32 v128, 1.0, v128
	v_rcp_f32_e32 v128, v128
	v_lshlrev_b32_e32 v134, 16, v151
	v_sub_f32_e32 v134, v134, v200
	v_add_f32_e32 v80, 1.0, v80
	v_fma_f32 v135, v128, v129, v170
	v_mul_f32_e32 v128, 0xbfb8aa3b, v131
	v_exp_f32_e32 v128, v128
	v_and_b32_e32 v129, 0xffff0000, v155
	v_rcp_f32_e32 v80, v80
	v_pk_fma_f32 v[76:77], v[76:77], v[190:191], v[112:113] op_sel_hi:[1,0,1]
	v_add_f32_e32 v128, 1.0, v128
	v_rcp_f32_e32 v128, v128
	v_mul_f32_e32 v77, 0xbfb8aa3b, v77
	v_exp_f32_e32 v77, v77
	v_pk_fma_f32 v[72:73], v[188:189], v[108:109], v[72:73] op_sel_hi:[0,1,1] neg_lo:[1,0,0] neg_hi:[1,0,0]
	v_fmac_f32_e32 v171, v128, v129
	v_cvt_pk_bf16_f32 v128, v132, v167
	v_cvt_pk_bf16_f32 v129, v133, v165
	v_lshlrev_b64 v[132:133], 11, v[240:241]
	v_lshl_add_u64 v[132:133], s[44:45], 0, v[132:133]
	v_cvt_pk_bf16_f32 v131, v135, v171
	v_lshl_add_u64 v[132:133], v[132:133], 0, v[168:169]
	global_store_dwordx4 v[132:133], v[128:131], off sc1
	v_and_b32_e32 v135, 0xffff0000, v151
	v_sub_f32_e32 v135, v135, v200
	v_lshlrev_b32_e32 v130, 16, v148
	v_and_b32_e32 v131, 0xffff0000, v148
	v_sub_f32_e32 v131, v131, v200
	v_sub_f32_e32 v130, v130, v200
	v_pk_mul_f32 v[130:131], v[202:203], v[130:131] op_sel_hi:[0,1]
	v_lshlrev_b32_e32 v128, 16, v149
	v_and_b32_e32 v129, 0xffff0000, v149
	v_pk_fma_f32 v[130:131], v[136:137], v[130:131], v[140:141]
	v_lshlrev_b32_e32 v148, 16, v150
	v_and_b32_e32 v149, 0xffff0000, v150
	v_lshlrev_b32_e32 v150, 16, v144
	v_fma_f32 v100, v100, v150, v130
	v_and_b32_e32 v130, 0xffff0000, v144
	v_fmac_f32_e32 v131, v101, v130
	v_mul_f32_e32 v101, 0xbfb8aa3b, v102
	v_exp_f32_e32 v101, v101
	v_sub_f32_e32 v129, v129, v200
	v_sub_f32_e32 v128, v128, v200
	v_pk_mul_f32 v[128:129], v[202:203], v[128:129] op_sel_hi:[0,1]
	v_add_f32_e32 v101, 1.0, v101
	v_rcp_f32_e32 v101, v101
	v_pk_fma_f32 v[128:129], v[138:139], v[128:129], v[142:143]
	v_lshlrev_b32_e32 v102, 16, v145
	v_sub_f32_e32 v149, v149, v200
	v_fma_f32 v101, v101, v102, v128
	v_mul_f32_e32 v102, 0xbfb8aa3b, v103
	v_exp_f32_e32 v102, v102
	v_sub_f32_e32 v148, v148, v200
	v_pk_mul_f32 v[148:149], v[202:203], v[148:149] op_sel_hi:[0,1]
	v_and_b32_e32 v103, 0xffff0000, v145
	v_add_f32_e32 v102, 1.0, v102
	v_rcp_f32_e32 v102, v102
	v_pk_fma_f32 v[148:149], v[120:121], v[148:149], v[124:125]
	v_pk_mul_f32 v[134:135], v[202:203], v[134:135] op_sel_hi:[0,1]
	v_pk_fma_f32 v[134:135], v[122:123], v[134:135], v[126:127]
	v_fmac_f32_e32 v129, v102, v103
	v_lshlrev_b32_e32 v102, 16, v146
	v_fma_f32 v102, v96, v102, v148
	v_mul_f32_e32 v96, 0xbfb8aa3b, v97
	v_exp_f32_e32 v96, v96
	v_and_b32_e32 v97, 0xffff0000, v146
	v_lshlrev_b64 v[144:145], 10, v[236:237]
	v_add_f32_e32 v77, 1.0, v77
	v_add_f32_e32 v96, 1.0, v96
	v_rcp_f32_e32 v96, v96
	v_rcp_f32_e32 v77, v77
	v_pk_fma_f32 v[72:73], v[72:73], v[190:191], v[104:105] op_sel_hi:[1,0,1]
	v_pk_fma_f32 v[74:75], v[188:189], v[110:111], v[74:75] op_sel_hi:[0,1,1] neg_lo:[1,0,0] neg_hi:[1,0,0]
	v_fmac_f32_e32 v149, v96, v97
	v_mul_f32_e32 v96, 0xbfb8aa3b, v98
	v_exp_f32_e32 v96, v96
	v_lshlrev_b32_e32 v97, 16, v147
	v_cvt_pk_bf16_f32 v98, v102, v149
	v_mul_f32_e32 v72, 0xbfb8aa3b, v72
	v_add_f32_e32 v96, 1.0, v96
	v_rcp_f32_e32 v96, v96
	v_exp_f32_e32 v72, v72
	v_pk_fma_f32 v[74:75], v[74:75], v[190:191], v[106:107] op_sel_hi:[1,0,1]
	v_mul_f32_e32 v76, 0xbfb8aa3b, v76
	v_fma_f32 v103, v96, v97, v134
	v_mul_f32_e32 v96, 0xbfb8aa3b, v99
	v_exp_f32_e32 v96, v96
	v_and_b32_e32 v97, 0xffff0000, v147
	v_lshlrev_b64 v[146:147], 10, v[234:235]
	v_add_f32_e32 v72, 1.0, v72
	v_add_f32_e32 v96, 1.0, v96
	v_rcp_f32_e32 v96, v96
	v_rcp_f32_e32 v72, v72
	v_exp_f32_e32 v76, v76
; __device__ __forceinline__ unsigned cvt_pk_bf16(float lo, float hi) { unsigned r; asm("v_cvt_pk_bf16_f32 %0, %1, %2" : "=v"(r) : "v"(lo), "v"(hi)); return r; }
; __device__ __forceinline__ float fast_sigmoid(float v) { return __builtin_amdgcn_rcpf(1.0f + __builtin_amdgcn_exp2f(-1.4426950408889634f * v)); }
; __device__ __forceinline__ f32x4 ln_fix(const f32x4& a, float mu, float rs, const f32x4& cs, const f32x4& cb) { return (a - cs * mu) * rs + cb; }
; __device__ __forceinline__ float bf_lo(unsigned w) { return __uint_as_float(w << 16); }
; __device__ __forceinline__ float bf_hi(unsigned w) { return __uint_as_float(w & 0xffff0000u); }
;     __device__ __forceinline__ void operator()(const f32x4 (&acc)[2][2][4][2], const Unit& u, int wr, int wc, int fr_in, int fq_in) const {
;     ...
;                 for (int m = (am * GR) & 3; m < ((am * GR) & 3) + GR; ++m) { const size_t off = (size_t)(row0 + ai * HALF + m * 16) * 1024 + col0 + bj * HALF; const float mu = rst.mu[ai][m], rs = rst.rs[ai][m];
;                     const u32x4 pw = ppw[m]; const u32x4 zw = pzw[m];
;                     const f32x4 x0 = ((f32x4){bf_lo(zw.x), bf_hi(zw.x), bf_lo(zw.y), bf_hi(zw.y)} - mu) * rs * gv[0] + bv[0], x1 = ((f32x4){bf_lo(zw.z), bf_hi(zw.z), bf_lo(zw.w), bf_hi(zw.w)} - mu) * rs * gv[1] + bv[1];
;                     const f32x4 a0 = ln_fix(acc[ai][bj][m][0], mu, rs, csv[0], cbv[0]), a1 = ln_fix(acc[ai][bj][m][1], mu, rs, csv[1], cbv[1]); f32x4 o0, o1;
;                     o0[0] = x0[0] + fast_sigmoid(a0[0]) * bf_lo(pw.x); o0[1] = x0[1] + fast_sigmoid(a0[1]) * bf_hi(pw.x);
;                     o0[2] = x0[2] + fast_sigmoid(a0[2]) * bf_lo(pw.y); o0[3] = x0[3] + fast_sigmoid(a0[3]) * bf_hi(pw.y);
;                     o1[0] = x1[0] + fast_sigmoid(a1[0]) * bf_lo(pw.z); o1[1] = x1[1] + fast_sigmoid(a1[1]) * bf_hi(pw.z);
;                     o1[2] = x1[2] + fast_sigmoid(a1[2]) * bf_lo(pw.w); o1[3] = x1[3] + fast_sigmoid(a1[3]) * bf_hi(pw.w);
;                     if constexpr (FINAL) { *(f32x4*)(outf + off) = o0; *(f32x4*)(outf + off + 4) = o1; }
;                     else { u32x4 w; w.x = cvt_pk_bf16(o0[0], o0[1]); w.y = cvt_pk_bf16(o0[2], o0[3]); w.z = cvt_pk_bf16(o1[0], o1[1]); w.w = cvt_pk_bf16(o1[2], o1[3]); *(u32x4*)(pexb + off) = w; } } } }
	v_pk_fma_f32 v[68:69], v[116:117], v[184:185], v[68:69] op_sel_hi:[1,0,1] neg_lo:[1,0,0] neg_hi:[1,0,0]
	v_fmac_f32_e32 v135, v96, v97
	v_cvt_pk_bf16_f32 v96, v100, v131
	v_cvt_pk_bf16_f32 v97, v101, v129
	v_lshlrev_b64 v[100:101], 11, v[238:239]
	v_lshl_add_u64 v[100:101], s[44:45], 0, v[100:101]
	v_cvt_pk_bf16_f32 v99, v103, v135
	v_lshl_add_u64 v[134:135], v[100:101], 0, v[168:169]
	global_store_dwordx4 v[134:135], v[96:99], off sc1
	v_add_f32_e32 v76, 1.0, v76
	v_rcp_f32_e32 v76, v76
	v_lshl_add_u64 v[96:97], v[144:145], 0, v[216:217]
	v_lshlrev_b64 v[96:97], 1, v[96:97]
	v_lshl_add_u64 v[98:99], s[44:45], 0, v[96:97]
	v_lshl_add_u64 v[96:97], s[40:41], 0, v[96:97]
	global_load_dwordx4 v[100:103], v[98:99], off
	global_load_dwordx4 v[148:151], v[96:97], off
	v_lshl_add_u64 v[96:97], v[146:147], 0, v[216:217]
	v_lshlrev_b64 v[128:129], 1, v[96:97]
	v_lshl_add_u64 v[96:97], s[44:45], 0, v[128:129]
	v_lshl_add_u64 v[128:129], s[40:41], 0, v[128:129]
	global_load_dwordx4 v[96:99], v[96:97], off
	v_pk_fma_f32 v[68:69], v[68:69], v[186:187], v[112:113] op_sel_hi:[1,0,1]
	global_load_dwordx4 v[128:131], v[128:129], off
	v_mul_f32_e32 v68, 0xbfb8aa3b, v68
	v_exp_f32_e32 v68, v68
	v_mul_f32_e32 v69, 0xbfb8aa3b, v69
	v_exp_f32_e32 v69, v69
	v_pk_fma_f32 v[64:65], v[108:109], v[184:185], v[64:65] op_sel_hi:[1,0,1] neg_lo:[1,0,0] neg_hi:[1,0,0]
	v_add_f32_e32 v68, 1.0, v68
	v_rcp_f32_e32 v68, v68
	v_add_f32_e32 v69, 1.0, v69
	v_rcp_f32_e32 v69, v69
	v_pk_fma_f32 v[64:65], v[64:65], v[186:187], v[104:105] op_sel_hi:[1,0,1]
	s_waitcnt vmcnt(0)
	v_lshlrev_b32_e32 v164, 16, v100
	v_lshlrev_b32_e32 v152, 16, v148
	v_and_b32_e32 v153, 0xffff0000, v148
	v_sub_f32_e32 v153, v153, v196
	v_sub_f32_e32 v152, v152, v196
	v_pk_mul_f32 v[152:153], v[198:199], v[152:153] op_sel_hi:[0,1]
	v_pk_fma_f32 v[152:153], v[136:137], v[152:153], v[140:141]
	v_and_b32_e32 v100, 0xffff0000, v100
	v_fmac_f32_e32 v153, v93, v100
	v_mul_f32_e32 v93, 0xbfb8aa3b, v94
	v_exp_f32_e32 v93, v93
	v_lshlrev_b32_e32 v148, 16, v149
	v_and_b32_e32 v149, 0xffff0000, v149
	v_sub_f32_e32 v149, v149, v196
	v_add_f32_e32 v93, 1.0, v93
	v_rcp_f32_e32 v93, v93
	v_sub_f32_e32 v148, v148, v196
	v_pk_mul_f32 v[148:149], v[198:199], v[148:149] op_sel_hi:[0,1]
	v_pk_fma_f32 v[148:149], v[138:139], v[148:149], v[142:143]
	v_lshlrev_b32_e32 v94, 16, v101
	v_fma_f32 v93, v93, v94, v148
	v_mul_f32_e32 v94, 0xbfb8aa3b, v95
	v_exp_f32_e32 v94, v94
	v_lshlrev_b32_e32 v154, 16, v150
	v_and_b32_e32 v155, 0xffff0000, v150
	v_sub_f32_e32 v155, v155, v196
	v_add_f32_e32 v94, 1.0, v94
	v_rcp_f32_e32 v94, v94
	v_sub_f32_e32 v154, v154, v196
	v_pk_mul_f32 v[154:155], v[198:199], v[154:155] op_sel_hi:[0,1]
	v_and_b32_e32 v95, 0xffff0000, v101
	v_pk_fma_f32 v[154:155], v[120:121], v[154:155], v[124:125]
	v_fmac_f32_e32 v149, v94, v95
	v_lshlrev_b32_e32 v94, 16, v102
	v_fma_f32 v94, v88, v94, v154
	v_mul_f32_e32 v88, 0xbfb8aa3b, v89
	v_exp_f32_e32 v88, v88
	v_and_b32_e32 v89, 0xffff0000, v102
	v_lshlrev_b32_e32 v150, 16, v151
	v_and_b32_e32 v151, 0xffff0000, v151
	v_add_f32_e32 v88, 1.0, v88
	v_rcp_f32_e32 v88, v88
	v_sub_f32_e32 v151, v151, v196
	v_sub_f32_e32 v150, v150, v196
	v_pk_mul_f32 v[150:151], v[198:199], v[150:151] op_sel_hi:[0,1]
	v_fmac_f32_e32 v155, v88, v89
	v_mul_f32_e32 v88, 0xbfb8aa3b, v90
	v_exp_f32_e32 v88, v88
	v_pk_fma_f32 v[150:151], v[122:123], v[150:151], v[126:127]
	v_lshlrev_b32_e32 v89, 16, v103
	v_fma_f32 v92, v92, v164, v152
	v_add_f32_e32 v88, 1.0, v88
	v_rcp_f32_e32 v88, v88
	v_cvt_pk_bf16_f32 v90, v94, v155
	v_lshlrev_b32_e32 v102, 16, v96
	v_lshlrev_b32_e32 v94, 16, v130
	v_fma_f32 v95, v88, v89, v150
	v_mul_f32_e32 v88, 0xbfb8aa3b, v91
	v_exp_f32_e32 v88, v88
	v_and_b32_e32 v89, 0xffff0000, v103
	v_sub_f32_e32 v94, v94, v192
	v_mul_f32_e32 v64, 0xbfb8aa3b, v64
	v_add_f32_e32 v88, 1.0, v88
	v_rcp_f32_e32 v88, v88
	v_exp_f32_e32 v64, v64
	v_fmac_f32_e32 v151, v88, v89
	v_cvt_pk_bf16_f32 v88, v92, v153
	v_cvt_pk_bf16_f32 v89, v93, v149
	v_lshlrev_b64 v[92:93], 11, v[236:237]
	v_lshl_add_u64 v[92:93], s[44:45], 0, v[92:93]
	v_cvt_pk_bf16_f32 v91, v95, v151
	v_lshl_add_u64 v[148:149], v[92:93], 0, v[168:169]
	v_lshlrev_b32_e32 v92, 16, v131
	v_and_b32_e32 v93, 0xffff0000, v131
	global_store_dwordx4 v[148:149], v[88:91], off sc1
	v_sub_f32_e32 v93, v93, v192
	v_sub_f32_e32 v92, v92, v192
	v_lshlrev_b32_e32 v90, 16, v128
	v_and_b32_e32 v91, 0xffff0000, v128
	v_sub_f32_e32 v91, v91, v192
	v_sub_f32_e32 v90, v90, v192
	v_pk_mul_f32 v[92:93], v[194:195], v[92:93] op_sel_hi:[0,1]
	v_pk_mul_f32 v[90:91], v[194:195], v[90:91] op_sel_hi:[0,1]
	v_pk_fma_f32 v[100:101], v[122:123], v[92:93], v[126:127]
	v_xor_b32_e32 v93, 0x80000000, v119
	v_xor_b32_e32 v92, 0x80000000, v118
	v_pk_fma_f32 v[90:91], v[136:137], v[90:91], v[140:141]
	v_pk_fma_f32 v[86:87], v[92:93], v[192:193], v[86:87] op_sel_hi:[1,0,1]
	v_fma_f32 v84, v84, v102, v90
	v_pk_fma_f32 v[86:87], v[86:87], v[194:195], v[114:115] op_sel_hi:[1,0,1]
	v_and_b32_e32 v90, 0xffff0000, v96
	v_fmac_f32_e32 v91, v85, v90
	v_mul_f32_e32 v85, 0xbfb8aa3b, v86
	v_exp_f32_e32 v85, v85
	v_lshlrev_b32_e32 v88, 16, v129
	v_and_b32_e32 v89, 0xffff0000, v129
	v_sub_f32_e32 v89, v89, v192
	v_add_f32_e32 v85, 1.0, v85
	v_rcp_f32_e32 v85, v85
	v_sub_f32_e32 v88, v88, v192
	v_pk_mul_f32 v[88:89], v[194:195], v[88:89] op_sel_hi:[0,1]
	v_pk_fma_f32 v[88:89], v[138:139], v[88:89], v[142:143]
	v_lshlrev_b32_e32 v86, 16, v97
	v_fma_f32 v85, v85, v86, v88
	v_mul_f32_e32 v86, 0xbfb8aa3b, v87
	v_exp_f32_e32 v86, v86
	v_and_b32_e32 v95, 0xffff0000, v130
	v_sub_f32_e32 v95, v95, v192
	v_pk_mul_f32 v[94:95], v[194:195], v[94:95] op_sel_hi:[0,1]
	v_add_f32_e32 v86, 1.0, v86
; __device__ __forceinline__ unsigned cvt_pk_bf16(float lo, float hi) { unsigned r; asm("v_cvt_pk_bf16_f32 %0, %1, %2" : "=v"(r) : "v"(lo), "v"(hi)); return r; }
; __device__ __forceinline__ float fast_sigmoid(float v) { return __builtin_amdgcn_rcpf(1.0f + __builtin_amdgcn_exp2f(-1.4426950408889634f * v)); }
; __device__ __forceinline__ f32x4 ln_fix(const f32x4& a, float mu, float rs, const f32x4& cs, const f32x4& cb) { return (a - cs * mu) * rs + cb; }
; __device__ __forceinline__ float bf_lo(unsigned w) { return __uint_as_float(w << 16); }
; __device__ __forceinline__ float bf_hi(unsigned w) { return __uint_as_float(w & 0xffff0000u); }
;     __device__ __forceinline__ void operator()(const f32x4 (&acc)[2][2][4][2], const Unit& u, int wr, int wc, int fr_in, int fq_in) const {
;     ...
;                 for (int m = (am * GR) & 3; m < ((am * GR) & 3) + GR; ++m) { const size_t off = (size_t)(row0 + ai * HALF + m * 16) * 1024 + col0 + bj * HALF; const float mu = rst.mu[ai][m], rs = rst.rs[ai][m];
;                     const u32x4 pw = ppw[m]; const u32x4 zw = pzw[m];
;                     const f32x4 x0 = ((f32x4){bf_lo(zw.x), bf_hi(zw.x), bf_lo(zw.y), bf_hi(zw.y)} - mu) * rs * gv[0] + bv[0], x1 = ((f32x4){bf_lo(zw.z), bf_hi(zw.z), bf_lo(zw.w), bf_hi(zw.w)} - mu) * rs * gv[1] + bv[1];
;                     const f32x4 a0 = ln_fix(acc[ai][bj][m][0], mu, rs, csv[0], cbv[0]), a1 = ln_fix(acc[ai][bj][m][1], mu, rs, csv[1], cbv[1]); f32x4 o0, o1;
;                     o0[0] = x0[0] + fast_sigmoid(a0[0]) * bf_lo(pw.x); o0[1] = x0[1] + fast_sigmoid(a0[1]) * bf_hi(pw.x);
;                     o0[2] = x0[2] + fast_sigmoid(a0[2]) * bf_lo(pw.y); o0[3] = x0[3] + fast_sigmoid(a0[3]) * bf_hi(pw.y);
;                     o1[0] = x1[0] + fast_sigmoid(a1[0]) * bf_lo(pw.z); o1[1] = x1[1] + fast_sigmoid(a1[1]) * bf_hi(pw.z);
;                     o1[2] = x1[2] + fast_sigmoid(a1[2]) * bf_lo(pw.w); o1[3] = x1[3] + fast_sigmoid(a1[3]) * bf_hi(pw.w);
;                     if constexpr (FINAL) { *(f32x4*)(outf + off) = o0; *(f32x4*)(outf + off + 4) = o1; }
;                     else { u32x4 w; w.x = cvt_pk_bf16(o0[0], o0[1]); w.y = cvt_pk_bf16(o0[2], o0[3]); w.z = cvt_pk_bf16(o1[0], o1[1]); w.w = cvt_pk_bf16(o1[2], o1[3]); *(u32x4*)(pexb + off) = w; } } } }
	v_rcp_f32_e32 v86, v86
	v_and_b32_e32 v87, 0xffff0000, v97
	v_pk_fma_f32 v[94:95], v[120:121], v[94:95], v[124:125]
	v_lshlrev_b64 v[128:129], 10, v[220:221]
	v_fmac_f32_e32 v89, v86, v87
	v_lshlrev_b32_e32 v86, 16, v98
	v_fma_f32 v86, v80, v86, v94
	v_mul_f32_e32 v80, 0xbfb8aa3b, v81
	v_exp_f32_e32 v80, v80
	v_and_b32_e32 v81, 0xffff0000, v98
	v_lshlrev_b64 v[130:131], 10, v[218:219]
	v_pk_fma_f32 v[78:79], v[92:93], v[188:189], v[78:79] op_sel_hi:[1,0,1]
	v_add_f32_e32 v80, 1.0, v80
	v_rcp_f32_e32 v80, v80
	v_pk_fma_f32 v[78:79], v[78:79], v[190:191], v[114:115] op_sel_hi:[1,0,1]
	v_pk_fma_f32 v[70:71], v[92:93], v[184:185], v[70:71] op_sel_hi:[1,0,1]
	v_add_f32_e32 v64, 1.0, v64
	v_fmac_f32_e32 v95, v80, v81
	v_mul_f32_e32 v80, 0xbfb8aa3b, v82
	v_exp_f32_e32 v80, v80
	v_lshlrev_b32_e32 v81, 16, v99
	v_cvt_pk_bf16_f32 v82, v86, v95
	v_pk_fma_f32 v[70:71], v[70:71], v[186:187], v[114:115] op_sel_hi:[1,0,1]
	v_add_f32_e32 v80, 1.0, v80
	v_rcp_f32_e32 v80, v80
	v_rcp_f32_e32 v64, v64
	v_fma_f32 v87, v80, v81, v100
	v_mul_f32_e32 v80, 0xbfb8aa3b, v83
	v_exp_f32_e32 v80, v80
	v_and_b32_e32 v81, 0xffff0000, v99
	v_add_f32_e32 v80, 1.0, v80
	v_rcp_f32_e32 v80, v80
	s_nop 0
	v_fmac_f32_e32 v101, v80, v81
	v_cvt_pk_bf16_f32 v80, v84, v91
	v_cvt_pk_bf16_f32 v81, v85, v89
	v_lshlrev_b64 v[84:85], 11, v[234:235]
	v_lshl_add_u64 v[84:85], s[44:45], 0, v[84:85]
	v_lshl_add_u64 v[118:119], v[84:85], 0, v[168:169]
	v_cvt_pk_bf16_f32 v83, v87, v101
	global_store_dwordx4 v[118:119], v[80:83], off sc1
	s_nop 1
	v_lshl_add_u64 v[80:81], v[128:129], 0, v[216:217]
	v_lshlrev_b64 v[80:81], 1, v[80:81]
	v_lshl_add_u64 v[82:83], s[44:45], 0, v[80:81]
	v_lshl_add_u64 v[80:81], s[40:41], 0, v[80:81]
	global_load_dwordx4 v[84:87], v[82:83], off
	global_load_dwordx4 v[94:97], v[80:81], off
	v_lshl_add_u64 v[80:81], v[130:131], 0, v[216:217]
	v_lshlrev_b64 v[88:89], 1, v[80:81]
	v_lshl_add_u64 v[80:81], s[44:45], 0, v[88:89]
	v_lshl_add_u64 v[88:89], s[40:41], 0, v[88:89]
	global_load_dwordx4 v[80:83], v[80:81], off
	s_waitcnt vmcnt(0)
	v_lshlrev_b32_e32 v102, 16, v84
	global_load_dwordx4 v[88:91], v[88:89], off
	v_lshlrev_b32_e32 v98, 16, v94
	v_and_b32_e32 v99, 0xffff0000, v94
	v_sub_f32_e32 v99, v99, v188
	v_sub_f32_e32 v98, v98, v188
	v_pk_mul_f32 v[98:99], v[190:191], v[98:99] op_sel_hi:[0,1]
	v_pk_fma_f32 v[98:99], v[136:137], v[98:99], v[140:141]
	v_and_b32_e32 v84, 0xffff0000, v84
	v_fmac_f32_e32 v99, v77, v84
	v_mul_f32_e32 v77, 0xbfb8aa3b, v78
	v_exp_f32_e32 v77, v77
	v_lshlrev_b32_e32 v94, 16, v95
	v_and_b32_e32 v95, 0xffff0000, v95
	v_sub_f32_e32 v95, v95, v188
	v_add_f32_e32 v77, 1.0, v77
	v_rcp_f32_e32 v77, v77
	v_sub_f32_e32 v94, v94, v188
	v_pk_mul_f32 v[94:95], v[190:191], v[94:95] op_sel_hi:[0,1]
	v_pk_fma_f32 v[94:95], v[138:139], v[94:95], v[142:143]
	v_lshlrev_b32_e32 v78, 16, v85
	v_fma_f32 v77, v77, v78, v94
	v_mul_f32_e32 v78, 0xbfb8aa3b, v79
	v_exp_f32_e32 v78, v78
	v_lshlrev_b32_e32 v100, 16, v96
	v_and_b32_e32 v101, 0xffff0000, v96
	v_sub_f32_e32 v101, v101, v188
	v_add_f32_e32 v78, 1.0, v78
	v_rcp_f32_e32 v78, v78
	v_sub_f32_e32 v100, v100, v188
	v_pk_mul_f32 v[100:101], v[190:191], v[100:101] op_sel_hi:[0,1]
	v_and_b32_e32 v79, 0xffff0000, v85
	v_pk_fma_f32 v[100:101], v[120:121], v[100:101], v[124:125]
	v_fmac_f32_e32 v95, v78, v79
	v_lshlrev_b32_e32 v78, 16, v86
	v_fma_f32 v78, v72, v78, v100
	v_mul_f32_e32 v72, 0xbfb8aa3b, v73
	v_exp_f32_e32 v72, v72
	v_and_b32_e32 v73, 0xffff0000, v86
	v_lshlrev_b32_e32 v96, 16, v97
	v_and_b32_e32 v97, 0xffff0000, v97
	v_add_f32_e32 v72, 1.0, v72
	v_rcp_f32_e32 v72, v72
	v_sub_f32_e32 v97, v97, v188
	v_sub_f32_e32 v96, v96, v188
	v_pk_mul_f32 v[96:97], v[190:191], v[96:97] op_sel_hi:[0,1]
	v_fmac_f32_e32 v101, v72, v73
	v_mul_f32_e32 v72, 0xbfb8aa3b, v74
	v_exp_f32_e32 v72, v72
	v_pk_fma_f32 v[96:97], v[122:123], v[96:97], v[126:127]
	v_lshlrev_b32_e32 v73, 16, v87
	v_fma_f32 v76, v76, v102, v98
	v_add_f32_e32 v72, 1.0, v72
	v_rcp_f32_e32 v72, v72
	v_cvt_pk_bf16_f32 v74, v78, v101
	v_xor_b32_e32 v85, 0x80000000, v111
	v_fma_f32 v79, v72, v73, v96
	v_mul_f32_e32 v72, 0xbfb8aa3b, v75
	v_exp_f32_e32 v72, v72
	v_and_b32_e32 v73, 0xffff0000, v87
	v_xor_b32_e32 v84, 0x80000000, v110
	v_pk_fma_f32 v[66:67], v[84:85], v[184:185], v[66:67] op_sel_hi:[1,0,1]
	v_add_f32_e32 v72, 1.0, v72
	v_rcp_f32_e32 v72, v72
	v_lshlrev_b32_e32 v84, 16, v80
	v_pk_fma_f32 v[66:67], v[66:67], v[186:187], v[106:107] op_sel_hi:[1,0,1]
	v_lshl_add_u64 v[110:111], v[216:217], 0, s[52:53]
	v_fmac_f32_e32 v97, v72, v73
	v_cvt_pk_bf16_f32 v72, v76, v99
	v_cvt_pk_bf16_f32 v73, v77, v95
	v_lshlrev_b64 v[76:77], 11, v[220:221]
	v_lshl_add_u64 v[76:77], s[44:45], 0, v[76:77]
	v_cvt_pk_bf16_f32 v75, v79, v97
	v_lshl_add_u64 v[150:151], v[76:77], 0, v[168:169]
	global_store_dwordx4 v[150:151], v[72:75], off sc1
	v_lshl_add_u64 v[96:97], v[110:111], 0, v[230:231]
	v_lshl_add_u64 v[96:97], v[96:97], 1, s[40:41]
	v_lshl_add_u64 v[104:105], v[110:111], 0, v[232:233]
	v_lshl_add_u64 v[104:105], v[104:105], 1, s[40:41]
	s_waitcnt vmcnt(0)
; __device__ __forceinline__ unsigned cvt_pk_bf16(float lo, float hi) { unsigned r; asm("v_cvt_pk_bf16_f32 %0, %1, %2" : "=v"(r) : "v"(lo), "v"(hi)); return r; }
; __device__ __forceinline__ float fast_sigmoid(float v) { return __builtin_amdgcn_rcpf(1.0f + __builtin_amdgcn_exp2f(-1.4426950408889634f * v)); }
; __device__ __forceinline__ f32x4 ln_fix(const f32x4& a, float mu, float rs, const f32x4& cs, const f32x4& cb) { return (a - cs * mu) * rs + cb; }
; __device__ __forceinline__ float bf_lo(unsigned w) { return __uint_as_float(w << 16); }
; __device__ __forceinline__ float bf_hi(unsigned w) { return __uint_as_float(w & 0xffff0000u); }
;     __device__ __forceinline__ void operator()(const f32x4 (&acc)[2][2][4][2], const Unit& u, int wr, int wc, int fr_in, int fq_in) const {
;     ...
;                 for (int m = (am * GR) & 3; m < ((am * GR) & 3) + GR; ++m) { const size_t off = (size_t)(row0 + ai * HALF + m * 16) * 1024 + col0 + bj * HALF; const float mu = rst.mu[ai][m], rs = rst.rs[ai][m];
;                     const u32x4 pw = ppw[m]; const u32x4 zw = pzw[m];
;                     const f32x4 x0 = ((f32x4){bf_lo(zw.x), bf_hi(zw.x), bf_lo(zw.y), bf_hi(zw.y)} - mu) * rs * gv[0] + bv[0], x1 = ((f32x4){bf_lo(zw.z), bf_hi(zw.z), bf_lo(zw.w), bf_hi(zw.w)} - mu) * rs * gv[1] + bv[1];
;                     const f32x4 a0 = ln_fix(acc[ai][bj][m][0], mu, rs, csv[0], cbv[0]), a1 = ln_fix(acc[ai][bj][m][1], mu, rs, csv[1], cbv[1]); f32x4 o0, o1;
;                     o0[0] = x0[0] + fast_sigmoid(a0[0]) * bf_lo(pw.x); o0[1] = x0[1] + fast_sigmoid(a0[1]) * bf_hi(pw.x);
;                     o0[2] = x0[2] + fast_sigmoid(a0[2]) * bf_lo(pw.y); o0[3] = x0[3] + fast_sigmoid(a0[3]) * bf_hi(pw.y);
;                     o1[0] = x1[0] + fast_sigmoid(a1[0]) * bf_lo(pw.z); o1[1] = x1[1] + fast_sigmoid(a1[1]) * bf_hi(pw.z);
;                     o1[2] = x1[2] + fast_sigmoid(a1[2]) * bf_lo(pw.w); o1[3] = x1[3] + fast_sigmoid(a1[3]) * bf_hi(pw.w);
;                     if constexpr (FINAL) { *(f32x4*)(outf + off) = o0; *(f32x4*)(outf + off + 4) = o1; }
;                     else { u32x4 w; w.x = cvt_pk_bf16(o0[0], o0[1]); w.y = cvt_pk_bf16(o0[2], o0[3]); w.z = cvt_pk_bf16(o1[0], o1[1]); w.w = cvt_pk_bf16(o1[2], o1[3]); *(u32x4*)(pexb + off) = w; } } } }
	v_lshlrev_b32_e32 v74, 16, v88
	v_and_b32_e32 v75, 0xffff0000, v88
	v_sub_f32_e32 v75, v75, v184
	v_sub_f32_e32 v74, v74, v184
	v_pk_mul_f32 v[74:75], v[186:187], v[74:75] op_sel_hi:[0,1]
	v_pk_fma_f32 v[74:75], v[136:137], v[74:75], v[140:141]
	v_lshlrev_b32_e32 v72, 16, v89
	v_fma_f32 v68, v68, v84, v74
	v_and_b32_e32 v74, 0xffff0000, v80
	v_fmac_f32_e32 v75, v69, v74
	v_mul_f32_e32 v69, 0xbfb8aa3b, v70
	v_exp_f32_e32 v69, v69
	v_and_b32_e32 v73, 0xffff0000, v89
	v_sub_f32_e32 v73, v73, v184
	v_sub_f32_e32 v72, v72, v184
	v_add_f32_e32 v69, 1.0, v69
	v_rcp_f32_e32 v69, v69
	v_pk_mul_f32 v[72:73], v[186:187], v[72:73] op_sel_hi:[0,1]
	v_pk_fma_f32 v[72:73], v[138:139], v[72:73], v[142:143]
	v_lshlrev_b32_e32 v70, 16, v81
	v_fma_f32 v69, v69, v70, v72
	v_mul_f32_e32 v70, 0xbfb8aa3b, v71
	v_exp_f32_e32 v70, v70
	v_lshlrev_b32_e32 v78, 16, v90
	v_and_b32_e32 v79, 0xffff0000, v90
	v_sub_f32_e32 v79, v79, v184
	v_add_f32_e32 v70, 1.0, v70
	v_rcp_f32_e32 v70, v70
	v_sub_f32_e32 v78, v78, v184
	v_pk_mul_f32 v[78:79], v[186:187], v[78:79] op_sel_hi:[0,1]
	v_and_b32_e32 v71, 0xffff0000, v81
	v_pk_fma_f32 v[78:79], v[120:121], v[78:79], v[124:125]
	v_fmac_f32_e32 v73, v70, v71
	v_lshlrev_b32_e32 v70, 16, v82
	v_fma_f32 v70, v64, v70, v78
	v_mul_f32_e32 v64, 0xbfb8aa3b, v65
	v_exp_f32_e32 v64, v64
	v_and_b32_e32 v65, 0xffff0000, v82
	v_lshlrev_b32_e32 v76, 16, v91
	v_and_b32_e32 v77, 0xffff0000, v91
	v_add_f32_e32 v64, 1.0, v64
	v_rcp_f32_e32 v64, v64
	v_sub_f32_e32 v77, v77, v184
	v_sub_f32_e32 v76, v76, v184
	v_pk_mul_f32 v[76:77], v[186:187], v[76:77] op_sel_hi:[0,1]
	v_fmac_f32_e32 v79, v64, v65
	v_mul_f32_e32 v64, 0xbfb8aa3b, v66
	v_exp_f32_e32 v64, v64
	v_pk_fma_f32 v[76:77], v[122:123], v[76:77], v[126:127]
	v_lshlrev_b32_e32 v65, 16, v83
	v_cvt_pk_bf16_f32 v66, v70, v79
	v_add_f32_e32 v64, 1.0, v64
	v_rcp_f32_e32 v64, v64
	s_nop 0
	v_fma_f32 v71, v64, v65, v76
	v_mul_f32_e32 v64, 0xbfb8aa3b, v67
	v_exp_f32_e32 v64, v64
	v_and_b32_e32 v65, 0xffff0000, v83
	v_add_f32_e32 v64, 1.0, v64
	v_rcp_f32_e32 v64, v64
	s_nop 0
	v_fmac_f32_e32 v77, v64, v65
	v_cvt_pk_bf16_f32 v64, v68, v75
	v_cvt_pk_bf16_f32 v65, v69, v73
	v_lshlrev_b64 v[68:69], 11, v[218:219]
	v_lshl_add_u64 v[68:69], s[44:45], 0, v[68:69]
	v_lshl_add_u64 v[108:109], v[68:69], 0, v[168:169]
	v_cvt_pk_bf16_f32 v67, v71, v77
	global_store_dwordx4 v[108:109], v[64:67], off sc1
	global_load_dwordx4 v[64:67], v[228:229], off offset:528
	s_nop 0
	global_load_dwordx4 v[72:75], v[228:229], off offset:512
	global_load_dwordx4 v[68:71], v[226:227], off offset:528
	global_load_dwordx4 v[76:79], v[226:227], off offset:512
	global_load_dwordx4 v[80:83], v[224:225], off offset:528
	global_load_dwordx4 v[88:91], v[224:225], off offset:512
	global_load_dwordx4 v[84:87], v[222:223], off offset:528
	global_load_dwordx4 v[92:95], v[222:223], off offset:512
	global_load_dwordx4 v[112:115], v[96:97], off
	global_load_dwordx4 v[100:103], v[156:157], off offset:256
	s_waitcnt vmcnt(0)
	v_pk_fma_f32 v[56:57], v[212:213], v[64:65], v[56:57] op_sel_hi:[0,1,1] neg_lo:[1,0,0] neg_hi:[1,0,0]
	global_load_dwordx4 v[104:107], v[104:105], off
	v_pk_fma_f32 v[60:61], v[212:213], v[72:73], v[60:61] op_sel_hi:[0,1,1] neg_lo:[1,0,0] neg_hi:[1,0,0]
	global_load_dwordx4 v[96:99], v[158:159], off offset:256
	v_pk_fma_f32 v[60:61], v[214:215], v[60:61], v[76:77] op_sel_hi:[0,1,1]
	v_mul_f32_e32 v61, 0xbfb8aa3b, v61
	v_exp_f32_e32 v61, v61
	v_pk_fma_f32 v[62:63], v[212:213], v[74:75], v[62:63] op_sel_hi:[0,1,1] neg_lo:[1,0,0] neg_hi:[1,0,0]
	v_lshlrev_b32_e32 v116, 16, v112
	v_and_b32_e32 v117, 0xffff0000, v112
	v_add_f32_e32 v61, 1.0, v61
	v_rcp_f32_e32 v61, v61
	v_sub_f32_e32 v117, v117, v212
	v_sub_f32_e32 v116, v116, v212
	v_pk_mul_f32 v[116:117], v[214:215], v[116:117] op_sel_hi:[0,1]
	v_pk_fma_f32 v[116:117], v[88:89], v[116:117], v[92:93]
	v_pk_fma_f32 v[62:63], v[214:215], v[62:63], v[78:79] op_sel_hi:[0,1,1]
	v_lshlrev_b32_e32 v122, 16, v100
	v_and_b32_e32 v100, 0xffff0000, v100
	v_fmac_f32_e32 v117, v61, v100
	v_mul_f32_e32 v61, 0xbfb8aa3b, v62
	v_exp_f32_e32 v61, v61
	v_lshlrev_b32_e32 v112, 16, v113
	v_and_b32_e32 v113, 0xffff0000, v113
	v_sub_f32_e32 v113, v113, v212
	v_add_f32_e32 v61, 1.0, v61
	v_rcp_f32_e32 v61, v61
	v_sub_f32_e32 v112, v112, v212
	v_pk_mul_f32 v[112:113], v[214:215], v[112:113] op_sel_hi:[0,1]
	v_pk_fma_f32 v[112:113], v[90:91], v[112:113], v[94:95]
	v_lshlrev_b32_e32 v62, 16, v101
	v_pk_fma_f32 v[56:57], v[214:215], v[56:57], v[68:69] op_sel_hi:[0,1,1]
	v_fma_f32 v61, v61, v62, v112
	v_mul_f32_e32 v62, 0xbfb8aa3b, v63
	v_exp_f32_e32 v62, v62
	v_mul_f32_e32 v56, 0xbfb8aa3b, v56
	v_exp_f32_e32 v56, v56
	v_lshlrev_b32_e32 v120, 16, v114
	v_add_f32_e32 v62, 1.0, v62
	v_rcp_f32_e32 v62, v62
	v_add_f32_e32 v56, 1.0, v56
	v_and_b32_e32 v121, 0xffff0000, v114
	v_rcp_f32_e32 v56, v56
	v_sub_f32_e32 v121, v121, v212
	v_sub_f32_e32 v120, v120, v212
	v_pk_mul_f32 v[120:121], v[214:215], v[120:121] op_sel_hi:[0,1]
	v_and_b32_e32 v63, 0xffff0000, v101
	v_pk_fma_f32 v[120:121], v[80:81], v[120:121], v[84:85]
	v_fmac_f32_e32 v113, v62, v63
	v_lshlrev_b32_e32 v62, 16, v102
	v_fma_f32 v62, v56, v62, v120
	v_mul_f32_e32 v56, 0xbfb8aa3b, v57
	v_exp_f32_e32 v56, v56
	v_pk_fma_f32 v[58:59], v[212:213], v[66:67], v[58:59] op_sel_hi:[0,1,1] neg_lo:[1,0,0] neg_hi:[1,0,0]
	v_pk_fma_f32 v[58:59], v[214:215], v[58:59], v[70:71] op_sel_hi:[0,1,1]
	v_and_b32_e32 v57, 0xffff0000, v102
	v_add_f32_e32 v56, 1.0, v56
	v_rcp_f32_e32 v56, v56
	v_lshlrev_b32_e32 v114, 16, v115
	v_and_b32_e32 v115, 0xffff0000, v115
	v_sub_f32_e32 v115, v115, v212
	v_fmac_f32_e32 v121, v56, v57
	v_mul_f32_e32 v56, 0xbfb8aa3b, v58
	v_exp_f32_e32 v56, v56
	v_sub_f32_e32 v114, v114, v212
	v_pk_mul_f32 v[114:115], v[214:215], v[114:115] op_sel_hi:[0,1]
	v_pk_fma_f32 v[114:115], v[82:83], v[114:115], v[86:87]
	v_add_f32_e32 v56, 1.0, v56
	v_rcp_f32_e32 v56, v56
	v_lshlrev_b32_e32 v57, 16, v103
	v_mul_f32_e32 v60, 0xbfb8aa3b, v60
	v_exp_f32_e32 v60, v60
	v_fma_f32 v63, v56, v57, v114
	v_mul_f32_e32 v56, 0xbfb8aa3b, v59
	v_exp_f32_e32 v56, v56
	v_pk_fma_f32 v[52:53], v[208:209], v[72:73], v[52:53] op_sel_hi:[0,1,1] neg_lo:[1,0,0] neg_hi:[1,0,0]
	v_pk_fma_f32 v[52:53], v[210:211], v[52:53], v[76:77] op_sel_hi:[0,1,1]
	v_mul_f32_e32 v52, 0xbfb8aa3b, v52
	v_add_f32_e32 v56, 1.0, v56
	v_add_f32_e32 v60, 1.0, v60
	v_rcp_f32_e32 v56, v56
	v_exp_f32_e32 v52, v52
	v_mul_f32_e32 v53, 0xbfb8aa3b, v53
	v_rcp_f32_e32 v60, v60
	v_exp_f32_e32 v53, v53
	v_and_b32_e32 v57, 0xffff0000, v103
	v_fmac_f32_e32 v115, v56, v57
	v_cvt_pk_bf16_f32 v58, v62, v121
	v_cvt_pk_bf16_f32 v59, v63, v115
	v_add_f32_e32 v52, 1.0, v52
	v_fma_f32 v60, v60, v122, v116
	v_cvt_pk_bf16_f32 v56, v60, v117
	v_cvt_pk_bf16_f32 v57, v61, v113
	global_store_dwordx4 v[156:157], v[56:59], off offset:256 sc1
	v_rcp_f32_e32 v52, v52
	v_add_f32_e32 v53, 1.0, v53
	s_waitcnt vmcnt(0)
; __device__ __forceinline__ unsigned cvt_pk_bf16(float lo, float hi) { unsigned r; asm("v_cvt_pk_bf16_f32 %0, %1, %2" : "=v"(r) : "v"(lo), "v"(hi)); return r; }
; __device__ __forceinline__ float fast_sigmoid(float v) { return __builtin_amdgcn_rcpf(1.0f + __builtin_amdgcn_exp2f(-1.4426950408889634f * v)); }
; __device__ __forceinline__ f32x4 ln_fix(const f32x4& a, float mu, float rs, const f32x4& cs, const f32x4& cb) { return (a - cs * mu) * rs + cb; }
; __device__ __forceinline__ float bf_lo(unsigned w) { return __uint_as_float(w << 16); }
; __device__ __forceinline__ float bf_hi(unsigned w) { return __uint_as_float(w & 0xffff0000u); }
;     __device__ __forceinline__ void operator()(const f32x4 (&acc)[2][2][4][2], const Unit& u, int wr, int wc, int fr_in, int fq_in) const {
;     ...
;                 for (int m = (am * GR) & 3; m < ((am * GR) & 3) + GR; ++m) { const size_t off = (size_t)(row0 + ai * HALF + m * 16) * 1024 + col0 + bj * HALF; const float mu = rst.mu[ai][m], rs = rst.rs[ai][m];
;                     const u32x4 pw = ppw[m]; const u32x4 zw = pzw[m];
;                     const f32x4 x0 = ((f32x4){bf_lo(zw.x), bf_hi(zw.x), bf_lo(zw.y), bf_hi(zw.y)} - mu) * rs * gv[0] + bv[0], x1 = ((f32x4){bf_lo(zw.z), bf_hi(zw.z), bf_lo(zw.w), bf_hi(zw.w)} - mu) * rs * gv[1] + bv[1];
;                     const f32x4 a0 = ln_fix(acc[ai][bj][m][0], mu, rs, csv[0], cbv[0]), a1 = ln_fix(acc[ai][bj][m][1], mu, rs, csv[1], cbv[1]); f32x4 o0, o1;
;                     o0[0] = x0[0] + fast_sigmoid(a0[0]) * bf_lo(pw.x); o0[1] = x0[1] + fast_sigmoid(a0[1]) * bf_hi(pw.x);
;                     o0[2] = x0[2] + fast_sigmoid(a0[2]) * bf_lo(pw.y); o0[3] = x0[3] + fast_sigmoid(a0[3]) * bf_hi(pw.y);
;                     o1[0] = x1[0] + fast_sigmoid(a1[0]) * bf_lo(pw.z); o1[1] = x1[1] + fast_sigmoid(a1[1]) * bf_hi(pw.z);
;                     o1[2] = x1[2] + fast_sigmoid(a1[2]) * bf_lo(pw.w); o1[3] = x1[3] + fast_sigmoid(a1[3]) * bf_hi(pw.w);
;                     if constexpr (FINAL) { *(f32x4*)(outf + off) = o0; *(f32x4*)(outf + off + 4) = o1; }
;                     else { u32x4 w; w.x = cvt_pk_bf16(o0[0], o0[1]); w.y = cvt_pk_bf16(o0[2], o0[3]); w.z = cvt_pk_bf16(o1[0], o1[1]); w.w = cvt_pk_bf16(o1[2], o1[3]); *(u32x4*)(pexb + off) = w; } } } }
	v_lshlrev_b32_e32 v58, 16, v104
	v_and_b32_e32 v59, 0xffff0000, v104
	v_sub_f32_e32 v59, v59, v208
	v_sub_f32_e32 v58, v58, v208
	v_rcp_f32_e32 v53, v53
	v_pk_mul_f32 v[58:59], v[210:211], v[58:59] op_sel_hi:[0,1]
	v_pk_fma_f32 v[58:59], v[88:89], v[58:59], v[92:93]
	v_pk_fma_f32 v[54:55], v[208:209], v[74:75], v[54:55] op_sel_hi:[0,1,1] neg_lo:[1,0,0] neg_hi:[1,0,0]
	v_lshlrev_b32_e32 v100, 16, v96
	v_pk_fma_f32 v[54:55], v[210:211], v[54:55], v[78:79] op_sel_hi:[0,1,1]
	v_fma_f32 v52, v52, v100, v58
	v_and_b32_e32 v58, 0xffff0000, v96
	v_fmac_f32_e32 v59, v53, v58
	v_mul_f32_e32 v53, 0xbfb8aa3b, v54
	v_exp_f32_e32 v53, v53
	v_lshlrev_b32_e32 v56, 16, v105
	v_and_b32_e32 v57, 0xffff0000, v105
	v_sub_f32_e32 v57, v57, v208
	v_add_f32_e32 v53, 1.0, v53
	v_rcp_f32_e32 v53, v53
	v_sub_f32_e32 v56, v56, v208
	v_pk_mul_f32 v[56:57], v[210:211], v[56:57] op_sel_hi:[0,1]
	v_pk_fma_f32 v[56:57], v[90:91], v[56:57], v[94:95]
	v_pk_fma_f32 v[48:49], v[208:209], v[64:65], v[48:49] op_sel_hi:[0,1,1] neg_lo:[1,0,0] neg_hi:[1,0,0]
	v_lshlrev_b32_e32 v54, 16, v97
	v_pk_fma_f32 v[48:49], v[210:211], v[48:49], v[68:69] op_sel_hi:[0,1,1]
	v_fma_f32 v53, v53, v54, v56
	v_mul_f32_e32 v54, 0xbfb8aa3b, v55
	v_exp_f32_e32 v54, v54
	v_mul_f32_e32 v48, 0xbfb8aa3b, v48
	v_exp_f32_e32 v48, v48
	v_lshlrev_b32_e32 v62, 16, v106
	v_add_f32_e32 v54, 1.0, v54
	v_rcp_f32_e32 v54, v54
	v_add_f32_e32 v48, 1.0, v48
	v_and_b32_e32 v63, 0xffff0000, v106
	v_rcp_f32_e32 v48, v48
	v_sub_f32_e32 v63, v63, v208
	v_sub_f32_e32 v62, v62, v208
	v_pk_mul_f32 v[62:63], v[210:211], v[62:63] op_sel_hi:[0,1]
	v_and_b32_e32 v55, 0xffff0000, v97
	v_pk_fma_f32 v[62:63], v[80:81], v[62:63], v[84:85]
	v_fmac_f32_e32 v57, v54, v55
	v_lshlrev_b32_e32 v54, 16, v98
	v_fma_f32 v54, v48, v54, v62
	v_mul_f32_e32 v48, 0xbfb8aa3b, v49
	v_exp_f32_e32 v48, v48
	v_pk_fma_f32 v[50:51], v[208:209], v[66:67], v[50:51] op_sel_hi:[0,1,1] neg_lo:[1,0,0] neg_hi:[1,0,0]
	v_pk_fma_f32 v[50:51], v[210:211], v[50:51], v[70:71] op_sel_hi:[0,1,1]
	v_and_b32_e32 v49, 0xffff0000, v98
	v_add_f32_e32 v48, 1.0, v48
	v_rcp_f32_e32 v48, v48
	v_lshlrev_b32_e32 v60, 16, v107
	v_and_b32_e32 v61, 0xffff0000, v107
	v_sub_f32_e32 v61, v61, v208
	v_fmac_f32_e32 v63, v48, v49
	v_mul_f32_e32 v48, 0xbfb8aa3b, v50
	v_exp_f32_e32 v48, v48
	v_sub_f32_e32 v60, v60, v208
	v_pk_mul_f32 v[60:61], v[210:211], v[60:61] op_sel_hi:[0,1]
	v_pk_fma_f32 v[60:61], v[82:83], v[60:61], v[86:87]
	v_add_f32_e32 v48, 1.0, v48
	v_rcp_f32_e32 v48, v48
	v_lshlrev_b32_e32 v49, 16, v99
	v_cvt_pk_bf16_f32 v50, v54, v63
	v_pk_fma_f32 v[44:45], v[204:205], v[72:73], v[44:45] op_sel_hi:[0,1,1] neg_lo:[1,0,0] neg_hi:[1,0,0]
	v_fma_f32 v55, v48, v49, v60
	v_mul_f32_e32 v48, 0xbfb8aa3b, v51
	v_exp_f32_e32 v48, v48
	v_and_b32_e32 v49, 0xffff0000, v99
	v_pk_fma_f32 v[44:45], v[206:207], v[44:45], v[76:77] op_sel_hi:[0,1,1]
	v_mul_f32_e32 v45, 0xbfb8aa3b, v45
	v_add_f32_e32 v48, 1.0, v48
	v_rcp_f32_e32 v48, v48
	v_exp_f32_e32 v45, v45
	v_pk_fma_f32 v[46:47], v[204:205], v[74:75], v[46:47] op_sel_hi:[0,1,1] neg_lo:[1,0,0] neg_hi:[1,0,0]
	v_pk_fma_f32 v[46:47], v[206:207], v[46:47], v[78:79] op_sel_hi:[0,1,1]
	v_fmac_f32_e32 v61, v48, v49
	v_cvt_pk_bf16_f32 v48, v52, v59
	v_cvt_pk_bf16_f32 v49, v53, v57
	v_cvt_pk_bf16_f32 v51, v55, v61
	global_store_dwordx4 v[158:159], v[48:51], off offset:256 sc1
	global_load_dwordx4 v[56:59], v[132:133], off offset:256
	v_lshl_add_u64 v[52:53], v[110:111], 0, v[162:163]
	v_lshl_add_u64 v[48:49], v[110:111], 0, v[160:161]
	v_lshl_add_u64 v[48:49], v[48:49], 1, s[40:41]
	global_load_dwordx4 v[60:63], v[48:49], off
	v_lshl_add_u64 v[52:53], v[52:53], 1, s[40:41]
	global_load_dwordx4 v[52:55], v[52:53], off
	v_add_f32_e32 v45, 1.0, v45
	global_load_dwordx4 v[48:51], v[134:135], off offset:256
	v_rcp_f32_e32 v45, v45
	v_pk_fma_f32 v[40:41], v[204:205], v[64:65], v[40:41] op_sel_hi:[0,1,1] neg_lo:[1,0,0] neg_hi:[1,0,0]
	v_pk_fma_f32 v[40:41], v[206:207], v[40:41], v[68:69] op_sel_hi:[0,1,1]
	v_mul_f32_e32 v40, 0xbfb8aa3b, v40
	v_exp_f32_e32 v40, v40
	v_pk_fma_f32 v[42:43], v[204:205], v[66:67], v[42:43] op_sel_hi:[0,1,1] neg_lo:[1,0,0] neg_hi:[1,0,0]
	v_pk_fma_f32 v[42:43], v[206:207], v[42:43], v[70:71] op_sel_hi:[0,1,1]
	v_mul_f32_e32 v44, 0xbfb8aa3b, v44
	v_add_f32_e32 v40, 1.0, v40
	v_rcp_f32_e32 v40, v40
	v_exp_f32_e32 v44, v44
	v_pk_fma_f32 v[36:37], v[200:201], v[72:73], v[36:37] op_sel_hi:[0,1,1] neg_lo:[1,0,0] neg_hi:[1,0,0]
	v_pk_fma_f32 v[36:37], v[202:203], v[36:37], v[76:77] op_sel_hi:[0,1,1]
	v_mul_f32_e32 v36, 0xbfb8aa3b, v36
	v_add_f32_e32 v44, 1.0, v44
	v_exp_f32_e32 v36, v36
	v_mul_f32_e32 v37, 0xbfb8aa3b, v37
	v_rcp_f32_e32 v44, v44
	v_exp_f32_e32 v37, v37
	v_add_f32_e32 v36, 1.0, v36
	v_rcp_f32_e32 v36, v36
	v_add_f32_e32 v37, 1.0, v37
	v_rcp_f32_e32 v37, v37
	v_pk_fma_f32 v[38:39], v[200:201], v[74:75], v[38:39] op_sel_hi:[0,1,1] neg_lo:[1,0,0] neg_hi:[1,0,0]
	v_pk_fma_f32 v[38:39], v[202:203], v[38:39], v[78:79] op_sel_hi:[0,1,1]
	v_pk_fma_f32 v[32:33], v[200:201], v[64:65], v[32:33] op_sel_hi:[0,1,1] neg_lo:[1,0,0] neg_hi:[1,0,0]
	v_pk_fma_f32 v[32:33], v[202:203], v[32:33], v[68:69] op_sel_hi:[0,1,1]
	v_mul_f32_e32 v32, 0xbfb8aa3b, v32
	v_exp_f32_e32 v32, v32
	v_pk_fma_f32 v[34:35], v[200:201], v[66:67], v[34:35] op_sel_hi:[0,1,1] neg_lo:[1,0,0] neg_hi:[1,0,0]
	v_pk_fma_f32 v[34:35], v[202:203], v[34:35], v[70:71] op_sel_hi:[0,1,1]
	v_pk_fma_f32 v[28:29], v[196:197], v[72:73], v[28:29] op_sel_hi:[0,1,1] neg_lo:[1,0,0] neg_hi:[1,0,0]
	v_add_f32_e32 v32, 1.0, v32
	v_rcp_f32_e32 v32, v32
	v_pk_fma_f32 v[28:29], v[198:199], v[28:29], v[76:77] op_sel_hi:[0,1,1]
	v_mul_f32_e32 v29, 0xbfb8aa3b, v29
	v_exp_f32_e32 v29, v29
; __device__ __forceinline__ unsigned cvt_pk_bf16(float lo, float hi) { unsigned r; asm("v_cvt_pk_bf16_f32 %0, %1, %2" : "=v"(r) : "v"(lo), "v"(hi)); return r; }
; __device__ __forceinline__ float fast_sigmoid(float v) { return __builtin_amdgcn_rcpf(1.0f + __builtin_amdgcn_exp2f(-1.4426950408889634f * v)); }
; __device__ __forceinline__ f32x4 ln_fix(const f32x4& a, float mu, float rs, const f32x4& cs, const f32x4& cb) { return (a - cs * mu) * rs + cb; }
; __device__ __forceinline__ float bf_lo(unsigned w) { return __uint_as_float(w << 16); }
; __device__ __forceinline__ float bf_hi(unsigned w) { return __uint_as_float(w & 0xffff0000u); }
;     __device__ __forceinline__ void operator()(const f32x4 (&acc)[2][2][4][2], const Unit& u, int wr, int wc, int fr_in, int fq_in) const {
;     ...
;                 for (int m = (am * GR) & 3; m < ((am * GR) & 3) + GR; ++m) { const size_t off = (size_t)(row0 + ai * HALF + m * 16) * 1024 + col0 + bj * HALF; const float mu = rst.mu[ai][m], rs = rst.rs[ai][m];
;                     const u32x4 pw = ppw[m]; const u32x4 zw = pzw[m];
;                     const f32x4 x0 = ((f32x4){bf_lo(zw.x), bf_hi(zw.x), bf_lo(zw.y), bf_hi(zw.y)} - mu) * rs * gv[0] + bv[0], x1 = ((f32x4){bf_lo(zw.z), bf_hi(zw.z), bf_lo(zw.w), bf_hi(zw.w)} - mu) * rs * gv[1] + bv[1];
;                     const f32x4 a0 = ln_fix(acc[ai][bj][m][0], mu, rs, csv[0], cbv[0]), a1 = ln_fix(acc[ai][bj][m][1], mu, rs, csv[1], cbv[1]); f32x4 o0, o1;
;                     o0[0] = x0[0] + fast_sigmoid(a0[0]) * bf_lo(pw.x); o0[1] = x0[1] + fast_sigmoid(a0[1]) * bf_hi(pw.x);
;                     o0[2] = x0[2] + fast_sigmoid(a0[2]) * bf_lo(pw.y); o0[3] = x0[3] + fast_sigmoid(a0[3]) * bf_hi(pw.y);
;                     o1[0] = x1[0] + fast_sigmoid(a1[0]) * bf_lo(pw.z); o1[1] = x1[1] + fast_sigmoid(a1[1]) * bf_hi(pw.z);
;                     o1[2] = x1[2] + fast_sigmoid(a1[2]) * bf_lo(pw.w); o1[3] = x1[3] + fast_sigmoid(a1[3]) * bf_hi(pw.w);
;                     if constexpr (FINAL) { *(f32x4*)(outf + off) = o0; *(f32x4*)(outf + off + 4) = o1; }
;                     else { u32x4 w; w.x = cvt_pk_bf16(o0[0], o0[1]); w.y = cvt_pk_bf16(o0[2], o0[3]); w.z = cvt_pk_bf16(o1[0], o1[1]); w.w = cvt_pk_bf16(o1[2], o1[3]); *(u32x4*)(pexb + off) = w; } } } }
	v_pk_fma_f32 v[30:31], v[196:197], v[74:75], v[30:31] op_sel_hi:[0,1,1] neg_lo:[1,0,0] neg_hi:[1,0,0]
	v_pk_fma_f32 v[30:31], v[198:199], v[30:31], v[78:79] op_sel_hi:[0,1,1]
	v_pk_fma_f32 v[24:25], v[196:197], v[64:65], v[24:25] op_sel_hi:[0,1,1] neg_lo:[1,0,0] neg_hi:[1,0,0]
	v_add_f32_e32 v29, 1.0, v29
	v_rcp_f32_e32 v29, v29
	v_pk_fma_f32 v[24:25], v[198:199], v[24:25], v[68:69] op_sel_hi:[0,1,1]
	v_mul_f32_e32 v24, 0xbfb8aa3b, v24
	v_exp_f32_e32 v24, v24
	v_pk_fma_f32 v[26:27], v[196:197], v[66:67], v[26:27] op_sel_hi:[0,1,1] neg_lo:[1,0,0] neg_hi:[1,0,0]
	v_pk_fma_f32 v[26:27], v[198:199], v[26:27], v[70:71] op_sel_hi:[0,1,1]
	v_mul_f32_e32 v28, 0xbfb8aa3b, v28
	v_add_f32_e32 v24, 1.0, v24
	v_rcp_f32_e32 v24, v24
	v_exp_f32_e32 v28, v28
	v_pk_fma_f32 v[20:21], v[192:193], v[72:73], v[20:21] op_sel_hi:[0,1,1] neg_lo:[1,0,0] neg_hi:[1,0,0]
	v_pk_fma_f32 v[20:21], v[194:195], v[20:21], v[76:77] op_sel_hi:[0,1,1]
	v_mul_f32_e32 v20, 0xbfb8aa3b, v20
	v_add_f32_e32 v28, 1.0, v28
	v_exp_f32_e32 v20, v20
	v_mul_f32_e32 v21, 0xbfb8aa3b, v21
	v_rcp_f32_e32 v28, v28
	v_exp_f32_e32 v21, v21
	v_add_f32_e32 v20, 1.0, v20
	v_rcp_f32_e32 v20, v20
	v_pk_fma_f32 v[22:23], v[192:193], v[74:75], v[22:23] op_sel_hi:[0,1,1] neg_lo:[1,0,0] neg_hi:[1,0,0]
	v_add_f32_e32 v21, 1.0, v21
	v_rcp_f32_e32 v21, v21
	v_pk_fma_f32 v[22:23], v[194:195], v[22:23], v[78:79] op_sel_hi:[0,1,1]
	v_pk_fma_f32 v[16:17], v[192:193], v[64:65], v[16:17] op_sel_hi:[0,1,1] neg_lo:[1,0,0] neg_hi:[1,0,0]
	v_pk_fma_f32 v[16:17], v[194:195], v[16:17], v[68:69] op_sel_hi:[0,1,1]
	v_mul_f32_e32 v16, 0xbfb8aa3b, v16
	v_exp_f32_e32 v16, v16
	v_pk_fma_f32 v[18:19], v[192:193], v[66:67], v[18:19] op_sel_hi:[0,1,1] neg_lo:[1,0,0] neg_hi:[1,0,0]
	s_waitcnt vmcnt(0)
	v_lshlrev_b32_e32 v100, 16, v56
	v_and_b32_e32 v56, 0xffff0000, v56
	v_add_f32_e32 v16, 1.0, v16
	v_rcp_f32_e32 v16, v16
	v_lshlrev_b32_e32 v96, 16, v60
	v_and_b32_e32 v97, 0xffff0000, v60
	v_sub_f32_e32 v97, v97, v204
	v_sub_f32_e32 v96, v96, v204
	v_pk_mul_f32 v[96:97], v[206:207], v[96:97] op_sel_hi:[0,1]
	v_pk_fma_f32 v[96:97], v[88:89], v[96:97], v[92:93]
	v_lshlrev_b32_e32 v60, 16, v61
	v_fmac_f32_e32 v97, v45, v56
	v_mul_f32_e32 v45, 0xbfb8aa3b, v46
	v_exp_f32_e32 v45, v45
	v_and_b32_e32 v61, 0xffff0000, v61
	v_sub_f32_e32 v61, v61, v204
	v_sub_f32_e32 v60, v60, v204
	v_add_f32_e32 v45, 1.0, v45
	v_rcp_f32_e32 v45, v45
	v_pk_mul_f32 v[60:61], v[206:207], v[60:61] op_sel_hi:[0,1]
	v_pk_fma_f32 v[60:61], v[90:91], v[60:61], v[94:95]
	v_lshlrev_b32_e32 v46, 16, v57
	v_fma_f32 v45, v45, v46, v60
	v_mul_f32_e32 v46, 0xbfb8aa3b, v47
	v_exp_f32_e32 v46, v46
	v_lshlrev_b32_e32 v98, 16, v62
	v_and_b32_e32 v99, 0xffff0000, v62
	v_sub_f32_e32 v99, v99, v204
	v_add_f32_e32 v46, 1.0, v46
	v_rcp_f32_e32 v46, v46
	v_sub_f32_e32 v98, v98, v204
	v_pk_mul_f32 v[98:99], v[206:207], v[98:99] op_sel_hi:[0,1]
	v_and_b32_e32 v47, 0xffff0000, v57
	v_pk_fma_f32 v[98:99], v[80:81], v[98:99], v[84:85]
	v_fmac_f32_e32 v61, v46, v47
	v_lshlrev_b32_e32 v46, 16, v58
	v_fma_f32 v46, v40, v46, v98
	v_mul_f32_e32 v40, 0xbfb8aa3b, v41
	v_exp_f32_e32 v40, v40
	v_and_b32_e32 v41, 0xffff0000, v58
	v_lshlrev_b32_e32 v62, 16, v63
	v_and_b32_e32 v63, 0xffff0000, v63
	v_add_f32_e32 v40, 1.0, v40
	v_rcp_f32_e32 v40, v40
	v_sub_f32_e32 v63, v63, v204
	v_sub_f32_e32 v62, v62, v204
	v_pk_mul_f32 v[62:63], v[206:207], v[62:63] op_sel_hi:[0,1]
	v_fmac_f32_e32 v99, v40, v41
	v_mul_f32_e32 v40, 0xbfb8aa3b, v42
	v_exp_f32_e32 v40, v40
	v_pk_fma_f32 v[62:63], v[82:83], v[62:63], v[86:87]
	v_lshlrev_b32_e32 v41, 16, v59
	v_cvt_pk_bf16_f32 v42, v46, v99
	v_add_f32_e32 v40, 1.0, v40
	v_rcp_f32_e32 v40, v40
	v_fma_f32 v44, v44, v100, v96
	v_lshlrev_b32_e32 v46, 16, v54
	v_sub_f32_e32 v46, v46, v200
	v_fma_f32 v47, v40, v41, v62
	v_mul_f32_e32 v40, 0xbfb8aa3b, v43
	v_exp_f32_e32 v40, v40
	v_and_b32_e32 v41, 0xffff0000, v59
	v_pk_fma_f32 v[18:19], v[194:195], v[18:19], v[70:71] op_sel_hi:[0,1,1]
	v_pk_fma_f32 v[12:13], v[188:189], v[72:73], v[12:13] op_sel_hi:[0,1,1] neg_lo:[1,0,0] neg_hi:[1,0,0]
	v_add_f32_e32 v40, 1.0, v40
	v_rcp_f32_e32 v40, v40
	v_pk_fma_f32 v[12:13], v[190:191], v[12:13], v[76:77] op_sel_hi:[0,1,1]
	v_mul_f32_e32 v13, 0xbfb8aa3b, v13
	v_exp_f32_e32 v13, v13
	v_fmac_f32_e32 v63, v40, v41
	v_cvt_pk_bf16_f32 v43, v47, v63
	v_cvt_pk_bf16_f32 v40, v44, v97
	v_cvt_pk_bf16_f32 v41, v45, v61
	global_store_dwordx4 v[132:133], v[40:43], off offset:256 sc1
	v_and_b32_e32 v47, 0xffff0000, v54
	v_sub_f32_e32 v47, v47, v200
	v_lshlrev_b32_e32 v42, 16, v52
	v_and_b32_e32 v43, 0xffff0000, v52
	v_sub_f32_e32 v43, v43, v200
	v_sub_f32_e32 v42, v42, v200
	v_pk_mul_f32 v[42:43], v[202:203], v[42:43] op_sel_hi:[0,1]
	v_pk_fma_f32 v[42:43], v[88:89], v[42:43], v[92:93]
	v_lshlrev_b32_e32 v52, 16, v48
	v_fma_f32 v36, v36, v52, v42
	v_and_b32_e32 v42, 0xffff0000, v48
	v_fmac_f32_e32 v43, v37, v42
	v_mul_f32_e32 v37, 0xbfb8aa3b, v38
	v_exp_f32_e32 v37, v37
	v_lshlrev_b32_e32 v40, 16, v53
	v_and_b32_e32 v41, 0xffff0000, v53
	v_sub_f32_e32 v41, v41, v200
	v_add_f32_e32 v37, 1.0, v37
	v_rcp_f32_e32 v37, v37
	v_sub_f32_e32 v40, v40, v200
	v_pk_mul_f32 v[40:41], v[202:203], v[40:41] op_sel_hi:[0,1]
	v_pk_fma_f32 v[40:41], v[90:91], v[40:41], v[94:95]
	v_lshlrev_b32_e32 v38, 16, v49
	v_fma_f32 v37, v37, v38, v40
	v_mul_f32_e32 v38, 0xbfb8aa3b, v39
	v_exp_f32_e32 v38, v38
	v_pk_mul_f32 v[46:47], v[202:203], v[46:47] op_sel_hi:[0,1]
	v_and_b32_e32 v39, 0xffff0000, v49
	v_pk_fma_f32 v[46:47], v[80:81], v[46:47], v[84:85]
	v_add_f32_e32 v38, 1.0, v38
	v_rcp_f32_e32 v38, v38
	v_lshlrev_b32_e32 v44, 16, v55
	v_and_b32_e32 v45, 0xffff0000, v55
	v_sub_f32_e32 v45, v45, v200
	v_fmac_f32_e32 v41, v38, v39
; __device__ __forceinline__ unsigned cvt_pk_bf16(float lo, float hi) { unsigned r; asm("v_cvt_pk_bf16_f32 %0, %1, %2" : "=v"(r) : "v"(lo), "v"(hi)); return r; }
; __device__ __forceinline__ float fast_sigmoid(float v) { return __builtin_amdgcn_rcpf(1.0f + __builtin_amdgcn_exp2f(-1.4426950408889634f * v)); }
; __device__ __forceinline__ f32x4 ln_fix(const f32x4& a, float mu, float rs, const f32x4& cs, const f32x4& cb) { return (a - cs * mu) * rs + cb; }
; __device__ __forceinline__ float bf_lo(unsigned w) { return __uint_as_float(w << 16); }
; __device__ __forceinline__ float bf_hi(unsigned w) { return __uint_as_float(w & 0xffff0000u); }
;     __device__ __forceinline__ void operator()(const f32x4 (&acc)[2][2][4][2], const Unit& u, int wr, int wc, int fr_in, int fq_in) const {
;     ...
;                 for (int m = (am * GR) & 3; m < ((am * GR) & 3) + GR; ++m) { const size_t off = (size_t)(row0 + ai * HALF + m * 16) * 1024 + col0 + bj * HALF; const float mu = rst.mu[ai][m], rs = rst.rs[ai][m];
;                     const u32x4 pw = ppw[m]; const u32x4 zw = pzw[m];
;                     const f32x4 x0 = ((f32x4){bf_lo(zw.x), bf_hi(zw.x), bf_lo(zw.y), bf_hi(zw.y)} - mu) * rs * gv[0] + bv[0], x1 = ((f32x4){bf_lo(zw.z), bf_hi(zw.z), bf_lo(zw.w), bf_hi(zw.w)} - mu) * rs * gv[1] + bv[1];
;                     const f32x4 a0 = ln_fix(acc[ai][bj][m][0], mu, rs, csv[0], cbv[0]), a1 = ln_fix(acc[ai][bj][m][1], mu, rs, csv[1], cbv[1]); f32x4 o0, o1;
;                     o0[0] = x0[0] + fast_sigmoid(a0[0]) * bf_lo(pw.x); o0[1] = x0[1] + fast_sigmoid(a0[1]) * bf_hi(pw.x);
;                     o0[2] = x0[2] + fast_sigmoid(a0[2]) * bf_lo(pw.y); o0[3] = x0[3] + fast_sigmoid(a0[3]) * bf_hi(pw.y);
;                     o1[0] = x1[0] + fast_sigmoid(a1[0]) * bf_lo(pw.z); o1[1] = x1[1] + fast_sigmoid(a1[1]) * bf_hi(pw.z);
;                     o1[2] = x1[2] + fast_sigmoid(a1[2]) * bf_lo(pw.w); o1[3] = x1[3] + fast_sigmoid(a1[3]) * bf_hi(pw.w);
;                     if constexpr (FINAL) { *(f32x4*)(outf + off) = o0; *(f32x4*)(outf + off + 4) = o1; }
;                     else { u32x4 w; w.x = cvt_pk_bf16(o0[0], o0[1]); w.y = cvt_pk_bf16(o0[2], o0[3]); w.z = cvt_pk_bf16(o1[0], o1[1]); w.w = cvt_pk_bf16(o1[2], o1[3]); *(u32x4*)(pexb + off) = w; } } } }
	v_lshlrev_b32_e32 v38, 16, v50
	v_fma_f32 v38, v32, v38, v46
	v_mul_f32_e32 v32, 0xbfb8aa3b, v33
	v_exp_f32_e32 v32, v32
	v_and_b32_e32 v33, 0xffff0000, v50
	v_sub_f32_e32 v44, v44, v200
	v_pk_mul_f32 v[44:45], v[202:203], v[44:45] op_sel_hi:[0,1]
	v_add_f32_e32 v32, 1.0, v32
	v_rcp_f32_e32 v32, v32
	v_pk_fma_f32 v[44:45], v[82:83], v[44:45], v[86:87]
	v_add_f32_e32 v13, 1.0, v13
	v_rcp_f32_e32 v13, v13
	v_fmac_f32_e32 v47, v32, v33
	v_mul_f32_e32 v32, 0xbfb8aa3b, v34
	v_exp_f32_e32 v32, v32
	v_lshlrev_b32_e32 v33, 16, v51
	v_cvt_pk_bf16_f32 v34, v38, v47
	v_pk_fma_f32 v[14:15], v[188:189], v[74:75], v[14:15] op_sel_hi:[0,1,1] neg_lo:[1,0,0] neg_hi:[1,0,0]
	v_add_f32_e32 v32, 1.0, v32
	v_rcp_f32_e32 v32, v32
	v_pk_fma_f32 v[14:15], v[190:191], v[14:15], v[78:79] op_sel_hi:[0,1,1]
	v_pk_fma_f32 v[8:9], v[188:189], v[64:65], v[8:9] op_sel_hi:[0,1,1] neg_lo:[1,0,0] neg_hi:[1,0,0]
	v_pk_fma_f32 v[8:9], v[190:191], v[8:9], v[68:69] op_sel_hi:[0,1,1]
	v_fma_f32 v39, v32, v33, v44
	v_mul_f32_e32 v32, 0xbfb8aa3b, v35
	v_exp_f32_e32 v32, v32
	v_and_b32_e32 v33, 0xffff0000, v51
	v_mul_f32_e32 v8, 0xbfb8aa3b, v8
	v_exp_f32_e32 v8, v8
	v_add_f32_e32 v32, 1.0, v32
	v_rcp_f32_e32 v32, v32
	v_pk_fma_f32 v[10:11], v[188:189], v[66:67], v[10:11] op_sel_hi:[0,1,1] neg_lo:[1,0,0] neg_hi:[1,0,0]
	v_add_f32_e32 v8, 1.0, v8
	v_rcp_f32_e32 v8, v8
	v_fmac_f32_e32 v45, v32, v33
	v_cvt_pk_bf16_f32 v32, v36, v43
	v_cvt_pk_bf16_f32 v33, v37, v41
	v_cvt_pk_bf16_f32 v35, v39, v45
	global_store_dwordx4 v[134:135], v[32:35], off offset:256 sc1
	global_load_dwordx4 v[40:43], v[148:149], off offset:256
	v_lshl_add_u64 v[36:37], v[110:111], 0, v[146:147]
	v_lshl_add_u64 v[32:33], v[110:111], 0, v[144:145]
	v_lshl_add_u64 v[32:33], v[32:33], 1, s[40:41]
	global_load_dwordx4 v[44:47], v[32:33], off
	v_lshl_add_u64 v[36:37], v[36:37], 1, s[40:41]
	global_load_dwordx4 v[36:39], v[36:37], off
	v_pk_fma_f32 v[10:11], v[190:191], v[10:11], v[70:71] op_sel_hi:[0,1,1]
	global_load_dwordx4 v[32:35], v[118:119], off offset:256
	v_mul_f32_e32 v12, 0xbfb8aa3b, v12
	v_exp_f32_e32 v12, v12
	v_pk_fma_f32 v[4:5], v[184:185], v[72:73], v[4:5] op_sel_hi:[0,1,1] neg_lo:[1,0,0] neg_hi:[1,0,0]
	v_pk_fma_f32 v[4:5], v[186:187], v[4:5], v[76:77] op_sel_hi:[0,1,1]
	v_mul_f32_e32 v4, 0xbfb8aa3b, v4
	v_add_f32_e32 v12, 1.0, v12
	v_exp_f32_e32 v4, v4
	v_mul_f32_e32 v5, 0xbfb8aa3b, v5
	v_rcp_f32_e32 v12, v12
	v_exp_f32_e32 v5, v5
	v_add_f32_e32 v4, 1.0, v4
	v_rcp_f32_e32 v4, v4
	v_pk_fma_f32 v[6:7], v[184:185], v[74:75], v[6:7] op_sel_hi:[0,1,1] neg_lo:[1,0,0] neg_hi:[1,0,0]
	v_add_f32_e32 v5, 1.0, v5
	v_rcp_f32_e32 v5, v5
	v_pk_fma_f32 v[6:7], v[186:187], v[6:7], v[78:79] op_sel_hi:[0,1,1]
	v_pk_fma_f32 v[0:1], v[184:185], v[64:65], v[0:1] op_sel_hi:[0,1,1] neg_lo:[1,0,0] neg_hi:[1,0,0]
	v_pk_fma_f32 v[0:1], v[186:187], v[0:1], v[68:69] op_sel_hi:[0,1,1]
	v_mul_f32_e32 v0, 0xbfb8aa3b, v0
	v_exp_f32_e32 v0, v0
	v_pk_fma_f32 v[2:3], v[184:185], v[66:67], v[2:3] op_sel_hi:[0,1,1] neg_lo:[1,0,0] neg_hi:[1,0,0]
	v_pk_fma_f32 v[2:3], v[186:187], v[2:3], v[70:71] op_sel_hi:[0,1,1]
	v_add_f32_e32 v0, 1.0, v0
	v_rcp_f32_e32 v0, v0
	s_waitcnt vmcnt(0)
	v_lshlrev_b32_e32 v52, 16, v40
	v_and_b32_e32 v40, 0xffff0000, v40
	v_lshlrev_b32_e32 v48, 16, v44
	v_and_b32_e32 v49, 0xffff0000, v44
	v_sub_f32_e32 v49, v49, v196
	v_sub_f32_e32 v48, v48, v196
	v_pk_mul_f32 v[48:49], v[198:199], v[48:49] op_sel_hi:[0,1]
	v_pk_fma_f32 v[48:49], v[88:89], v[48:49], v[92:93]
	v_lshlrev_b32_e32 v44, 16, v45
	v_fmac_f32_e32 v49, v29, v40
	v_mul_f32_e32 v29, 0xbfb8aa3b, v30
	v_exp_f32_e32 v29, v29
	v_and_b32_e32 v45, 0xffff0000, v45
	v_sub_f32_e32 v45, v45, v196
	v_sub_f32_e32 v44, v44, v196
	v_add_f32_e32 v29, 1.0, v29
	v_rcp_f32_e32 v29, v29
	v_pk_mul_f32 v[44:45], v[198:199], v[44:45] op_sel_hi:[0,1]
	v_pk_fma_f32 v[44:45], v[90:91], v[44:45], v[94:95]
	v_lshlrev_b32_e32 v30, 16, v41
	v_fma_f32 v29, v29, v30, v44
	v_mul_f32_e32 v30, 0xbfb8aa3b, v31
	v_exp_f32_e32 v30, v30
	v_lshlrev_b32_e32 v50, 16, v46
	v_and_b32_e32 v51, 0xffff0000, v46
	v_sub_f32_e32 v51, v51, v196
	v_add_f32_e32 v30, 1.0, v30
	v_rcp_f32_e32 v30, v30
	v_sub_f32_e32 v50, v50, v196
	v_pk_mul_f32 v[50:51], v[198:199], v[50:51] op_sel_hi:[0,1]
	v_and_b32_e32 v31, 0xffff0000, v41
	v_pk_fma_f32 v[50:51], v[80:81], v[50:51], v[84:85]
	v_fmac_f32_e32 v45, v30, v31
	v_lshlrev_b32_e32 v30, 16, v42
	v_fma_f32 v30, v24, v30, v50
	v_mul_f32_e32 v24, 0xbfb8aa3b, v25
	v_exp_f32_e32 v24, v24
	v_and_b32_e32 v25, 0xffff0000, v42
	v_lshlrev_b32_e32 v46, 16, v47
	v_and_b32_e32 v47, 0xffff0000, v47
	v_add_f32_e32 v24, 1.0, v24
	v_rcp_f32_e32 v24, v24
	v_sub_f32_e32 v47, v47, v196
	v_sub_f32_e32 v46, v46, v196
	v_pk_mul_f32 v[46:47], v[198:199], v[46:47] op_sel_hi:[0,1]
	v_fmac_f32_e32 v51, v24, v25
	v_mul_f32_e32 v24, 0xbfb8aa3b, v26
	v_exp_f32_e32 v24, v24
	v_pk_fma_f32 v[46:47], v[82:83], v[46:47], v[86:87]
	v_lshlrev_b32_e32 v25, 16, v43
	v_cvt_pk_bf16_f32 v26, v30, v51
	v_add_f32_e32 v24, 1.0, v24
	v_rcp_f32_e32 v24, v24
	v_fma_f32 v28, v28, v52, v48
	v_lshlrev_b32_e32 v30, 16, v38
	v_sub_f32_e32 v30, v30, v192
	v_fma_f32 v31, v24, v25, v46
	v_mul_f32_e32 v24, 0xbfb8aa3b, v27
	v_exp_f32_e32 v24, v24
	v_and_b32_e32 v25, 0xffff0000, v43
	v_add_f32_e32 v24, 1.0, v24
	v_rcp_f32_e32 v24, v24
	s_nop 0
	v_fmac_f32_e32 v47, v24, v25
	v_cvt_pk_bf16_f32 v27, v31, v47
	v_cvt_pk_bf16_f32 v24, v28, v49
	v_cvt_pk_bf16_f32 v25, v29, v45
	global_store_dwordx4 v[148:149], v[24:27], off offset:256 sc1
	v_and_b32_e32 v31, 0xffff0000, v38
	v_sub_f32_e32 v31, v31, v192
	v_lshlrev_b32_e32 v26, 16, v36
	v_and_b32_e32 v27, 0xffff0000, v36
	v_sub_f32_e32 v27, v27, v192
	v_sub_f32_e32 v26, v26, v192
; __device__ __forceinline__ unsigned cvt_pk_bf16(float lo, float hi) { unsigned r; asm("v_cvt_pk_bf16_f32 %0, %1, %2" : "=v"(r) : "v"(lo), "v"(hi)); return r; }
; __device__ __forceinline__ float fast_sigmoid(float v) { return __builtin_amdgcn_rcpf(1.0f + __builtin_amdgcn_exp2f(-1.4426950408889634f * v)); }
; __device__ __forceinline__ f32x4 ln_fix(const f32x4& a, float mu, float rs, const f32x4& cs, const f32x4& cb) { return (a - cs * mu) * rs + cb; }
; __device__ __forceinline__ float bf_lo(unsigned w) { return __uint_as_float(w << 16); }
; __device__ __forceinline__ float bf_hi(unsigned w) { return __uint_as_float(w & 0xffff0000u); }
;     __device__ __forceinline__ void operator()(const f32x4 (&acc)[2][2][4][2], const Unit& u, int wr, int wc, int fr_in, int fq_in) const {
;     ...
;                 for (int m = (am * GR) & 3; m < ((am * GR) & 3) + GR; ++m) { const size_t off = (size_t)(row0 + ai * HALF + m * 16) * 1024 + col0 + bj * HALF; const float mu = rst.mu[ai][m], rs = rst.rs[ai][m];
;                     const u32x4 pw = ppw[m]; const u32x4 zw = pzw[m];
;                     const f32x4 x0 = ((f32x4){bf_lo(zw.x), bf_hi(zw.x), bf_lo(zw.y), bf_hi(zw.y)} - mu) * rs * gv[0] + bv[0], x1 = ((f32x4){bf_lo(zw.z), bf_hi(zw.z), bf_lo(zw.w), bf_hi(zw.w)} - mu) * rs * gv[1] + bv[1];
;                     const f32x4 a0 = ln_fix(acc[ai][bj][m][0], mu, rs, csv[0], cbv[0]), a1 = ln_fix(acc[ai][bj][m][1], mu, rs, csv[1], cbv[1]); f32x4 o0, o1;
;                     o0[0] = x0[0] + fast_sigmoid(a0[0]) * bf_lo(pw.x); o0[1] = x0[1] + fast_sigmoid(a0[1]) * bf_hi(pw.x);
;                     o0[2] = x0[2] + fast_sigmoid(a0[2]) * bf_lo(pw.y); o0[3] = x0[3] + fast_sigmoid(a0[3]) * bf_hi(pw.y);
;                     o1[0] = x1[0] + fast_sigmoid(a1[0]) * bf_lo(pw.z); o1[1] = x1[1] + fast_sigmoid(a1[1]) * bf_hi(pw.z);
;                     o1[2] = x1[2] + fast_sigmoid(a1[2]) * bf_lo(pw.w); o1[3] = x1[3] + fast_sigmoid(a1[3]) * bf_hi(pw.w);
;                     if constexpr (FINAL) { *(f32x4*)(outf + off) = o0; *(f32x4*)(outf + off + 4) = o1; }
;                     else { u32x4 w; w.x = cvt_pk_bf16(o0[0], o0[1]); w.y = cvt_pk_bf16(o0[2], o0[3]); w.z = cvt_pk_bf16(o1[0], o1[1]); w.w = cvt_pk_bf16(o1[2], o1[3]); *(u32x4*)(pexb + off) = w; } } } }
	v_pk_mul_f32 v[26:27], v[194:195], v[26:27] op_sel_hi:[0,1]
	v_pk_fma_f32 v[26:27], v[88:89], v[26:27], v[92:93]
	v_lshlrev_b32_e32 v36, 16, v32
	v_fma_f32 v20, v20, v36, v26
	v_and_b32_e32 v26, 0xffff0000, v32
	v_fmac_f32_e32 v27, v21, v26
	v_mul_f32_e32 v21, 0xbfb8aa3b, v22
	v_exp_f32_e32 v21, v21
	v_lshlrev_b32_e32 v24, 16, v37
	v_and_b32_e32 v25, 0xffff0000, v37
	v_sub_f32_e32 v25, v25, v192
	v_add_f32_e32 v21, 1.0, v21
	v_rcp_f32_e32 v21, v21
	v_sub_f32_e32 v24, v24, v192
	v_pk_mul_f32 v[24:25], v[194:195], v[24:25] op_sel_hi:[0,1]
	v_pk_fma_f32 v[24:25], v[90:91], v[24:25], v[94:95]
	v_lshlrev_b32_e32 v22, 16, v33
	v_fma_f32 v21, v21, v22, v24
	v_mul_f32_e32 v22, 0xbfb8aa3b, v23
	v_exp_f32_e32 v22, v22
	v_pk_mul_f32 v[30:31], v[194:195], v[30:31] op_sel_hi:[0,1]
	v_and_b32_e32 v23, 0xffff0000, v33
	v_pk_fma_f32 v[30:31], v[80:81], v[30:31], v[84:85]
	v_add_f32_e32 v22, 1.0, v22
	v_rcp_f32_e32 v22, v22
	v_lshlrev_b32_e32 v28, 16, v39
	v_and_b32_e32 v29, 0xffff0000, v39
	v_sub_f32_e32 v29, v29, v192
	v_fmac_f32_e32 v25, v22, v23
	v_lshlrev_b32_e32 v22, 16, v34
	v_fma_f32 v22, v16, v22, v30
	v_mul_f32_e32 v16, 0xbfb8aa3b, v17
	v_exp_f32_e32 v16, v16
	v_and_b32_e32 v17, 0xffff0000, v34
	v_sub_f32_e32 v28, v28, v192
	v_pk_mul_f32 v[28:29], v[194:195], v[28:29] op_sel_hi:[0,1]
	v_add_f32_e32 v16, 1.0, v16
	v_rcp_f32_e32 v16, v16
	v_pk_fma_f32 v[28:29], v[82:83], v[28:29], v[86:87]
	v_fmac_f32_e32 v31, v16, v17
	v_mul_f32_e32 v16, 0xbfb8aa3b, v18
	v_exp_f32_e32 v16, v16
	v_lshlrev_b32_e32 v17, 16, v35
	v_cvt_pk_bf16_f32 v18, v22, v31
	v_add_f32_e32 v16, 1.0, v16
	v_rcp_f32_e32 v16, v16
	s_nop 0
	v_fma_f32 v23, v16, v17, v28
	v_mul_f32_e32 v16, 0xbfb8aa3b, v19
	v_exp_f32_e32 v16, v16
	v_and_b32_e32 v17, 0xffff0000, v35
	v_add_f32_e32 v16, 1.0, v16
	v_rcp_f32_e32 v16, v16
	s_nop 0
	v_fmac_f32_e32 v29, v16, v17
	v_cvt_pk_bf16_f32 v16, v20, v27
	v_cvt_pk_bf16_f32 v17, v21, v25
	v_cvt_pk_bf16_f32 v19, v23, v29
	global_store_dwordx4 v[118:119], v[16:19], off offset:256 sc1
	global_load_dwordx4 v[24:27], v[150:151], off offset:256
	v_lshl_add_u64 v[20:21], v[110:111], 0, v[130:131]
	v_lshl_add_u64 v[16:17], v[110:111], 0, v[128:129]
	v_lshl_add_u64 v[16:17], v[16:17], 1, s[40:41]
	global_load_dwordx4 v[28:31], v[16:17], off
	v_lshl_add_u64 v[20:21], v[20:21], 1, s[40:41]
	global_load_dwordx4 v[20:23], v[20:21], off
	s_waitcnt vmcnt(0)
	v_lshlrev_b32_e32 v32, 16, v28
	global_load_dwordx4 v[16:19], v[108:109], off offset:256
	v_and_b32_e32 v33, 0xffff0000, v28
	v_sub_f32_e32 v33, v33, v188
	v_sub_f32_e32 v32, v32, v188
	v_pk_mul_f32 v[32:33], v[190:191], v[32:33] op_sel_hi:[0,1]
	v_pk_fma_f32 v[32:33], v[88:89], v[32:33], v[92:93]
	v_lshlrev_b32_e32 v36, 16, v24
	v_and_b32_e32 v24, 0xffff0000, v24
	v_fmac_f32_e32 v33, v13, v24
	v_mul_f32_e32 v13, 0xbfb8aa3b, v14
	v_exp_f32_e32 v13, v13
	v_lshlrev_b32_e32 v28, 16, v29
	v_and_b32_e32 v29, 0xffff0000, v29
	v_sub_f32_e32 v29, v29, v188
	v_add_f32_e32 v13, 1.0, v13
	v_rcp_f32_e32 v13, v13
	v_sub_f32_e32 v28, v28, v188
	v_pk_mul_f32 v[28:29], v[190:191], v[28:29] op_sel_hi:[0,1]
	v_pk_fma_f32 v[28:29], v[90:91], v[28:29], v[94:95]
	v_lshlrev_b32_e32 v14, 16, v25
	v_fma_f32 v13, v13, v14, v28
	v_mul_f32_e32 v14, 0xbfb8aa3b, v15
	v_exp_f32_e32 v14, v14
	v_lshlrev_b32_e32 v34, 16, v30
	v_and_b32_e32 v35, 0xffff0000, v30
	v_sub_f32_e32 v35, v35, v188
	v_add_f32_e32 v14, 1.0, v14
	v_rcp_f32_e32 v14, v14
	v_sub_f32_e32 v34, v34, v188
	v_pk_mul_f32 v[34:35], v[190:191], v[34:35] op_sel_hi:[0,1]
	v_and_b32_e32 v15, 0xffff0000, v25
	v_pk_fma_f32 v[34:35], v[80:81], v[34:35], v[84:85]
	v_fmac_f32_e32 v29, v14, v15
	v_lshlrev_b32_e32 v14, 16, v26
	v_fma_f32 v14, v8, v14, v34
	v_mul_f32_e32 v8, 0xbfb8aa3b, v9
	v_exp_f32_e32 v8, v8
	v_and_b32_e32 v9, 0xffff0000, v26
	v_lshlrev_b32_e32 v30, 16, v31
	v_and_b32_e32 v31, 0xffff0000, v31
	v_add_f32_e32 v8, 1.0, v8
	v_rcp_f32_e32 v8, v8
	v_sub_f32_e32 v31, v31, v188
	v_sub_f32_e32 v30, v30, v188
	v_pk_mul_f32 v[30:31], v[190:191], v[30:31] op_sel_hi:[0,1]
	v_fmac_f32_e32 v35, v8, v9
	v_mul_f32_e32 v8, 0xbfb8aa3b, v10
	v_exp_f32_e32 v8, v8
	v_pk_fma_f32 v[30:31], v[82:83], v[30:31], v[86:87]
	v_lshlrev_b32_e32 v9, 16, v27
	v_cvt_pk_bf16_f32 v10, v14, v35
	v_add_f32_e32 v8, 1.0, v8
	v_rcp_f32_e32 v8, v8
	v_fma_f32 v12, v12, v36, v32
	v_lshlrev_b32_e32 v14, 16, v22
	v_fma_f32 v15, v8, v9, v30
	v_mul_f32_e32 v8, 0xbfb8aa3b, v11
	v_exp_f32_e32 v8, v8
	v_and_b32_e32 v9, 0xffff0000, v27
	v_sub_f32_e32 v14, v14, v184
	v_add_f32_e32 v8, 1.0, v8
	v_rcp_f32_e32 v8, v8
	s_nop 0
	v_fmac_f32_e32 v31, v8, v9
	v_cvt_pk_bf16_f32 v11, v15, v31
	v_cvt_pk_bf16_f32 v8, v12, v33
	v_cvt_pk_bf16_f32 v9, v13, v29
	global_store_dwordx4 v[150:151], v[8:11], off offset:256 sc1
	v_and_b32_e32 v15, 0xffff0000, v22
	v_sub_f32_e32 v15, v15, v184
	v_lshlrev_b32_e32 v10, 16, v20
	v_and_b32_e32 v11, 0xffff0000, v20
	v_sub_f32_e32 v11, v11, v184
	v_sub_f32_e32 v10, v10, v184
	v_pk_mul_f32 v[10:11], v[186:187], v[10:11] op_sel_hi:[0,1]
	v_pk_fma_f32 v[10:11], v[88:89], v[10:11], v[92:93]
	s_waitcnt vmcnt(0)
	v_lshlrev_b32_e32 v20, 16, v16
	v_fma_f32 v4, v4, v20, v10
	v_and_b32_e32 v10, 0xffff0000, v16
	v_fmac_f32_e32 v11, v5, v10
	v_mul_f32_e32 v5, 0xbfb8aa3b, v6
	v_exp_f32_e32 v5, v5
	v_lshlrev_b32_e32 v8, 16, v21
	v_and_b32_e32 v9, 0xffff0000, v21
	v_sub_f32_e32 v9, v9, v184
	v_add_f32_e32 v5, 1.0, v5
	v_rcp_f32_e32 v5, v5
	v_sub_f32_e32 v8, v8, v184
	v_pk_mul_f32 v[8:9], v[186:187], v[8:9] op_sel_hi:[0,1]
	v_pk_fma_f32 v[8:9], v[90:91], v[8:9], v[94:95]
	v_lshlrev_b32_e32 v6, 16, v17
	v_fma_f32 v5, v5, v6, v8
	v_mul_f32_e32 v6, 0xbfb8aa3b, v7
	v_exp_f32_e32 v6, v6
	v_pk_mul_f32 v[14:15], v[186:187], v[14:15] op_sel_hi:[0,1]
	v_and_b32_e32 v7, 0xffff0000, v17
	v_pk_fma_f32 v[14:15], v[80:81], v[14:15], v[84:85]
	v_add_f32_e32 v6, 1.0, v6
	v_rcp_f32_e32 v6, v6
	v_lshlrev_b32_e32 v12, 16, v23
	v_and_b32_e32 v13, 0xffff0000, v23
	v_sub_f32_e32 v13, v13, v184
	v_fmac_f32_e32 v9, v6, v7
	v_lshlrev_b32_e32 v6, 16, v18
	v_fma_f32 v6, v0, v6, v14
	v_mul_f32_e32 v0, 0xbfb8aa3b, v1
	v_exp_f32_e32 v0, v0
	v_and_b32_e32 v1, 0xffff0000, v18
	v_sub_f32_e32 v12, v12, v184
	v_pk_mul_f32 v[12:13], v[186:187], v[12:13] op_sel_hi:[0,1]
	v_add_f32_e32 v0, 1.0, v0
	v_rcp_f32_e32 v0, v0
	v_pk_fma_f32 v[12:13], v[82:83], v[12:13], v[86:87]
	v_fmac_f32_e32 v15, v0, v1
	v_mul_f32_e32 v0, 0xbfb8aa3b, v2
	v_exp_f32_e32 v0, v0
	v_lshlrev_b32_e32 v1, 16, v19
	v_cvt_pk_bf16_f32 v2, v6, v15
	v_add_f32_e32 v0, 1.0, v0
	v_rcp_f32_e32 v0, v0
	s_nop 0
	v_fma_f32 v7, v0, v1, v12
	v_mul_f32_e32 v0, 0xbfb8aa3b, v3
	v_exp_f32_e32 v0, v0
	v_and_b32_e32 v1, 0xffff0000, v19
	v_add_f32_e32 v0, 1.0, v0
	v_rcp_f32_e32 v0, v0
	s_nop 0
	v_fmac_f32_e32 v13, v0, v1
	v_cvt_pk_bf16_f32 v0, v4, v11
	v_cvt_pk_bf16_f32 v1, v5, v9
	v_cvt_pk_bf16_f32 v3, v7, v13
	global_store_dwordx4 v[108:109], v[0:3], off offset:256 sc1
	s_cbranch_vccnz .LBB0_1446
	s_andn2_b64 vcc, exec, s[42:43]
	s_cbranch_vccnz .LBB0_1445
	s_barrier
	s_branch .LBB0_1445

; __device__ __forceinline__ unsigned cvt_pk_bf16(float lo, float hi) { unsigned r; asm("v_cvt_pk_bf16_f32 %0, %1, %2" : "=v"(r) : "v"(lo), "v"(hi)); return r; }
; __device__ __forceinline__ float fast_sigmoid(float v) { return __builtin_amdgcn_rcpf(1.0f + __builtin_amdgcn_exp2f(-1.4426950408889634f * v)); }
; __device__ __forceinline__ f32x4 ln_fix(const f32x4& a, float mu, float rs, const f32x4& cs, const f32x4& cb) { return (a - cs * mu) * rs + cb; }
;     __device__ __forceinline__ void operator()(const f32x4 (&acc)[2][2][4][2], const Unit& u, int wr, int wc, int fr_in, int fq_in) const {
;     ...
;             for (int m = 0; m < 4; ++m) { bf16_t* rowp = H + ((size_t)kt * mrows + (row0 + ai * HALF + m * 16)) * 64 + cin;
;                 float h[8];
; #pragma unroll
;                 for (int n = 0; n < 2; ++n) { f32x4 g = acc[ai][0][m][n], uu = acc[ai][1][m][n];
;                     if constexpr (LN) { g = ln_fix(g, rst.mu[ai][m], rst.rs[ai][m], csv[0][n], cbv[0][n]); uu = ln_fix(uu, rst.mu[ai][m], rst.rs[ai][m], csv[1][n], cbv[1][n]); }
; #pragma unroll
;                     for (int j = 0; j < 4; ++j) h[4 * n + j] = g[j] * fast_sigmoid(g[j]) * uu[j]; }
;                 u32x4 w; w.x = cvt_pk_bf16(h[0], h[1]); w.y = cvt_pk_bf16(h[2], h[3]); w.z = cvt_pk_bf16(h[4], h[5]); w.w = cvt_pk_bf16(h[6], h[7]);
;                 *(u32x4*)rowp = w; }
.LBB0_1526:
	v_mov_b32_e32 v144, v146
	v_mov_b32_e32 v145, v147
	s_lshl_b32 s23, s30, 8
	s_lshl_b32 s25, s31, 1
	s_or_b32 s30, s25, s51
	s_add_i32 s23, s23, s47
	s_ashr_i32 s31, s30, 31
	v_add_u32_e32 v144, s23, v144
	v_lshl_add_u32 v152, v145, 3, s52
	s_lshl_b64 s[30:31], s[30:31], 15
	v_ashrrev_i32_e32 v145, 31, v144
	v_lshl_add_u64 v[154:155], s[30:31], 0, v[144:145]
	v_mul_f32_e32 v145, 0xbfb8aa3b, v120
	v_exp_f32_e32 v145, v145
	v_ashrrev_i32_e32 v153, 31, v152
	v_lshlrev_b64 v[154:155], 7, v[154:155]
	v_lshl_add_u64 v[154:155], s[6:7], 0, v[154:155]
	v_add_f32_e32 v145, 1.0, v145
	v_rcp_f32_e32 v145, v145
	s_andn2_b64 vcc, exec, s[40:41]
	v_mul_f32_e32 v120, v120, v145
	v_mul_f32_e32 v120, v124, v120
	v_mul_f32_e32 v124, 0xbfb8aa3b, v121
	v_exp_f32_e32 v124, v124
	s_nop 0
	v_add_f32_e32 v124, 1.0, v124
	v_rcp_f32_e32 v124, v124
	s_nop 0
	v_mul_f32_e32 v121, v121, v124
	v_mul_f32_e32 v124, 0xbfb8aa3b, v122
	v_exp_f32_e32 v124, v124
	v_mul_f32_e32 v121, v125, v121
	v_add_f32_e32 v124, 1.0, v124
	v_rcp_f32_e32 v124, v124
	s_nop 0
	v_mul_f32_e32 v122, v122, v124
	v_mul_f32_e32 v124, 0xbfb8aa3b, v123
	v_exp_f32_e32 v124, v124
	v_mul_f32_e32 v122, v126, v122
	v_add_f32_e32 v124, 1.0, v124
	v_rcp_f32_e32 v124, v124
	s_nop 0
	v_mul_f32_e32 v123, v123, v124
	v_mul_f32_e32 v124, 0xbfb8aa3b, v116
	v_exp_f32_e32 v124, v124
	v_mul_f32_e32 v123, v127, v123
	v_add_f32_e32 v124, 1.0, v124
	v_rcp_f32_e32 v124, v124
	s_nop 0
	v_mul_f32_e32 v116, v116, v124
	v_mul_f32_e32 v116, v112, v116
	v_mul_f32_e32 v112, 0xbfb8aa3b, v117
	v_exp_f32_e32 v112, v112
	s_nop 0
	v_add_f32_e32 v112, 1.0, v112
	v_rcp_f32_e32 v112, v112
	s_nop 0
	v_mul_f32_e32 v112, v117, v112
	v_mul_f32_e32 v117, v113, v112
	v_mul_f32_e32 v112, 0xbfb8aa3b, v118
	v_exp_f32_e32 v112, v112
	v_cvt_pk_bf16_f32 v116, v116, v117
	s_nop 0
	v_add_f32_e32 v112, 1.0, v112
	v_rcp_f32_e32 v112, v112
	s_nop 0
	v_mul_f32_e32 v112, v118, v112
	v_mul_f32_e32 v124, v114, v112
	v_mul_f32_e32 v112, 0xbfb8aa3b, v119
	v_exp_f32_e32 v112, v112
	v_cvt_pk_bf16_f32 v114, v120, v121
	s_nop 0
	v_add_f32_e32 v112, 1.0, v112
	v_rcp_f32_e32 v112, v112
	s_nop 0
	v_mul_f32_e32 v112, v119, v112
	v_mul_f32_e32 v125, v115, v112
	v_lshlrev_b64 v[112:113], 1, v[152:153]
	v_lshl_add_u64 v[118:119], v[154:155], 0, v[112:113]
	v_cvt_pk_bf16_f32 v115, v122, v123
	v_cvt_pk_bf16_f32 v117, v124, v125
	global_store_dwordx4 v[118:119], v[114:117], off sc1
	s_nop 1
	v_mul_f32_e32 v116, 0xbfb8aa3b, v108
	v_exp_f32_e32 v116, v116
	v_add_u32_e32 v114, 16, v144
	v_ashrrev_i32_e32 v115, 31, v114
	v_lshl_add_u64 v[114:115], s[30:31], 0, v[114:115]
	v_add_f32_e32 v116, 1.0, v116
	v_rcp_f32_e32 v116, v116
	v_lshlrev_b64 v[114:115], 7, v[114:115]
	v_lshl_add_u64 v[114:115], s[6:7], 0, v[114:115]
	v_mul_f32_e32 v108, v108, v116
	v_mul_f32_e32 v104, v104, v108
	v_mul_f32_e32 v108, 0xbfb8aa3b, v109
	v_exp_f32_e32 v108, v108
	s_nop 0
	v_add_f32_e32 v108, 1.0, v108
	v_rcp_f32_e32 v108, v108
	s_nop 0
	v_mul_f32_e32 v108, v109, v108
	v_mul_f32_e32 v105, v105, v108
	v_mul_f32_e32 v108, 0xbfb8aa3b, v110
	v_exp_f32_e32 v108, v108
	s_nop 0
	v_add_f32_e32 v108, 1.0, v108
	v_rcp_f32_e32 v108, v108
	s_nop 0
	v_mul_f32_e32 v108, v110, v108
	v_mul_f32_e32 v106, v106, v108
	v_mul_f32_e32 v108, 0xbfb8aa3b, v111
	v_exp_f32_e32 v108, v108
	s_nop 0
	v_add_f32_e32 v108, 1.0, v108
	v_rcp_f32_e32 v108, v108
	s_nop 0
	v_mul_f32_e32 v108, v111, v108
	v_mul_f32_e32 v107, v107, v108
	v_mul_f32_e32 v108, 0xbfb8aa3b, v100
	v_exp_f32_e32 v108, v108
	s_nop 0
	v_add_f32_e32 v108, 1.0, v108
	v_rcp_f32_e32 v108, v108
	s_nop 0
	v_mul_f32_e32 v100, v100, v108
	v_mul_f32_e32 v108, v96, v100
	v_mul_f32_e32 v96, 0xbfb8aa3b, v101
	v_exp_f32_e32 v96, v96
	s_nop 0
	v_add_f32_e32 v96, 1.0, v96
	v_rcp_f32_e32 v96, v96
	s_nop 0
	v_mul_f32_e32 v96, v101, v96
	v_mul_f32_e32 v109, v97, v96
	v_mul_f32_e32 v96, 0xbfb8aa3b, v102
	v_exp_f32_e32 v96, v96
	v_lshl_add_u64 v[100:101], v[114:115], 0, v[112:113]
	v_cvt_pk_bf16_f32 v97, v106, v107
	v_add_f32_e32 v96, 1.0, v96
	v_rcp_f32_e32 v96, v96
	s_nop 0
	v_mul_f32_e32 v96, v102, v96
	v_mul_f32_e32 v102, v98, v96
	v_mul_f32_e32 v96, 0xbfb8aa3b, v103
	v_exp_f32_e32 v96, v96
	v_cvt_pk_bf16_f32 v98, v108, v109
	s_nop 0
	v_add_f32_e32 v96, 1.0, v96
	v_rcp_f32_e32 v96, v96
	s_nop 0
	v_mul_f32_e32 v96, v103, v96
	v_mul_f32_e32 v99, v99, v96
	v_cvt_pk_bf16_f32 v96, v104, v105
	v_cvt_pk_bf16_f32 v99, v102, v99
	global_store_dwordx4 v[100:101], v[96:99], off sc1
	s_nop 1
	v_mul_f32_e32 v98, 0xbfb8aa3b, v92
	v_exp_f32_e32 v98, v98
	v_add_u32_e32 v96, 32, v144
	v_ashrrev_i32_e32 v97, 31, v96
	v_lshl_add_u64 v[96:97], s[30:31], 0, v[96:97]
	v_add_f32_e32 v98, 1.0, v98
	v_rcp_f32_e32 v98, v98
	v_lshlrev_b64 v[96:97], 7, v[96:97]
	v_lshl_add_u64 v[96:97], s[6:7], 0, v[96:97]
	v_mul_f32_e32 v92, v92, v98
	v_mul_f32_e32 v88, v88, v92
	v_mul_f32_e32 v92, 0xbfb8aa3b, v93
	v_exp_f32_e32 v92, v92
	s_nop 0
	v_add_f32_e32 v92, 1.0, v92
	v_rcp_f32_e32 v92, v92
	s_nop 0
	v_mul_f32_e32 v92, v93, v92
	v_mul_f32_e32 v89, v89, v92
	v_mul_f32_e32 v92, 0xbfb8aa3b, v94
	v_exp_f32_e32 v92, v92
	s_nop 0
	v_add_f32_e32 v92, 1.0, v92
	v_rcp_f32_e32 v92, v92
	s_nop 0
	v_mul_f32_e32 v92, v94, v92
	v_mul_f32_e32 v90, v90, v92
	v_mul_f32_e32 v92, 0xbfb8aa3b, v95
	v_exp_f32_e32 v92, v92
	s_nop 0
	v_add_f32_e32 v92, 1.0, v92
	v_rcp_f32_e32 v92, v92
	s_nop 0
	v_mul_f32_e32 v92, v95, v92
	v_mul_f32_e32 v91, v91, v92
	v_mul_f32_e32 v92, 0xbfb8aa3b, v84
	v_exp_f32_e32 v92, v92
	s_nop 0
	v_add_f32_e32 v92, 1.0, v92
	v_rcp_f32_e32 v92, v92
	s_nop 0
	v_mul_f32_e32 v84, v84, v92
	v_mul_f32_e32 v92, v80, v84
	v_mul_f32_e32 v80, 0xbfb8aa3b, v85
	v_exp_f32_e32 v80, v80
	s_nop 0
	v_add_f32_e32 v80, 1.0, v80
; __device__ __forceinline__ unsigned cvt_pk_bf16(float lo, float hi) { unsigned r; asm("v_cvt_pk_bf16_f32 %0, %1, %2" : "=v"(r) : "v"(lo), "v"(hi)); return r; }
; __device__ __forceinline__ float fast_sigmoid(float v) { return __builtin_amdgcn_rcpf(1.0f + __builtin_amdgcn_exp2f(-1.4426950408889634f * v)); }
; __device__ __forceinline__ f32x4 ln_fix(const f32x4& a, float mu, float rs, const f32x4& cs, const f32x4& cb) { return (a - cs * mu) * rs + cb; }
;     __device__ __forceinline__ void operator()(const f32x4 (&acc)[2][2][4][2], const Unit& u, int wr, int wc, int fr_in, int fq_in) const {
;     ...
;             for (int m = 0; m < 4; ++m) { bf16_t* rowp = H + ((size_t)kt * mrows + (row0 + ai * HALF + m * 16)) * 64 + cin;
;                 float h[8];
; #pragma unroll
;                 for (int n = 0; n < 2; ++n) { f32x4 g = acc[ai][0][m][n], uu = acc[ai][1][m][n];
;                     if constexpr (LN) { g = ln_fix(g, rst.mu[ai][m], rst.rs[ai][m], csv[0][n], cbv[0][n]); uu = ln_fix(uu, rst.mu[ai][m], rst.rs[ai][m], csv[1][n], cbv[1][n]); }
; #pragma unroll
;                     for (int j = 0; j < 4; ++j) h[4 * n + j] = g[j] * fast_sigmoid(g[j]) * uu[j]; }
;                 u32x4 w; w.x = cvt_pk_bf16(h[0], h[1]); w.y = cvt_pk_bf16(h[2], h[3]); w.z = cvt_pk_bf16(h[4], h[5]); w.w = cvt_pk_bf16(h[6], h[7]);
;                 *(u32x4*)rowp = w; }
	v_rcp_f32_e32 v80, v80
	s_nop 0
	v_mul_f32_e32 v80, v85, v80
	v_mul_f32_e32 v93, v81, v80
	v_mul_f32_e32 v80, 0xbfb8aa3b, v86
	v_exp_f32_e32 v80, v80
	v_lshl_add_u64 v[84:85], v[96:97], 0, v[112:113]
	v_cvt_pk_bf16_f32 v81, v90, v91
	v_add_f32_e32 v80, 1.0, v80
	v_rcp_f32_e32 v80, v80
	s_nop 0
	v_mul_f32_e32 v80, v86, v80
	v_mul_f32_e32 v86, v82, v80
	v_mul_f32_e32 v80, 0xbfb8aa3b, v87
	v_exp_f32_e32 v80, v80
	v_cvt_pk_bf16_f32 v82, v92, v93
	s_nop 0
	v_add_f32_e32 v80, 1.0, v80
	v_rcp_f32_e32 v80, v80
	s_nop 0
	v_mul_f32_e32 v80, v87, v80
	v_mul_f32_e32 v83, v83, v80
	v_cvt_pk_bf16_f32 v80, v88, v89
	v_cvt_pk_bf16_f32 v83, v86, v83
	global_store_dwordx4 v[84:85], v[80:83], off sc1
	s_nop 1
	v_mul_f32_e32 v82, 0xbfb8aa3b, v76
	v_exp_f32_e32 v82, v82
	v_add_u32_e32 v80, 48, v144
	v_ashrrev_i32_e32 v81, 31, v80
	v_lshl_add_u64 v[80:81], s[30:31], 0, v[80:81]
	v_add_f32_e32 v82, 1.0, v82
	v_rcp_f32_e32 v82, v82
	v_lshlrev_b64 v[80:81], 7, v[80:81]
	v_lshl_add_u64 v[80:81], s[6:7], 0, v[80:81]
	v_mul_f32_e32 v76, v76, v82
	v_mul_f32_e32 v72, v72, v76
	v_mul_f32_e32 v76, 0xbfb8aa3b, v77
	v_exp_f32_e32 v76, v76
	s_nop 0
	v_add_f32_e32 v76, 1.0, v76
	v_rcp_f32_e32 v76, v76
	s_nop 0
	v_mul_f32_e32 v76, v77, v76
	v_mul_f32_e32 v73, v73, v76
	v_mul_f32_e32 v76, 0xbfb8aa3b, v78
	v_exp_f32_e32 v76, v76
	s_nop 0
	v_add_f32_e32 v76, 1.0, v76
	v_rcp_f32_e32 v76, v76
	s_nop 0
	v_mul_f32_e32 v76, v78, v76
	v_mul_f32_e32 v74, v74, v76
	v_mul_f32_e32 v76, 0xbfb8aa3b, v79
	v_exp_f32_e32 v76, v76
	s_nop 0
	v_add_f32_e32 v76, 1.0, v76
	v_rcp_f32_e32 v76, v76
	s_nop 0
	v_mul_f32_e32 v76, v79, v76
	v_mul_f32_e32 v75, v75, v76
	v_mul_f32_e32 v76, 0xbfb8aa3b, v68
	v_exp_f32_e32 v76, v76
	s_nop 0
	v_add_f32_e32 v76, 1.0, v76
	v_rcp_f32_e32 v76, v76
	s_nop 0
	v_mul_f32_e32 v68, v68, v76
	v_mul_f32_e32 v76, v64, v68
	v_mul_f32_e32 v64, 0xbfb8aa3b, v69
	v_exp_f32_e32 v64, v64
	s_nop 0
	v_add_f32_e32 v64, 1.0, v64
	v_rcp_f32_e32 v64, v64
	s_nop 0
	v_mul_f32_e32 v64, v69, v64
	v_mul_f32_e32 v77, v65, v64
	v_mul_f32_e32 v64, 0xbfb8aa3b, v70
	v_exp_f32_e32 v64, v64
	v_lshl_add_u64 v[68:69], v[80:81], 0, v[112:113]
	v_cvt_pk_bf16_f32 v65, v74, v75
	v_add_f32_e32 v64, 1.0, v64
	v_rcp_f32_e32 v64, v64
	s_nop 0
	v_mul_f32_e32 v64, v70, v64
	v_mul_f32_e32 v70, v66, v64
	v_mul_f32_e32 v64, 0xbfb8aa3b, v71
	v_exp_f32_e32 v64, v64
	v_cvt_pk_bf16_f32 v66, v76, v77
	s_nop 0
	v_add_f32_e32 v64, 1.0, v64
	v_rcp_f32_e32 v64, v64
	s_nop 0
	v_mul_f32_e32 v64, v71, v64
	v_mul_f32_e32 v67, v67, v64
	v_cvt_pk_bf16_f32 v64, v72, v73
	v_cvt_pk_bf16_f32 v67, v70, v67
	global_store_dwordx4 v[68:69], v[64:67], off sc1
	s_nop 1
	v_mul_f32_e32 v66, 0xbfb8aa3b, v60
	v_exp_f32_e32 v66, v66
	v_add_u32_e32 v64, 0x80, v144
	v_ashrrev_i32_e32 v65, 31, v64
	v_lshl_add_u64 v[64:65], s[30:31], 0, v[64:65]
	v_add_f32_e32 v66, 1.0, v66
	v_rcp_f32_e32 v66, v66
	v_lshlrev_b64 v[64:65], 7, v[64:65]
	v_lshl_add_u64 v[64:65], s[6:7], 0, v[64:65]
	v_mul_f32_e32 v60, v60, v66
	v_mul_f32_e32 v56, v56, v60
	v_mul_f32_e32 v60, 0xbfb8aa3b, v61
	v_exp_f32_e32 v60, v60
	s_nop 0
	v_add_f32_e32 v60, 1.0, v60
	v_rcp_f32_e32 v60, v60
	s_nop 0
	v_mul_f32_e32 v60, v61, v60
	v_mul_f32_e32 v57, v57, v60
	v_mul_f32_e32 v60, 0xbfb8aa3b, v62
	v_exp_f32_e32 v60, v60
	s_nop 0
	v_add_f32_e32 v60, 1.0, v60
	v_rcp_f32_e32 v60, v60
	s_nop 0
	v_mul_f32_e32 v60, v62, v60
	v_mul_f32_e32 v58, v58, v60
	v_mul_f32_e32 v60, 0xbfb8aa3b, v63
	v_exp_f32_e32 v60, v60
	s_nop 0
	v_add_f32_e32 v60, 1.0, v60
	v_rcp_f32_e32 v60, v60
	s_nop 0
	v_mul_f32_e32 v60, v63, v60
	v_mul_f32_e32 v59, v59, v60
	v_mul_f32_e32 v60, 0xbfb8aa3b, v52
	v_exp_f32_e32 v60, v60
	s_nop 0
	v_add_f32_e32 v60, 1.0, v60
	v_rcp_f32_e32 v60, v60
	s_nop 0
	v_mul_f32_e32 v52, v52, v60
	v_mul_f32_e32 v60, v48, v52
	v_mul_f32_e32 v48, 0xbfb8aa3b, v53
	v_exp_f32_e32 v48, v48
	s_nop 0
	v_add_f32_e32 v48, 1.0, v48
	v_rcp_f32_e32 v48, v48
	s_nop 0
	v_mul_f32_e32 v48, v53, v48
	v_mul_f32_e32 v61, v49, v48
	v_mul_f32_e32 v48, 0xbfb8aa3b, v54
	v_exp_f32_e32 v48, v48
	v_lshl_add_u64 v[52:53], v[64:65], 0, v[112:113]
	v_cvt_pk_bf16_f32 v49, v58, v59
	v_add_f32_e32 v48, 1.0, v48
	v_rcp_f32_e32 v48, v48
	s_nop 0
	v_mul_f32_e32 v48, v54, v48
	v_mul_f32_e32 v54, v50, v48
	v_mul_f32_e32 v48, 0xbfb8aa3b, v55
	v_exp_f32_e32 v48, v48
	v_cvt_pk_bf16_f32 v50, v60, v61
	s_nop 0
	v_add_f32_e32 v48, 1.0, v48
	v_rcp_f32_e32 v48, v48
	s_nop 0
	v_mul_f32_e32 v48, v55, v48
	v_mul_f32_e32 v51, v51, v48
	v_cvt_pk_bf16_f32 v48, v56, v57
	v_cvt_pk_bf16_f32 v51, v54, v51
	global_store_dwordx4 v[52:53], v[48:51], off sc1
	s_nop 1
	v_mul_f32_e32 v50, 0xbfb8aa3b, v44
	v_exp_f32_e32 v50, v50
	v_add_u32_e32 v48, 0x90, v144
	v_ashrrev_i32_e32 v49, 31, v48
	v_lshl_add_u64 v[48:49], s[30:31], 0, v[48:49]
	v_add_f32_e32 v50, 1.0, v50
	v_rcp_f32_e32 v50, v50
	v_lshlrev_b64 v[48:49], 7, v[48:49]
	v_lshl_add_u64 v[48:49], s[6:7], 0, v[48:49]
	v_mul_f32_e32 v44, v44, v50
	v_mul_f32_e32 v40, v40, v44
	v_mul_f32_e32 v44, 0xbfb8aa3b, v45
	v_exp_f32_e32 v44, v44
	s_nop 0
	v_add_f32_e32 v44, 1.0, v44
	v_rcp_f32_e32 v44, v44
	s_nop 0
	v_mul_f32_e32 v44, v45, v44
	v_mul_f32_e32 v41, v41, v44
	v_mul_f32_e32 v44, 0xbfb8aa3b, v46
	v_exp_f32_e32 v44, v44
	s_nop 0
	v_add_f32_e32 v44, 1.0, v44
; __device__ __forceinline__ unsigned cvt_pk_bf16(float lo, float hi) { unsigned r; asm("v_cvt_pk_bf16_f32 %0, %1, %2" : "=v"(r) : "v"(lo), "v"(hi)); return r; }
; __device__ __forceinline__ float fast_sigmoid(float v) { return __builtin_amdgcn_rcpf(1.0f + __builtin_amdgcn_exp2f(-1.4426950408889634f * v)); }
; __device__ __forceinline__ f32x4 ln_fix(const f32x4& a, float mu, float rs, const f32x4& cs, const f32x4& cb) { return (a - cs * mu) * rs + cb; }
;     __device__ __forceinline__ void operator()(const f32x4 (&acc)[2][2][4][2], const Unit& u, int wr, int wc, int fr_in, int fq_in) const {
;     ...
;             for (int m = 0; m < 4; ++m) { bf16_t* rowp = H + ((size_t)kt * mrows + (row0 + ai * HALF + m * 16)) * 64 + cin;
;                 float h[8];
; #pragma unroll
;                 for (int n = 0; n < 2; ++n) { f32x4 g = acc[ai][0][m][n], uu = acc[ai][1][m][n];
;                     if constexpr (LN) { g = ln_fix(g, rst.mu[ai][m], rst.rs[ai][m], csv[0][n], cbv[0][n]); uu = ln_fix(uu, rst.mu[ai][m], rst.rs[ai][m], csv[1][n], cbv[1][n]); }
; #pragma unroll
;                     for (int j = 0; j < 4; ++j) h[4 * n + j] = g[j] * fast_sigmoid(g[j]) * uu[j]; }
;                 u32x4 w; w.x = cvt_pk_bf16(h[0], h[1]); w.y = cvt_pk_bf16(h[2], h[3]); w.z = cvt_pk_bf16(h[4], h[5]); w.w = cvt_pk_bf16(h[6], h[7]);
;                 *(u32x4*)rowp = w; }
	v_rcp_f32_e32 v44, v44
	s_nop 0
	v_mul_f32_e32 v44, v46, v44
	v_mul_f32_e32 v42, v42, v44
	v_mul_f32_e32 v44, 0xbfb8aa3b, v47
	v_exp_f32_e32 v44, v44
	s_nop 0
	v_add_f32_e32 v44, 1.0, v44
	v_rcp_f32_e32 v44, v44
	s_nop 0
	v_mul_f32_e32 v44, v47, v44
	v_mul_f32_e32 v43, v43, v44
	v_mul_f32_e32 v44, 0xbfb8aa3b, v36
	v_exp_f32_e32 v44, v44
	s_nop 0
	v_add_f32_e32 v44, 1.0, v44
	v_rcp_f32_e32 v44, v44
	s_nop 0
	v_mul_f32_e32 v36, v36, v44
	v_mul_f32_e32 v44, v32, v36
	v_mul_f32_e32 v32, 0xbfb8aa3b, v37
	v_exp_f32_e32 v32, v32
	s_nop 0
	v_add_f32_e32 v32, 1.0, v32
	v_rcp_f32_e32 v32, v32
	s_nop 0
	v_mul_f32_e32 v32, v37, v32
	v_mul_f32_e32 v45, v33, v32
	v_mul_f32_e32 v32, 0xbfb8aa3b, v38
	v_exp_f32_e32 v32, v32
	v_lshl_add_u64 v[36:37], v[48:49], 0, v[112:113]
	v_cvt_pk_bf16_f32 v33, v42, v43
	v_add_f32_e32 v32, 1.0, v32
	v_rcp_f32_e32 v32, v32
	s_nop 0
	v_mul_f32_e32 v32, v38, v32
	v_mul_f32_e32 v38, v34, v32
	v_mul_f32_e32 v32, 0xbfb8aa3b, v39
	v_exp_f32_e32 v32, v32
	v_cvt_pk_bf16_f32 v34, v44, v45
	s_nop 0
	v_add_f32_e32 v32, 1.0, v32
	v_rcp_f32_e32 v32, v32
	s_nop 0
	v_mul_f32_e32 v32, v39, v32
	v_mul_f32_e32 v35, v35, v32
	v_cvt_pk_bf16_f32 v32, v40, v41
	v_cvt_pk_bf16_f32 v35, v38, v35
	global_store_dwordx4 v[36:37], v[32:35], off sc1
	s_nop 1
	v_mul_f32_e32 v34, 0xbfb8aa3b, v28
	v_exp_f32_e32 v34, v34
	v_add_u32_e32 v32, 0xa0, v144
	v_ashrrev_i32_e32 v33, 31, v32
	v_lshl_add_u64 v[32:33], s[30:31], 0, v[32:33]
	v_add_f32_e32 v34, 1.0, v34
	v_rcp_f32_e32 v34, v34
	v_lshlrev_b64 v[32:33], 7, v[32:33]
	v_lshl_add_u64 v[32:33], s[6:7], 0, v[32:33]
	v_mul_f32_e32 v28, v28, v34
	v_mul_f32_e32 v24, v24, v28
	v_mul_f32_e32 v28, 0xbfb8aa3b, v29
	v_exp_f32_e32 v28, v28
	s_nop 0
	v_add_f32_e32 v28, 1.0, v28
	v_rcp_f32_e32 v28, v28
	s_nop 0
	v_mul_f32_e32 v28, v29, v28
	v_mul_f32_e32 v25, v25, v28
	v_mul_f32_e32 v28, 0xbfb8aa3b, v30
	v_exp_f32_e32 v28, v28
	s_nop 0
	v_add_f32_e32 v28, 1.0, v28
	v_rcp_f32_e32 v28, v28
	s_nop 0
	v_mul_f32_e32 v28, v30, v28
	v_mul_f32_e32 v26, v26, v28
	v_mul_f32_e32 v28, 0xbfb8aa3b, v31
	v_exp_f32_e32 v28, v28
	s_nop 0
	v_add_f32_e32 v28, 1.0, v28
	v_rcp_f32_e32 v28, v28
	s_nop 0
	v_mul_f32_e32 v28, v31, v28
	v_mul_f32_e32 v27, v27, v28
	v_mul_f32_e32 v28, 0xbfb8aa3b, v20
	v_exp_f32_e32 v28, v28
	s_nop 0
	v_add_f32_e32 v28, 1.0, v28
	v_rcp_f32_e32 v28, v28
	s_nop 0
	v_mul_f32_e32 v20, v20, v28
	v_mul_f32_e32 v28, v16, v20
	v_mul_f32_e32 v16, 0xbfb8aa3b, v21
	v_exp_f32_e32 v16, v16
	s_nop 0
	v_add_f32_e32 v16, 1.0, v16
	v_rcp_f32_e32 v16, v16
	s_nop 0
	v_mul_f32_e32 v16, v21, v16
	v_mul_f32_e32 v29, v17, v16
	v_mul_f32_e32 v16, 0xbfb8aa3b, v22
	v_exp_f32_e32 v16, v16
	v_lshl_add_u64 v[20:21], v[32:33], 0, v[112:113]
	v_cvt_pk_bf16_f32 v17, v26, v27
	v_add_f32_e32 v16, 1.0, v16
	v_rcp_f32_e32 v16, v16
	s_nop 0
	v_mul_f32_e32 v16, v22, v16
	v_mul_f32_e32 v22, v18, v16
	v_mul_f32_e32 v16, 0xbfb8aa3b, v23
	v_exp_f32_e32 v16, v16
	v_cvt_pk_bf16_f32 v18, v28, v29
	s_nop 0
	v_add_f32_e32 v16, 1.0, v16
	v_rcp_f32_e32 v16, v16
	s_nop 0
	v_mul_f32_e32 v16, v23, v16
	v_mul_f32_e32 v19, v19, v16
	v_cvt_pk_bf16_f32 v16, v24, v25
	v_cvt_pk_bf16_f32 v19, v22, v19
	global_store_dwordx4 v[20:21], v[16:19], off sc1
	s_nop 1
	v_mul_f32_e32 v18, 0xbfb8aa3b, v12
	v_exp_f32_e32 v18, v18
	v_add_u32_e32 v16, 0xb0, v144
	v_ashrrev_i32_e32 v17, 31, v16
	v_lshl_add_u64 v[16:17], s[30:31], 0, v[16:17]
	v_add_f32_e32 v18, 1.0, v18
	v_rcp_f32_e32 v18, v18
	v_lshlrev_b64 v[16:17], 7, v[16:17]
	v_lshl_add_u64 v[16:17], s[6:7], 0, v[16:17]
	s_mov_b64 s[30:31], -1
	v_mul_f32_e32 v12, v12, v18
	v_mul_f32_e32 v8, v8, v12
	v_mul_f32_e32 v12, 0xbfb8aa3b, v13
	v_exp_f32_e32 v12, v12
	s_nop 0
	v_add_f32_e32 v12, 1.0, v12
	v_rcp_f32_e32 v12, v12
	s_nop 0
	v_mul_f32_e32 v12, v13, v12
	v_mul_f32_e32 v9, v9, v12
	v_mul_f32_e32 v12, 0xbfb8aa3b, v14
	v_exp_f32_e32 v12, v12
	s_nop 0
	v_add_f32_e32 v12, 1.0, v12
	v_rcp_f32_e32 v12, v12
	s_nop 0
	v_mul_f32_e32 v12, v14, v12
	v_mul_f32_e32 v10, v10, v12
	v_mul_f32_e32 v12, 0xbfb8aa3b, v15
	v_exp_f32_e32 v12, v12
	s_nop 0
	v_add_f32_e32 v12, 1.0, v12
	v_rcp_f32_e32 v12, v12
	s_nop 0
	v_mul_f32_e32 v12, v15, v12
	v_mul_f32_e32 v11, v11, v12
	v_mul_f32_e32 v12, 0xbfb8aa3b, v4
	v_exp_f32_e32 v12, v12
	s_nop 0
	v_add_f32_e32 v12, 1.0, v12
	v_rcp_f32_e32 v12, v12
	s_nop 0
	v_mul_f32_e32 v4, v4, v12
	v_mul_f32_e32 v12, v0, v4
	v_mul_f32_e32 v0, 0xbfb8aa3b, v5
	v_exp_f32_e32 v0, v0
	s_nop 0
	v_add_f32_e32 v0, 1.0, v0
	v_rcp_f32_e32 v0, v0
	s_nop 0
	v_mul_f32_e32 v0, v5, v0
	v_mul_f32_e32 v13, v1, v0
	v_mul_f32_e32 v0, 0xbfb8aa3b, v6
	v_exp_f32_e32 v0, v0
	v_lshl_add_u64 v[4:5], v[16:17], 0, v[112:113]
	v_cvt_pk_bf16_f32 v1, v10, v11
	v_add_f32_e32 v0, 1.0, v0
	v_rcp_f32_e32 v0, v0
	s_nop 0
	v_mul_f32_e32 v0, v6, v0
	v_mul_f32_e32 v6, v2, v0
	v_mul_f32_e32 v0, 0xbfb8aa3b, v7
	v_exp_f32_e32 v0, v0
	v_cvt_pk_bf16_f32 v2, v12, v13
	s_nop 0
	v_add_f32_e32 v0, 1.0, v0
	v_rcp_f32_e32 v0, v0
	s_nop 0
	v_mul_f32_e32 v0, v7, v0
	v_mul_f32_e32 v3, v3, v0
	v_cvt_pk_bf16_f32 v0, v8, v9
	v_cvt_pk_bf16_f32 v3, v6, v3
	global_store_dwordx4 v[4:5], v[0:3], off sc1
	s_cbranch_vccnz .LBB0_1518
	s_andn2_b64 vcc, exec, s[4:5]
	s_cbranch_vccnz .LBB0_1517
	s_barrier
	s_branch .LBB0_1517

; __device__ __forceinline__ unsigned cvt_pk_bf16(float lo, float hi) { unsigned r; asm("v_cvt_pk_bf16_f32 %0, %1, %2" : "=v"(r) : "v"(lo), "v"(hi)); return r; }
; __device__ __forceinline__ float bf_lo(unsigned w) { return __uint_as_float(w << 16); }
; __device__ __forceinline__ float bf_hi(unsigned w) { return __uint_as_float(w & 0xffff0000u); }
;     __device__ __forceinline__ void operator()(const f32x4 (&acc)[2][2][4][2], const Unit& u, int wr, int wc, int fr_in, int fq_in) const {
;     ...
;                 for (int m = 0; m < 4; ++m) { const size_t off = (size_t)(row0 + ai * HALF + m * 16) * 1024 + col0 + bj * HALF;
;                     if constexpr (BASE == 0) { pf[m][0] = *(const f32x4*)(basef + off); pf[m][1] = *(const f32x4*)(basef + off + 4); } else pb[m] = *(const u32x4*)(baseb + off); }
; #pragma unroll
;                 for (int m = 0; m < 4; ++m) { const size_t off = (size_t)(row0 + ai * HALF + m * 16) * 1024 + col0 + bj * HALF; f32x4 b[2];
;                     if constexpr (BASE == 0) { b[0] = pf[m][0]; b[1] = pf[m][1]; }
;                     else { const u32x4 pw = pb[m]; b[0] = (f32x4){bf_lo(pw.x), bf_hi(pw.x), bf_lo(pw.y), bf_hi(pw.y)}; b[1] = (f32x4){bf_lo(pw.z), bf_hi(pw.z), bf_lo(pw.w), bf_hi(pw.w)}; }
;                     f32x4 z[2];
; #pragma unroll
;                     for (int n = 0; n < 2; ++n) { if constexpr (BASE == 1) b[n] = (b[n] - rst.mu[ai][m]) * rst.rs[ai][m] * gv[n] + bv[n];
;                         z[n] = b[n] * al_ + acc[ai][bj][m][n] * s_; }
;                     u32x4 w; w.x = cvt_pk_bf16(z[0][0], z[0][1]); w.y = cvt_pk_bf16(z[0][2], z[0][3]); w.z = cvt_pk_bf16(z[1][0], z[1][1]); w.w = cvt_pk_bf16(z[1][2], z[1][3]);
;                     *(u32x4*)(zb + off) = w;
.LBB0_1605:
	s_lshl_b32 s5, s40, 8
	v_mov_b32_e32 v189, v155
	v_mov_b32_e32 v190, v157
	s_add_i32 s8, s5, s53
	v_mov_b32_e32 v156, 0x3fb504f3
	v_add_u32_e32 v128, s8, v189
	s_lshl_b32 s8, s4, 8
	s_or_b32 s8, s8, s54
	v_lshl_add_u32 v130, v190, 3, s8
	v_ashrrev_i32_e32 v131, 31, v130
	v_lshlrev_b64 v[162:163], 1, v[130:131]
	v_ashrrev_i32_e32 v129, 31, v128
	v_lshl_add_u64 v[174:175], s[12:13], 0, v[162:163]
	v_lshlrev_b64 v[176:177], 11, v[128:129]
	v_mov_b32_e32 v154, 0.5
	v_lshl_add_u64 v[164:165], v[174:175], 0, v[176:177]
	s_mov_b64 s[8:9], 0x8000
	global_load_dwordx4 v[158:161], v[164:165], off
	v_lshl_add_u64 v[182:183], v[176:177], 0, s[8:9]
	v_lshl_add_u64 v[166:167], v[174:175], 0, v[182:183]
	global_load_dwordx4 v[192:195], v[166:167], off
	s_mov_b64 s[8:9], 0x10000
	v_lshl_add_u64 v[180:181], v[176:177], 0, s[8:9]
	v_lshl_add_u64 v[168:169], v[174:175], 0, v[180:181]
	global_load_dwordx4 v[132:135], v[168:169], off
	s_mov_b64 s[8:9], 0x18000
	v_lshl_add_u64 v[178:179], v[176:177], 0, s[8:9]
	v_lshl_add_u64 v[170:171], v[174:175], 0, v[178:179]
	global_load_dwordx4 v[128:131], v[170:171], off
	s_mov_b64 s[8:9], 0x40000
	s_waitcnt vmcnt(0)
	v_lshlrev_b32_e32 v172, 16, v158
	v_and_b32_e32 v173, 0xffff0000, v158
	v_lshlrev_b32_e32 v158, 16, v159
	v_and_b32_e32 v159, 0xffff0000, v159
	v_lshlrev_b32_e32 v196, 16, v160
	v_and_b32_e32 v197, 0xffff0000, v160
	v_pk_mul_f32 v[158:159], v[156:157], v[158:159] op_sel_hi:[0,1]
	v_pk_fma_f32 v[126:127], v[126:127], v[154:155], v[158:159] op_sel_hi:[1,0,1]
	v_pk_mul_f32 v[158:159], v[156:157], v[196:197] op_sel_hi:[0,1]
	v_lshlrev_b32_e32 v196, 16, v192
	v_and_b32_e32 v197, 0xffff0000, v192
	v_lshlrev_b32_e32 v192, 16, v193
	v_and_b32_e32 v193, 0xffff0000, v193
	v_lshlrev_b32_e32 v198, 16, v194
	v_and_b32_e32 v199, 0xffff0000, v194
	v_lshlrev_b32_e32 v194, 16, v195
	v_and_b32_e32 v195, 0xffff0000, v195
	v_pk_mul_f32 v[192:193], v[156:157], v[192:193] op_sel_hi:[0,1]
	v_pk_mul_f32 v[196:197], v[156:157], v[196:197] op_sel_hi:[0,1]
	v_pk_fma_f32 v[122:123], v[122:123], v[154:155], v[192:193] op_sel_hi:[1,0,1]
	v_pk_mul_f32 v[192:193], v[156:157], v[198:199] op_sel_hi:[0,1]
	v_pk_mul_f32 v[194:195], v[156:157], v[194:195] op_sel_hi:[0,1]
	v_pk_fma_f32 v[120:121], v[120:121], v[154:155], v[196:197] op_sel_hi:[1,0,1]
	v_pk_fma_f32 v[194:195], v[102:103], v[154:155], v[194:195] op_sel_hi:[1,0,1]
	v_pk_fma_f32 v[102:103], v[100:101], v[154:155], v[192:193] op_sel_hi:[1,0,1]
	v_cvt_pk_bf16_f32 v101, v122, v123
	v_lshlrev_b32_e32 v122, 16, v132
	v_and_b32_e32 v123, 0xffff0000, v132
	v_lshlrev_b32_e32 v132, 16, v133
	v_and_b32_e32 v133, 0xffff0000, v133
	v_cvt_pk_bf16_f32 v100, v120, v121
	v_lshl_add_u64 v[120:121], s[10:11], 0, v[182:183]
	v_lshlrev_b32_e32 v182, 16, v134
	v_and_b32_e32 v183, 0xffff0000, v134
	v_lshlrev_b32_e32 v134, 16, v135
	v_and_b32_e32 v135, 0xffff0000, v135
	v_pk_mul_f32 v[122:123], v[156:157], v[122:123] op_sel_hi:[0,1]
	v_pk_mul_f32 v[132:133], v[156:157], v[132:133] op_sel_hi:[0,1]
	v_pk_fma_f32 v[118:119], v[118:119], v[154:155], v[132:133] op_sel_hi:[1,0,1]
	v_pk_fma_f32 v[116:117], v[116:117], v[154:155], v[122:123] op_sel_hi:[1,0,1]
	v_pk_mul_f32 v[122:123], v[156:157], v[182:183] op_sel_hi:[0,1]
	v_pk_mul_f32 v[132:133], v[156:157], v[134:135] op_sel_hi:[0,1]
	v_pk_fma_f32 v[132:133], v[114:115], v[154:155], v[132:133] op_sel_hi:[1,0,1]
	v_pk_fma_f32 v[114:115], v[112:113], v[154:155], v[122:123] op_sel_hi:[1,0,1]
	v_cvt_pk_bf16_f32 v112, v116, v117
	v_lshl_add_u64 v[116:117], s[10:11], 0, v[180:181]
	v_cvt_pk_bf16_f32 v113, v118, v119
	v_lshl_add_u64 v[122:123], v[116:117], 0, v[162:163]
	v_lshlrev_b32_e32 v116, 16, v128
	v_and_b32_e32 v117, 0xffff0000, v128
	v_lshlrev_b32_e32 v118, 16, v129
	v_and_b32_e32 v119, 0xffff0000, v129
	v_lshlrev_b32_e32 v160, 16, v161
	v_and_b32_e32 v161, 0xffff0000, v161
	v_pk_mul_f32 v[172:173], v[156:157], v[172:173] op_sel_hi:[0,1]
	v_lshlrev_b32_e32 v128, 16, v130
	v_and_b32_e32 v129, 0xffff0000, v130
	v_lshlrev_b32_e32 v130, 16, v131
	v_and_b32_e32 v131, 0xffff0000, v131
	v_pk_mul_f32 v[116:117], v[156:157], v[116:117] op_sel_hi:[0,1]
	v_pk_mul_f32 v[118:119], v[156:157], v[118:119] op_sel_hi:[0,1]
	v_pk_fma_f32 v[124:125], v[124:125], v[154:155], v[172:173] op_sel_hi:[1,0,1]
	v_pk_mul_f32 v[160:161], v[156:157], v[160:161] op_sel_hi:[0,1]
	v_pk_fma_f32 v[110:111], v[110:111], v[154:155], v[118:119] op_sel_hi:[1,0,1]
	v_pk_fma_f32 v[108:109], v[108:109], v[154:155], v[116:117] op_sel_hi:[1,0,1]
	v_pk_mul_f32 v[116:117], v[156:157], v[128:129] op_sel_hi:[0,1]
	v_pk_mul_f32 v[118:119], v[156:157], v[130:131] op_sel_hi:[0,1]
	v_pk_fma_f32 v[160:161], v[98:99], v[154:155], v[160:161] op_sel_hi:[1,0,1]
	v_pk_fma_f32 v[98:99], v[96:97], v[154:155], v[158:159] op_sel_hi:[1,0,1]
	v_cvt_pk_bf16_f32 v96, v124, v125
	v_lshl_add_u64 v[124:125], s[10:11], 0, v[176:177]
	v_pk_fma_f32 v[118:119], v[106:107], v[154:155], v[118:119] op_sel_hi:[1,0,1]
	v_pk_fma_f32 v[106:107], v[104:105], v[154:155], v[116:117] op_sel_hi:[1,0,1]
	v_cvt_pk_bf16_f32 v104, v108, v109
	v_lshl_add_u64 v[108:109], s[10:11], 0, v[178:179]
	v_lshl_add_u64 v[172:173], v[124:125], 0, v[162:163]
	v_lshl_add_u64 v[120:121], v[120:121], 0, v[162:163]
	v_lshl_add_u64 v[128:129], v[108:109], 0, v[162:163]
	v_cvt_pk_bf16_f32 v97, v126, v127
	v_cvt_pk_bf16_f32 v98, v98, v99
	v_cvt_pk_bf16_f32 v99, v160, v161
	global_store_dwordx4 v[172:173], v[96:99], off sc1
	v_cvt_pk_bf16_f32 v102, v102, v103
	v_cvt_pk_bf16_f32 v103, v194, v195
	global_store_dwordx4 v[120:121], v[100:103], off sc1
	v_cvt_pk_bf16_f32 v114, v114, v115
	v_cvt_pk_bf16_f32 v115, v132, v133
	global_store_dwordx4 v[122:123], v[112:115], off sc1
	v_cvt_pk_bf16_f32 v105, v110, v111
	v_cvt_pk_bf16_f32 v106, v106, v107
	v_cvt_pk_bf16_f32 v107, v118, v119
	global_store_dwordx4 v[128:129], v[104:107], off sc1
	v_lshl_add_u64 v[182:183], v[176:177], 0, s[8:9]
	v_lshl_add_u64 v[130:131], v[174:175], 0, v[182:183]
	global_load_dwordx4 v[192:195], v[130:131], off
	s_mov_b64 s[8:9], 0x48000
	v_lshl_add_u64 v[180:181], v[176:177], 0, s[8:9]
	v_lshl_add_u64 v[132:133], v[174:175], 0, v[180:181]
	global_load_dwordx4 v[196:199], v[132:133], off
	s_mov_b64 s[8:9], 0x50000
	v_lshl_add_u64 v[178:179], v[176:177], 0, s[8:9]
	v_lshl_add_u64 v[134:135], v[174:175], 0, v[178:179]
	global_load_dwordx4 v[116:119], v[134:135], off
	s_mov_b64 s[8:9], 0x58000
	v_lshl_add_u64 v[176:177], v[176:177], 0, s[8:9]
	v_lshl_add_u64 v[174:175], v[174:175], 0, v[176:177]
	global_load_dwordx4 v[108:111], v[174:175], off
	v_and_b32_e32 v160, 0xffff0000, v96
	v_lshlrev_b32_e32 v158, 16, v97
	v_and_b32_e32 v126, 0xffff0000, v98
	v_lshlrev_b32_e32 v124, 16, v99
	s_waitcnt vmcnt(0)
; __device__ __forceinline__ unsigned cvt_pk_bf16(float lo, float hi) { unsigned r; asm("v_cvt_pk_bf16_f32 %0, %1, %2" : "=v"(r) : "v"(lo), "v"(hi)); return r; }
; __device__ __forceinline__ float bf_lo(unsigned w) { return __uint_as_float(w << 16); }
; __device__ __forceinline__ float bf_hi(unsigned w) { return __uint_as_float(w & 0xffff0000u); }
;     __device__ __forceinline__ void operator()(const f32x4 (&acc)[2][2][4][2], const Unit& u, int wr, int wc, int fr_in, int fq_in) const {
;     ...
;                 for (int m = 0; m < 4; ++m) { const size_t off = (size_t)(row0 + ai * HALF + m * 16) * 1024 + col0 + bj * HALF;
;                     if constexpr (BASE == 0) { pf[m][0] = *(const f32x4*)(basef + off); pf[m][1] = *(const f32x4*)(basef + off + 4); } else pb[m] = *(const u32x4*)(baseb + off); }
; #pragma unroll
;                 for (int m = 0; m < 4; ++m) { const size_t off = (size_t)(row0 + ai * HALF + m * 16) * 1024 + col0 + bj * HALF; f32x4 b[2];
;                     if constexpr (BASE == 0) { b[0] = pf[m][0]; b[1] = pf[m][1]; }
;                     else { const u32x4 pw = pb[m]; b[0] = (f32x4){bf_lo(pw.x), bf_hi(pw.x), bf_lo(pw.y), bf_hi(pw.y)}; b[1] = (f32x4){bf_lo(pw.z), bf_hi(pw.z), bf_lo(pw.w), bf_hi(pw.w)}; }
;                     f32x4 z[2];
; #pragma unroll
;                     for (int n = 0; n < 2; ++n) { if constexpr (BASE == 1) b[n] = (b[n] - rst.mu[ai][m]) * rst.rs[ai][m] * gv[n] + bv[n];
;                         z[n] = b[n] * al_ + acc[ai][bj][m][n] * s_; }
;                     u32x4 w; w.x = cvt_pk_bf16(z[0][0], z[0][1]); w.y = cvt_pk_bf16(z[0][2], z[0][3]); w.z = cvt_pk_bf16(z[1][0], z[1][1]); w.w = cvt_pk_bf16(z[1][2], z[1][3]);
;                     *(u32x4*)(zb + off) = w;
	v_lshlrev_b32_e32 v200, 16, v192
	v_and_b32_e32 v201, 0xffff0000, v192
	v_lshlrev_b32_e32 v192, 16, v193
	v_and_b32_e32 v193, 0xffff0000, v193
	v_lshlrev_b32_e32 v202, 16, v194
	v_and_b32_e32 v203, 0xffff0000, v194
	v_lshlrev_b32_e32 v194, 16, v195
	v_and_b32_e32 v195, 0xffff0000, v195
	v_pk_mul_f32 v[200:201], v[156:157], v[200:201] op_sel_hi:[0,1]
	v_pk_mul_f32 v[192:193], v[156:157], v[192:193] op_sel_hi:[0,1]
	v_pk_fma_f32 v[94:95], v[94:95], v[154:155], v[192:193] op_sel_hi:[1,0,1]
	v_pk_fma_f32 v[92:93], v[92:93], v[154:155], v[200:201] op_sel_hi:[1,0,1]
	v_pk_mul_f32 v[192:193], v[156:157], v[202:203] op_sel_hi:[0,1]
	v_pk_mul_f32 v[194:195], v[156:157], v[194:195] op_sel_hi:[0,1]
	v_pk_fma_f32 v[194:195], v[90:91], v[154:155], v[194:195] op_sel_hi:[1,0,1]
	v_pk_fma_f32 v[90:91], v[88:89], v[154:155], v[192:193] op_sel_hi:[1,0,1]
	v_cvt_pk_bf16_f32 v88, v92, v93
	v_cvt_pk_bf16_f32 v89, v94, v95
	v_lshl_add_u64 v[92:93], s[10:11], 0, v[182:183]
	v_lshlrev_b32_e32 v94, 16, v196
	v_and_b32_e32 v95, 0xffff0000, v196
	v_lshlrev_b32_e32 v182, 16, v197
	v_and_b32_e32 v183, 0xffff0000, v197
	v_cvt_pk_bf16_f32 v90, v90, v91
	v_cvt_pk_bf16_f32 v91, v194, v195
	v_lshlrev_b32_e32 v192, 16, v198
	v_and_b32_e32 v193, 0xffff0000, v198
	v_lshlrev_b32_e32 v194, 16, v199
	v_and_b32_e32 v195, 0xffff0000, v199
	v_pk_mul_f32 v[94:95], v[156:157], v[94:95] op_sel_hi:[0,1]
	v_pk_mul_f32 v[182:183], v[156:157], v[182:183] op_sel_hi:[0,1]
	v_pk_fma_f32 v[86:87], v[86:87], v[154:155], v[182:183] op_sel_hi:[1,0,1]
	v_pk_fma_f32 v[84:85], v[84:85], v[154:155], v[94:95] op_sel_hi:[1,0,1]
	v_pk_mul_f32 v[94:95], v[156:157], v[192:193] op_sel_hi:[0,1]
	v_pk_mul_f32 v[182:183], v[156:157], v[194:195] op_sel_hi:[0,1]
	v_pk_fma_f32 v[182:183], v[82:83], v[154:155], v[182:183] op_sel_hi:[1,0,1]
	v_pk_fma_f32 v[82:83], v[80:81], v[154:155], v[94:95] op_sel_hi:[1,0,1]
	v_cvt_pk_bf16_f32 v81, v86, v87
	v_lshlrev_b32_e32 v86, 16, v116
	v_and_b32_e32 v87, 0xffff0000, v116
	v_lshlrev_b32_e32 v94, 16, v117
	v_and_b32_e32 v95, 0xffff0000, v117
	v_lshlrev_b32_e32 v116, 16, v118
	v_and_b32_e32 v117, 0xffff0000, v118
	v_lshlrev_b32_e32 v118, 16, v119
	v_and_b32_e32 v119, 0xffff0000, v119
	v_pk_mul_f32 v[86:87], v[156:157], v[86:87] op_sel_hi:[0,1]
	v_pk_mul_f32 v[94:95], v[156:157], v[94:95] op_sel_hi:[0,1]
	v_pk_fma_f32 v[78:79], v[78:79], v[154:155], v[94:95] op_sel_hi:[1,0,1]
	v_pk_fma_f32 v[76:77], v[76:77], v[154:155], v[86:87] op_sel_hi:[1,0,1]
	v_pk_mul_f32 v[86:87], v[156:157], v[116:117] op_sel_hi:[0,1]
	v_pk_mul_f32 v[94:95], v[156:157], v[118:119] op_sel_hi:[0,1]
	v_pk_fma_f32 v[94:95], v[74:75], v[154:155], v[94:95] op_sel_hi:[1,0,1]
	v_pk_fma_f32 v[74:75], v[72:73], v[154:155], v[86:87] op_sel_hi:[1,0,1]
	v_cvt_pk_bf16_f32 v73, v78, v79
	v_lshlrev_b32_e32 v78, 16, v108
	v_and_b32_e32 v79, 0xffff0000, v108
	v_lshlrev_b32_e32 v86, 16, v109
	v_and_b32_e32 v87, 0xffff0000, v109
	v_cvt_pk_bf16_f32 v74, v74, v75
	v_cvt_pk_bf16_f32 v75, v94, v95
	v_lshlrev_b32_e32 v94, 16, v110
	v_and_b32_e32 v95, 0xffff0000, v110
	v_lshlrev_b32_e32 v108, 16, v111
	v_and_b32_e32 v109, 0xffff0000, v111
	v_pk_mul_f32 v[78:79], v[156:157], v[78:79] op_sel_hi:[0,1]
	v_pk_mul_f32 v[86:87], v[156:157], v[86:87] op_sel_hi:[0,1]
	v_pk_fma_f32 v[70:71], v[70:71], v[154:155], v[86:87] op_sel_hi:[1,0,1]
	v_pk_fma_f32 v[68:69], v[68:69], v[154:155], v[78:79] op_sel_hi:[1,0,1]
	v_pk_mul_f32 v[78:79], v[156:157], v[94:95] op_sel_hi:[0,1]
	v_pk_mul_f32 v[86:87], v[156:157], v[108:109] op_sel_hi:[0,1]
	v_cvt_pk_bf16_f32 v80, v84, v85
	v_lshl_add_u64 v[84:85], s[10:11], 0, v[180:181]
	v_cvt_pk_bf16_f32 v72, v76, v77
	v_lshl_add_u64 v[76:77], s[10:11], 0, v[178:179]
	v_pk_fma_f32 v[86:87], v[66:67], v[154:155], v[86:87] op_sel_hi:[1,0,1]
	v_pk_fma_f32 v[66:67], v[64:65], v[154:155], v[78:79] op_sel_hi:[1,0,1]
	v_cvt_pk_bf16_f32 v64, v68, v69
	v_lshl_add_u64 v[68:69], s[10:11], 0, v[176:177]
	v_lshl_add_u64 v[92:93], v[92:93], 0, v[162:163]
	v_lshl_add_u64 v[84:85], v[84:85], 0, v[162:163]
	v_lshl_add_u64 v[76:77], v[76:77], 0, v[162:163]
	v_lshl_add_u64 v[78:79], v[68:69], 0, v[162:163]
	global_store_dwordx4 v[92:93], v[88:91], off sc1
	v_cvt_pk_bf16_f32 v82, v82, v83
	v_cvt_pk_bf16_f32 v83, v182, v183
	global_store_dwordx4 v[84:85], v[80:83], off sc1
	global_store_dwordx4 v[76:77], v[72:75], off sc1
	v_cvt_pk_bf16_f32 v65, v70, v71
	v_cvt_pk_bf16_f32 v66, v66, v67
	v_cvt_pk_bf16_f32 v67, v86, v87
	global_store_dwordx4 v[78:79], v[64:67], off sc1
	global_load_dwordx4 v[108:111], v[164:165], off offset:256
	global_load_dwordx4 v[116:119], v[166:167], off offset:256
	s_nop 0
	global_load_dwordx4 v[162:165], v[168:169], off offset:256
	global_load_dwordx4 v[68:71], v[170:171], off offset:256
	s_waitcnt vmcnt(0)
; __device__ __forceinline__ unsigned cvt_pk_bf16(float lo, float hi) { unsigned r; asm("v_cvt_pk_bf16_f32 %0, %1, %2" : "=v"(r) : "v"(lo), "v"(hi)); return r; }
; __device__ __forceinline__ float bf_lo(unsigned w) { return __uint_as_float(w << 16); }
; __device__ __forceinline__ float bf_hi(unsigned w) { return __uint_as_float(w & 0xffff0000u); }
;     __device__ __forceinline__ void operator()(const f32x4 (&acc)[2][2][4][2], const Unit& u, int wr, int wc, int fr_in, int fq_in) const {
;     ...
;                 for (int m = 0; m < 4; ++m) { const size_t off = (size_t)(row0 + ai * HALF + m * 16) * 1024 + col0 + bj * HALF;
;                     if constexpr (BASE == 0) { pf[m][0] = *(const f32x4*)(basef + off); pf[m][1] = *(const f32x4*)(basef + off + 4); } else pb[m] = *(const u32x4*)(baseb + off); }
; #pragma unroll
;                 for (int m = 0; m < 4; ++m) { const size_t off = (size_t)(row0 + ai * HALF + m * 16) * 1024 + col0 + bj * HALF; f32x4 b[2];
;                     if constexpr (BASE == 0) { b[0] = pf[m][0]; b[1] = pf[m][1]; }
;                     else { const u32x4 pw = pb[m]; b[0] = (f32x4){bf_lo(pw.x), bf_hi(pw.x), bf_lo(pw.y), bf_hi(pw.y)}; b[1] = (f32x4){bf_lo(pw.z), bf_hi(pw.z), bf_lo(pw.w), bf_hi(pw.w)}; }
;                     f32x4 z[2];
; #pragma unroll
;                     for (int n = 0; n < 2; ++n) { if constexpr (BASE == 1) b[n] = (b[n] - rst.mu[ai][m]) * rst.rs[ai][m] * gv[n] + bv[n];
;                         z[n] = b[n] * al_ + acc[ai][bj][m][n] * s_; }
;                     u32x4 w; w.x = cvt_pk_bf16(z[0][0], z[0][1]); w.y = cvt_pk_bf16(z[0][2], z[0][3]); w.z = cvt_pk_bf16(z[1][0], z[1][1]); w.w = cvt_pk_bf16(z[1][2], z[1][3]);
;                     *(u32x4*)(zb + off) = w;
	v_lshlrev_b32_e32 v86, 16, v108
	v_and_b32_e32 v87, 0xffff0000, v108
	v_lshlrev_b32_e32 v94, 16, v109
	v_and_b32_e32 v95, 0xffff0000, v109
	v_lshlrev_b32_e32 v108, 16, v110
	v_and_b32_e32 v109, 0xffff0000, v110
	v_lshlrev_b32_e32 v110, 16, v111
	v_and_b32_e32 v111, 0xffff0000, v111
	v_pk_mul_f32 v[86:87], v[156:157], v[86:87] op_sel_hi:[0,1]
	v_pk_mul_f32 v[94:95], v[156:157], v[94:95] op_sel_hi:[0,1]
	v_pk_fma_f32 v[62:63], v[62:63], v[154:155], v[94:95] op_sel_hi:[1,0,1]
	v_pk_fma_f32 v[60:61], v[60:61], v[154:155], v[86:87] op_sel_hi:[1,0,1]
	v_pk_mul_f32 v[86:87], v[156:157], v[108:109] op_sel_hi:[0,1]
	v_pk_mul_f32 v[94:95], v[156:157], v[110:111] op_sel_hi:[0,1]
	v_pk_fma_f32 v[94:95], v[58:59], v[154:155], v[94:95] op_sel_hi:[1,0,1]
	v_pk_fma_f32 v[58:59], v[56:57], v[154:155], v[86:87] op_sel_hi:[1,0,1]
	v_lshlrev_b32_e32 v86, 16, v116
	v_cvt_pk_bf16_f32 v58, v58, v59
	v_cvt_pk_bf16_f32 v59, v94, v95
	v_and_b32_e32 v87, 0xffff0000, v116
	v_lshlrev_b32_e32 v94, 16, v117
	v_and_b32_e32 v95, 0xffff0000, v117
	v_lshlrev_b32_e32 v108, 16, v118
	v_and_b32_e32 v109, 0xffff0000, v118
	v_lshlrev_b32_e32 v110, 16, v119
	v_and_b32_e32 v111, 0xffff0000, v119
	v_pk_mul_f32 v[86:87], v[156:157], v[86:87] op_sel_hi:[0,1]
	v_pk_mul_f32 v[94:95], v[156:157], v[94:95] op_sel_hi:[0,1]
	v_pk_fma_f32 v[54:55], v[54:55], v[154:155], v[94:95] op_sel_hi:[1,0,1]
	v_pk_fma_f32 v[52:53], v[52:53], v[154:155], v[86:87] op_sel_hi:[1,0,1]
	v_pk_mul_f32 v[86:87], v[156:157], v[108:109] op_sel_hi:[0,1]
	v_pk_mul_f32 v[94:95], v[156:157], v[110:111] op_sel_hi:[0,1]
	v_pk_fma_f32 v[94:95], v[50:51], v[154:155], v[94:95] op_sel_hi:[1,0,1]
	v_pk_fma_f32 v[50:51], v[48:49], v[154:155], v[86:87] op_sel_hi:[1,0,1]
	v_cvt_pk_bf16_f32 v48, v52, v53
	v_cvt_pk_bf16_f32 v49, v54, v55
	v_lshlrev_b32_e32 v52, 16, v162
	v_and_b32_e32 v53, 0xffff0000, v162
	v_lshlrev_b32_e32 v54, 16, v163
	v_and_b32_e32 v55, 0xffff0000, v163
	v_cvt_pk_bf16_f32 v50, v50, v51
	v_cvt_pk_bf16_f32 v51, v94, v95
	v_lshlrev_b32_e32 v86, 16, v164
	v_and_b32_e32 v87, 0xffff0000, v164
	v_lshlrev_b32_e32 v94, 16, v165
	v_and_b32_e32 v95, 0xffff0000, v165
	v_pk_mul_f32 v[52:53], v[156:157], v[52:53] op_sel_hi:[0,1]
	v_pk_mul_f32 v[54:55], v[156:157], v[54:55] op_sel_hi:[0,1]
	v_pk_fma_f32 v[46:47], v[46:47], v[154:155], v[54:55] op_sel_hi:[1,0,1]
	v_pk_fma_f32 v[44:45], v[44:45], v[154:155], v[52:53] op_sel_hi:[1,0,1]
	v_pk_mul_f32 v[52:53], v[156:157], v[86:87] op_sel_hi:[0,1]
	v_pk_mul_f32 v[54:55], v[156:157], v[94:95] op_sel_hi:[0,1]
	v_pk_fma_f32 v[54:55], v[42:43], v[154:155], v[54:55] op_sel_hi:[1,0,1]
	v_pk_fma_f32 v[42:43], v[40:41], v[154:155], v[52:53] op_sel_hi:[1,0,1]
	v_cvt_pk_bf16_f32 v40, v44, v45
	v_cvt_pk_bf16_f32 v41, v46, v47
	v_lshlrev_b32_e32 v44, 16, v68
	v_and_b32_e32 v45, 0xffff0000, v68
	v_lshlrev_b32_e32 v46, 16, v69
	v_and_b32_e32 v47, 0xffff0000, v69
	v_cvt_pk_bf16_f32 v42, v42, v43
	v_cvt_pk_bf16_f32 v43, v54, v55
	v_lshlrev_b32_e32 v52, 16, v70
	v_and_b32_e32 v53, 0xffff0000, v70
	v_lshlrev_b32_e32 v54, 16, v71
	v_and_b32_e32 v55, 0xffff0000, v71
	v_pk_mul_f32 v[44:45], v[156:157], v[44:45] op_sel_hi:[0,1]
	v_pk_mul_f32 v[46:47], v[156:157], v[46:47] op_sel_hi:[0,1]
	v_pk_fma_f32 v[38:39], v[38:39], v[154:155], v[46:47] op_sel_hi:[1,0,1]
	v_pk_fma_f32 v[36:37], v[36:37], v[154:155], v[44:45] op_sel_hi:[1,0,1]
	v_pk_mul_f32 v[44:45], v[156:157], v[52:53] op_sel_hi:[0,1]
	v_pk_mul_f32 v[46:47], v[156:157], v[54:55] op_sel_hi:[0,1]
	v_pk_fma_f32 v[46:47], v[34:35], v[154:155], v[46:47] op_sel_hi:[1,0,1]
	v_pk_fma_f32 v[34:35], v[32:33], v[154:155], v[44:45] op_sel_hi:[1,0,1]
	v_cvt_pk_bf16_f32 v56, v60, v61
	v_cvt_pk_bf16_f32 v57, v62, v63
	global_store_dwordx4 v[172:173], v[56:59], off offset:256 sc1
	global_store_dwordx4 v[120:121], v[48:51], off offset:256 sc1
	global_store_dwordx4 v[122:123], v[40:43], off offset:256 sc1
	v_cvt_pk_bf16_f32 v32, v36, v37
	v_cvt_pk_bf16_f32 v33, v38, v39
	v_cvt_pk_bf16_f32 v34, v34, v35
	v_cvt_pk_bf16_f32 v35, v46, v47
	global_store_dwordx4 v[128:129], v[32:35], off offset:256 sc1
	global_load_dwordx4 v[36:39], v[130:131], off offset:256
	global_load_dwordx4 v[44:47], v[132:133], off offset:256
	global_load_dwordx4 v[52:55], v[134:135], off offset:256
	global_load_dwordx4 v[68:71], v[174:175], off offset:256
	v_and_b32_e32 v63, 0xffff0000, v59
	v_and_b32_e32 v62, 0xffff0000, v58
	v_lshlrev_b32_e32 v61, 16, v59
	v_lshlrev_b32_e32 v60, 16, v58
	v_pk_mul_f32 v[58:59], v[62:63], v[62:63]
	s_waitcnt vmcnt(0)
; __device__ __forceinline__ unsigned cvt_pk_bf16(float lo, float hi) { unsigned r; asm("v_cvt_pk_bf16_f32 %0, %1, %2" : "=v"(r) : "v"(lo), "v"(hi)); return r; }
; __device__ __forceinline__ float bf_lo(unsigned w) { return __uint_as_float(w << 16); }
; __device__ __forceinline__ float bf_hi(unsigned w) { return __uint_as_float(w & 0xffff0000u); }
; __device__ __forceinline__ void emit_row_stats(float (&s1)[2][4], float (&s2)[2][4], float* sp_new, const Unit& u, int wr, int wc, int fr, int fq, PG8_LAS unsigned char* xl) {
;     ...
;         for (int m = 0; m < 4; ++m) { float a = s1[ai][m], b = s2[ai][m]; a += __shfl_xor(a, 16); b += __shfl_xor(b, 16); a += __shfl_xor(a, 32); b += __shfl_xor(b, 32);
;             if (fq == 0) P[(ai * HALF + wr * 64 + m * 16 + fr) * 4 + wc] = (f32x2v){a, b}; }
;     __device__ __forceinline__ void operator()(const f32x4 (&acc)[2][2][4][2], const Unit& u, int wr, int wc, int fr_in, int fq_in) const {
;     ...
;                 for (int m = 0; m < 4; ++m) { const size_t off = (size_t)(row0 + ai * HALF + m * 16) * 1024 + col0 + bj * HALF; f32x4 b[2];
;                     if constexpr (BASE == 0) { b[0] = pf[m][0]; b[1] = pf[m][1]; }
;                     else { const u32x4 pw = pb[m]; b[0] = (f32x4){bf_lo(pw.x), bf_hi(pw.x), bf_lo(pw.y), bf_hi(pw.y)}; b[1] = (f32x4){bf_lo(pw.z), bf_hi(pw.z), bf_lo(pw.w), bf_hi(pw.w)}; }
;                     f32x4 z[2];
; #pragma unroll
;                     for (int n = 0; n < 2; ++n) { if constexpr (BASE == 1) b[n] = (b[n] - rst.mu[ai][m]) * rst.rs[ai][m] * gv[n] + bv[n];
;                         z[n] = b[n] * al_ + acc[ai][bj][m][n] * s_; }
;                     u32x4 w; w.x = cvt_pk_bf16(z[0][0], z[0][1]); w.y = cvt_pk_bf16(z[0][2], z[0][3]); w.z = cvt_pk_bf16(z[1][0], z[1][1]); w.w = cvt_pk_bf16(z[1][2], z[1][3]);
;                     *(u32x4*)(zb + off) = w;
;                     const float r0 = bf_lo(w.x), r1 = bf_hi(w.x), r2 = bf_lo(w.y), r3 = bf_hi(w.y), r4 = bf_lo(w.z), r5 = bf_hi(w.z), r6 = bf_lo(w.w), r7 = bf_hi(w.w);
;                     s1[ai][m] += ((r0 + r1) + (r2 + r3)) + ((r4 + r5) + (r6 + r7)); s2[ai][m] += ((r0 * r0 + r1 * r1) + (r2 * r2 + r3 * r3)) + ((r4 * r4 + r5 * r5) + (r6 * r6 + r7 * r7)); }
	v_lshlrev_b32_e32 v86, 16, v36
	v_and_b32_e32 v87, 0xffff0000, v36
	v_lshlrev_b32_e32 v36, 16, v37
	v_and_b32_e32 v37, 0xffff0000, v37
	v_lshlrev_b32_e32 v94, 16, v38
	v_and_b32_e32 v95, 0xffff0000, v38
	v_lshlrev_b32_e32 v38, 16, v39
	v_and_b32_e32 v39, 0xffff0000, v39
	v_pk_mul_f32 v[86:87], v[156:157], v[86:87] op_sel_hi:[0,1]
	v_pk_mul_f32 v[36:37], v[156:157], v[36:37] op_sel_hi:[0,1]
	v_pk_fma_f32 v[30:31], v[30:31], v[154:155], v[36:37] op_sel_hi:[1,0,1]
	v_pk_fma_f32 v[28:29], v[28:29], v[154:155], v[86:87] op_sel_hi:[1,0,1]
	v_pk_mul_f32 v[36:37], v[156:157], v[94:95] op_sel_hi:[0,1]
	v_pk_mul_f32 v[38:39], v[156:157], v[38:39] op_sel_hi:[0,1]
	v_pk_fma_f32 v[38:39], v[26:27], v[154:155], v[38:39] op_sel_hi:[1,0,1]
	v_pk_fma_f32 v[26:27], v[24:25], v[154:155], v[36:37] op_sel_hi:[1,0,1]
	v_cvt_pk_bf16_f32 v24, v28, v29
	v_cvt_pk_bf16_f32 v25, v30, v31
	v_lshlrev_b32_e32 v28, 16, v44
	v_and_b32_e32 v29, 0xffff0000, v44
	v_lshlrev_b32_e32 v30, 16, v45
	v_and_b32_e32 v31, 0xffff0000, v45
	v_cvt_pk_bf16_f32 v26, v26, v27
	v_cvt_pk_bf16_f32 v27, v38, v39
	v_lshlrev_b32_e32 v36, 16, v46
	v_and_b32_e32 v37, 0xffff0000, v46
	v_lshlrev_b32_e32 v38, 16, v47
	v_and_b32_e32 v39, 0xffff0000, v47
	v_pk_mul_f32 v[28:29], v[156:157], v[28:29] op_sel_hi:[0,1]
	v_pk_mul_f32 v[30:31], v[156:157], v[30:31] op_sel_hi:[0,1]
	v_pk_fma_f32 v[22:23], v[22:23], v[154:155], v[30:31] op_sel_hi:[1,0,1]
	v_pk_fma_f32 v[20:21], v[20:21], v[154:155], v[28:29] op_sel_hi:[1,0,1]
	v_pk_mul_f32 v[28:29], v[156:157], v[36:37] op_sel_hi:[0,1]
	v_pk_mul_f32 v[30:31], v[156:157], v[38:39] op_sel_hi:[0,1]
	v_pk_fma_f32 v[30:31], v[18:19], v[154:155], v[30:31] op_sel_hi:[1,0,1]
	v_pk_fma_f32 v[18:19], v[16:17], v[154:155], v[28:29] op_sel_hi:[1,0,1]
	v_cvt_pk_bf16_f32 v16, v20, v21
	v_cvt_pk_bf16_f32 v17, v22, v23
	v_lshlrev_b32_e32 v20, 16, v52
	v_and_b32_e32 v21, 0xffff0000, v52
	v_lshlrev_b32_e32 v22, 16, v53
	v_and_b32_e32 v23, 0xffff0000, v53
	v_cvt_pk_bf16_f32 v18, v18, v19
	v_cvt_pk_bf16_f32 v19, v30, v31
	v_lshlrev_b32_e32 v28, 16, v54
	v_and_b32_e32 v29, 0xffff0000, v54
	v_lshlrev_b32_e32 v30, 16, v55
	v_and_b32_e32 v31, 0xffff0000, v55
	v_pk_mul_f32 v[20:21], v[156:157], v[20:21] op_sel_hi:[0,1]
	v_pk_mul_f32 v[22:23], v[156:157], v[22:23] op_sel_hi:[0,1]
	v_pk_fma_f32 v[14:15], v[14:15], v[154:155], v[22:23] op_sel_hi:[1,0,1]
	v_pk_fma_f32 v[12:13], v[12:13], v[154:155], v[20:21] op_sel_hi:[1,0,1]
	v_pk_mul_f32 v[20:21], v[156:157], v[28:29] op_sel_hi:[0,1]
	v_pk_mul_f32 v[22:23], v[156:157], v[30:31] op_sel_hi:[0,1]
	v_pk_fma_f32 v[22:23], v[10:11], v[154:155], v[22:23] op_sel_hi:[1,0,1]
	v_pk_fma_f32 v[10:11], v[8:9], v[154:155], v[20:21] op_sel_hi:[1,0,1]
	v_cvt_pk_bf16_f32 v8, v12, v13
	v_cvt_pk_bf16_f32 v9, v14, v15
	v_lshlrev_b32_e32 v12, 16, v68
	v_and_b32_e32 v13, 0xffff0000, v68
	v_lshlrev_b32_e32 v14, 16, v69
	v_and_b32_e32 v15, 0xffff0000, v69
	v_cvt_pk_bf16_f32 v10, v10, v11
	v_cvt_pk_bf16_f32 v11, v22, v23
	v_lshlrev_b32_e32 v20, 16, v70
	v_and_b32_e32 v21, 0xffff0000, v70
	v_lshlrev_b32_e32 v22, 16, v71
	v_and_b32_e32 v23, 0xffff0000, v71
	v_pk_mul_f32 v[12:13], v[156:157], v[12:13] op_sel_hi:[0,1]
	v_pk_mul_f32 v[14:15], v[156:157], v[14:15] op_sel_hi:[0,1]
	v_pk_fma_f32 v[6:7], v[6:7], v[154:155], v[14:15] op_sel_hi:[1,0,1]
	v_pk_fma_f32 v[4:5], v[4:5], v[154:155], v[12:13] op_sel_hi:[1,0,1]
	v_pk_mul_f32 v[12:13], v[156:157], v[20:21] op_sel_hi:[0,1]
	v_pk_mul_f32 v[14:15], v[156:157], v[22:23] op_sel_hi:[0,1]
	v_pk_fma_f32 v[14:15], v[2:3], v[154:155], v[14:15] op_sel_hi:[1,0,1]
	v_pk_fma_f32 v[2:3], v[0:1], v[154:155], v[12:13] op_sel_hi:[1,0,1]
	v_cvt_pk_bf16_f32 v0, v4, v5
	v_and_b32_e32 v5, 64, v188
	v_xor_b32_e32 v4, 16, v188
	v_add_u32_e32 v5, 64, v5
	v_cmp_lt_i32_e32 vcc, v4, v5
	v_cvt_pk_bf16_f32 v1, v6, v7
	v_and_b32_e32 v21, 0xffff0000, v56
	v_cvt_pk_bf16_f32 v2, v2, v3
	v_cvt_pk_bf16_f32 v3, v14, v15
	v_and_b32_e32 v20, 0xffff0000, v97
	v_cndmask_b32_e32 v4, v188, v4, vcc
	v_lshlrev_b32_e32 v13, 2, v4
	v_xor_b32_e32 v4, 32, v188
	v_cmp_lt_i32_e32 vcc, v4, v5
	v_lshlrev_b32_e32 v5, 16, v56
	v_mov_b32_e32 v161, v5
	v_cndmask_b32_e32 v4, v188, v4, vcc
	v_lshlrev_b32_e32 v12, 2, v4
	v_lshlrev_b32_e32 v4, 16, v96
	v_pk_mul_f32 v[6:7], v[4:5], v[4:5]
	v_pk_mul_f32 v[14:15], v[160:161], v[160:161]
	v_mov_b32_e32 v159, v21
	v_pk_mov_b32 v[54:55], v[4:5], v[6:7] op_sel:[1,0]
	v_pk_add_f32 v[4:5], v[4:5], v[160:161]
	v_pk_mul_f32 v[22:23], v[158:159], v[158:159]
	v_pk_mul_f32 v[28:29], v[20:21], v[20:21]
	v_lshlrev_b32_e32 v30, 16, v98
	v_lshlrev_b32_e32 v31, 16, v57
	v_and_b32_e32 v45, 0xffff0000, v57
	v_and_b32_e32 v44, 0xffff0000, v99
	v_pk_mov_b32 v[14:15], v[20:21], v[14:15] op_sel:[1,0]
	v_mov_b32_e32 v5, v7
	v_pk_add_f32 v[6:7], v[20:21], v[158:159]
	v_mov_b32_e32 v127, v31
	v_mov_b32_e32 v125, v45
	v_pk_add_f32 v[14:15], v[54:55], v[14:15]
	v_pk_mov_b32 v[22:23], v[30:31], v[22:23] op_sel:[1,0]
	v_pk_mov_b32 v[54:55], v[44:45], v[28:29] op_sel:[1,0]
	v_mov_b32_e32 v7, v29
	v_pk_mul_f32 v[36:37], v[30:31], v[30:31]
	v_pk_mul_f32 v[38:39], v[126:127], v[126:127]
	v_pk_mul_f32 v[46:47], v[124:125], v[124:125]
	v_pk_mul_f32 v[52:53], v[44:45], v[44:45]
	v_pk_add_f32 v[22:23], v[22:23], v[54:55]
	v_pk_add_f32 v[4:5], v[4:5], v[6:7]
	v_pk_add_f32 v[6:7], v[30:31], v[126:127]
	v_pk_add_f32 v[20:21], v[44:45], v[124:125]
	v_pk_fma_f32 v[58:59], v[60:61], v[60:61], v[58:59]
	v_pk_add_f32 v[14:15], v[14:15], v[22:23]
	v_mov_b32_e32 v22, v60
	v_mov_b32_e32 v23, v36
	v_mov_b32_e32 v54, v62
	v_mov_b32_e32 v55, v38
	v_pk_mov_b32 v[38:39], v[60:61], v[46:47] op_sel:[1,0]
	v_pk_mov_b32 v[46:47], v[62:63], v[52:53] op_sel:[1,0]
	v_mov_b32_e32 v7, v37
	v_mov_b32_e32 v21, v53
	v_pk_add_f32 v[58:59], v[58:59], v[58:59] op_sel_hi:[0,1]
	v_pk_add_f32 v[22:23], v[22:23], v[54:55]
	v_pk_add_f32 v[38:39], v[38:39], v[46:47]
	v_pk_add_f32 v[6:7], v[6:7], v[20:21]
	v_pk_add_f32 v[22:23], v[22:23], v[38:39]
	v_pk_add_f32 v[4:5], v[4:5], v[6:7]
	v_mov_b32_e32 v145, v59
	v_pk_add_f32 v[14:15], v[14:15], v[22:23]
	v_pk_add_f32 v[4:5], v[4:5], v[144:145]
	global_store_dwordx4 v[92:93], v[24:27], off offset:256 sc1
	v_pk_add_f32 v[4:5], v[14:15], v[4:5]
	ds_bpermute_b32 v6, v13, v4
	ds_bpermute_b32 v7, v13, v5
	global_store_dwordx4 v[84:85], v[16:19], off offset:256 sc1
	global_store_dwordx4 v[76:77], v[8:11], off offset:256 sc1
	global_store_dwordx4 v[78:79], v[0:3], off offset:256 sc1
	s_waitcnt lgkmcnt(0)
	v_pk_add_f32 v[4:5], v[4:5], v[6:7]
	ds_bpermute_b32 v6, v12, v4
	ds_bpermute_b32 v7, v12, v5
	v_cmp_eq_u32_e32 vcc, 0, v190
	v_lshl_add_u32 v14, v189, 5, s61
	s_and_saveexec_b64 s[8:9], vcc
	s_cbranch_execz .LBB0_1607
	s_waitcnt lgkmcnt(0)
	v_pk_add_f32 v[4:5], v[4:5], v[6:7]
	ds_write_b64 v14, v[4:5]

; __device__ __forceinline__ void emit_row_stats(float (&s1)[2][4], float (&s2)[2][4], float* sp_new, const Unit& u, int wr, int wc, int fr, int fq, PG8_LAS unsigned char* xl) {
;     ...
;     asm volatile("s_waitcnt lgkmcnt(0)" ::: "memory"); __builtin_amdgcn_s_barrier(); asm volatile("" ::: "memory");
;     const int tid = (wr * 4 + wc) * 64 + fq * 16 + fr;
;     if (tid < 256) { const f32x2v a = P[tid * 4 + 0], b = P[tid * 4 + 1], c = P[tid * 4 + 2], d = P[tid * 4 + 3];
;         f32x2v o; o.x = (a.x + b.x) + (c.x + d.x); o.y = (a.y + b.y) + (c.y + d.y);
;         *(f32x2v*)(sp_new + ((size_t)(u.pm * BM + tid) * 4 + u.pn) * 2) = o; }
.LBB0_1621:
	s_or_b64 exec, exec, s[8:9]
	s_waitcnt lgkmcnt(0)
	s_barrier
	v_lshlrev_b32_e32 v0, 4, v190
	v_add3_u32 v0, s58, v189, v0
	s_movk_i32 s8, 0x100
	v_cmp_gt_i32_e32 vcc, s8, v0
	s_and_saveexec_b64 s[40:41], vcc
	s_cbranch_execz .LBB0_1623
	v_lshl_add_u32 v1, v0, 5, 0
	v_add_u32_e32 v1, 0x20400, v1
	s_waitcnt lgkmcnt(0)
	ds_read_b128 v[2:5], v1
	ds_read_b128 v[6:9], v1 offset:16
	v_add_u32_e32 v0, s5, v0
	v_ashrrev_i32_e32 v1, 31, v0
	v_lshlrev_b64 v[0:1], 5, v[0:1]
	s_waitcnt lgkmcnt(1)
	v_pk_add_f32 v[2:3], v[2:3], v[4:5]
	s_waitcnt lgkmcnt(0)
	v_pk_add_f32 v[4:5], v[6:7], v[8:9]
	s_ashr_i32 s5, s4, 31
	v_lshl_add_u64 v[0:1], s[22:23], 0, v[0:1]
	v_pk_add_f32 v[2:3], v[2:3], v[4:5]
	v_lshl_add_u64 v[0:1], s[4:5], 3, v[0:1]
	global_store_dwordx2 v[0:1], v[2:3], off sc1

; __device__ __forceinline__ f32x4 ln_fix(const f32x4& a, float mu, float rs, const f32x4& cs, const f32x4& cb) { return (a - cs * mu) * rs + cb; }
; __device__ __forceinline__ void load_row_stats(const float* sp, int row0, RowStats& r) {
;     ...
;         for (int m = 0; m < 4; ++m) { const float* p = sp + (size_t)(row0 + ai * HALF + m * 16) * 8; const f32x4 a = *(const f32x4*)p, b = *(const f32x4*)(p + 4);
;             const float s1 = (a[0] + a[2]) + (b[0] + b[2]), s2 = (a[1] + a[3]) + (b[1] + b[3]); const float mu = s1 * (1.f / 1024.f); const float var = s2 * (1.f / 1024.f) - mu * mu;
;             r.mu[ai][m] = mu; r.rs[ai][m] = __builtin_amdgcn_rsqf(__builtin_fmaxf(var, 0.f) + 1e-5f); } }
;     __device__ __forceinline__ void operator()(const f32x4 (&acc)[2][2][4][2], const Unit& u, int wr, int wc, int fr_in, int fq_in) const {
;     ...
;         const int row0 = u.pm * BM + wr * 64 + fr; const int t = u.pn >> 2; bf16_t* base = t ? V : U;
;         const int col0 = (u.pn & 3) * BM + wc * 32 + 8 * fq, n0 = u.pn * BM + wc * 32 + 8 * fq;
;         RowStats rst; load_row_stats(sp, row0, rst);
; #pragma unroll
;         for (int bj = 0; bj < 2; ++bj) { f32x4 csv[2], cbv[2];
; #pragma unroll
;             for (int n = 0; n < 2; ++n) { csv[n] = *(const f32x4*)(cs + n0 + bj * HALF + 4 * n); cbv[n] = *(const f32x4*)(cb + n0 + bj * HALF + 4 * n) + *(const f32x4*)(bias + n0 + bj * HALF + 4 * n); }
; #pragma unroll
;             for (int ai = 0; ai < 2; ++ai)
; #pragma unroll
;                 for (int m = 0; m < 4; ++m) { bf16_t* rowp = base + (size_t)(row0 + ai * HALF + m * 16) * 1024 + col0 + bj * HALF;
;                     f32x4 v0 = ln_fix(acc[ai][bj][m][0], rst.mu[ai][m], rst.rs[ai][m], csv[0], cbv[0]), v1 = ln_fix(acc[ai][bj][m][1], rst.mu[ai][m], rst.rs[ai][m], csv[1], cbv[1]);
.Lrs5_skip:
	s_waitcnt vmcnt(0) lgkmcnt(0)
	s_barrier
	v_and_b32_e32 v126, 0xff, v222
	v_lshlrev_b32_e32 v126, 3, v126
	v_add_u32_e32 v126, 0x22400, v126
	ds_read_b64 v[196:197], v126
	ds_read_b64 v[192:193], v126 offset:128
	ds_read_b64 v[188:189], v126 offset:256
	ds_read_b64 v[184:185], v126 offset:384
	ds_read_b64 v[180:181], v126 offset:1024
	ds_read_b64 v[176:177], v126 offset:1152
	ds_read_b64 v[172:173], v126 offset:1280
	ds_read_b64 v[168:169], v126 offset:1408
	s_cmp_lg_u32 s99, 0
	s_waitcnt lgkmcnt(0)
	v_add_u32_e32 v220, 16, v222
	v_ashrrev_i32_e32 v221, 31, v220
	v_add_u32_e32 v218, 32, v222
	v_ashrrev_i32_e32 v219, 31, v218
	v_add_u32_e32 v216, 48, v222
	v_ashrrev_i32_e32 v217, 31, v216
	v_add_u32_e32 v214, 0x80, v222
	v_ashrrev_i32_e32 v215, 31, v214
	v_add_u32_e32 v212, 0x90, v222
	v_ashrrev_i32_e32 v213, 31, v212
	v_add_u32_e32 v210, 0xa0, v222
	v_ashrrev_i32_e32 v211, 31, v210
	v_add_u32_e32 v208, 0xb0, v222
	v_ashrrev_i32_e32 v209, 31, v208
	v_lshlrev_b32_e32 v120, 3, v121
	s_mov_b32 s10, 0xbc00000
	s_cselect_b32 s10, s10, 0xfc00000
	s_add_u32 s10, s4, s10
	s_addc_u32 s11, s5, 0
	s_lshl_b32 s12, s18, 8
	s_and_b32 s13, s12, 0x300
	s_or_b32 s13, s13, s16
	s_or_b32 s12, s12, s16
	v_add_u32_e32 v122, s13, v120
	v_add_u32_e32 v120, s12, v120
	v_ashrrev_i32_e32 v123, 31, v122
	v_lshl_add_u64 v[202:203], v[122:123], 1, s[10:11]
	s_mov_b64 s[10:11], -1
	s_andn2_b64 vcc, exec, s[38:39]
	v_fma_f32 v121, -v196, v196, v197
	v_max_f32_e32 v121, 0, v121
	v_add_f32_e32 v121, 0x3727c5ac, v121
	v_rsq_f32_e32 v198, v121
	v_fma_f32 v121, -v192, v192, v193
	v_max_f32_e32 v121, 0, v121
	v_add_f32_e32 v121, 0x3727c5ac, v121
	v_rsq_f32_e32 v194, v121
	v_fma_f32 v121, -v188, v188, v189
	v_max_f32_e32 v121, 0, v121
	v_add_f32_e32 v121, 0x3727c5ac, v121
	v_rsq_f32_e32 v190, v121
	v_fma_f32 v121, -v184, v184, v185
	v_max_f32_e32 v121, 0, v121
	v_add_f32_e32 v121, 0x3727c5ac, v121
	v_rsq_f32_e32 v186, v121
	v_fma_f32 v121, -v180, v180, v181
	v_max_f32_e32 v121, 0, v121
	v_add_f32_e32 v121, 0x3727c5ac, v121
	v_rsq_f32_e32 v182, v121
	v_fma_f32 v121, -v176, v176, v177
	v_max_f32_e32 v121, 0, v121
	v_add_f32_e32 v121, 0x3727c5ac, v121
	v_rsq_f32_e32 v178, v121
	v_fma_f32 v121, -v172, v172, v173
	v_max_f32_e32 v121, 0, v121
	v_add_f32_e32 v121, 0x3727c5ac, v121
	v_rsq_f32_e32 v174, v121
	s_nop 0
	v_fma_f32 v121, -v168, v168, v169
	v_max_f32_e32 v121, 0, v121
	v_add_f32_e32 v121, 0x3727c5ac, v121
	v_rsq_f32_e32 v170, v121
	v_ashrrev_i32_e32 v121, 31, v120
	v_lshlrev_b64 v[120:121], 2, v[120:121]
	v_lshl_add_u64 v[204:205], s[26:27], 0, v[120:121]
	v_lshl_add_u64 v[206:207], s[28:29], 0, v[120:121]
	s_waitcnt lgkmcnt(0)
	v_lshl_add_u64 v[200:201], s[6:7], 0, v[120:121]
	global_load_dwordx4 v[120:123], v[204:205], off offset:16
	global_load_dwordx4 v[124:127], v[204:205], off
	global_load_dwordx4 v[136:139], v[206:207], off offset:16
	global_load_dwordx4 v[144:147], v[206:207], off
	global_load_dwordx4 v[140:143], v[200:201], off offset:16
	global_load_dwordx4 v[148:151], v[200:201], off
	s_waitcnt vmcnt(5)
	v_pk_fma_f32 v[128:129], v[196:197], v[120:121], v[128:129] op_sel_hi:[0,1,1] neg_lo:[1,0,0] neg_hi:[1,0,0]
	s_waitcnt vmcnt(4)
	v_pk_fma_f32 v[132:133], v[196:197], v[124:125], v[132:133] op_sel_hi:[0,1,1] neg_lo:[1,0,0] neg_hi:[1,0,0]
	v_pk_fma_f32 v[134:135], v[196:197], v[126:127], v[134:135] op_sel_hi:[0,1,1] neg_lo:[1,0,0] neg_hi:[1,0,0]
	v_pk_fma_f32 v[130:131], v[196:197], v[122:123], v[130:131] op_sel_hi:[0,1,1] neg_lo:[1,0,0] neg_hi:[1,0,0]
	s_waitcnt vmcnt(1)
	v_pk_add_f32 v[138:139], v[138:139], v[142:143]
	s_waitcnt vmcnt(0)
	v_pk_add_f32 v[144:145], v[144:145], v[148:149]
	v_pk_add_f32 v[136:137], v[136:137], v[140:141]
	v_pk_fma_f32 v[132:133], v[198:199], v[132:133], v[144:145] op_sel_hi:[0,1,1]
	v_mul_f32_e32 v142, 0x3d372713, v132
	v_mul_f32_e32 v142, v132, v142
	v_fma_f32 v142, v132, v142, v132
	v_mul_f32_e32 v142, 0x3f4c422a, v142
	v_add_f32_e32 v142, v142, v142
	v_mul_f32_e32 v142, 0xbfb8aa3b, v142
	v_exp_f32_e32 v142, v142
	v_pk_fma_f32 v[128:129], v[198:199], v[128:129], v[136:137] op_sel_hi:[0,1,1]
	v_pk_add_f32 v[146:147], v[146:147], v[150:151]
	v_pk_fma_f32 v[130:131], v[198:199], v[130:131], v[138:139] op_sel_hi:[0,1,1]
	v_add_f32_e32 v142, 1.0, v142
	v_rcp_f32_e32 v142, v142
	v_pk_fma_f32 v[134:135], v[198:199], v[134:135], v[146:147] op_sel_hi:[0,1,1]
	v_lshlrev_b64 v[140:141], 11, v[222:223]
	v_pk_fma_f32 v[116:117], v[192:193], v[124:125], v[116:117] op_sel_hi:[0,1,1] neg_lo:[1,0,0] neg_hi:[1,0,0]
	v_mul_f32_e32 v132, v132, v142
	v_mul_f32_e32 v142, 0x3d372713, v128
	v_mul_f32_e32 v142, v128, v142
	v_fma_f32 v142, v128, v142, v128
	v_mul_f32_e32 v142, 0x3f4c422a, v142
	v_add_f32_e32 v142, v142, v142
	v_mul_f32_e32 v142, 0xbfb8aa3b, v142
	v_exp_f32_e32 v142, v142
	v_pk_fma_f32 v[116:117], v[194:195], v[116:117], v[144:145] op_sel_hi:[0,1,1]
	v_pk_fma_f32 v[112:113], v[192:193], v[120:121], v[112:113] op_sel_hi:[0,1,1] neg_lo:[1,0,0] neg_hi:[1,0,0]
	v_pk_fma_f32 v[112:113], v[194:195], v[112:113], v[136:137] op_sel_hi:[0,1,1]
	v_add_f32_e32 v142, 1.0, v142
	v_rcp_f32_e32 v142, v142
	v_pk_fma_f32 v[118:119], v[192:193], v[126:127], v[118:119] op_sel_hi:[0,1,1] neg_lo:[1,0,0] neg_hi:[1,0,0]
	v_pk_fma_f32 v[118:119], v[194:195], v[118:119], v[146:147] op_sel_hi:[0,1,1]
	v_pk_fma_f32 v[114:115], v[192:193], v[122:123], v[114:115] op_sel_hi:[0,1,1] neg_lo:[1,0,0] neg_hi:[1,0,0]
	v_mul_f32_e32 v142, v128, v142
	v_mul_f32_e32 v128, 0x3d372713, v133
	v_mul_f32_e32 v128, v133, v128
	v_fma_f32 v128, v133, v128, v133
	v_mul_f32_e32 v128, 0x3f4c422a, v128
	v_add_f32_e32 v128, v128, v128
	v_mul_f32_e32 v128, 0xbfb8aa3b, v128
; __device__ __forceinline__ unsigned cvt_pk_bf16(float lo, float hi) { unsigned r; asm("v_cvt_pk_bf16_f32 %0, %1, %2" : "=v"(r) : "v"(lo), "v"(hi)); return r; }
; __device__ __forceinline__ float gelu_tanh(float v) { const float u = 0.7978845608028654f * (v + 0.044715f * v * v * v); return v * fast_sigmoid(2.0f * u); }
; __device__ __forceinline__ f32x4 ln_fix(const f32x4& a, float mu, float rs, const f32x4& cs, const f32x4& cb) { return (a - cs * mu) * rs + cb; }
; __device__ __forceinline__ float fast_sigmoid(float v) { return __builtin_amdgcn_rcpf(1.0f + __builtin_amdgcn_exp2f(-1.4426950408889634f * v)); }
;     __device__ __forceinline__ void operator()(const f32x4 (&acc)[2][2][4][2], const Unit& u, int wr, int wc, int fr_in, int fq_in) const {
;     ...
;                 for (int m = 0; m < 4; ++m) { bf16_t* rowp = base + (size_t)(row0 + ai * HALF + m * 16) * 1024 + col0 + bj * HALF;
;                     f32x4 v0 = ln_fix(acc[ai][bj][m][0], rst.mu[ai][m], rst.rs[ai][m], csv[0], cbv[0]), v1 = ln_fix(acc[ai][bj][m][1], rst.mu[ai][m], rst.rs[ai][m], csv[1], cbv[1]);
; #pragma unroll
;                     for (int j = 0; j < 4; ++j) { v0[j] = gelu_tanh(v0[j]); v1[j] = gelu_tanh(v1[j]); }
;                     u32x4 w; w.x = cvt_pk_bf16(v0[0], v0[1]); w.y = cvt_pk_bf16(v0[2], v0[3]); w.z = cvt_pk_bf16(v1[0], v1[1]); w.w = cvt_pk_bf16(v1[2], v1[3]);
;                     *(u32x4*)rowp = w; } }
	v_exp_f32_e32 v128, v128
	v_pk_fma_f32 v[114:115], v[194:195], v[114:115], v[138:139] op_sel_hi:[0,1,1]
	v_pk_fma_f32 v[108:109], v[188:189], v[124:125], v[108:109] op_sel_hi:[0,1,1] neg_lo:[1,0,0] neg_hi:[1,0,0]
	v_pk_fma_f32 v[108:109], v[190:191], v[108:109], v[144:145] op_sel_hi:[0,1,1]
	v_add_f32_e32 v128, 1.0, v128
	v_rcp_f32_e32 v128, v128
	v_pk_fma_f32 v[104:105], v[188:189], v[120:121], v[104:105] op_sel_hi:[0,1,1] neg_lo:[1,0,0] neg_hi:[1,0,0]
	v_pk_fma_f32 v[104:105], v[190:191], v[104:105], v[136:137] op_sel_hi:[0,1,1]
	v_pk_fma_f32 v[110:111], v[188:189], v[126:127], v[110:111] op_sel_hi:[0,1,1] neg_lo:[1,0,0] neg_hi:[1,0,0]
	v_mul_f32_e32 v133, v133, v128
	v_mul_f32_e32 v128, 0x3d372713, v129
	v_mul_f32_e32 v128, v129, v128
	v_fma_f32 v128, v129, v128, v129
	v_mul_f32_e32 v128, 0x3f4c422a, v128
	v_add_f32_e32 v128, v128, v128
	v_mul_f32_e32 v128, 0xbfb8aa3b, v128
	v_exp_f32_e32 v128, v128
	v_pk_fma_f32 v[110:111], v[190:191], v[110:111], v[146:147] op_sel_hi:[0,1,1]
	v_pk_fma_f32 v[106:107], v[188:189], v[122:123], v[106:107] op_sel_hi:[0,1,1] neg_lo:[1,0,0] neg_hi:[1,0,0]
	v_pk_fma_f32 v[106:107], v[190:191], v[106:107], v[138:139] op_sel_hi:[0,1,1]
	v_add_f32_e32 v128, 1.0, v128
	v_rcp_f32_e32 v128, v128
	v_pk_fma_f32 v[100:101], v[184:185], v[124:125], v[100:101] op_sel_hi:[0,1,1] neg_lo:[1,0,0] neg_hi:[1,0,0]
	v_pk_fma_f32 v[100:101], v[186:187], v[100:101], v[144:145] op_sel_hi:[0,1,1]
	v_pk_fma_f32 v[96:97], v[184:185], v[120:121], v[96:97] op_sel_hi:[0,1,1] neg_lo:[1,0,0] neg_hi:[1,0,0]
	v_mul_f32_e32 v143, v129, v128
	v_mul_f32_e32 v128, 0x3d372713, v134
	v_mul_f32_e32 v128, v134, v128
	v_fma_f32 v128, v134, v128, v134
	v_mul_f32_e32 v128, 0x3f4c422a, v128
	v_add_f32_e32 v128, v128, v128
	v_mul_f32_e32 v128, 0xbfb8aa3b, v128
	v_exp_f32_e32 v128, v128
	v_pk_fma_f32 v[96:97], v[186:187], v[96:97], v[136:137] op_sel_hi:[0,1,1]
	v_pk_fma_f32 v[102:103], v[184:185], v[126:127], v[102:103] op_sel_hi:[0,1,1] neg_lo:[1,0,0] neg_hi:[1,0,0]
	v_pk_fma_f32 v[102:103], v[186:187], v[102:103], v[146:147] op_sel_hi:[0,1,1]
	v_add_f32_e32 v128, 1.0, v128
	v_rcp_f32_e32 v128, v128
	v_pk_fma_f32 v[98:99], v[184:185], v[122:123], v[98:99] op_sel_hi:[0,1,1] neg_lo:[1,0,0] neg_hi:[1,0,0]
	v_pk_fma_f32 v[98:99], v[186:187], v[98:99], v[138:139] op_sel_hi:[0,1,1]
	v_pk_fma_f32 v[92:93], v[180:181], v[124:125], v[92:93] op_sel_hi:[0,1,1] neg_lo:[1,0,0] neg_hi:[1,0,0]
	v_mul_f32_e32 v134, v134, v128
	v_mul_f32_e32 v128, 0x3d372713, v130
	v_mul_f32_e32 v128, v130, v128
	v_fma_f32 v128, v130, v128, v130
	v_mul_f32_e32 v128, 0x3f4c422a, v128
	v_add_f32_e32 v128, v128, v128
	v_mul_f32_e32 v128, 0xbfb8aa3b, v128
	v_exp_f32_e32 v128, v128
	v_pk_fma_f32 v[92:93], v[92:93], v[182:183], v[144:145] op_sel_hi:[1,0,1]
	v_pk_fma_f32 v[88:89], v[180:181], v[120:121], v[88:89] op_sel_hi:[0,1,1] neg_lo:[1,0,0] neg_hi:[1,0,0]
	v_pk_fma_f32 v[88:89], v[182:183], v[88:89], v[136:137] op_sel_hi:[0,1,1]
	v_add_f32_e32 v128, 1.0, v128
	v_rcp_f32_e32 v128, v128
	v_pk_fma_f32 v[94:95], v[180:181], v[126:127], v[94:95] op_sel_hi:[0,1,1] neg_lo:[1,0,0] neg_hi:[1,0,0]
	v_pk_fma_f32 v[94:95], v[94:95], v[182:183], v[146:147] op_sel_hi:[1,0,1]
	v_pk_fma_f32 v[90:91], v[180:181], v[122:123], v[90:91] op_sel_hi:[0,1,1] neg_lo:[1,0,0] neg_hi:[1,0,0]
	v_mul_f32_e32 v148, v130, v128
	v_mul_f32_e32 v128, 0x3d372713, v135
	v_mul_f32_e32 v128, v135, v128
	v_fma_f32 v128, v135, v128, v135
	v_mul_f32_e32 v128, 0x3f4c422a, v128
	v_add_f32_e32 v128, v128, v128
	v_mul_f32_e32 v128, 0xbfb8aa3b, v128
	v_exp_f32_e32 v128, v128
	v_cvt_pk_bf16_f32 v130, v132, v133
	v_cvt_pk_bf16_f32 v132, v142, v143
	v_pk_fma_f32 v[90:91], v[182:183], v[90:91], v[138:139] op_sel_hi:[0,1,1]
	v_add_f32_e32 v128, 1.0, v128
	v_rcp_f32_e32 v128, v128
	v_pk_fma_f32 v[80:81], v[176:177], v[120:121], v[80:81] op_sel_hi:[0,1,1] neg_lo:[1,0,0] neg_hi:[1,0,0]
	v_pk_fma_f32 v[80:81], v[80:81], v[178:179], v[136:137] op_sel_hi:[1,0,1]
	v_pk_fma_f32 v[82:83], v[176:177], v[122:123], v[82:83] op_sel_hi:[0,1,1] neg_lo:[1,0,0] neg_hi:[1,0,0]
	v_mul_f32_e32 v135, v135, v128
	v_mul_f32_e32 v128, 0x3d372713, v131
	v_mul_f32_e32 v128, v131, v128
	v_fma_f32 v128, v131, v128, v131
	v_mul_f32_e32 v128, 0x3f4c422a, v128
	v_add_f32_e32 v128, v128, v128
	v_mul_f32_e32 v128, 0xbfb8aa3b, v128
	v_exp_f32_e32 v128, v128
	v_pk_fma_f32 v[82:83], v[82:83], v[178:179], v[138:139] op_sel_hi:[1,0,1]
	v_pk_fma_f32 v[76:77], v[124:125], v[172:173], v[76:77] op_sel_hi:[1,0,1] neg_lo:[1,0,0] neg_hi:[1,0,0]
	v_pk_fma_f32 v[72:73], v[172:173], v[120:121], v[72:73] op_sel_hi:[0,1,1] neg_lo:[1,0,0] neg_hi:[1,0,0]
	v_add_f32_e32 v128, 1.0, v128
	v_rcp_f32_e32 v128, v128
	v_pk_fma_f32 v[76:77], v[76:77], v[174:175], v[144:145] op_sel_hi:[1,0,1]
	v_pk_fma_f32 v[72:73], v[72:73], v[174:175], v[136:137] op_sel_hi:[1,0,1]
	v_pk_fma_f32 v[74:75], v[172:173], v[122:123], v[74:75] op_sel_hi:[0,1,1] neg_lo:[1,0,0] neg_hi:[1,0,0]
	v_mul_f32_e32 v149, v131, v128
	v_lshl_add_u64 v[128:129], v[202:203], 0, v[140:141]
	v_cvt_pk_bf16_f32 v131, v134, v135
	v_cvt_pk_bf16_f32 v133, v148, v149
	global_store_dwordx4 v[128:129], v[130:133], off sc1
	v_pk_fma_f32 v[74:75], v[74:75], v[174:175], v[138:139] op_sel_hi:[1,0,1]
	v_pk_fma_f32 v[68:69], v[124:125], v[168:169], v[68:69] op_sel_hi:[1,0,1] neg_lo:[1,0,0] neg_hi:[1,0,0]
	v_mul_f32_e32 v132, 0x3d372713, v116
	v_mul_f32_e32 v132, v116, v132
	v_fma_f32 v132, v116, v132, v116
	v_mul_f32_e32 v132, 0x3f4c422a, v132
	v_add_f32_e32 v132, v132, v132
	v_mul_f32_e32 v132, 0xbfb8aa3b, v132
	v_exp_f32_e32 v132, v132
	v_lshlrev_b64 v[130:131], 11, v[220:221]
	v_pk_fma_f32 v[68:69], v[68:69], v[170:171], v[144:145] op_sel_hi:[1,0,1]
; __device__ __forceinline__ unsigned cvt_pk_bf16(float lo, float hi) { unsigned r; asm("v_cvt_pk_bf16_f32 %0, %1, %2" : "=v"(r) : "v"(lo), "v"(hi)); return r; }
; __device__ __forceinline__ float gelu_tanh(float v) { const float u = 0.7978845608028654f * (v + 0.044715f * v * v * v); return v * fast_sigmoid(2.0f * u); }
; __device__ __forceinline__ f32x4 ln_fix(const f32x4& a, float mu, float rs, const f32x4& cs, const f32x4& cb) { return (a - cs * mu) * rs + cb; }
; __device__ __forceinline__ float fast_sigmoid(float v) { return __builtin_amdgcn_rcpf(1.0f + __builtin_amdgcn_exp2f(-1.4426950408889634f * v)); }
;     __device__ __forceinline__ void operator()(const f32x4 (&acc)[2][2][4][2], const Unit& u, int wr, int wc, int fr_in, int fq_in) const {
;     ...
;                 for (int m = 0; m < 4; ++m) { bf16_t* rowp = base + (size_t)(row0 + ai * HALF + m * 16) * 1024 + col0 + bj * HALF;
;                     f32x4 v0 = ln_fix(acc[ai][bj][m][0], rst.mu[ai][m], rst.rs[ai][m], csv[0], cbv[0]), v1 = ln_fix(acc[ai][bj][m][1], rst.mu[ai][m], rst.rs[ai][m], csv[1], cbv[1]);
; #pragma unroll
;                     for (int j = 0; j < 4; ++j) { v0[j] = gelu_tanh(v0[j]); v1[j] = gelu_tanh(v1[j]); }
;                     u32x4 w; w.x = cvt_pk_bf16(v0[0], v0[1]); w.y = cvt_pk_bf16(v0[2], v0[3]); w.z = cvt_pk_bf16(v1[0], v1[1]); w.w = cvt_pk_bf16(v1[2], v1[3]);
;                     *(u32x4*)rowp = w; } }
	v_pk_fma_f32 v[64:65], v[120:121], v[168:169], v[64:65] op_sel_hi:[1,0,1] neg_lo:[1,0,0] neg_hi:[1,0,0]
	v_add_f32_e32 v132, 1.0, v132
	v_rcp_f32_e32 v132, v132
	v_pk_fma_f32 v[64:65], v[64:65], v[170:171], v[136:137] op_sel_hi:[1,0,1]
	v_mul_f32_e32 v116, v116, v132
	v_mul_f32_e32 v132, 0x3d372713, v112
	v_mul_f32_e32 v132, v112, v132
	v_fma_f32 v132, v112, v132, v112
	v_mul_f32_e32 v132, 0x3f4c422a, v132
	v_add_f32_e32 v132, v132, v132
	v_mul_f32_e32 v132, 0xbfb8aa3b, v132
	v_exp_f32_e32 v132, v132
	s_nop 0
	v_add_f32_e32 v132, 1.0, v132
	v_rcp_f32_e32 v132, v132
	s_nop 0
	v_mul_f32_e32 v132, v112, v132
	v_mul_f32_e32 v112, 0x3d372713, v117
	v_mul_f32_e32 v112, v117, v112
	v_fma_f32 v112, v117, v112, v117
	v_mul_f32_e32 v112, 0x3f4c422a, v112
	v_add_f32_e32 v112, v112, v112
	v_mul_f32_e32 v112, 0xbfb8aa3b, v112
	v_exp_f32_e32 v112, v112
	s_nop 0
	v_add_f32_e32 v112, 1.0, v112
	v_rcp_f32_e32 v112, v112
	s_nop 0
	v_mul_f32_e32 v117, v117, v112
	v_mul_f32_e32 v112, 0x3d372713, v113
	v_mul_f32_e32 v112, v113, v112
	v_fma_f32 v112, v113, v112, v113
	v_mul_f32_e32 v112, 0x3f4c422a, v112
	v_add_f32_e32 v112, v112, v112
	v_mul_f32_e32 v112, 0xbfb8aa3b, v112
	v_exp_f32_e32 v112, v112
	s_nop 0
	v_add_f32_e32 v112, 1.0, v112
	v_rcp_f32_e32 v112, v112
	s_nop 0
	v_mul_f32_e32 v133, v113, v112
	v_mul_f32_e32 v112, 0x3d372713, v118
	v_mul_f32_e32 v112, v118, v112
	v_fma_f32 v112, v118, v112, v118
	v_mul_f32_e32 v112, 0x3f4c422a, v112
	v_add_f32_e32 v112, v112, v112
	v_mul_f32_e32 v112, 0xbfb8aa3b, v112
	v_exp_f32_e32 v112, v112
	s_nop 0
	v_add_f32_e32 v112, 1.0, v112
	v_rcp_f32_e32 v112, v112
	s_nop 0
	v_mul_f32_e32 v118, v118, v112
	v_mul_f32_e32 v112, 0x3d372713, v114
	v_mul_f32_e32 v112, v114, v112
	v_fma_f32 v112, v114, v112, v114
	v_mul_f32_e32 v112, 0x3f4c422a, v112
	v_add_f32_e32 v112, v112, v112
	v_mul_f32_e32 v112, 0xbfb8aa3b, v112
	v_exp_f32_e32 v112, v112
	s_nop 0
	v_add_f32_e32 v112, 1.0, v112
	v_rcp_f32_e32 v112, v112
	s_nop 0
	v_mul_f32_e32 v134, v114, v112
	v_mul_f32_e32 v112, 0x3d372713, v119
	v_mul_f32_e32 v112, v119, v112
	v_fma_f32 v112, v119, v112, v119
	v_mul_f32_e32 v112, 0x3f4c422a, v112
	v_add_f32_e32 v112, v112, v112
	v_mul_f32_e32 v112, 0xbfb8aa3b, v112
	v_exp_f32_e32 v112, v112
	v_cvt_pk_bf16_f32 v114, v116, v117
	v_cvt_pk_bf16_f32 v116, v132, v133
	s_nop 0
	v_add_f32_e32 v112, 1.0, v112
	v_rcp_f32_e32 v112, v112
	s_nop 0
	v_mul_f32_e32 v119, v119, v112
	v_mul_f32_e32 v112, 0x3d372713, v115
	v_mul_f32_e32 v112, v115, v112
	v_fma_f32 v112, v115, v112, v115
	v_mul_f32_e32 v112, 0x3f4c422a, v112
	v_add_f32_e32 v112, v112, v112
	v_mul_f32_e32 v112, 0xbfb8aa3b, v112
	v_exp_f32_e32 v112, v112
	s_nop 0
	v_add_f32_e32 v112, 1.0, v112
	v_rcp_f32_e32 v112, v112
	s_nop 0
	v_mul_f32_e32 v135, v115, v112
	v_lshl_add_u64 v[112:113], v[202:203], 0, v[130:131]
	v_cvt_pk_bf16_f32 v115, v118, v119
	v_cvt_pk_bf16_f32 v117, v134, v135
	global_store_dwordx4 v[112:113], v[114:117], off sc1
	s_nop 1
	v_mul_f32_e32 v116, 0x3d372713, v108
	v_mul_f32_e32 v116, v108, v116
	v_fma_f32 v116, v108, v116, v108
	v_mul_f32_e32 v116, 0x3f4c422a, v116
	v_add_f32_e32 v116, v116, v116
	v_mul_f32_e32 v116, 0xbfb8aa3b, v116
	v_exp_f32_e32 v116, v116
	v_lshlrev_b64 v[114:115], 11, v[218:219]
	v_add_f32_e32 v116, 1.0, v116
	v_rcp_f32_e32 v116, v116
	s_nop 0
	v_mul_f32_e32 v108, v108, v116
	v_mul_f32_e32 v116, 0x3d372713, v104
	v_mul_f32_e32 v116, v104, v116
	v_fma_f32 v116, v104, v116, v104
	v_mul_f32_e32 v116, 0x3f4c422a, v116
	v_add_f32_e32 v116, v116, v116
	v_mul_f32_e32 v116, 0xbfb8aa3b, v116
	v_exp_f32_e32 v116, v116
	s_nop 0
	v_add_f32_e32 v116, 1.0, v116
	v_rcp_f32_e32 v116, v116
	s_nop 0
	v_mul_f32_e32 v116, v104, v116
	v_mul_f32_e32 v104, 0x3d372713, v109
	v_mul_f32_e32 v104, v109, v104
	v_fma_f32 v104, v109, v104, v109
	v_mul_f32_e32 v104, 0x3f4c422a, v104
	v_add_f32_e32 v104, v104, v104
	v_mul_f32_e32 v104, 0xbfb8aa3b, v104
	v_exp_f32_e32 v104, v104
	s_nop 0
	v_add_f32_e32 v104, 1.0, v104
	v_rcp_f32_e32 v104, v104
	s_nop 0
	v_mul_f32_e32 v109, v109, v104
	v_mul_f32_e32 v104, 0x3d372713, v105
	v_mul_f32_e32 v104, v105, v104
	v_fma_f32 v104, v105, v104, v105
	v_mul_f32_e32 v104, 0x3f4c422a, v104
	v_add_f32_e32 v104, v104, v104
	v_mul_f32_e32 v104, 0xbfb8aa3b, v104
	v_exp_f32_e32 v104, v104
	s_nop 0
	v_add_f32_e32 v104, 1.0, v104
	v_rcp_f32_e32 v104, v104
	s_nop 0
	v_mul_f32_e32 v117, v105, v104
	v_mul_f32_e32 v104, 0x3d372713, v110
	v_mul_f32_e32 v104, v110, v104
	v_fma_f32 v104, v110, v104, v110
	v_mul_f32_e32 v104, 0x3f4c422a, v104
	v_add_f32_e32 v104, v104, v104
	v_mul_f32_e32 v104, 0xbfb8aa3b, v104
	v_exp_f32_e32 v104, v104
	s_nop 0
	v_add_f32_e32 v104, 1.0, v104
	v_rcp_f32_e32 v104, v104
	s_nop 0
	v_mul_f32_e32 v110, v110, v104
	v_mul_f32_e32 v104, 0x3d372713, v106
	v_mul_f32_e32 v104, v106, v104
	v_fma_f32 v104, v106, v104, v106
	v_mul_f32_e32 v104, 0x3f4c422a, v104
	v_add_f32_e32 v104, v104, v104
	v_mul_f32_e32 v104, 0xbfb8aa3b, v104
	v_exp_f32_e32 v104, v104
	s_nop 0
	v_add_f32_e32 v104, 1.0, v104
	v_rcp_f32_e32 v104, v104
	s_nop 0
	v_mul_f32_e32 v118, v106, v104
	v_mul_f32_e32 v104, 0x3d372713, v111
	v_mul_f32_e32 v104, v111, v104
	v_fma_f32 v104, v111, v104, v111
	v_mul_f32_e32 v104, 0x3f4c422a, v104
	v_add_f32_e32 v104, v104, v104
	v_mul_f32_e32 v104, 0xbfb8aa3b, v104
	v_exp_f32_e32 v104, v104
	v_cvt_pk_bf16_f32 v106, v108, v109
	v_cvt_pk_bf16_f32 v108, v116, v117
	s_nop 0
	v_add_f32_e32 v104, 1.0, v104
	v_rcp_f32_e32 v104, v104
	s_nop 0
	v_mul_f32_e32 v111, v111, v104
	v_mul_f32_e32 v104, 0x3d372713, v107
	v_mul_f32_e32 v104, v107, v104
	v_fma_f32 v104, v107, v104, v107
	v_mul_f32_e32 v104, 0x3f4c422a, v104
	v_add_f32_e32 v104, v104, v104
; __device__ __forceinline__ unsigned cvt_pk_bf16(float lo, float hi) { unsigned r; asm("v_cvt_pk_bf16_f32 %0, %1, %2" : "=v"(r) : "v"(lo), "v"(hi)); return r; }
; __device__ __forceinline__ float gelu_tanh(float v) { const float u = 0.7978845608028654f * (v + 0.044715f * v * v * v); return v * fast_sigmoid(2.0f * u); }
; __device__ __forceinline__ f32x4 ln_fix(const f32x4& a, float mu, float rs, const f32x4& cs, const f32x4& cb) { return (a - cs * mu) * rs + cb; }
; __device__ __forceinline__ float fast_sigmoid(float v) { return __builtin_amdgcn_rcpf(1.0f + __builtin_amdgcn_exp2f(-1.4426950408889634f * v)); }
;     __device__ __forceinline__ void operator()(const f32x4 (&acc)[2][2][4][2], const Unit& u, int wr, int wc, int fr_in, int fq_in) const {
;     ...
;                 for (int m = 0; m < 4; ++m) { bf16_t* rowp = base + (size_t)(row0 + ai * HALF + m * 16) * 1024 + col0 + bj * HALF;
;                     f32x4 v0 = ln_fix(acc[ai][bj][m][0], rst.mu[ai][m], rst.rs[ai][m], csv[0], cbv[0]), v1 = ln_fix(acc[ai][bj][m][1], rst.mu[ai][m], rst.rs[ai][m], csv[1], cbv[1]);
; #pragma unroll
;                     for (int j = 0; j < 4; ++j) { v0[j] = gelu_tanh(v0[j]); v1[j] = gelu_tanh(v1[j]); }
;                     u32x4 w; w.x = cvt_pk_bf16(v0[0], v0[1]); w.y = cvt_pk_bf16(v0[2], v0[3]); w.z = cvt_pk_bf16(v1[0], v1[1]); w.w = cvt_pk_bf16(v1[2], v1[3]);
;                     *(u32x4*)rowp = w; } }
	v_mul_f32_e32 v104, 0xbfb8aa3b, v104
	v_exp_f32_e32 v104, v104
	s_nop 0
	v_add_f32_e32 v104, 1.0, v104
	v_rcp_f32_e32 v104, v104
	s_nop 0
	v_mul_f32_e32 v119, v107, v104
	v_lshl_add_u64 v[104:105], v[202:203], 0, v[114:115]
	v_cvt_pk_bf16_f32 v107, v110, v111
	v_cvt_pk_bf16_f32 v109, v118, v119
	global_store_dwordx4 v[104:105], v[106:109], off sc1
	s_nop 1
	v_mul_f32_e32 v108, 0x3d372713, v100
	v_mul_f32_e32 v108, v100, v108
	v_fma_f32 v108, v100, v108, v100
	v_mul_f32_e32 v108, 0x3f4c422a, v108
	v_add_f32_e32 v108, v108, v108
	v_mul_f32_e32 v108, 0xbfb8aa3b, v108
	v_exp_f32_e32 v108, v108
	v_lshlrev_b64 v[106:107], 11, v[216:217]
	v_add_f32_e32 v108, 1.0, v108
	v_rcp_f32_e32 v108, v108
	s_nop 0
	v_mul_f32_e32 v100, v100, v108
	v_mul_f32_e32 v108, 0x3d372713, v96
	v_mul_f32_e32 v108, v96, v108
	v_fma_f32 v108, v96, v108, v96
	v_mul_f32_e32 v108, 0x3f4c422a, v108
	v_add_f32_e32 v108, v108, v108
	v_mul_f32_e32 v108, 0xbfb8aa3b, v108
	v_exp_f32_e32 v108, v108
	s_nop 0
	v_add_f32_e32 v108, 1.0, v108
	v_rcp_f32_e32 v108, v108
	s_nop 0
	v_mul_f32_e32 v108, v96, v108
	v_mul_f32_e32 v96, 0x3d372713, v101
	v_mul_f32_e32 v96, v101, v96
	v_fma_f32 v96, v101, v96, v101
	v_mul_f32_e32 v96, 0x3f4c422a, v96
	v_add_f32_e32 v96, v96, v96
	v_mul_f32_e32 v96, 0xbfb8aa3b, v96
	v_exp_f32_e32 v96, v96
	s_nop 0
	v_add_f32_e32 v96, 1.0, v96
	v_rcp_f32_e32 v96, v96
	s_nop 0
	v_mul_f32_e32 v101, v101, v96
	v_mul_f32_e32 v96, 0x3d372713, v97
	v_mul_f32_e32 v96, v97, v96
	v_fma_f32 v96, v97, v96, v97
	v_mul_f32_e32 v96, 0x3f4c422a, v96
	v_add_f32_e32 v96, v96, v96
	v_mul_f32_e32 v96, 0xbfb8aa3b, v96
	v_exp_f32_e32 v96, v96
	s_nop 0
	v_add_f32_e32 v96, 1.0, v96
	v_rcp_f32_e32 v96, v96
	s_nop 0
	v_mul_f32_e32 v109, v97, v96
	v_mul_f32_e32 v96, 0x3d372713, v102
	v_mul_f32_e32 v96, v102, v96
	v_fma_f32 v96, v102, v96, v102
	v_mul_f32_e32 v96, 0x3f4c422a, v96
	v_add_f32_e32 v96, v96, v96
	v_mul_f32_e32 v96, 0xbfb8aa3b, v96
	v_exp_f32_e32 v96, v96
	s_nop 0
	v_add_f32_e32 v96, 1.0, v96
	v_rcp_f32_e32 v96, v96
	s_nop 0
	v_mul_f32_e32 v102, v102, v96
	v_mul_f32_e32 v96, 0x3d372713, v98
	v_mul_f32_e32 v96, v98, v96
	v_fma_f32 v96, v98, v96, v98
	v_mul_f32_e32 v96, 0x3f4c422a, v96
	v_add_f32_e32 v96, v96, v96
	v_mul_f32_e32 v96, 0xbfb8aa3b, v96
	v_exp_f32_e32 v96, v96
	s_nop 0
	v_add_f32_e32 v96, 1.0, v96
	v_rcp_f32_e32 v96, v96
	s_nop 0
	v_mul_f32_e32 v110, v98, v96
	v_mul_f32_e32 v96, 0x3d372713, v103
	v_mul_f32_e32 v96, v103, v96
	v_fma_f32 v96, v103, v96, v103
	v_mul_f32_e32 v96, 0x3f4c422a, v96
	v_add_f32_e32 v96, v96, v96
	v_mul_f32_e32 v96, 0xbfb8aa3b, v96
	v_exp_f32_e32 v96, v96
	v_cvt_pk_bf16_f32 v98, v100, v101
	v_cvt_pk_bf16_f32 v100, v108, v109
	s_nop 0
	v_add_f32_e32 v96, 1.0, v96
	v_rcp_f32_e32 v96, v96
	s_nop 0
	v_mul_f32_e32 v103, v103, v96
	v_mul_f32_e32 v96, 0x3d372713, v99
	v_mul_f32_e32 v96, v99, v96
	v_fma_f32 v96, v99, v96, v99
	v_mul_f32_e32 v96, 0x3f4c422a, v96
	v_add_f32_e32 v96, v96, v96
	v_mul_f32_e32 v96, 0xbfb8aa3b, v96
	v_exp_f32_e32 v96, v96
	s_nop 0
	v_add_f32_e32 v96, 1.0, v96
	v_rcp_f32_e32 v96, v96
	s_nop 0
	v_mul_f32_e32 v111, v99, v96
	v_lshl_add_u64 v[96:97], v[202:203], 0, v[106:107]
	v_cvt_pk_bf16_f32 v99, v102, v103
	v_cvt_pk_bf16_f32 v101, v110, v111
	global_store_dwordx4 v[96:97], v[98:101], off sc1
	s_nop 1
	v_mul_f32_e32 v100, 0x3d372713, v92
	v_mul_f32_e32 v100, v92, v100
	v_fma_f32 v100, v92, v100, v92
	v_mul_f32_e32 v100, 0x3f4c422a, v100
	v_add_f32_e32 v100, v100, v100
	v_mul_f32_e32 v100, 0xbfb8aa3b, v100
	v_exp_f32_e32 v100, v100
	v_lshlrev_b64 v[98:99], 11, v[214:215]
	v_add_f32_e32 v100, 1.0, v100
	v_rcp_f32_e32 v100, v100
	s_nop 0
	v_mul_f32_e32 v92, v92, v100
	v_mul_f32_e32 v100, 0x3d372713, v88
	v_mul_f32_e32 v100, v88, v100
	v_fma_f32 v100, v88, v100, v88
	v_mul_f32_e32 v100, 0x3f4c422a, v100
	v_add_f32_e32 v100, v100, v100
	v_mul_f32_e32 v100, 0xbfb8aa3b, v100
	v_exp_f32_e32 v100, v100
	s_nop 0
	v_add_f32_e32 v100, 1.0, v100
	v_rcp_f32_e32 v100, v100
	s_nop 0
	v_mul_f32_e32 v100, v88, v100
	v_mul_f32_e32 v88, 0x3d372713, v93
	v_mul_f32_e32 v88, v93, v88
	v_fma_f32 v88, v93, v88, v93
	v_mul_f32_e32 v88, 0x3f4c422a, v88
	v_add_f32_e32 v88, v88, v88
	v_mul_f32_e32 v88, 0xbfb8aa3b, v88
	v_exp_f32_e32 v88, v88
	s_nop 0
	v_add_f32_e32 v88, 1.0, v88
	v_rcp_f32_e32 v88, v88
	s_nop 0
	v_mul_f32_e32 v93, v93, v88
	v_mul_f32_e32 v88, 0x3d372713, v89
	v_mul_f32_e32 v88, v89, v88
	v_fma_f32 v88, v89, v88, v89
	v_mul_f32_e32 v88, 0x3f4c422a, v88
	v_add_f32_e32 v88, v88, v88
	v_mul_f32_e32 v88, 0xbfb8aa3b, v88
	v_exp_f32_e32 v88, v88
	s_nop 0
	v_add_f32_e32 v88, 1.0, v88
	v_rcp_f32_e32 v88, v88
	s_nop 0
	v_mul_f32_e32 v101, v89, v88
	v_mul_f32_e32 v88, 0x3d372713, v94
	v_mul_f32_e32 v88, v94, v88
	v_fma_f32 v88, v94, v88, v94
	v_mul_f32_e32 v88, 0x3f4c422a, v88
	v_add_f32_e32 v88, v88, v88
	v_mul_f32_e32 v88, 0xbfb8aa3b, v88
	v_exp_f32_e32 v88, v88
	s_nop 0
	v_add_f32_e32 v88, 1.0, v88
	v_rcp_f32_e32 v88, v88
	s_nop 0
	v_mul_f32_e32 v94, v94, v88
	v_mul_f32_e32 v88, 0x3d372713, v90
	v_mul_f32_e32 v88, v90, v88
	v_fma_f32 v88, v90, v88, v90
	v_mul_f32_e32 v88, 0x3f4c422a, v88
	v_add_f32_e32 v88, v88, v88
	v_mul_f32_e32 v88, 0xbfb8aa3b, v88
	v_exp_f32_e32 v88, v88
	s_nop 0
	v_add_f32_e32 v88, 1.0, v88
	v_rcp_f32_e32 v88, v88
	s_nop 0
	v_mul_f32_e32 v102, v90, v88
	v_mul_f32_e32 v88, 0x3d372713, v95
	v_mul_f32_e32 v88, v95, v88
	v_fma_f32 v88, v95, v88, v95
	v_mul_f32_e32 v88, 0x3f4c422a, v88
	v_add_f32_e32 v88, v88, v88
	v_mul_f32_e32 v88, 0xbfb8aa3b, v88
	v_exp_f32_e32 v88, v88
	v_cvt_pk_bf16_f32 v90, v92, v93
	v_cvt_pk_bf16_f32 v92, v100, v101
	s_nop 0
	v_add_f32_e32 v88, 1.0, v88
	v_rcp_f32_e32 v88, v88
	s_nop 0
	v_mul_f32_e32 v95, v95, v88
; __device__ __forceinline__ unsigned cvt_pk_bf16(float lo, float hi) { unsigned r; asm("v_cvt_pk_bf16_f32 %0, %1, %2" : "=v"(r) : "v"(lo), "v"(hi)); return r; }
; __device__ __forceinline__ float gelu_tanh(float v) { const float u = 0.7978845608028654f * (v + 0.044715f * v * v * v); return v * fast_sigmoid(2.0f * u); }
; __device__ __forceinline__ f32x4 ln_fix(const f32x4& a, float mu, float rs, const f32x4& cs, const f32x4& cb) { return (a - cs * mu) * rs + cb; }
; __device__ __forceinline__ float fast_sigmoid(float v) { return __builtin_amdgcn_rcpf(1.0f + __builtin_amdgcn_exp2f(-1.4426950408889634f * v)); }
;     __device__ __forceinline__ void operator()(const f32x4 (&acc)[2][2][4][2], const Unit& u, int wr, int wc, int fr_in, int fq_in) const {
;     ...
;                 for (int m = 0; m < 4; ++m) { bf16_t* rowp = base + (size_t)(row0 + ai * HALF + m * 16) * 1024 + col0 + bj * HALF;
;                     f32x4 v0 = ln_fix(acc[ai][bj][m][0], rst.mu[ai][m], rst.rs[ai][m], csv[0], cbv[0]), v1 = ln_fix(acc[ai][bj][m][1], rst.mu[ai][m], rst.rs[ai][m], csv[1], cbv[1]);
; #pragma unroll
;                     for (int j = 0; j < 4; ++j) { v0[j] = gelu_tanh(v0[j]); v1[j] = gelu_tanh(v1[j]); }
;                     u32x4 w; w.x = cvt_pk_bf16(v0[0], v0[1]); w.y = cvt_pk_bf16(v0[2], v0[3]); w.z = cvt_pk_bf16(v1[0], v1[1]); w.w = cvt_pk_bf16(v1[2], v1[3]);
;                     *(u32x4*)rowp = w; } }
	v_mul_f32_e32 v88, 0x3d372713, v91
	v_mul_f32_e32 v88, v91, v88
	v_fma_f32 v88, v91, v88, v91
	v_mul_f32_e32 v88, 0x3f4c422a, v88
	v_add_f32_e32 v88, v88, v88
	v_mul_f32_e32 v88, 0xbfb8aa3b, v88
	v_exp_f32_e32 v88, v88
	s_nop 0
	v_add_f32_e32 v88, 1.0, v88
	v_rcp_f32_e32 v88, v88
	s_nop 0
	v_mul_f32_e32 v103, v91, v88
	v_lshl_add_u64 v[88:89], v[202:203], 0, v[98:99]
	v_cvt_pk_bf16_f32 v93, v102, v103
	v_cvt_pk_bf16_f32 v91, v94, v95
	global_store_dwordx4 v[88:89], v[90:93], off sc1
	s_nop 1
	v_pk_fma_f32 v[92:93], v[124:125], v[176:177], v[84:85] op_sel_hi:[1,0,1] neg_lo:[1,0,0] neg_hi:[1,0,0]
	v_xor_b32_e32 v85, 0x80000000, v127
	v_pk_fma_f32 v[92:93], v[92:93], v[178:179], v[144:145] op_sel_hi:[1,0,1]
	v_xor_b32_e32 v84, 0x80000000, v126
	v_mul_f32_e32 v94, 0x3d372713, v92
	v_mul_f32_e32 v94, v92, v94
	v_fma_f32 v94, v92, v94, v92
	v_mul_f32_e32 v94, 0x3f4c422a, v94
	v_add_f32_e32 v94, v94, v94
	v_mul_f32_e32 v94, 0xbfb8aa3b, v94
	v_exp_f32_e32 v94, v94
	v_pk_fma_f32 v[86:87], v[84:85], v[176:177], v[86:87] op_sel_hi:[1,0,1]
	v_lshlrev_b64 v[90:91], 11, v[212:213]
	v_pk_fma_f32 v[86:87], v[86:87], v[178:179], v[146:147] op_sel_hi:[1,0,1]
	v_add_f32_e32 v94, 1.0, v94
	v_rcp_f32_e32 v94, v94
	v_pk_fma_f32 v[78:79], v[84:85], v[172:173], v[78:79] op_sel_hi:[1,0,1]
	v_pk_fma_f32 v[70:71], v[84:85], v[168:169], v[70:71] op_sel_hi:[1,0,1]
	v_pk_fma_f32 v[78:79], v[78:79], v[174:175], v[146:147] op_sel_hi:[1,0,1]
	v_mul_f32_e32 v92, v92, v94
	v_mul_f32_e32 v94, 0x3d372713, v80
	v_mul_f32_e32 v94, v80, v94
	v_fma_f32 v94, v80, v94, v80
	v_mul_f32_e32 v94, 0x3f4c422a, v94
	v_add_f32_e32 v94, v94, v94
	v_mul_f32_e32 v94, 0xbfb8aa3b, v94
	v_exp_f32_e32 v94, v94
	v_pk_fma_f32 v[70:71], v[70:71], v[170:171], v[146:147] op_sel_hi:[1,0,1]
	v_add_f32_e32 v94, 1.0, v94
	v_rcp_f32_e32 v94, v94
	s_nop 0
	v_mul_f32_e32 v94, v80, v94
	v_mul_f32_e32 v80, 0x3d372713, v93
	v_mul_f32_e32 v80, v93, v80
	v_fma_f32 v80, v93, v80, v93
	v_mul_f32_e32 v80, 0x3f4c422a, v80
	v_add_f32_e32 v80, v80, v80
	v_mul_f32_e32 v80, 0xbfb8aa3b, v80
	v_exp_f32_e32 v80, v80
	s_nop 0
	v_add_f32_e32 v80, 1.0, v80
	v_rcp_f32_e32 v80, v80
	s_nop 0
	v_mul_f32_e32 v93, v93, v80
	v_mul_f32_e32 v80, 0x3d372713, v81
	v_mul_f32_e32 v80, v81, v80
	v_fma_f32 v80, v81, v80, v81
	v_mul_f32_e32 v80, 0x3f4c422a, v80
	v_add_f32_e32 v80, v80, v80
	v_mul_f32_e32 v80, 0xbfb8aa3b, v80
	v_exp_f32_e32 v80, v80
	s_nop 0
	v_add_f32_e32 v80, 1.0, v80
	v_rcp_f32_e32 v80, v80
	s_nop 0
	v_mul_f32_e32 v95, v81, v80
	v_mul_f32_e32 v80, 0x3d372713, v86
	v_mul_f32_e32 v80, v86, v80
	v_fma_f32 v80, v86, v80, v86
	v_mul_f32_e32 v80, 0x3f4c422a, v80
	v_add_f32_e32 v80, v80, v80
	v_mul_f32_e32 v80, 0xbfb8aa3b, v80
	v_exp_f32_e32 v80, v80
	s_nop 0
	v_add_f32_e32 v80, 1.0, v80
	v_rcp_f32_e32 v80, v80
	s_nop 0
	v_mul_f32_e32 v86, v86, v80
	v_mul_f32_e32 v80, 0x3d372713, v82
	v_mul_f32_e32 v80, v82, v80
	v_fma_f32 v80, v82, v80, v82
	v_mul_f32_e32 v80, 0x3f4c422a, v80
	v_add_f32_e32 v80, v80, v80
	v_mul_f32_e32 v80, 0xbfb8aa3b, v80
	v_exp_f32_e32 v80, v80
	s_nop 0
	v_add_f32_e32 v80, 1.0, v80
	v_rcp_f32_e32 v80, v80
	s_nop 0
	v_mul_f32_e32 v82, v82, v80
	v_mul_f32_e32 v80, 0x3d372713, v87
	v_mul_f32_e32 v80, v87, v80
	v_fma_f32 v80, v87, v80, v87
	v_mul_f32_e32 v80, 0x3f4c422a, v80
	v_add_f32_e32 v80, v80, v80
	v_mul_f32_e32 v80, 0xbfb8aa3b, v80
	v_exp_f32_e32 v80, v80
	s_nop 0
	v_add_f32_e32 v80, 1.0, v80
	v_rcp_f32_e32 v80, v80
	s_nop 0
	v_mul_f32_e32 v87, v87, v80
	v_mul_f32_e32 v80, 0x3d372713, v83
	v_mul_f32_e32 v80, v83, v80
	v_fma_f32 v80, v83, v80, v83
	v_mul_f32_e32 v80, 0x3f4c422a, v80
	v_add_f32_e32 v80, v80, v80
	v_mul_f32_e32 v80, 0xbfb8aa3b, v80
	v_exp_f32_e32 v80, v80
	s_nop 0
	v_add_f32_e32 v80, 1.0, v80
	v_rcp_f32_e32 v80, v80
	s_nop 0
	v_mul_f32_e32 v83, v83, v80
	v_lshl_add_u64 v[80:81], v[202:203], 0, v[90:91]
	v_cvt_pk_bf16_f32 v91, v86, v87
	v_mul_f32_e32 v86, 0x3d372713, v76
	v_mul_f32_e32 v86, v76, v86
	v_fma_f32 v86, v76, v86, v76
	v_mul_f32_e32 v86, 0x3f4c422a, v86
	v_add_f32_e32 v86, v86, v86
	v_mul_f32_e32 v86, 0xbfb8aa3b, v86
	v_exp_f32_e32 v86, v86
	v_cvt_pk_bf16_f32 v90, v92, v93
	v_cvt_pk_bf16_f32 v92, v94, v95
	v_cvt_pk_bf16_f32 v93, v82, v83
	global_store_dwordx4 v[80:81], v[90:93], off sc1
	v_add_f32_e32 v86, 1.0, v86
	v_rcp_f32_e32 v86, v86
	v_lshlrev_b64 v[82:83], 11, v[210:211]
	v_mul_f32_e32 v76, v76, v86
	v_mul_f32_e32 v86, 0x3d372713, v72
	v_mul_f32_e32 v86, v72, v86
	v_fma_f32 v86, v72, v86, v72
	v_mul_f32_e32 v86, 0x3f4c422a, v86
	v_add_f32_e32 v86, v86, v86
	v_mul_f32_e32 v86, 0xbfb8aa3b, v86
	v_exp_f32_e32 v86, v86
	s_nop 0
	v_add_f32_e32 v86, 1.0, v86
	v_rcp_f32_e32 v86, v86
	s_nop 0
	v_mul_f32_e32 v86, v72, v86
	v_mul_f32_e32 v72, 0x3d372713, v77
	v_mul_f32_e32 v72, v77, v72
	v_fma_f32 v72, v77, v72, v77
	v_mul_f32_e32 v72, 0x3f4c422a, v72
	v_add_f32_e32 v72, v72, v72
	v_mul_f32_e32 v72, 0xbfb8aa3b, v72
	v_exp_f32_e32 v72, v72
	s_nop 0
	v_add_f32_e32 v72, 1.0, v72
	v_rcp_f32_e32 v72, v72
	s_nop 0
	v_mul_f32_e32 v77, v77, v72
	v_mul_f32_e32 v72, 0x3d372713, v73
	v_mul_f32_e32 v72, v73, v72
	v_fma_f32 v72, v73, v72, v73
	v_mul_f32_e32 v72, 0x3f4c422a, v72
	v_add_f32_e32 v72, v72, v72
	v_mul_f32_e32 v72, 0xbfb8aa3b, v72
	v_exp_f32_e32 v72, v72
	s_nop 0
	v_add_f32_e32 v72, 1.0, v72
	v_rcp_f32_e32 v72, v72
	s_nop 0
	v_mul_f32_e32 v87, v73, v72
	v_mul_f32_e32 v72, 0x3d372713, v78
	v_mul_f32_e32 v72, v78, v72
	v_fma_f32 v72, v78, v72, v78
	v_mul_f32_e32 v72, 0x3f4c422a, v72
	v_add_f32_e32 v72, v72, v72
	v_mul_f32_e32 v72, 0xbfb8aa3b, v72
	v_exp_f32_e32 v72, v72
	s_nop 0
	v_add_f32_e32 v72, 1.0, v72
	v_rcp_f32_e32 v72, v72
	s_nop 0
	v_mul_f32_e32 v78, v78, v72
; __device__ __forceinline__ unsigned cvt_pk_bf16(float lo, float hi) { unsigned r; asm("v_cvt_pk_bf16_f32 %0, %1, %2" : "=v"(r) : "v"(lo), "v"(hi)); return r; }
; __device__ __forceinline__ float gelu_tanh(float v) { const float u = 0.7978845608028654f * (v + 0.044715f * v * v * v); return v * fast_sigmoid(2.0f * u); }
; __device__ __forceinline__ f32x4 ln_fix(const f32x4& a, float mu, float rs, const f32x4& cs, const f32x4& cb) { return (a - cs * mu) * rs + cb; }
; __device__ __forceinline__ float fast_sigmoid(float v) { return __builtin_amdgcn_rcpf(1.0f + __builtin_amdgcn_exp2f(-1.4426950408889634f * v)); }
;     __device__ __forceinline__ void operator()(const f32x4 (&acc)[2][2][4][2], const Unit& u, int wr, int wc, int fr_in, int fq_in) const {
;     ...
;                 for (int m = 0; m < 4; ++m) { bf16_t* rowp = base + (size_t)(row0 + ai * HALF + m * 16) * 1024 + col0 + bj * HALF;
;                     f32x4 v0 = ln_fix(acc[ai][bj][m][0], rst.mu[ai][m], rst.rs[ai][m], csv[0], cbv[0]), v1 = ln_fix(acc[ai][bj][m][1], rst.mu[ai][m], rst.rs[ai][m], csv[1], cbv[1]);
; #pragma unroll
;                     for (int j = 0; j < 4; ++j) { v0[j] = gelu_tanh(v0[j]); v1[j] = gelu_tanh(v1[j]); }
;                     u32x4 w; w.x = cvt_pk_bf16(v0[0], v0[1]); w.y = cvt_pk_bf16(v0[2], v0[3]); w.z = cvt_pk_bf16(v1[0], v1[1]); w.w = cvt_pk_bf16(v1[2], v1[3]);
;                     *(u32x4*)rowp = w; } }
	v_mul_f32_e32 v72, 0x3d372713, v74
	v_mul_f32_e32 v72, v74, v72
	v_fma_f32 v72, v74, v72, v74
	v_mul_f32_e32 v72, 0x3f4c422a, v72
	v_add_f32_e32 v72, v72, v72
	v_mul_f32_e32 v72, 0xbfb8aa3b, v72
	v_exp_f32_e32 v72, v72
	s_nop 0
	v_add_f32_e32 v72, 1.0, v72
	v_rcp_f32_e32 v72, v72
	s_nop 0
	v_mul_f32_e32 v90, v74, v72
	v_mul_f32_e32 v72, 0x3d372713, v79
	v_mul_f32_e32 v72, v79, v72
	v_fma_f32 v72, v79, v72, v79
	v_mul_f32_e32 v72, 0x3f4c422a, v72
	v_add_f32_e32 v72, v72, v72
	v_mul_f32_e32 v72, 0xbfb8aa3b, v72
	v_exp_f32_e32 v72, v72
	v_cvt_pk_bf16_f32 v74, v76, v77
	v_cvt_pk_bf16_f32 v76, v86, v87
	s_nop 0
	v_add_f32_e32 v72, 1.0, v72
	v_rcp_f32_e32 v72, v72
	s_nop 0
	v_mul_f32_e32 v79, v79, v72
	v_mul_f32_e32 v72, 0x3d372713, v75
	v_mul_f32_e32 v72, v75, v72
	v_fma_f32 v72, v75, v72, v75
	v_mul_f32_e32 v72, 0x3f4c422a, v72
	v_add_f32_e32 v72, v72, v72
	v_mul_f32_e32 v72, 0xbfb8aa3b, v72
	v_exp_f32_e32 v72, v72
	s_nop 0
	v_add_f32_e32 v72, 1.0, v72
	v_rcp_f32_e32 v72, v72
	s_nop 0
	v_mul_f32_e32 v91, v75, v72
	v_lshl_add_u64 v[72:73], v[202:203], 0, v[82:83]
	v_cvt_pk_bf16_f32 v77, v90, v91
	v_cvt_pk_bf16_f32 v75, v78, v79
	global_store_dwordx4 v[72:73], v[74:77], off sc1
	s_nop 1
	v_xor_b32_e32 v77, 0x80000000, v123
	v_xor_b32_e32 v76, 0x80000000, v122
	v_pk_fma_f32 v[66:67], v[76:77], v[168:169], v[66:67] op_sel_hi:[1,0,1]
	v_mul_f32_e32 v76, 0x3d372713, v68
	v_mul_f32_e32 v76, v68, v76
	v_fma_f32 v76, v68, v76, v68
	v_mul_f32_e32 v76, 0x3f4c422a, v76
	v_add_f32_e32 v76, v76, v76
	v_mul_f32_e32 v76, 0xbfb8aa3b, v76
	v_exp_f32_e32 v76, v76
	v_pk_fma_f32 v[66:67], v[66:67], v[170:171], v[138:139] op_sel_hi:[1,0,1]
	v_lshlrev_b64 v[74:75], 11, v[208:209]
	v_lshl_add_u64 v[74:75], v[202:203], 0, v[74:75]
	v_add_f32_e32 v76, 1.0, v76
	v_rcp_f32_e32 v76, v76
	s_nop 0
	v_mul_f32_e32 v68, v68, v76
	v_mul_f32_e32 v76, 0x3d372713, v64
	v_mul_f32_e32 v76, v64, v76
	v_fma_f32 v76, v64, v76, v64
	v_mul_f32_e32 v76, 0x3f4c422a, v76
	v_add_f32_e32 v76, v76, v76
	v_mul_f32_e32 v76, 0xbfb8aa3b, v76
	v_exp_f32_e32 v76, v76
	s_nop 0
	v_add_f32_e32 v76, 1.0, v76
	v_rcp_f32_e32 v76, v76
	s_nop 0
	v_mul_f32_e32 v76, v64, v76
	v_mul_f32_e32 v64, 0x3d372713, v69
	v_mul_f32_e32 v64, v69, v64
	v_fma_f32 v64, v69, v64, v69
	v_mul_f32_e32 v64, 0x3f4c422a, v64
	v_add_f32_e32 v64, v64, v64
	v_mul_f32_e32 v64, 0xbfb8aa3b, v64
	v_exp_f32_e32 v64, v64
	s_nop 0
	v_add_f32_e32 v64, 1.0, v64
	v_rcp_f32_e32 v64, v64
	s_nop 0
	v_mul_f32_e32 v64, v69, v64
	v_mul_f32_e32 v69, 0x3d372713, v65
	v_mul_f32_e32 v69, v65, v69
	v_fma_f32 v69, v65, v69, v65
	v_mul_f32_e32 v69, 0x3f4c422a, v69
	v_add_f32_e32 v69, v69, v69
	v_mul_f32_e32 v69, 0xbfb8aa3b, v69
	v_exp_f32_e32 v69, v69
	v_cvt_pk_bf16_f32 v64, v68, v64
	s_nop 0
	v_add_f32_e32 v69, 1.0, v69
	v_rcp_f32_e32 v69, v69
	s_nop 0
	v_mul_f32_e32 v69, v65, v69
	v_mul_f32_e32 v65, 0x3d372713, v70
	v_mul_f32_e32 v65, v70, v65
	v_fma_f32 v65, v70, v65, v70
	v_mul_f32_e32 v65, 0x3f4c422a, v65
	v_add_f32_e32 v65, v65, v65
	v_mul_f32_e32 v65, 0xbfb8aa3b, v65
	v_exp_f32_e32 v65, v65
	s_nop 0
	v_add_f32_e32 v65, 1.0, v65
	v_rcp_f32_e32 v65, v65
	s_nop 0
	v_mul_f32_e32 v65, v70, v65
	v_mul_f32_e32 v70, 0x3d372713, v66
	v_mul_f32_e32 v70, v66, v70
	v_fma_f32 v70, v66, v70, v66
	v_mul_f32_e32 v70, 0x3f4c422a, v70
	v_add_f32_e32 v70, v70, v70
	v_mul_f32_e32 v70, 0xbfb8aa3b, v70
	v_exp_f32_e32 v70, v70
	s_nop 0
	v_add_f32_e32 v70, 1.0, v70
	v_rcp_f32_e32 v70, v70
	s_nop 0
	v_mul_f32_e32 v70, v66, v70
	v_mul_f32_e32 v66, 0x3d372713, v71
	v_mul_f32_e32 v66, v71, v66
	v_fma_f32 v66, v71, v66, v71
	v_mul_f32_e32 v66, 0x3f4c422a, v66
	v_add_f32_e32 v66, v66, v66
	v_mul_f32_e32 v66, 0xbfb8aa3b, v66
	v_exp_f32_e32 v66, v66
	s_nop 0
	v_add_f32_e32 v66, 1.0, v66
	v_rcp_f32_e32 v66, v66
	s_nop 0
	v_mul_f32_e32 v66, v71, v66
	v_mul_f32_e32 v71, 0x3d372713, v67
	v_mul_f32_e32 v71, v67, v71
	v_fma_f32 v71, v67, v71, v67
	v_mul_f32_e32 v71, 0x3f4c422a, v71
	v_add_f32_e32 v71, v71, v71
	v_mul_f32_e32 v71, 0xbfb8aa3b, v71
	v_exp_f32_e32 v71, v71
	v_cvt_pk_bf16_f32 v65, v65, v66
	v_cvt_pk_bf16_f32 v66, v76, v69
	s_nop 0
	v_add_f32_e32 v71, 1.0, v71
	v_rcp_f32_e32 v71, v71
	s_nop 0
	v_mul_f32_e32 v67, v67, v71
	v_cvt_pk_bf16_f32 v67, v70, v67
	global_store_dwordx4 v[74:75], v[64:67], off sc1
	global_load_dwordx4 v[64:67], v[204:205], off offset:528
	s_nop 0
	global_load_dwordx4 v[68:71], v[204:205], off offset:512
	global_load_dwordx4 v[84:87], v[206:207], off offset:528
	global_load_dwordx4 v[90:93], v[206:207], off offset:512
	global_load_dwordx4 v[98:101], v[200:201], off offset:528
	global_load_dwordx4 v[106:109], v[200:201], off offset:512
	s_waitcnt vmcnt(5)
	v_pk_fma_f32 v[56:57], v[196:197], v[64:65], v[56:57] op_sel_hi:[0,1,1] neg_lo:[1,0,0] neg_hi:[1,0,0]
	s_waitcnt vmcnt(4)
	v_pk_fma_f32 v[60:61], v[196:197], v[68:69], v[60:61] op_sel_hi:[0,1,1] neg_lo:[1,0,0] neg_hi:[1,0,0]
	v_pk_fma_f32 v[62:63], v[196:197], v[70:71], v[62:63] op_sel_hi:[0,1,1] neg_lo:[1,0,0] neg_hi:[1,0,0]
	v_pk_fma_f32 v[58:59], v[196:197], v[66:67], v[58:59] op_sel_hi:[0,1,1] neg_lo:[1,0,0] neg_hi:[1,0,0]
	s_waitcnt vmcnt(1)
	v_pk_add_f32 v[82:83], v[86:87], v[100:101]
	s_waitcnt vmcnt(0)
; __device__ __forceinline__ unsigned cvt_pk_bf16(float lo, float hi) { unsigned r; asm("v_cvt_pk_bf16_f32 %0, %1, %2" : "=v"(r) : "v"(lo), "v"(hi)); return r; }
; __device__ __forceinline__ float gelu_tanh(float v) { const float u = 0.7978845608028654f * (v + 0.044715f * v * v * v); return v * fast_sigmoid(2.0f * u); }
; __device__ __forceinline__ f32x4 ln_fix(const f32x4& a, float mu, float rs, const f32x4& cs, const f32x4& cb) { return (a - cs * mu) * rs + cb; }
;     __device__ __forceinline__ void operator()(const f32x4 (&acc)[2][2][4][2], const Unit& u, int wr, int wc, int fr_in, int fq_in) const {
;     ...
;         for (int bj = 0; bj < 2; ++bj) { f32x4 csv[2], cbv[2];
; #pragma unroll
;             for (int n = 0; n < 2; ++n) { csv[n] = *(const f32x4*)(cs + n0 + bj * HALF + 4 * n); cbv[n] = *(const f32x4*)(cb + n0 + bj * HALF + 4 * n) + *(const f32x4*)(bias + n0 + bj * HALF + 4 * n); }
; #pragma unroll
;             for (int ai = 0; ai < 2; ++ai)
; #pragma unroll
;                 for (int m = 0; m < 4; ++m) { bf16_t* rowp = base + (size_t)(row0 + ai * HALF + m * 16) * 1024 + col0 + bj * HALF;
;                     f32x4 v0 = ln_fix(acc[ai][bj][m][0], rst.mu[ai][m], rst.rs[ai][m], csv[0], cbv[0]), v1 = ln_fix(acc[ai][bj][m][1], rst.mu[ai][m], rst.rs[ai][m], csv[1], cbv[1]);
; #pragma unroll
;                     for (int j = 0; j < 4; ++j) { v0[j] = gelu_tanh(v0[j]); v1[j] = gelu_tanh(v1[j]); }
;                     u32x4 w; w.x = cvt_pk_bf16(v0[0], v0[1]); w.y = cvt_pk_bf16(v0[2], v0[3]); w.z = cvt_pk_bf16(v1[0], v1[1]); w.w = cvt_pk_bf16(v1[2], v1[3]);
;                     *(u32x4*)rowp = w; } }
	v_pk_add_f32 v[78:79], v[90:91], v[106:107]
	v_pk_add_f32 v[84:85], v[84:85], v[98:99]
	v_pk_fma_f32 v[60:61], v[198:199], v[60:61], v[78:79] op_sel_hi:[0,1,1]
	v_mul_f32_e32 v86, 0x3d372713, v60
	v_mul_f32_e32 v86, v60, v86
	v_fma_f32 v86, v60, v86, v60
	v_mul_f32_e32 v86, 0x3f4c422a, v86
	v_add_f32_e32 v86, v86, v86
	v_mul_f32_e32 v86, 0xbfb8aa3b, v86
	v_exp_f32_e32 v86, v86
	v_pk_fma_f32 v[56:57], v[198:199], v[56:57], v[84:85] op_sel_hi:[0,1,1]
	v_pk_add_f32 v[76:77], v[92:93], v[108:109]
	v_pk_fma_f32 v[58:59], v[198:199], v[58:59], v[82:83] op_sel_hi:[0,1,1]
	v_add_f32_e32 v86, 1.0, v86
	v_rcp_f32_e32 v86, v86
	v_pk_fma_f32 v[62:63], v[198:199], v[62:63], v[76:77] op_sel_hi:[0,1,1]
	v_pk_fma_f32 v[52:53], v[192:193], v[68:69], v[52:53] op_sel_hi:[0,1,1] neg_lo:[1,0,0] neg_hi:[1,0,0]
	v_pk_fma_f32 v[52:53], v[194:195], v[52:53], v[78:79] op_sel_hi:[0,1,1]
	v_mul_f32_e32 v60, v60, v86
	v_mul_f32_e32 v86, 0x3d372713, v56
	v_mul_f32_e32 v86, v56, v86
	v_fma_f32 v86, v56, v86, v56
	v_mul_f32_e32 v86, 0x3f4c422a, v86
	v_add_f32_e32 v86, v86, v86
	v_mul_f32_e32 v86, 0xbfb8aa3b, v86
	v_exp_f32_e32 v86, v86
	v_pk_fma_f32 v[48:49], v[192:193], v[64:65], v[48:49] op_sel_hi:[0,1,1] neg_lo:[1,0,0] neg_hi:[1,0,0]
	v_pk_fma_f32 v[48:49], v[194:195], v[48:49], v[84:85] op_sel_hi:[0,1,1]
	v_pk_fma_f32 v[54:55], v[192:193], v[70:71], v[54:55] op_sel_hi:[0,1,1] neg_lo:[1,0,0] neg_hi:[1,0,0]
	v_add_f32_e32 v86, 1.0, v86
	v_rcp_f32_e32 v86, v86
	v_pk_fma_f32 v[54:55], v[194:195], v[54:55], v[76:77] op_sel_hi:[0,1,1]
	v_pk_fma_f32 v[50:51], v[192:193], v[66:67], v[50:51] op_sel_hi:[0,1,1] neg_lo:[1,0,0] neg_hi:[1,0,0]
	v_pk_fma_f32 v[50:51], v[194:195], v[50:51], v[82:83] op_sel_hi:[0,1,1]
	v_mul_f32_e32 v86, v56, v86
	v_mul_f32_e32 v56, 0x3d372713, v61
	v_mul_f32_e32 v56, v61, v56
	v_fma_f32 v56, v61, v56, v61
	v_mul_f32_e32 v56, 0x3f4c422a, v56
	v_add_f32_e32 v56, v56, v56
	v_mul_f32_e32 v56, 0xbfb8aa3b, v56
	v_exp_f32_e32 v56, v56
	v_pk_fma_f32 v[44:45], v[188:189], v[68:69], v[44:45] op_sel_hi:[0,1,1] neg_lo:[1,0,0] neg_hi:[1,0,0]
	v_pk_fma_f32 v[44:45], v[190:191], v[44:45], v[78:79] op_sel_hi:[0,1,1]
	v_pk_fma_f32 v[40:41], v[188:189], v[64:65], v[40:41] op_sel_hi:[0,1,1] neg_lo:[1,0,0] neg_hi:[1,0,0]
	v_add_f32_e32 v56, 1.0, v56
	v_rcp_f32_e32 v56, v56
	v_pk_fma_f32 v[40:41], v[190:191], v[40:41], v[84:85] op_sel_hi:[0,1,1]
	v_pk_fma_f32 v[46:47], v[188:189], v[70:71], v[46:47] op_sel_hi:[0,1,1] neg_lo:[1,0,0] neg_hi:[1,0,0]
	v_pk_fma_f32 v[46:47], v[190:191], v[46:47], v[76:77] op_sel_hi:[0,1,1]
	v_mul_f32_e32 v56, v61, v56
	v_mul_f32_e32 v61, 0x3d372713, v57
	v_mul_f32_e32 v61, v57, v61
	v_fma_f32 v61, v57, v61, v57
	v_mul_f32_e32 v61, 0x3f4c422a, v61
	v_add_f32_e32 v61, v61, v61
	v_mul_f32_e32 v61, 0xbfb8aa3b, v61
	v_exp_f32_e32 v61, v61
	v_cvt_pk_bf16_f32 v56, v60, v56
	v_pk_fma_f32 v[42:43], v[188:189], v[66:67], v[42:43] op_sel_hi:[0,1,1] neg_lo:[1,0,0] neg_hi:[1,0,0]
	v_pk_fma_f32 v[42:43], v[190:191], v[42:43], v[82:83] op_sel_hi:[0,1,1]
	v_add_f32_e32 v61, 1.0, v61
	v_rcp_f32_e32 v61, v61
	v_pk_fma_f32 v[36:37], v[184:185], v[68:69], v[36:37] op_sel_hi:[0,1,1] neg_lo:[1,0,0] neg_hi:[1,0,0]
	v_pk_fma_f32 v[36:37], v[186:187], v[36:37], v[78:79] op_sel_hi:[0,1,1]
	v_pk_fma_f32 v[32:33], v[184:185], v[64:65], v[32:33] op_sel_hi:[0,1,1] neg_lo:[1,0,0] neg_hi:[1,0,0]
	v_mul_f32_e32 v61, v57, v61
	v_mul_f32_e32 v57, 0x3d372713, v62
	v_mul_f32_e32 v57, v62, v57
	v_fma_f32 v57, v62, v57, v62
	v_mul_f32_e32 v57, 0x3f4c422a, v57
	v_add_f32_e32 v57, v57, v57
	v_mul_f32_e32 v57, 0xbfb8aa3b, v57
	v_exp_f32_e32 v57, v57
	v_pk_fma_f32 v[32:33], v[186:187], v[32:33], v[84:85] op_sel_hi:[0,1,1]
	v_pk_fma_f32 v[38:39], v[184:185], v[70:71], v[38:39] op_sel_hi:[0,1,1] neg_lo:[1,0,0] neg_hi:[1,0,0]
	v_pk_fma_f32 v[38:39], v[186:187], v[38:39], v[76:77] op_sel_hi:[0,1,1]
	v_add_f32_e32 v57, 1.0, v57
	v_rcp_f32_e32 v57, v57
	v_pk_fma_f32 v[34:35], v[184:185], v[66:67], v[34:35] op_sel_hi:[0,1,1] neg_lo:[1,0,0] neg_hi:[1,0,0]
	v_pk_fma_f32 v[34:35], v[186:187], v[34:35], v[82:83] op_sel_hi:[0,1,1]
	v_pk_fma_f32 v[28:29], v[180:181], v[68:69], v[28:29] op_sel_hi:[0,1,1] neg_lo:[1,0,0] neg_hi:[1,0,0]
	v_mul_f32_e32 v57, v62, v57
	v_mul_f32_e32 v62, 0x3d372713, v58
	v_mul_f32_e32 v62, v58, v62
	v_fma_f32 v62, v58, v62, v58
	v_mul_f32_e32 v62, 0x3f4c422a, v62
	v_add_f32_e32 v62, v62, v62
	v_mul_f32_e32 v62, 0xbfb8aa3b, v62
	v_exp_f32_e32 v62, v62
	v_pk_fma_f32 v[28:29], v[182:183], v[28:29], v[78:79] op_sel_hi:[0,1,1]
	v_pk_fma_f32 v[24:25], v[180:181], v[64:65], v[24:25] op_sel_hi:[0,1,1] neg_lo:[1,0,0] neg_hi:[1,0,0]
	v_pk_fma_f32 v[24:25], v[182:183], v[24:25], v[84:85] op_sel_hi:[0,1,1]
	v_add_f32_e32 v62, 1.0, v62
	v_rcp_f32_e32 v62, v62
	v_pk_fma_f32 v[30:31], v[180:181], v[70:71], v[30:31] op_sel_hi:[0,1,1] neg_lo:[1,0,0] neg_hi:[1,0,0]
	v_pk_fma_f32 v[30:31], v[182:183], v[30:31], v[76:77] op_sel_hi:[0,1,1]
	v_pk_fma_f32 v[26:27], v[180:181], v[66:67], v[26:27] op_sel_hi:[0,1,1] neg_lo:[1,0,0] neg_hi:[1,0,0]
	v_mul_f32_e32 v62, v58, v62
	v_mul_f32_e32 v58, 0x3d372713, v63
	v_mul_f32_e32 v58, v63, v58
	v_fma_f32 v58, v63, v58, v63
	v_mul_f32_e32 v58, 0x3f4c422a, v58
	v_add_f32_e32 v58, v58, v58
	v_mul_f32_e32 v58, 0xbfb8aa3b, v58
	v_exp_f32_e32 v58, v58
	v_pk_fma_f32 v[26:27], v[182:183], v[26:27], v[82:83] op_sel_hi:[0,1,1]
	v_pk_fma_f32 v[20:21], v[176:177], v[68:69], v[20:21] op_sel_hi:[0,1,1] neg_lo:[1,0,0] neg_hi:[1,0,0]
	v_pk_fma_f32 v[20:21], v[178:179], v[20:21], v[78:79] op_sel_hi:[0,1,1]
	v_add_f32_e32 v58, 1.0, v58
	v_rcp_f32_e32 v58, v58
	v_pk_fma_f32 v[16:17], v[176:177], v[64:65], v[16:17] op_sel_hi:[0,1,1] neg_lo:[1,0,0] neg_hi:[1,0,0]
; __device__ __forceinline__ unsigned cvt_pk_bf16(float lo, float hi) { unsigned r; asm("v_cvt_pk_bf16_f32 %0, %1, %2" : "=v"(r) : "v"(lo), "v"(hi)); return r; }
; __device__ __forceinline__ float gelu_tanh(float v) { const float u = 0.7978845608028654f * (v + 0.044715f * v * v * v); return v * fast_sigmoid(2.0f * u); }
; __device__ __forceinline__ f32x4 ln_fix(const f32x4& a, float mu, float rs, const f32x4& cs, const f32x4& cb) { return (a - cs * mu) * rs + cb; }
; __device__ __forceinline__ float fast_sigmoid(float v) { return __builtin_amdgcn_rcpf(1.0f + __builtin_amdgcn_exp2f(-1.4426950408889634f * v)); }
;     __device__ __forceinline__ void operator()(const f32x4 (&acc)[2][2][4][2], const Unit& u, int wr, int wc, int fr_in, int fq_in) const {
;     ...
;                 for (int m = 0; m < 4; ++m) { bf16_t* rowp = base + (size_t)(row0 + ai * HALF + m * 16) * 1024 + col0 + bj * HALF;
;                     f32x4 v0 = ln_fix(acc[ai][bj][m][0], rst.mu[ai][m], rst.rs[ai][m], csv[0], cbv[0]), v1 = ln_fix(acc[ai][bj][m][1], rst.mu[ai][m], rst.rs[ai][m], csv[1], cbv[1]);
; #pragma unroll
;                     for (int j = 0; j < 4; ++j) { v0[j] = gelu_tanh(v0[j]); v1[j] = gelu_tanh(v1[j]); }
;                     u32x4 w; w.x = cvt_pk_bf16(v0[0], v0[1]); w.y = cvt_pk_bf16(v0[2], v0[3]); w.z = cvt_pk_bf16(v1[0], v1[1]); w.w = cvt_pk_bf16(v1[2], v1[3]);
;                     *(u32x4*)rowp = w; } }
	v_pk_fma_f32 v[16:17], v[178:179], v[16:17], v[84:85] op_sel_hi:[0,1,1]
	v_pk_fma_f32 v[22:23], v[176:177], v[70:71], v[22:23] op_sel_hi:[0,1,1] neg_lo:[1,0,0] neg_hi:[1,0,0]
	v_mul_f32_e32 v58, v63, v58
	v_mul_f32_e32 v63, 0x3d372713, v59
	v_mul_f32_e32 v63, v59, v63
	v_fma_f32 v63, v59, v63, v59
	v_mul_f32_e32 v63, 0x3f4c422a, v63
	v_add_f32_e32 v63, v63, v63
	v_mul_f32_e32 v63, 0xbfb8aa3b, v63
	v_exp_f32_e32 v63, v63
	v_cvt_pk_bf16_f32 v57, v57, v58
	v_cvt_pk_bf16_f32 v58, v86, v61
	v_pk_fma_f32 v[22:23], v[178:179], v[22:23], v[76:77] op_sel_hi:[0,1,1]
	v_add_f32_e32 v63, 1.0, v63
	v_rcp_f32_e32 v63, v63
	v_pk_fma_f32 v[18:19], v[176:177], v[66:67], v[18:19] op_sel_hi:[0,1,1] neg_lo:[1,0,0] neg_hi:[1,0,0]
	v_pk_fma_f32 v[18:19], v[178:179], v[18:19], v[82:83] op_sel_hi:[0,1,1]
	v_pk_fma_f32 v[12:13], v[172:173], v[68:69], v[12:13] op_sel_hi:[0,1,1] neg_lo:[1,0,0] neg_hi:[1,0,0]
	v_mul_f32_e32 v59, v59, v63
	v_cvt_pk_bf16_f32 v59, v62, v59
	global_store_dwordx4 v[128:129], v[56:59], off offset:256 sc1
	v_pk_fma_f32 v[12:13], v[174:175], v[12:13], v[78:79] op_sel_hi:[0,1,1]
	v_pk_fma_f32 v[8:9], v[172:173], v[64:65], v[8:9] op_sel_hi:[0,1,1] neg_lo:[1,0,0] neg_hi:[1,0,0]
	v_mul_f32_e32 v56, 0x3d372713, v52
	v_mul_f32_e32 v56, v52, v56
	v_fma_f32 v56, v52, v56, v52
	v_mul_f32_e32 v56, 0x3f4c422a, v56
	v_add_f32_e32 v56, v56, v56
	v_mul_f32_e32 v56, 0xbfb8aa3b, v56
	v_exp_f32_e32 v56, v56
	v_pk_fma_f32 v[8:9], v[174:175], v[8:9], v[84:85] op_sel_hi:[0,1,1]
	v_pk_fma_f32 v[14:15], v[172:173], v[70:71], v[14:15] op_sel_hi:[0,1,1] neg_lo:[1,0,0] neg_hi:[1,0,0]
	v_pk_fma_f32 v[14:15], v[174:175], v[14:15], v[76:77] op_sel_hi:[0,1,1]
	v_add_f32_e32 v56, 1.0, v56
	v_rcp_f32_e32 v56, v56
	v_pk_fma_f32 v[10:11], v[172:173], v[66:67], v[10:11] op_sel_hi:[0,1,1] neg_lo:[1,0,0] neg_hi:[1,0,0]
	v_pk_fma_f32 v[10:11], v[174:175], v[10:11], v[82:83] op_sel_hi:[0,1,1]
	v_pk_fma_f32 v[4:5], v[168:169], v[68:69], v[4:5] op_sel_hi:[0,1,1] neg_lo:[1,0,0] neg_hi:[1,0,0]
	v_mul_f32_e32 v52, v52, v56
	v_mul_f32_e32 v56, 0x3d372713, v48
	v_mul_f32_e32 v56, v48, v56
	v_fma_f32 v56, v48, v56, v48
	v_mul_f32_e32 v56, 0x3f4c422a, v56
	v_add_f32_e32 v56, v56, v56
	v_mul_f32_e32 v56, 0xbfb8aa3b, v56
	v_exp_f32_e32 v56, v56
	v_pk_fma_f32 v[4:5], v[170:171], v[4:5], v[78:79] op_sel_hi:[0,1,1]
	v_pk_fma_f32 v[0:1], v[168:169], v[64:65], v[0:1] op_sel_hi:[0,1,1] neg_lo:[1,0,0] neg_hi:[1,0,0]
	v_pk_fma_f32 v[0:1], v[170:171], v[0:1], v[84:85] op_sel_hi:[0,1,1]
	v_add_f32_e32 v56, 1.0, v56
	v_rcp_f32_e32 v56, v56
	v_pk_fma_f32 v[6:7], v[168:169], v[70:71], v[6:7] op_sel_hi:[0,1,1] neg_lo:[1,0,0] neg_hi:[1,0,0]
	v_pk_fma_f32 v[6:7], v[170:171], v[6:7], v[76:77] op_sel_hi:[0,1,1]
	v_pk_fma_f32 v[2:3], v[168:169], v[66:67], v[2:3] op_sel_hi:[0,1,1] neg_lo:[1,0,0] neg_hi:[1,0,0]
	v_mul_f32_e32 v56, v48, v56
	v_mul_f32_e32 v48, 0x3d372713, v53
	v_mul_f32_e32 v48, v53, v48
	v_fma_f32 v48, v53, v48, v53
	v_mul_f32_e32 v48, 0x3f4c422a, v48
	v_add_f32_e32 v48, v48, v48
	v_mul_f32_e32 v48, 0xbfb8aa3b, v48
	v_exp_f32_e32 v48, v48
	v_pk_fma_f32 v[2:3], v[170:171], v[2:3], v[82:83] op_sel_hi:[0,1,1]
	v_add_f32_e32 v48, 1.0, v48
	v_rcp_f32_e32 v48, v48
	s_nop 0
	v_mul_f32_e32 v48, v53, v48
	v_mul_f32_e32 v53, 0x3d372713, v49
	v_mul_f32_e32 v53, v49, v53
	v_fma_f32 v53, v49, v53, v49
	v_mul_f32_e32 v53, 0x3f4c422a, v53
	v_add_f32_e32 v53, v53, v53
	v_mul_f32_e32 v53, 0xbfb8aa3b, v53
	v_exp_f32_e32 v53, v53
	v_cvt_pk_bf16_f32 v48, v52, v48
	s_nop 0
	v_add_f32_e32 v53, 1.0, v53
	v_rcp_f32_e32 v53, v53
	s_nop 0
	v_mul_f32_e32 v53, v49, v53
	v_mul_f32_e32 v49, 0x3d372713, v54
	v_mul_f32_e32 v49, v54, v49
	v_fma_f32 v49, v54, v49, v54
	v_mul_f32_e32 v49, 0x3f4c422a, v49
	v_add_f32_e32 v49, v49, v49
	v_mul_f32_e32 v49, 0xbfb8aa3b, v49
	v_exp_f32_e32 v49, v49
	s_nop 0
	v_add_f32_e32 v49, 1.0, v49
	v_rcp_f32_e32 v49, v49
	s_nop 0
	v_mul_f32_e32 v49, v54, v49
	v_mul_f32_e32 v54, 0x3d372713, v50
	v_mul_f32_e32 v54, v50, v54
	v_fma_f32 v54, v50, v54, v50
	v_mul_f32_e32 v54, 0x3f4c422a, v54
	v_add_f32_e32 v54, v54, v54
	v_mul_f32_e32 v54, 0xbfb8aa3b, v54
	v_exp_f32_e32 v54, v54
	s_nop 0
	v_add_f32_e32 v54, 1.0, v54
	v_rcp_f32_e32 v54, v54
	s_nop 0
	v_mul_f32_e32 v54, v50, v54
	v_mul_f32_e32 v50, 0x3d372713, v55
	v_mul_f32_e32 v50, v55, v50
	v_fma_f32 v50, v55, v50, v55
	v_mul_f32_e32 v50, 0x3f4c422a, v50
	v_add_f32_e32 v50, v50, v50
	v_mul_f32_e32 v50, 0xbfb8aa3b, v50
	v_exp_f32_e32 v50, v50
	s_nop 0
	v_add_f32_e32 v50, 1.0, v50
	v_rcp_f32_e32 v50, v50
	s_nop 0
	v_mul_f32_e32 v50, v55, v50
	v_mul_f32_e32 v55, 0x3d372713, v51
	v_mul_f32_e32 v55, v51, v55
	v_fma_f32 v55, v51, v55, v51
	v_mul_f32_e32 v55, 0x3f4c422a, v55
	v_add_f32_e32 v55, v55, v55
	v_mul_f32_e32 v55, 0xbfb8aa3b, v55
	v_exp_f32_e32 v55, v55
	v_cvt_pk_bf16_f32 v49, v49, v50
	v_cvt_pk_bf16_f32 v50, v56, v53
	s_nop 0
	v_add_f32_e32 v55, 1.0, v55
	v_rcp_f32_e32 v55, v55
	s_nop 0
	v_mul_f32_e32 v51, v51, v55
	v_cvt_pk_bf16_f32 v51, v54, v51
	global_store_dwordx4 v[112:113], v[48:51], off offset:256 sc1
	s_nop 1
	v_mul_f32_e32 v48, 0x3d372713, v44
	v_mul_f32_e32 v48, v44, v48
	v_fma_f32 v48, v44, v48, v44
	v_mul_f32_e32 v48, 0x3f4c422a, v48
	v_add_f32_e32 v48, v48, v48
	v_mul_f32_e32 v48, 0xbfb8aa3b, v48
	v_exp_f32_e32 v48, v48
	s_nop 0
	v_add_f32_e32 v48, 1.0, v48
	v_rcp_f32_e32 v48, v48
	s_nop 0
	v_mul_f32_e32 v44, v44, v48
	v_mul_f32_e32 v48, 0x3d372713, v40
	v_mul_f32_e32 v48, v40, v48
	v_fma_f32 v48, v40, v48, v40
	v_mul_f32_e32 v48, 0x3f4c422a, v48
	v_add_f32_e32 v48, v48, v48
	v_mul_f32_e32 v48, 0xbfb8aa3b, v48
	v_exp_f32_e32 v48, v48
	s_nop 0
	v_add_f32_e32 v48, 1.0, v48
	v_rcp_f32_e32 v48, v48
	s_nop 0
	v_mul_f32_e32 v48, v40, v48
; __device__ __forceinline__ unsigned cvt_pk_bf16(float lo, float hi) { unsigned r; asm("v_cvt_pk_bf16_f32 %0, %1, %2" : "=v"(r) : "v"(lo), "v"(hi)); return r; }
; __device__ __forceinline__ float gelu_tanh(float v) { const float u = 0.7978845608028654f * (v + 0.044715f * v * v * v); return v * fast_sigmoid(2.0f * u); }
; __device__ __forceinline__ f32x4 ln_fix(const f32x4& a, float mu, float rs, const f32x4& cs, const f32x4& cb) { return (a - cs * mu) * rs + cb; }
; __device__ __forceinline__ float fast_sigmoid(float v) { return __builtin_amdgcn_rcpf(1.0f + __builtin_amdgcn_exp2f(-1.4426950408889634f * v)); }
;     __device__ __forceinline__ void operator()(const f32x4 (&acc)[2][2][4][2], const Unit& u, int wr, int wc, int fr_in, int fq_in) const {
;     ...
;                 for (int m = 0; m < 4; ++m) { bf16_t* rowp = base + (size_t)(row0 + ai * HALF + m * 16) * 1024 + col0 + bj * HALF;
;                     f32x4 v0 = ln_fix(acc[ai][bj][m][0], rst.mu[ai][m], rst.rs[ai][m], csv[0], cbv[0]), v1 = ln_fix(acc[ai][bj][m][1], rst.mu[ai][m], rst.rs[ai][m], csv[1], cbv[1]);
; #pragma unroll
;                     for (int j = 0; j < 4; ++j) { v0[j] = gelu_tanh(v0[j]); v1[j] = gelu_tanh(v1[j]); }
;                     u32x4 w; w.x = cvt_pk_bf16(v0[0], v0[1]); w.y = cvt_pk_bf16(v0[2], v0[3]); w.z = cvt_pk_bf16(v1[0], v1[1]); w.w = cvt_pk_bf16(v1[2], v1[3]);
;                     *(u32x4*)rowp = w; } }
	v_mul_f32_e32 v40, 0x3d372713, v45
	v_mul_f32_e32 v40, v45, v40
	v_fma_f32 v40, v45, v40, v45
	v_mul_f32_e32 v40, 0x3f4c422a, v40
	v_add_f32_e32 v40, v40, v40
	v_mul_f32_e32 v40, 0xbfb8aa3b, v40
	v_exp_f32_e32 v40, v40
	s_nop 0
	v_add_f32_e32 v40, 1.0, v40
	v_rcp_f32_e32 v40, v40
	s_nop 0
	v_mul_f32_e32 v40, v45, v40
	v_mul_f32_e32 v45, 0x3d372713, v41
	v_mul_f32_e32 v45, v41, v45
	v_fma_f32 v45, v41, v45, v41
	v_mul_f32_e32 v45, 0x3f4c422a, v45
	v_add_f32_e32 v45, v45, v45
	v_mul_f32_e32 v45, 0xbfb8aa3b, v45
	v_exp_f32_e32 v45, v45
	v_cvt_pk_bf16_f32 v40, v44, v40
	s_nop 0
	v_add_f32_e32 v45, 1.0, v45
	v_rcp_f32_e32 v45, v45
	s_nop 0
	v_mul_f32_e32 v45, v41, v45
	v_mul_f32_e32 v41, 0x3d372713, v46
	v_mul_f32_e32 v41, v46, v41
	v_fma_f32 v41, v46, v41, v46
	v_mul_f32_e32 v41, 0x3f4c422a, v41
	v_add_f32_e32 v41, v41, v41
	v_mul_f32_e32 v41, 0xbfb8aa3b, v41
	v_exp_f32_e32 v41, v41
	s_nop 0
	v_add_f32_e32 v41, 1.0, v41
	v_rcp_f32_e32 v41, v41
	s_nop 0
	v_mul_f32_e32 v41, v46, v41
	v_mul_f32_e32 v46, 0x3d372713, v42
	v_mul_f32_e32 v46, v42, v46
	v_fma_f32 v46, v42, v46, v42
	v_mul_f32_e32 v46, 0x3f4c422a, v46
	v_add_f32_e32 v46, v46, v46
	v_mul_f32_e32 v46, 0xbfb8aa3b, v46
	v_exp_f32_e32 v46, v46
	s_nop 0
	v_add_f32_e32 v46, 1.0, v46
	v_rcp_f32_e32 v46, v46
	s_nop 0
	v_mul_f32_e32 v46, v42, v46
	v_mul_f32_e32 v42, 0x3d372713, v47
	v_mul_f32_e32 v42, v47, v42
	v_fma_f32 v42, v47, v42, v47
	v_mul_f32_e32 v42, 0x3f4c422a, v42
	v_add_f32_e32 v42, v42, v42
	v_mul_f32_e32 v42, 0xbfb8aa3b, v42
	v_exp_f32_e32 v42, v42
	s_nop 0
	v_add_f32_e32 v42, 1.0, v42
	v_rcp_f32_e32 v42, v42
	s_nop 0
	v_mul_f32_e32 v42, v47, v42
	v_mul_f32_e32 v47, 0x3d372713, v43
	v_mul_f32_e32 v47, v43, v47
	v_fma_f32 v47, v43, v47, v43
	v_mul_f32_e32 v47, 0x3f4c422a, v47
	v_add_f32_e32 v47, v47, v47
	v_mul_f32_e32 v47, 0xbfb8aa3b, v47
	v_exp_f32_e32 v47, v47
	v_cvt_pk_bf16_f32 v41, v41, v42
	v_cvt_pk_bf16_f32 v42, v48, v45
	s_nop 0
	v_add_f32_e32 v47, 1.0, v47
	v_rcp_f32_e32 v47, v47
	s_nop 0
	v_mul_f32_e32 v43, v43, v47
	v_cvt_pk_bf16_f32 v43, v46, v43
	global_store_dwordx4 v[104:105], v[40:43], off offset:256 sc1
	s_nop 1
	v_mul_f32_e32 v40, 0x3d372713, v36
	v_mul_f32_e32 v40, v36, v40
	v_fma_f32 v40, v36, v40, v36
	v_mul_f32_e32 v40, 0x3f4c422a, v40
	v_add_f32_e32 v40, v40, v40
	v_mul_f32_e32 v40, 0xbfb8aa3b, v40
	v_exp_f32_e32 v40, v40
	s_nop 0
	v_add_f32_e32 v40, 1.0, v40
	v_rcp_f32_e32 v40, v40
	s_nop 0
	v_mul_f32_e32 v36, v36, v40
	v_mul_f32_e32 v40, 0x3d372713, v32
	v_mul_f32_e32 v40, v32, v40
	v_fma_f32 v40, v32, v40, v32
	v_mul_f32_e32 v40, 0x3f4c422a, v40
	v_add_f32_e32 v40, v40, v40
	v_mul_f32_e32 v40, 0xbfb8aa3b, v40
	v_exp_f32_e32 v40, v40
	s_nop 0
	v_add_f32_e32 v40, 1.0, v40
	v_rcp_f32_e32 v40, v40
	s_nop 0
	v_mul_f32_e32 v40, v32, v40
	v_mul_f32_e32 v32, 0x3d372713, v37
	v_mul_f32_e32 v32, v37, v32
	v_fma_f32 v32, v37, v32, v37
	v_mul_f32_e32 v32, 0x3f4c422a, v32
	v_add_f32_e32 v32, v32, v32
	v_mul_f32_e32 v32, 0xbfb8aa3b, v32
	v_exp_f32_e32 v32, v32
	s_nop 0
	v_add_f32_e32 v32, 1.0, v32
	v_rcp_f32_e32 v32, v32
	s_nop 0
	v_mul_f32_e32 v32, v37, v32
	v_mul_f32_e32 v37, 0x3d372713, v33
	v_mul_f32_e32 v37, v33, v37
	v_fma_f32 v37, v33, v37, v33
	v_mul_f32_e32 v37, 0x3f4c422a, v37
	v_add_f32_e32 v37, v37, v37
	v_mul_f32_e32 v37, 0xbfb8aa3b, v37
	v_exp_f32_e32 v37, v37
	v_cvt_pk_bf16_f32 v32, v36, v32
	s_nop 0
	v_add_f32_e32 v37, 1.0, v37
	v_rcp_f32_e32 v37, v37
	s_nop 0
	v_mul_f32_e32 v37, v33, v37
	v_mul_f32_e32 v33, 0x3d372713, v38
	v_mul_f32_e32 v33, v38, v33
	v_fma_f32 v33, v38, v33, v38
	v_mul_f32_e32 v33, 0x3f4c422a, v33
	v_add_f32_e32 v33, v33, v33
	v_mul_f32_e32 v33, 0xbfb8aa3b, v33
	v_exp_f32_e32 v33, v33
	s_nop 0
	v_add_f32_e32 v33, 1.0, v33
	v_rcp_f32_e32 v33, v33
	s_nop 0
	v_mul_f32_e32 v33, v38, v33
	v_mul_f32_e32 v38, 0x3d372713, v34
	v_mul_f32_e32 v38, v34, v38
	v_fma_f32 v38, v34, v38, v34
	v_mul_f32_e32 v38, 0x3f4c422a, v38
	v_add_f32_e32 v38, v38, v38
	v_mul_f32_e32 v38, 0xbfb8aa3b, v38
	v_exp_f32_e32 v38, v38
	s_nop 0
	v_add_f32_e32 v38, 1.0, v38
	v_rcp_f32_e32 v38, v38
	s_nop 0
	v_mul_f32_e32 v38, v34, v38
	v_mul_f32_e32 v34, 0x3d372713, v39
	v_mul_f32_e32 v34, v39, v34
	v_fma_f32 v34, v39, v34, v39
	v_mul_f32_e32 v34, 0x3f4c422a, v34
	v_add_f32_e32 v34, v34, v34
	v_mul_f32_e32 v34, 0xbfb8aa3b, v34
	v_exp_f32_e32 v34, v34
	s_nop 0
	v_add_f32_e32 v34, 1.0, v34
	v_rcp_f32_e32 v34, v34
	s_nop 0
	v_mul_f32_e32 v34, v39, v34
	v_mul_f32_e32 v39, 0x3d372713, v35
	v_mul_f32_e32 v39, v35, v39
	v_fma_f32 v39, v35, v39, v35
	v_mul_f32_e32 v39, 0x3f4c422a, v39
	v_add_f32_e32 v39, v39, v39
	v_mul_f32_e32 v39, 0xbfb8aa3b, v39
	v_exp_f32_e32 v39, v39
	v_cvt_pk_bf16_f32 v33, v33, v34
	v_cvt_pk_bf16_f32 v34, v40, v37
	s_nop 0
	v_add_f32_e32 v39, 1.0, v39
	v_rcp_f32_e32 v39, v39
	s_nop 0
	v_mul_f32_e32 v35, v35, v39
	v_cvt_pk_bf16_f32 v35, v38, v35
	global_store_dwordx4 v[96:97], v[32:35], off offset:256 sc1
	s_nop 1
	v_mul_f32_e32 v32, 0x3d372713, v28
	v_mul_f32_e32 v32, v28, v32
	v_fma_f32 v32, v28, v32, v28
	v_mul_f32_e32 v32, 0x3f4c422a, v32
	v_add_f32_e32 v32, v32, v32
	v_mul_f32_e32 v32, 0xbfb8aa3b, v32
	v_exp_f32_e32 v32, v32
	s_nop 0
	v_add_f32_e32 v32, 1.0, v32
	v_rcp_f32_e32 v32, v32
	s_nop 0
	v_mul_f32_e32 v28, v28, v32
	v_mul_f32_e32 v32, 0x3d372713, v24
	v_mul_f32_e32 v32, v24, v32
	v_fma_f32 v32, v24, v32, v24
	v_mul_f32_e32 v32, 0x3f4c422a, v32
	v_add_f32_e32 v32, v32, v32
	v_mul_f32_e32 v32, 0xbfb8aa3b, v32
	v_exp_f32_e32 v32, v32
	s_nop 0
	v_add_f32_e32 v32, 1.0, v32
	v_rcp_f32_e32 v32, v32
	s_nop 0
	v_mul_f32_e32 v32, v24, v32
	v_mul_f32_e32 v24, 0x3d372713, v29
	v_mul_f32_e32 v24, v29, v24
	v_fma_f32 v24, v29, v24, v29
	v_mul_f32_e32 v24, 0x3f4c422a, v24
; __device__ __forceinline__ unsigned cvt_pk_bf16(float lo, float hi) { unsigned r; asm("v_cvt_pk_bf16_f32 %0, %1, %2" : "=v"(r) : "v"(lo), "v"(hi)); return r; }
; __device__ __forceinline__ float gelu_tanh(float v) { const float u = 0.7978845608028654f * (v + 0.044715f * v * v * v); return v * fast_sigmoid(2.0f * u); }
; __device__ __forceinline__ f32x4 ln_fix(const f32x4& a, float mu, float rs, const f32x4& cs, const f32x4& cb) { return (a - cs * mu) * rs + cb; }
; __device__ __forceinline__ float fast_sigmoid(float v) { return __builtin_amdgcn_rcpf(1.0f + __builtin_amdgcn_exp2f(-1.4426950408889634f * v)); }
;     __device__ __forceinline__ void operator()(const f32x4 (&acc)[2][2][4][2], const Unit& u, int wr, int wc, int fr_in, int fq_in) const {
;     ...
;                 for (int m = 0; m < 4; ++m) { bf16_t* rowp = base + (size_t)(row0 + ai * HALF + m * 16) * 1024 + col0 + bj * HALF;
;                     f32x4 v0 = ln_fix(acc[ai][bj][m][0], rst.mu[ai][m], rst.rs[ai][m], csv[0], cbv[0]), v1 = ln_fix(acc[ai][bj][m][1], rst.mu[ai][m], rst.rs[ai][m], csv[1], cbv[1]);
; #pragma unroll
;                     for (int j = 0; j < 4; ++j) { v0[j] = gelu_tanh(v0[j]); v1[j] = gelu_tanh(v1[j]); }
;                     u32x4 w; w.x = cvt_pk_bf16(v0[0], v0[1]); w.y = cvt_pk_bf16(v0[2], v0[3]); w.z = cvt_pk_bf16(v1[0], v1[1]); w.w = cvt_pk_bf16(v1[2], v1[3]);
;                     *(u32x4*)rowp = w; } }
	v_add_f32_e32 v24, v24, v24
	v_mul_f32_e32 v24, 0xbfb8aa3b, v24
	v_exp_f32_e32 v24, v24
	s_nop 0
	v_add_f32_e32 v24, 1.0, v24
	v_rcp_f32_e32 v24, v24
	s_nop 0
	v_mul_f32_e32 v24, v29, v24
	v_mul_f32_e32 v29, 0x3d372713, v25
	v_mul_f32_e32 v29, v25, v29
	v_fma_f32 v29, v25, v29, v25
	v_mul_f32_e32 v29, 0x3f4c422a, v29
	v_add_f32_e32 v29, v29, v29
	v_mul_f32_e32 v29, 0xbfb8aa3b, v29
	v_exp_f32_e32 v29, v29
	v_cvt_pk_bf16_f32 v24, v28, v24
	s_nop 0
	v_add_f32_e32 v29, 1.0, v29
	v_rcp_f32_e32 v29, v29
	s_nop 0
	v_mul_f32_e32 v29, v25, v29
	v_mul_f32_e32 v25, 0x3d372713, v30
	v_mul_f32_e32 v25, v30, v25
	v_fma_f32 v25, v30, v25, v30
	v_mul_f32_e32 v25, 0x3f4c422a, v25
	v_add_f32_e32 v25, v25, v25
	v_mul_f32_e32 v25, 0xbfb8aa3b, v25
	v_exp_f32_e32 v25, v25
	s_nop 0
	v_add_f32_e32 v25, 1.0, v25
	v_rcp_f32_e32 v25, v25
	s_nop 0
	v_mul_f32_e32 v25, v30, v25
	v_mul_f32_e32 v30, 0x3d372713, v26
	v_mul_f32_e32 v30, v26, v30
	v_fma_f32 v30, v26, v30, v26
	v_mul_f32_e32 v30, 0x3f4c422a, v30
	v_add_f32_e32 v30, v30, v30
	v_mul_f32_e32 v30, 0xbfb8aa3b, v30
	v_exp_f32_e32 v30, v30
	s_nop 0
	v_add_f32_e32 v30, 1.0, v30
	v_rcp_f32_e32 v30, v30
	s_nop 0
	v_mul_f32_e32 v30, v26, v30
	v_mul_f32_e32 v26, 0x3d372713, v31
	v_mul_f32_e32 v26, v31, v26
	v_fma_f32 v26, v31, v26, v31
	v_mul_f32_e32 v26, 0x3f4c422a, v26
	v_add_f32_e32 v26, v26, v26
	v_mul_f32_e32 v26, 0xbfb8aa3b, v26
	v_exp_f32_e32 v26, v26
	s_nop 0
	v_add_f32_e32 v26, 1.0, v26
	v_rcp_f32_e32 v26, v26
	s_nop 0
	v_mul_f32_e32 v26, v31, v26
	v_mul_f32_e32 v31, 0x3d372713, v27
	v_mul_f32_e32 v31, v27, v31
	v_fma_f32 v31, v27, v31, v27
	v_mul_f32_e32 v31, 0x3f4c422a, v31
	v_add_f32_e32 v31, v31, v31
	v_mul_f32_e32 v31, 0xbfb8aa3b, v31
	v_exp_f32_e32 v31, v31
	v_cvt_pk_bf16_f32 v25, v25, v26
	v_cvt_pk_bf16_f32 v26, v32, v29
	s_nop 0
	v_add_f32_e32 v31, 1.0, v31
	v_rcp_f32_e32 v31, v31
	s_nop 0
	v_mul_f32_e32 v27, v27, v31
	v_cvt_pk_bf16_f32 v27, v30, v27
	global_store_dwordx4 v[88:89], v[24:27], off offset:256 sc1
	s_nop 1
	v_mul_f32_e32 v24, 0x3d372713, v20
	v_mul_f32_e32 v24, v20, v24
	v_fma_f32 v24, v20, v24, v20
	v_mul_f32_e32 v24, 0x3f4c422a, v24
	v_add_f32_e32 v24, v24, v24
	v_mul_f32_e32 v24, 0xbfb8aa3b, v24
	v_exp_f32_e32 v24, v24
	s_nop 0
	v_add_f32_e32 v24, 1.0, v24
	v_rcp_f32_e32 v24, v24
	s_nop 0
	v_mul_f32_e32 v20, v20, v24
	v_mul_f32_e32 v24, 0x3d372713, v16
	v_mul_f32_e32 v24, v16, v24
	v_fma_f32 v24, v16, v24, v16
	v_mul_f32_e32 v24, 0x3f4c422a, v24
	v_add_f32_e32 v24, v24, v24
	v_mul_f32_e32 v24, 0xbfb8aa3b, v24
	v_exp_f32_e32 v24, v24
	s_nop 0
	v_add_f32_e32 v24, 1.0, v24
	v_rcp_f32_e32 v24, v24
	s_nop 0
	v_mul_f32_e32 v24, v16, v24
	v_mul_f32_e32 v16, 0x3d372713, v21
	v_mul_f32_e32 v16, v21, v16
	v_fma_f32 v16, v21, v16, v21
	v_mul_f32_e32 v16, 0x3f4c422a, v16
	v_add_f32_e32 v16, v16, v16
	v_mul_f32_e32 v16, 0xbfb8aa3b, v16
	v_exp_f32_e32 v16, v16
	s_nop 0
	v_add_f32_e32 v16, 1.0, v16
	v_rcp_f32_e32 v16, v16
	s_nop 0
	v_mul_f32_e32 v16, v21, v16
	v_mul_f32_e32 v21, 0x3d372713, v17
	v_mul_f32_e32 v21, v17, v21
	v_fma_f32 v21, v17, v21, v17
	v_mul_f32_e32 v21, 0x3f4c422a, v21
	v_add_f32_e32 v21, v21, v21
	v_mul_f32_e32 v21, 0xbfb8aa3b, v21
	v_exp_f32_e32 v21, v21
	v_cvt_pk_bf16_f32 v16, v20, v16
	s_nop 0
	v_add_f32_e32 v21, 1.0, v21
	v_rcp_f32_e32 v21, v21
	s_nop 0
	v_mul_f32_e32 v21, v17, v21
	v_mul_f32_e32 v17, 0x3d372713, v22
	v_mul_f32_e32 v17, v22, v17
	v_fma_f32 v17, v22, v17, v22
	v_mul_f32_e32 v17, 0x3f4c422a, v17
	v_add_f32_e32 v17, v17, v17
	v_mul_f32_e32 v17, 0xbfb8aa3b, v17
	v_exp_f32_e32 v17, v17
	s_nop 0
	v_add_f32_e32 v17, 1.0, v17
	v_rcp_f32_e32 v17, v17
	s_nop 0
	v_mul_f32_e32 v17, v22, v17
	v_mul_f32_e32 v22, 0x3d372713, v18
	v_mul_f32_e32 v22, v18, v22
	v_fma_f32 v22, v18, v22, v18
	v_mul_f32_e32 v22, 0x3f4c422a, v22
	v_add_f32_e32 v22, v22, v22
	v_mul_f32_e32 v22, 0xbfb8aa3b, v22
	v_exp_f32_e32 v22, v22
	s_nop 0
	v_add_f32_e32 v22, 1.0, v22
	v_rcp_f32_e32 v22, v22
	s_nop 0
	v_mul_f32_e32 v22, v18, v22
	v_mul_f32_e32 v18, 0x3d372713, v23
	v_mul_f32_e32 v18, v23, v18
	v_fma_f32 v18, v23, v18, v23
	v_mul_f32_e32 v18, 0x3f4c422a, v18
	v_add_f32_e32 v18, v18, v18
	v_mul_f32_e32 v18, 0xbfb8aa3b, v18
	v_exp_f32_e32 v18, v18
	s_nop 0
	v_add_f32_e32 v18, 1.0, v18
	v_rcp_f32_e32 v18, v18
	s_nop 0
	v_mul_f32_e32 v18, v23, v18
	v_mul_f32_e32 v23, 0x3d372713, v19
	v_mul_f32_e32 v23, v19, v23
	v_fma_f32 v23, v19, v23, v19
	v_mul_f32_e32 v23, 0x3f4c422a, v23
	v_add_f32_e32 v23, v23, v23
	v_mul_f32_e32 v23, 0xbfb8aa3b, v23
	v_exp_f32_e32 v23, v23
	v_cvt_pk_bf16_f32 v17, v17, v18
	v_cvt_pk_bf16_f32 v18, v24, v21
	s_nop 0
	v_add_f32_e32 v23, 1.0, v23
	v_rcp_f32_e32 v23, v23
	s_nop 0
	v_mul_f32_e32 v19, v19, v23
	v_cvt_pk_bf16_f32 v19, v22, v19
	global_store_dwordx4 v[80:81], v[16:19], off offset:256 sc1
	s_nop 1
	v_mul_f32_e32 v16, 0x3d372713, v12
	v_mul_f32_e32 v16, v12, v16
	v_fma_f32 v16, v12, v16, v12
	v_mul_f32_e32 v16, 0x3f4c422a, v16
	v_add_f32_e32 v16, v16, v16
	v_mul_f32_e32 v16, 0xbfb8aa3b, v16
	v_exp_f32_e32 v16, v16
	s_nop 0
	v_add_f32_e32 v16, 1.0, v16
	v_rcp_f32_e32 v16, v16
	s_nop 0
	v_mul_f32_e32 v12, v12, v16
; __device__ __forceinline__ unsigned cvt_pk_bf16(float lo, float hi) { unsigned r; asm("v_cvt_pk_bf16_f32 %0, %1, %2" : "=v"(r) : "v"(lo), "v"(hi)); return r; }
; __device__ __forceinline__ float gelu_tanh(float v) { const float u = 0.7978845608028654f * (v + 0.044715f * v * v * v); return v * fast_sigmoid(2.0f * u); }
; __device__ __forceinline__ f32x4 ln_fix(const f32x4& a, float mu, float rs, const f32x4& cs, const f32x4& cb) { return (a - cs * mu) * rs + cb; }
; #define PG8_BAR __builtin_amdgcn_s_barrier()
;     __device__ __forceinline__ void operator()(const f32x4 (&acc)[2][2][4][2], const Unit& u, int wr, int wc, int fr_in, int fq_in) const {
;     ...
;                 for (int m = 0; m < 4; ++m) { bf16_t* rowp = base + (size_t)(row0 + ai * HALF + m * 16) * 1024 + col0 + bj * HALF;
;                     f32x4 v0 = ln_fix(acc[ai][bj][m][0], rst.mu[ai][m], rst.rs[ai][m], csv[0], cbv[0]), v1 = ln_fix(acc[ai][bj][m][1], rst.mu[ai][m], rst.rs[ai][m], csv[1], cbv[1]);
; #pragma unroll
;                     for (int j = 0; j < 4; ++j) { v0[j] = gelu_tanh(v0[j]); v1[j] = gelu_tanh(v1[j]); }
;                     u32x4 w; w.x = cvt_pk_bf16(v0[0], v0[1]); w.y = cvt_pk_bf16(v0[2], v0[3]); w.z = cvt_pk_bf16(v1[0], v1[1]); w.w = cvt_pk_bf16(v1[2], v1[3]);
;                     *(u32x4*)rowp = w; } }
; template <class Epi, class Sched, bool ALIGN_EPI = false, bool SP2 = false>
; __device__ __forceinline__ void gemm_phase(PG8_LAS unsigned char* lds, const Gemm g, const Sched& S, const Epi& E) {
;     ...
;         if constexpr (ALIGN_EPI) { if (wr == 1) PG8_BAR; }
;     }
	v_mul_f32_e32 v16, 0x3d372713, v8
	v_mul_f32_e32 v16, v8, v16
	v_fma_f32 v16, v8, v16, v8
	v_mul_f32_e32 v16, 0x3f4c422a, v16
	v_add_f32_e32 v16, v16, v16
	v_mul_f32_e32 v16, 0xbfb8aa3b, v16
	v_exp_f32_e32 v16, v16
	s_nop 0
	v_add_f32_e32 v16, 1.0, v16
	v_rcp_f32_e32 v16, v16
	s_nop 0
	v_mul_f32_e32 v16, v8, v16
	v_mul_f32_e32 v8, 0x3d372713, v13
	v_mul_f32_e32 v8, v13, v8
	v_fma_f32 v8, v13, v8, v13
	v_mul_f32_e32 v8, 0x3f4c422a, v8
	v_add_f32_e32 v8, v8, v8
	v_mul_f32_e32 v8, 0xbfb8aa3b, v8
	v_exp_f32_e32 v8, v8
	s_nop 0
	v_add_f32_e32 v8, 1.0, v8
	v_rcp_f32_e32 v8, v8
	s_nop 0
	v_mul_f32_e32 v8, v13, v8
	v_mul_f32_e32 v13, 0x3d372713, v9
	v_mul_f32_e32 v13, v9, v13
	v_fma_f32 v13, v9, v13, v9
	v_mul_f32_e32 v13, 0x3f4c422a, v13
	v_add_f32_e32 v13, v13, v13
	v_mul_f32_e32 v13, 0xbfb8aa3b, v13
	v_exp_f32_e32 v13, v13
	v_cvt_pk_bf16_f32 v8, v12, v8
	s_nop 0
	v_add_f32_e32 v13, 1.0, v13
	v_rcp_f32_e32 v13, v13
	s_nop 0
	v_mul_f32_e32 v13, v9, v13
	v_mul_f32_e32 v9, 0x3d372713, v14
	v_mul_f32_e32 v9, v14, v9
	v_fma_f32 v9, v14, v9, v14
	v_mul_f32_e32 v9, 0x3f4c422a, v9
	v_add_f32_e32 v9, v9, v9
	v_mul_f32_e32 v9, 0xbfb8aa3b, v9
	v_exp_f32_e32 v9, v9
	s_nop 0
	v_add_f32_e32 v9, 1.0, v9
	v_rcp_f32_e32 v9, v9
	s_nop 0
	v_mul_f32_e32 v9, v14, v9
	v_mul_f32_e32 v14, 0x3d372713, v10
	v_mul_f32_e32 v14, v10, v14
	v_fma_f32 v14, v10, v14, v10
	v_mul_f32_e32 v14, 0x3f4c422a, v14
	v_add_f32_e32 v14, v14, v14
	v_mul_f32_e32 v14, 0xbfb8aa3b, v14
	v_exp_f32_e32 v14, v14
	s_nop 0
	v_add_f32_e32 v14, 1.0, v14
	v_rcp_f32_e32 v14, v14
	s_nop 0
	v_mul_f32_e32 v14, v10, v14
	v_mul_f32_e32 v10, 0x3d372713, v15
	v_mul_f32_e32 v10, v15, v10
	v_fma_f32 v10, v15, v10, v15
	v_mul_f32_e32 v10, 0x3f4c422a, v10
	v_add_f32_e32 v10, v10, v10
	v_mul_f32_e32 v10, 0xbfb8aa3b, v10
	v_exp_f32_e32 v10, v10
	s_nop 0
	v_add_f32_e32 v10, 1.0, v10
	v_rcp_f32_e32 v10, v10
	s_nop 0
	v_mul_f32_e32 v10, v15, v10
	v_mul_f32_e32 v15, 0x3d372713, v11
	v_mul_f32_e32 v15, v11, v15
	v_fma_f32 v15, v11, v15, v11
	v_mul_f32_e32 v15, 0x3f4c422a, v15
	v_add_f32_e32 v15, v15, v15
	v_mul_f32_e32 v15, 0xbfb8aa3b, v15
	v_exp_f32_e32 v15, v15
	v_cvt_pk_bf16_f32 v9, v9, v10
	v_cvt_pk_bf16_f32 v10, v16, v13
	s_nop 0
	v_add_f32_e32 v15, 1.0, v15
	v_rcp_f32_e32 v15, v15
	s_nop 0
	v_mul_f32_e32 v11, v11, v15
	v_cvt_pk_bf16_f32 v11, v14, v11
	global_store_dwordx4 v[72:73], v[8:11], off offset:256 sc1
	s_nop 1
	v_mul_f32_e32 v8, 0x3d372713, v4
	v_mul_f32_e32 v8, v4, v8
	v_fma_f32 v8, v4, v8, v4
	v_mul_f32_e32 v8, 0x3f4c422a, v8
	v_add_f32_e32 v8, v8, v8
	v_mul_f32_e32 v8, 0xbfb8aa3b, v8
	v_exp_f32_e32 v8, v8
	s_nop 0
	v_add_f32_e32 v8, 1.0, v8
	v_rcp_f32_e32 v8, v8
	s_nop 0
	v_mul_f32_e32 v4, v4, v8
	v_mul_f32_e32 v8, 0x3d372713, v0
	v_mul_f32_e32 v8, v0, v8
	v_fma_f32 v8, v0, v8, v0
	v_mul_f32_e32 v8, 0x3f4c422a, v8
	v_add_f32_e32 v8, v8, v8
	v_mul_f32_e32 v8, 0xbfb8aa3b, v8
	v_exp_f32_e32 v8, v8
	s_nop 0
	v_add_f32_e32 v8, 1.0, v8
	v_rcp_f32_e32 v8, v8
	s_nop 0
	v_mul_f32_e32 v8, v0, v8
	v_mul_f32_e32 v0, 0x3d372713, v5
	v_mul_f32_e32 v0, v5, v0
	v_fma_f32 v0, v5, v0, v5
	v_mul_f32_e32 v0, 0x3f4c422a, v0
	v_add_f32_e32 v0, v0, v0
	v_mul_f32_e32 v0, 0xbfb8aa3b, v0
	v_exp_f32_e32 v0, v0
	s_nop 0
	v_add_f32_e32 v0, 1.0, v0
	v_rcp_f32_e32 v0, v0
	s_nop 0
	v_mul_f32_e32 v0, v5, v0
	v_mul_f32_e32 v5, 0x3d372713, v1
	v_mul_f32_e32 v5, v1, v5
	v_fma_f32 v5, v1, v5, v1
	v_mul_f32_e32 v5, 0x3f4c422a, v5
	v_add_f32_e32 v5, v5, v5
	v_mul_f32_e32 v5, 0xbfb8aa3b, v5
	v_exp_f32_e32 v5, v5
	v_cvt_pk_bf16_f32 v0, v4, v0
	s_nop 0
	v_add_f32_e32 v5, 1.0, v5
	v_rcp_f32_e32 v5, v5
	s_nop 0
	v_mul_f32_e32 v5, v1, v5
	v_mul_f32_e32 v1, 0x3d372713, v6
	v_mul_f32_e32 v1, v6, v1
	v_fma_f32 v1, v6, v1, v6
	v_mul_f32_e32 v1, 0x3f4c422a, v1
	v_add_f32_e32 v1, v1, v1
	v_mul_f32_e32 v1, 0xbfb8aa3b, v1
	v_exp_f32_e32 v1, v1
	s_nop 0
	v_add_f32_e32 v1, 1.0, v1
	v_rcp_f32_e32 v1, v1
	s_nop 0
	v_mul_f32_e32 v1, v6, v1
	v_mul_f32_e32 v6, 0x3d372713, v2
	v_mul_f32_e32 v6, v2, v6
	v_fma_f32 v6, v2, v6, v2
	v_mul_f32_e32 v6, 0x3f4c422a, v6
	v_add_f32_e32 v6, v6, v6
	v_mul_f32_e32 v6, 0xbfb8aa3b, v6
	v_exp_f32_e32 v6, v6
	s_nop 0
	v_add_f32_e32 v6, 1.0, v6
	v_rcp_f32_e32 v6, v6
	s_nop 0
	v_mul_f32_e32 v6, v2, v6
	v_mul_f32_e32 v2, 0x3d372713, v7
	v_mul_f32_e32 v2, v7, v2
	v_fma_f32 v2, v7, v2, v7
	v_mul_f32_e32 v2, 0x3f4c422a, v2
	v_add_f32_e32 v2, v2, v2
	v_mul_f32_e32 v2, 0xbfb8aa3b, v2
	v_exp_f32_e32 v2, v2
	s_nop 0
	v_add_f32_e32 v2, 1.0, v2
	v_rcp_f32_e32 v2, v2
	s_nop 0
	v_mul_f32_e32 v2, v7, v2
	v_mul_f32_e32 v7, 0x3d372713, v3
	v_mul_f32_e32 v7, v3, v7
	v_fma_f32 v7, v3, v7, v3
	v_mul_f32_e32 v7, 0x3f4c422a, v7
	v_add_f32_e32 v7, v7, v7
	v_mul_f32_e32 v7, 0xbfb8aa3b, v7
	v_exp_f32_e32 v7, v7
	v_cvt_pk_bf16_f32 v1, v1, v2
	v_cvt_pk_bf16_f32 v2, v8, v5
	s_nop 0
	v_add_f32_e32 v7, 1.0, v7
	v_rcp_f32_e32 v7, v7
	s_nop 0
	v_mul_f32_e32 v3, v3, v7
	v_cvt_pk_bf16_f32 v3, v6, v3
	global_store_dwordx4 v[74:75], v[0:3], off offset:256 sc1
	s_cbranch_vccnz .LBB0_1686
	s_andn2_b64 vcc, exec, s[22:23]
	s_cbranch_vccnz .LBB0_1685
	s_barrier
	s_branch .LBB0_1685

; __device__ __forceinline__ unsigned cvt_pk_bf16(float lo, float hi) { unsigned r; asm("v_cvt_pk_bf16_f32 %0, %1, %2" : "=v"(r) : "v"(lo), "v"(hi)); return r; }
; __device__ __forceinline__ float fast_sigmoid(float v) { return __builtin_amdgcn_rcpf(1.0f + __builtin_amdgcn_exp2f(-1.4426950408889634f * v)); }
; __device__ __forceinline__ void load_row_stats(const float* sp, int row0, RowStats& r) {
;     ...
;         for (int m = 0; m < 4; ++m) { const float* p = sp + (size_t)(row0 + ai * HALF + m * 16) * 8; const f32x4 a = *(const f32x4*)p, b = *(const f32x4*)(p + 4);
;             const float s1 = (a[0] + a[2]) + (b[0] + b[2]), s2 = (a[1] + a[3]) + (b[1] + b[3]); const float mu = s1 * (1.f / 1024.f); const float var = s2 * (1.f / 1024.f) - mu * mu;
;             r.mu[ai][m] = mu; r.rs[ai][m] = __builtin_amdgcn_rsqf(__builtin_fmaxf(var, 0.f) + 1e-5f); } }
;     __device__ __forceinline__ void operator()(const f32x4 (&acc)[2][2][4][2], const Unit& u, int wr, int wc, int fr_in, int fq_in) const {
;     ...
;         const int row0 = u.pm * BM + wr * 64 + fr, n0 = u.pn * BM + wc * 32 + 8 * fq; const int kt = u.pn * 2 + (wc >> 1), cin = (wc & 1) * 32 + 8 * fq;
;         RowStats rst; f32x4 csv[2][2], cbv[2][2];
;         if constexpr (LN) { load_row_stats(sp, row0, rst);
; #pragma unroll
;             for (int bj = 0; bj < 2; ++bj)
; #pragma unroll
;                 for (int n = 0; n < 2; ++n) { csv[bj][n] = *(const f32x4*)(cs + n0 + bj * HALF + 4 * n); cbv[bj][n] = *(const f32x4*)(cb + n0 + bj * HALF + 4 * n); } }
; #pragma unroll
;         for (int ai = 0; ai < 2; ++ai)
; #pragma unroll
;             for (int m = 0; m < 4; ++m) { bf16_t* rowp = H + ((size_t)kt * mrows + (row0 + ai * HALF + m * 16)) * 64 + cin;
;                 float h[8];
; #pragma unroll
;                 for (int n = 0; n < 2; ++n) { f32x4 g = acc[ai][0][m][n], uu = acc[ai][1][m][n];
;                     if constexpr (LN) { g = ln_fix(g, rst.mu[ai][m], rst.rs[ai][m], csv[0][n], cbv[0][n]); uu = ln_fix(uu, rst.mu[ai][m], rst.rs[ai][m], csv[1][n], cbv[1][n]); }
; #pragma unroll
;                     for (int j = 0; j < 4; ++j) h[4 * n + j] = g[j] * fast_sigmoid(g[j]) * uu[j]; }
;                 u32x4 w; w.x = cvt_pk_bf16(h[0], h[1]); w.y = cvt_pk_bf16(h[2], h[3]); w.z = cvt_pk_bf16(h[4], h[5]); w.w = cvt_pk_bf16(h[6], h[7]);
;                 *(u32x4*)rowp = w; }
.Lrs9_skip:
	s_waitcnt vmcnt(0) lgkmcnt(0)
	s_barrier
	v_and_b32_e32 v116, 0xff, v192
	v_lshlrev_b32_e32 v116, 3, v116
	v_add_u32_e32 v116, 0x22400, v116
	ds_read_b64 v[226:227], v116
	ds_read_b64 v[220:221], v116 offset:128
	ds_read_b64 v[214:215], v116 offset:256
	ds_read_b64 v[200:201], v116 offset:384
	ds_read_b64 v[194:195], v116 offset:1024
	ds_read_b64 v[186:187], v116 offset:1152
	ds_read_b64 v[180:181], v116 offset:1280
	ds_read_b64 v[176:177], v116 offset:1408
	s_cmp_lg_u32 s99, 0
	s_waitcnt lgkmcnt(0)
	v_add_u32_e32 v224, 16, v192
	v_ashrrev_i32_e32 v225, 31, v224
	v_add_u32_e32 v218, 32, v192
	v_ashrrev_i32_e32 v219, 31, v218
	v_add_u32_e32 v212, 48, v192
	v_ashrrev_i32_e32 v213, 31, v212
	v_add_u32_e32 v204, 0x80, v192
	v_ashrrev_i32_e32 v205, 31, v204
	v_add_u32_e32 v196, 0x90, v192
	v_ashrrev_i32_e32 v197, 31, v196
	v_add_u32_e32 v188, 0xa0, v192
	v_ashrrev_i32_e32 v189, 31, v188
	v_add_u32_e32 v182, 0xb0, v192
	v_ashrrev_i32_e32 v183, 31, v182
	v_lshlrev_b32_e32 v206, 3, v113
	s_lshl_b32 s35, s45, 8
	s_or_b32 s35, s35, s55
	v_add_u32_e32 v112, s35, v206
	s_lshl_b32 s35, s45, 1
	s_or_b32 s44, s35, s59
	s_ashr_i32 s45, s44, 31
	s_lshl_b64 s[44:45], s[44:45], 15
	v_lshl_add_u64 v[192:193], s[44:45], 0, v[192:193]
	v_lshlrev_b64 v[192:193], 7, v[192:193]
	v_add_u32_e32 v230, s60, v206
	v_lshl_add_u64 v[232:233], s[6:7], 0, v[192:193]
	v_mov_b32_e32 v192, v144
	v_mov_b32_e32 v193, v140
	v_mov_b32_e32 v140, v145
	v_ashrrev_i32_e32 v231, 31, v230
	v_fma_f32 v113, -v226, v226, v227
	v_max_f32_e32 v113, 0, v113
	v_add_f32_e32 v113, 0x3727c5ac, v113
	v_rsq_f32_e32 v228, v113
	v_fma_f32 v113, -v220, v220, v221
	v_max_f32_e32 v113, 0, v113
	v_add_f32_e32 v113, 0x3727c5ac, v113
	v_rsq_f32_e32 v222, v113
	v_fma_f32 v113, -v214, v214, v215
	v_max_f32_e32 v113, 0, v113
	v_add_f32_e32 v113, 0x3727c5ac, v113
	v_rsq_f32_e32 v216, v113
	v_fma_f32 v113, -v200, v200, v201
	v_max_f32_e32 v113, 0, v113
	v_add_f32_e32 v113, 0x3727c5ac, v113
	v_rsq_f32_e32 v202, v113
	v_fma_f32 v113, -v194, v194, v195
	v_max_f32_e32 v113, 0, v113
	v_add_f32_e32 v113, 0x3727c5ac, v113
	v_rsq_f32_e32 v198, v113
	v_fma_f32 v113, -v186, v186, v187
	v_max_f32_e32 v113, 0, v113
	v_add_f32_e32 v113, 0x3727c5ac, v113
	v_rsq_f32_e32 v190, v113
	v_fma_f32 v113, -v180, v180, v181
	v_max_f32_e32 v113, 0, v113
	v_add_f32_e32 v113, 0x3727c5ac, v113
	v_rsq_f32_e32 v184, v113
	s_nop 0
	v_fma_f32 v113, -v176, v176, v177
	v_max_f32_e32 v113, 0, v113
	v_add_f32_e32 v113, 0x3727c5ac, v113
	v_rsq_f32_e32 v178, v113
	v_ashrrev_i32_e32 v113, 31, v112
	v_lshlrev_b64 v[112:113], 2, v[112:113]
	v_lshl_add_u64 v[136:137], s[12:13], 0, v[112:113]
	v_lshl_add_u64 v[156:157], s[22:23], 0, v[112:113]
	global_load_dwordx4 v[112:115], v[136:137], off offset:16
	global_load_dwordx4 v[128:131], v[136:137], off
	global_load_dwordx4 v[116:119], v[156:157], off offset:16
	global_load_dwordx4 v[132:135], v[156:157], off
	global_load_dwordx4 v[148:151], v[136:137], off offset:528
	s_nop 0
	global_load_dwordx4 v[136:139], v[136:137], off offset:512
	s_nop 0
	global_load_dwordx4 v[152:155], v[156:157], off offset:528
	s_nop 0
	global_load_dwordx4 v[156:159], v[156:157], off offset:512
	s_waitcnt vmcnt(0)
	v_mov_b32_e32 v207, v128
	v_mov_b32_e32 v211, v131
	v_mov_b32_e32 v206, v136
	v_pk_fma_f32 v[208:209], v[226:227], v[206:207], v[192:193] op_sel_hi:[0,1,1] neg_lo:[1,0,0] neg_hi:[1,0,0]
	v_mov_b32_e32 v192, v156
	v_mov_b32_e32 v193, v132
	v_pk_fma_f32 v[208:209], v[228:229], v[208:209], v[192:193] op_sel_hi:[0,1,1]
	v_mul_f32_e32 v132, 0xbfb8aa3b, v209
	v_exp_f32_e32 v132, v132
	v_mov_b32_e32 v156, v138
	v_mov_b32_e32 v210, v139
	v_add_f32_e32 v132, 1.0, v132
	v_rcp_f32_e32 v132, v132
	s_nop 0
	v_mul_f32_e32 v132, v209, v132
	v_mul_f32_e32 v223, v208, v132
	v_mov_b32_e32 v208, v137
	v_mov_b32_e32 v209, v129
	v_pk_fma_f32 v[140:141], v[226:227], v[208:209], v[140:141] op_sel_hi:[0,1,1] neg_lo:[1,0,0] neg_hi:[1,0,0]
	v_mov_b32_e32 v132, v157
	v_pk_fma_f32 v[140:141], v[228:229], v[140:141], v[132:133] op_sel_hi:[0,1,1]
	v_mul_f32_e32 v144, 0xbfb8aa3b, v141
	v_exp_f32_e32 v144, v144
	v_mov_b32_e32 v157, v130
	v_add_f32_e32 v144, 1.0, v144
	v_rcp_f32_e32 v144, v144
	s_nop 0
	v_mul_f32_e32 v141, v141, v144
	v_mul_f32_e32 v229, v140, v141
	v_mov_b32_e32 v140, v146
	v_mov_b32_e32 v141, v142
	v_pk_fma_f32 v[144:145], v[226:227], v[156:157], v[140:141] op_sel_hi:[0,1,1] neg_lo:[1,0,0] neg_hi:[1,0,0]
	v_mov_b32_e32 v140, v158
	v_mov_b32_e32 v141, v134
	v_pk_fma_f32 v[144:145], v[228:229], v[144:145], v[140:141] op_sel_hi:[0,1,1]
	v_mul_f32_e32 v134, 0xbfb8aa3b, v145
	v_exp_f32_e32 v134, v134
	v_mov_b32_e32 v142, v147
	v_pk_fma_f32 v[142:143], v[226:227], v[210:211], v[142:143] op_sel_hi:[0,1,1] neg_lo:[1,0,0] neg_hi:[1,0,0]
	v_add_f32_e32 v134, 1.0, v134
	v_rcp_f32_e32 v134, v134
	s_nop 0
	v_mul_f32_e32 v134, v145, v134
	v_mul_f32_e32 v158, v144, v134
	v_mov_b32_e32 v134, v159
	v_pk_fma_f32 v[142:143], v[228:229], v[142:143], v[134:135] op_sel_hi:[0,1,1]
	v_mul_f32_e32 v144, 0xbfb8aa3b, v143
	v_exp_f32_e32 v144, v144
	v_mov_b32_e32 v145, v120
	v_mov_b32_e32 v120, v125
	v_mov_b32_e32 v125, v122
	v_add_f32_e32 v144, 1.0, v144
	v_rcp_f32_e32 v144, v144
	v_mov_b32_e32 v122, v127
	v_mul_f32_e32 v143, v143, v144
	v_mul_f32_e32 v159, v142, v143
	v_mov_b32_e32 v142, v148
	v_mov_b32_e32 v143, v112
	v_mov_b32_e32 v144, v124
	v_pk_fma_f32 v[146:147], v[226:227], v[142:143], v[144:145] op_sel_hi:[0,1,1] neg_lo:[1,0,0] neg_hi:[1,0,0]
	v_mov_b32_e32 v144, v152
	v_mov_b32_e32 v145, v116
	v_pk_fma_f32 v[146:147], v[228:229], v[146:147], v[144:145] op_sel_hi:[0,1,1]
	v_mul_f32_e32 v112, 0xbfb8aa3b, v147
	v_exp_f32_e32 v112, v112
; __device__ __forceinline__ unsigned cvt_pk_bf16(float lo, float hi) { unsigned r; asm("v_cvt_pk_bf16_f32 %0, %1, %2" : "=v"(r) : "v"(lo), "v"(hi)); return r; }
; __device__ __forceinline__ f32x4 ln_fix(const f32x4& a, float mu, float rs, const f32x4& cs, const f32x4& cb) { return (a - cs * mu) * rs + cb; }
; __device__ __forceinline__ float fast_sigmoid(float v) { return __builtin_amdgcn_rcpf(1.0f + __builtin_amdgcn_exp2f(-1.4426950408889634f * v)); }
;     __device__ __forceinline__ void operator()(const f32x4 (&acc)[2][2][4][2], const Unit& u, int wr, int wc, int fr_in, int fq_in) const {
;     ...
;             for (int m = 0; m < 4; ++m) { bf16_t* rowp = H + ((size_t)kt * mrows + (row0 + ai * HALF + m * 16)) * 64 + cin;
;                 float h[8];
; #pragma unroll
;                 for (int n = 0; n < 2; ++n) { f32x4 g = acc[ai][0][m][n], uu = acc[ai][1][m][n];
;                     if constexpr (LN) { g = ln_fix(g, rst.mu[ai][m], rst.rs[ai][m], csv[0][n], cbv[0][n]); uu = ln_fix(uu, rst.mu[ai][m], rst.rs[ai][m], csv[1][n], cbv[1][n]); }
; #pragma unroll
;                     for (int j = 0; j < 4; ++j) h[4 * n + j] = g[j] * fast_sigmoid(g[j]) * uu[j]; }
;                 u32x4 w; w.x = cvt_pk_bf16(h[0], h[1]); w.y = cvt_pk_bf16(h[2], h[3]); w.z = cvt_pk_bf16(h[4], h[5]); w.w = cvt_pk_bf16(h[6], h[7]);
;                 *(u32x4*)rowp = w; }
	v_mov_b32_e32 v116, v153
	v_add_f32_e32 v112, 1.0, v112
	v_rcp_f32_e32 v112, v112
	s_nop 0
	v_mul_f32_e32 v112, v147, v112
	v_mul_f32_e32 v148, v146, v112
	v_mov_b32_e32 v112, v149
	v_pk_fma_f32 v[120:121], v[226:227], v[112:113], v[120:121] op_sel_hi:[0,1,1] neg_lo:[1,0,0] neg_hi:[1,0,0]
	v_pk_fma_f32 v[120:121], v[228:229], v[120:121], v[116:117] op_sel_hi:[0,1,1]
	v_mul_f32_e32 v124, 0xbfb8aa3b, v121
	v_exp_f32_e32 v124, v124
	s_nop 0
	v_add_f32_e32 v124, 1.0, v124
	v_rcp_f32_e32 v124, v124
	s_nop 0
	v_mul_f32_e32 v121, v121, v124
	v_mul_f32_e32 v149, v120, v121
	v_mov_b32_e32 v120, v150
	v_mov_b32_e32 v121, v114
	v_mov_b32_e32 v124, v126
	v_pk_fma_f32 v[146:147], v[226:227], v[120:121], v[124:125] op_sel_hi:[0,1,1] neg_lo:[1,0,0] neg_hi:[1,0,0]
	v_mov_b32_e32 v124, v154
	v_mov_b32_e32 v125, v118
	v_pk_fma_f32 v[146:147], v[228:229], v[146:147], v[124:125] op_sel_hi:[0,1,1]
	v_mul_f32_e32 v114, 0xbfb8aa3b, v147
	v_exp_f32_e32 v114, v114
	v_mov_b32_e32 v118, v155
	v_cvt_pk_bf16_f32 v148, v148, v149
	v_add_f32_e32 v114, 1.0, v114
	v_rcp_f32_e32 v114, v114
	s_nop 0
	v_mul_f32_e32 v114, v147, v114
	v_mul_f32_e32 v150, v146, v114
	v_mov_b32_e32 v114, v151
	v_pk_fma_f32 v[122:123], v[226:227], v[114:115], v[122:123] op_sel_hi:[0,1,1] neg_lo:[1,0,0] neg_hi:[1,0,0]
	v_pk_fma_f32 v[122:123], v[228:229], v[122:123], v[118:119] op_sel_hi:[0,1,1]
	v_mul_f32_e32 v126, 0xbfb8aa3b, v123
	v_exp_f32_e32 v126, v126
	v_cvt_pk_bf16_f32 v146, v223, v229
	v_cvt_pk_bf16_f32 v147, v158, v159
	s_nop 0
	v_add_f32_e32 v126, 1.0, v126
	v_rcp_f32_e32 v126, v126
	s_nop 0
	v_mul_f32_e32 v123, v123, v126
	v_mul_f32_e32 v151, v122, v123
	v_lshlrev_b64 v[122:123], 1, v[230:231]
	v_lshl_add_u64 v[126:127], v[232:233], 0, v[122:123]
	v_cvt_pk_bf16_f32 v149, v150, v151
	global_store_dwordx4 v[126:127], v[146:149], off sc1
	v_lshl_add_u64 v[126:127], s[44:45], 0, v[224:225]
	v_lshlrev_b64 v[126:127], 7, v[126:127]
	v_mov_b32_e32 v146, v108
	v_mov_b32_e32 v147, v104
	v_pk_fma_f32 v[146:147], v[220:221], v[206:207], v[146:147] op_sel_hi:[0,1,1] neg_lo:[1,0,0] neg_hi:[1,0,0]
	v_pk_fma_f32 v[146:147], v[222:223], v[146:147], v[192:193] op_sel_hi:[0,1,1]
	v_mul_f32_e32 v104, 0xbfb8aa3b, v147
	v_exp_f32_e32 v104, v104
	v_lshl_add_u64 v[126:127], s[6:7], 0, v[126:127]
	v_add_f32_e32 v104, 1.0, v104
	v_rcp_f32_e32 v104, v104
	s_nop 0
	v_mul_f32_e32 v104, v147, v104
	v_mul_f32_e32 v108, v146, v104
	v_mov_b32_e32 v104, v109
	v_pk_fma_f32 v[104:105], v[220:221], v[208:209], v[104:105] op_sel_hi:[0,1,1] neg_lo:[1,0,0] neg_hi:[1,0,0]
	v_pk_fma_f32 v[104:105], v[222:223], v[104:105], v[132:133] op_sel_hi:[0,1,1]
	v_mul_f32_e32 v109, 0xbfb8aa3b, v105
	v_exp_f32_e32 v109, v109
	s_nop 0
	v_add_f32_e32 v109, 1.0, v109
	v_rcp_f32_e32 v109, v109
	s_nop 0
	v_mul_f32_e32 v105, v105, v109
	v_mul_f32_e32 v109, v104, v105
	v_mov_b32_e32 v104, v110
	v_mov_b32_e32 v105, v106
	v_pk_fma_f32 v[104:105], v[220:221], v[156:157], v[104:105] op_sel_hi:[0,1,1] neg_lo:[1,0,0] neg_hi:[1,0,0]
	v_pk_fma_f32 v[104:105], v[222:223], v[104:105], v[140:141] op_sel_hi:[0,1,1]
	v_mul_f32_e32 v106, 0xbfb8aa3b, v105
	v_exp_f32_e32 v106, v106
	s_nop 0
	v_add_f32_e32 v106, 1.0, v106
	v_rcp_f32_e32 v106, v106
	s_nop 0
	v_mul_f32_e32 v105, v105, v106
	v_mov_b32_e32 v106, v111
	v_mul_f32_e32 v110, v104, v105
	v_pk_fma_f32 v[104:105], v[220:221], v[210:211], v[106:107] op_sel_hi:[0,1,1] neg_lo:[1,0,0] neg_hi:[1,0,0]
	v_pk_fma_f32 v[104:105], v[222:223], v[104:105], v[134:135] op_sel_hi:[0,1,1]
	v_mul_f32_e32 v106, 0xbfb8aa3b, v105
	v_exp_f32_e32 v106, v106
	s_nop 0
	v_add_f32_e32 v106, 1.0, v106
	v_rcp_f32_e32 v106, v106
	s_nop 0
	v_mul_f32_e32 v105, v105, v106
	v_mul_f32_e32 v106, v104, v105
	v_mov_b32_e32 v104, v100
	v_mov_b32_e32 v105, v96
	v_pk_fma_f32 v[104:105], v[220:221], v[142:143], v[104:105] op_sel_hi:[0,1,1] neg_lo:[1,0,0] neg_hi:[1,0,0]
	v_pk_fma_f32 v[104:105], v[222:223], v[104:105], v[144:145] op_sel_hi:[0,1,1]
	v_mul_f32_e32 v96, 0xbfb8aa3b, v105
	v_exp_f32_e32 v96, v96
	s_nop 0
	v_add_f32_e32 v96, 1.0, v96
	v_rcp_f32_e32 v96, v96
	s_nop 0
	v_mul_f32_e32 v96, v105, v96
	v_mul_f32_e32 v104, v104, v96
	v_mov_b32_e32 v96, v101
	v_pk_fma_f32 v[96:97], v[220:221], v[112:113], v[96:97] op_sel_hi:[0,1,1] neg_lo:[1,0,0] neg_hi:[1,0,0]
	v_pk_fma_f32 v[96:97], v[222:223], v[96:97], v[116:117] op_sel_hi:[0,1,1]
	v_mul_f32_e32 v100, 0xbfb8aa3b, v97
	v_exp_f32_e32 v100, v100
	s_nop 0
	v_add_f32_e32 v100, 1.0, v100
	v_rcp_f32_e32 v100, v100
	s_nop 0
	v_mul_f32_e32 v97, v97, v100
	v_mul_f32_e32 v105, v96, v97
	v_mov_b32_e32 v96, v102
	v_mov_b32_e32 v97, v98
	v_pk_fma_f32 v[96:97], v[220:221], v[120:121], v[96:97] op_sel_hi:[0,1,1] neg_lo:[1,0,0] neg_hi:[1,0,0]
	v_pk_fma_f32 v[96:97], v[222:223], v[96:97], v[124:125] op_sel_hi:[0,1,1]
	v_mul_f32_e32 v98, 0xbfb8aa3b, v97
	v_exp_f32_e32 v98, v98
	v_lshl_add_u64 v[100:101], v[126:127], 0, v[122:123]
	v_add_f32_e32 v98, 1.0, v98
	v_rcp_f32_e32 v98, v98
	s_nop 0
	v_mul_f32_e32 v97, v97, v98
	v_mov_b32_e32 v98, v103
	v_mul_f32_e32 v102, v96, v97
	v_pk_fma_f32 v[96:97], v[220:221], v[114:115], v[98:99] op_sel_hi:[0,1,1] neg_lo:[1,0,0] neg_hi:[1,0,0]
	v_pk_fma_f32 v[96:97], v[222:223], v[96:97], v[118:119] op_sel_hi:[0,1,1]
	v_mul_f32_e32 v98, 0xbfb8aa3b, v97
	v_exp_f32_e32 v98, v98
	s_nop 0
	v_add_f32_e32 v98, 1.0, v98
	v_rcp_f32_e32 v98, v98
	s_nop 0
	v_mul_f32_e32 v97, v97, v98
	v_mul_f32_e32 v99, v96, v97
	v_cvt_pk_bf16_f32 v98, v104, v105
	v_cvt_pk_bf16_f32 v99, v102, v99
	v_cvt_pk_bf16_f32 v96, v108, v109
	v_cvt_pk_bf16_f32 v97, v110, v106
	global_store_dwordx4 v[100:101], v[96:99], off sc1
	s_nop 1
	v_mov_b32_e32 v98, v92
	v_mov_b32_e32 v99, v88
; __device__ __forceinline__ unsigned cvt_pk_bf16(float lo, float hi) { unsigned r; asm("v_cvt_pk_bf16_f32 %0, %1, %2" : "=v"(r) : "v"(lo), "v"(hi)); return r; }
; __device__ __forceinline__ f32x4 ln_fix(const f32x4& a, float mu, float rs, const f32x4& cs, const f32x4& cb) { return (a - cs * mu) * rs + cb; }
; __device__ __forceinline__ float fast_sigmoid(float v) { return __builtin_amdgcn_rcpf(1.0f + __builtin_amdgcn_exp2f(-1.4426950408889634f * v)); }
;     __device__ __forceinline__ void operator()(const f32x4 (&acc)[2][2][4][2], const Unit& u, int wr, int wc, int fr_in, int fq_in) const {
;     ...
;             for (int m = 0; m < 4; ++m) { bf16_t* rowp = H + ((size_t)kt * mrows + (row0 + ai * HALF + m * 16)) * 64 + cin;
;                 float h[8];
; #pragma unroll
;                 for (int n = 0; n < 2; ++n) { f32x4 g = acc[ai][0][m][n], uu = acc[ai][1][m][n];
;                     if constexpr (LN) { g = ln_fix(g, rst.mu[ai][m], rst.rs[ai][m], csv[0][n], cbv[0][n]); uu = ln_fix(uu, rst.mu[ai][m], rst.rs[ai][m], csv[1][n], cbv[1][n]); }
; #pragma unroll
;                     for (int j = 0; j < 4; ++j) h[4 * n + j] = g[j] * fast_sigmoid(g[j]) * uu[j]; }
;                 u32x4 w; w.x = cvt_pk_bf16(h[0], h[1]); w.y = cvt_pk_bf16(h[2], h[3]); w.z = cvt_pk_bf16(h[4], h[5]); w.w = cvt_pk_bf16(h[6], h[7]);
;                 *(u32x4*)rowp = w; }
	v_pk_fma_f32 v[98:99], v[214:215], v[206:207], v[98:99] op_sel_hi:[0,1,1] neg_lo:[1,0,0] neg_hi:[1,0,0]
	v_pk_fma_f32 v[98:99], v[216:217], v[98:99], v[192:193] op_sel_hi:[0,1,1]
	v_mul_f32_e32 v88, 0xbfb8aa3b, v99
	v_exp_f32_e32 v88, v88
	v_lshl_add_u64 v[96:97], s[44:45], 0, v[218:219]
	v_lshlrev_b64 v[96:97], 7, v[96:97]
	v_lshl_add_u64 v[96:97], s[6:7], 0, v[96:97]
	v_add_f32_e32 v88, 1.0, v88
	v_rcp_f32_e32 v88, v88
	s_nop 0
	v_mul_f32_e32 v88, v99, v88
	v_mul_f32_e32 v92, v98, v88
	v_mov_b32_e32 v88, v93
	v_pk_fma_f32 v[88:89], v[214:215], v[208:209], v[88:89] op_sel_hi:[0,1,1] neg_lo:[1,0,0] neg_hi:[1,0,0]
	v_pk_fma_f32 v[88:89], v[216:217], v[88:89], v[132:133] op_sel_hi:[0,1,1]
	v_mul_f32_e32 v93, 0xbfb8aa3b, v89
	v_exp_f32_e32 v93, v93
	s_nop 0
	v_add_f32_e32 v93, 1.0, v93
	v_rcp_f32_e32 v93, v93
	s_nop 0
	v_mul_f32_e32 v89, v89, v93
	v_mul_f32_e32 v93, v88, v89
	v_mov_b32_e32 v88, v94
	v_mov_b32_e32 v89, v90
	v_pk_fma_f32 v[88:89], v[214:215], v[156:157], v[88:89] op_sel_hi:[0,1,1] neg_lo:[1,0,0] neg_hi:[1,0,0]
	v_pk_fma_f32 v[88:89], v[216:217], v[88:89], v[140:141] op_sel_hi:[0,1,1]
	v_mul_f32_e32 v90, 0xbfb8aa3b, v89
	v_exp_f32_e32 v90, v90
	s_nop 0
	v_add_f32_e32 v90, 1.0, v90
	v_rcp_f32_e32 v90, v90
	s_nop 0
	v_mul_f32_e32 v89, v89, v90
	v_mov_b32_e32 v90, v95
	v_mul_f32_e32 v94, v88, v89
	v_pk_fma_f32 v[88:89], v[214:215], v[210:211], v[90:91] op_sel_hi:[0,1,1] neg_lo:[1,0,0] neg_hi:[1,0,0]
	v_pk_fma_f32 v[88:89], v[216:217], v[88:89], v[134:135] op_sel_hi:[0,1,1]
	v_mul_f32_e32 v90, 0xbfb8aa3b, v89
	v_exp_f32_e32 v90, v90
	s_nop 0
	v_add_f32_e32 v90, 1.0, v90
	v_rcp_f32_e32 v90, v90
	s_nop 0
	v_mul_f32_e32 v89, v89, v90
	v_mul_f32_e32 v90, v88, v89
	v_mov_b32_e32 v88, v84
	v_mov_b32_e32 v89, v80
	v_pk_fma_f32 v[88:89], v[214:215], v[142:143], v[88:89] op_sel_hi:[0,1,1] neg_lo:[1,0,0] neg_hi:[1,0,0]
	v_pk_fma_f32 v[88:89], v[216:217], v[88:89], v[144:145] op_sel_hi:[0,1,1]
	v_mul_f32_e32 v80, 0xbfb8aa3b, v89
	v_exp_f32_e32 v80, v80
	s_nop 0
	v_add_f32_e32 v80, 1.0, v80
	v_rcp_f32_e32 v80, v80
	s_nop 0
	v_mul_f32_e32 v80, v89, v80
	v_mul_f32_e32 v88, v88, v80
	v_mov_b32_e32 v80, v85
	v_pk_fma_f32 v[80:81], v[214:215], v[112:113], v[80:81] op_sel_hi:[0,1,1] neg_lo:[1,0,0] neg_hi:[1,0,0]
	v_pk_fma_f32 v[80:81], v[216:217], v[80:81], v[116:117] op_sel_hi:[0,1,1]
	v_mul_f32_e32 v84, 0xbfb8aa3b, v81
	v_exp_f32_e32 v84, v84
	s_nop 0
	v_add_f32_e32 v84, 1.0, v84
	v_rcp_f32_e32 v84, v84
	s_nop 0
	v_mul_f32_e32 v81, v81, v84
	v_mul_f32_e32 v89, v80, v81
	v_mov_b32_e32 v80, v86
	v_mov_b32_e32 v81, v82
	v_pk_fma_f32 v[80:81], v[214:215], v[120:121], v[80:81] op_sel_hi:[0,1,1] neg_lo:[1,0,0] neg_hi:[1,0,0]
	v_pk_fma_f32 v[80:81], v[216:217], v[80:81], v[124:125] op_sel_hi:[0,1,1]
	v_mul_f32_e32 v82, 0xbfb8aa3b, v81
	v_exp_f32_e32 v82, v82
	v_lshl_add_u64 v[84:85], v[96:97], 0, v[122:123]
	v_add_f32_e32 v82, 1.0, v82
	v_rcp_f32_e32 v82, v82
	s_nop 0
	v_mul_f32_e32 v81, v81, v82
	v_mov_b32_e32 v82, v87
	v_mul_f32_e32 v86, v80, v81
	v_pk_fma_f32 v[80:81], v[214:215], v[114:115], v[82:83] op_sel_hi:[0,1,1] neg_lo:[1,0,0] neg_hi:[1,0,0]
	v_pk_fma_f32 v[80:81], v[216:217], v[80:81], v[118:119] op_sel_hi:[0,1,1]
	v_mul_f32_e32 v82, 0xbfb8aa3b, v81
	v_exp_f32_e32 v82, v82
	s_nop 0
	v_add_f32_e32 v82, 1.0, v82
	v_rcp_f32_e32 v82, v82
	s_nop 0
	v_mul_f32_e32 v81, v81, v82
	v_mul_f32_e32 v83, v80, v81
	v_cvt_pk_bf16_f32 v82, v88, v89
	v_cvt_pk_bf16_f32 v83, v86, v83
	v_cvt_pk_bf16_f32 v80, v92, v93
	v_cvt_pk_bf16_f32 v81, v94, v90
	global_store_dwordx4 v[84:85], v[80:83], off sc1
	s_nop 1
	v_mov_b32_e32 v82, v76
	v_mov_b32_e32 v83, v72
	v_pk_fma_f32 v[82:83], v[200:201], v[206:207], v[82:83] op_sel_hi:[0,1,1] neg_lo:[1,0,0] neg_hi:[1,0,0]
	v_pk_fma_f32 v[82:83], v[202:203], v[82:83], v[192:193] op_sel_hi:[0,1,1]
	v_mul_f32_e32 v72, 0xbfb8aa3b, v83
	v_exp_f32_e32 v72, v72
	v_lshl_add_u64 v[80:81], s[44:45], 0, v[212:213]
	v_lshlrev_b64 v[80:81], 7, v[80:81]
	v_lshl_add_u64 v[80:81], s[6:7], 0, v[80:81]
	v_add_f32_e32 v72, 1.0, v72
	v_rcp_f32_e32 v72, v72
	s_nop 0
	v_mul_f32_e32 v72, v83, v72
	v_mul_f32_e32 v76, v82, v72
	v_mov_b32_e32 v72, v77
	v_pk_fma_f32 v[72:73], v[200:201], v[208:209], v[72:73] op_sel_hi:[0,1,1] neg_lo:[1,0,0] neg_hi:[1,0,0]
	v_pk_fma_f32 v[72:73], v[202:203], v[72:73], v[132:133] op_sel_hi:[0,1,1]
	v_mul_f32_e32 v77, 0xbfb8aa3b, v73
	v_exp_f32_e32 v77, v77
	s_nop 0
	v_add_f32_e32 v77, 1.0, v77
	v_rcp_f32_e32 v77, v77
	s_nop 0
	v_mul_f32_e32 v73, v73, v77
	v_mul_f32_e32 v77, v72, v73
	v_mov_b32_e32 v72, v78
	v_mov_b32_e32 v73, v74
	v_pk_fma_f32 v[72:73], v[200:201], v[156:157], v[72:73] op_sel_hi:[0,1,1] neg_lo:[1,0,0] neg_hi:[1,0,0]
	v_pk_fma_f32 v[72:73], v[202:203], v[72:73], v[140:141] op_sel_hi:[0,1,1]
	v_mul_f32_e32 v74, 0xbfb8aa3b, v73
	v_exp_f32_e32 v74, v74
	s_nop 0
	v_add_f32_e32 v74, 1.0, v74
	v_rcp_f32_e32 v74, v74
	s_nop 0
	v_mul_f32_e32 v73, v73, v74
	v_mov_b32_e32 v74, v79
	v_mul_f32_e32 v78, v72, v73
	v_pk_fma_f32 v[72:73], v[200:201], v[210:211], v[74:75] op_sel_hi:[0,1,1] neg_lo:[1,0,0] neg_hi:[1,0,0]
	v_pk_fma_f32 v[72:73], v[202:203], v[72:73], v[134:135] op_sel_hi:[0,1,1]
	v_mul_f32_e32 v74, 0xbfb8aa3b, v73
	v_exp_f32_e32 v74, v74
	s_nop 0
	v_add_f32_e32 v74, 1.0, v74
	v_rcp_f32_e32 v74, v74
	s_nop 0
	v_mul_f32_e32 v73, v73, v74
	v_mul_f32_e32 v74, v72, v73
	v_mov_b32_e32 v72, v68
	v_mov_b32_e32 v73, v64
	v_pk_fma_f32 v[72:73], v[200:201], v[142:143], v[72:73] op_sel_hi:[0,1,1] neg_lo:[1,0,0] neg_hi:[1,0,0]
	v_pk_fma_f32 v[72:73], v[202:203], v[72:73], v[144:145] op_sel_hi:[0,1,1]
	v_mul_f32_e32 v64, 0xbfb8aa3b, v73
	v_exp_f32_e32 v64, v64
	s_nop 0
	v_add_f32_e32 v64, 1.0, v64
	v_rcp_f32_e32 v64, v64
; __device__ __forceinline__ unsigned cvt_pk_bf16(float lo, float hi) { unsigned r; asm("v_cvt_pk_bf16_f32 %0, %1, %2" : "=v"(r) : "v"(lo), "v"(hi)); return r; }
; __device__ __forceinline__ f32x4 ln_fix(const f32x4& a, float mu, float rs, const f32x4& cs, const f32x4& cb) { return (a - cs * mu) * rs + cb; }
; __device__ __forceinline__ float fast_sigmoid(float v) { return __builtin_amdgcn_rcpf(1.0f + __builtin_amdgcn_exp2f(-1.4426950408889634f * v)); }
;     __device__ __forceinline__ void operator()(const f32x4 (&acc)[2][2][4][2], const Unit& u, int wr, int wc, int fr_in, int fq_in) const {
;     ...
;             for (int m = 0; m < 4; ++m) { bf16_t* rowp = H + ((size_t)kt * mrows + (row0 + ai * HALF + m * 16)) * 64 + cin;
;                 float h[8];
; #pragma unroll
;                 for (int n = 0; n < 2; ++n) { f32x4 g = acc[ai][0][m][n], uu = acc[ai][1][m][n];
;                     if constexpr (LN) { g = ln_fix(g, rst.mu[ai][m], rst.rs[ai][m], csv[0][n], cbv[0][n]); uu = ln_fix(uu, rst.mu[ai][m], rst.rs[ai][m], csv[1][n], cbv[1][n]); }
; #pragma unroll
;                     for (int j = 0; j < 4; ++j) h[4 * n + j] = g[j] * fast_sigmoid(g[j]) * uu[j]; }
;                 u32x4 w; w.x = cvt_pk_bf16(h[0], h[1]); w.y = cvt_pk_bf16(h[2], h[3]); w.z = cvt_pk_bf16(h[4], h[5]); w.w = cvt_pk_bf16(h[6], h[7]);
;                 *(u32x4*)rowp = w; }
	s_nop 0
	v_mul_f32_e32 v64, v73, v64
	v_mul_f32_e32 v72, v72, v64
	v_mov_b32_e32 v64, v69
	v_pk_fma_f32 v[64:65], v[200:201], v[112:113], v[64:65] op_sel_hi:[0,1,1] neg_lo:[1,0,0] neg_hi:[1,0,0]
	v_pk_fma_f32 v[64:65], v[202:203], v[64:65], v[116:117] op_sel_hi:[0,1,1]
	v_mul_f32_e32 v68, 0xbfb8aa3b, v65
	v_exp_f32_e32 v68, v68
	s_nop 0
	v_add_f32_e32 v68, 1.0, v68
	v_rcp_f32_e32 v68, v68
	s_nop 0
	v_mul_f32_e32 v65, v65, v68
	v_mul_f32_e32 v73, v64, v65
	v_mov_b32_e32 v64, v70
	v_mov_b32_e32 v65, v66
	v_pk_fma_f32 v[64:65], v[200:201], v[120:121], v[64:65] op_sel_hi:[0,1,1] neg_lo:[1,0,0] neg_hi:[1,0,0]
	v_pk_fma_f32 v[64:65], v[202:203], v[64:65], v[124:125] op_sel_hi:[0,1,1]
	v_mul_f32_e32 v66, 0xbfb8aa3b, v65
	v_exp_f32_e32 v66, v66
	v_lshl_add_u64 v[68:69], v[80:81], 0, v[122:123]
	v_add_f32_e32 v66, 1.0, v66
	v_rcp_f32_e32 v66, v66
	s_nop 0
	v_mul_f32_e32 v65, v65, v66
	v_mov_b32_e32 v66, v71
	v_mul_f32_e32 v70, v64, v65
	v_pk_fma_f32 v[64:65], v[200:201], v[114:115], v[66:67] op_sel_hi:[0,1,1] neg_lo:[1,0,0] neg_hi:[1,0,0]
	v_pk_fma_f32 v[64:65], v[202:203], v[64:65], v[118:119] op_sel_hi:[0,1,1]
	v_mul_f32_e32 v66, 0xbfb8aa3b, v65
	v_exp_f32_e32 v66, v66
	s_nop 0
	v_add_f32_e32 v66, 1.0, v66
	v_rcp_f32_e32 v66, v66
	s_nop 0
	v_mul_f32_e32 v65, v65, v66
	v_mul_f32_e32 v67, v64, v65
	v_cvt_pk_bf16_f32 v66, v72, v73
	v_cvt_pk_bf16_f32 v67, v70, v67
	v_cvt_pk_bf16_f32 v64, v76, v77
	v_cvt_pk_bf16_f32 v65, v78, v74
	global_store_dwordx4 v[68:69], v[64:67], off sc1
	s_nop 1
	v_mov_b32_e32 v66, v60
	v_mov_b32_e32 v67, v56
	v_pk_fma_f32 v[66:67], v[194:195], v[206:207], v[66:67] op_sel_hi:[0,1,1] neg_lo:[1,0,0] neg_hi:[1,0,0]
	v_pk_fma_f32 v[66:67], v[198:199], v[66:67], v[192:193] op_sel_hi:[0,1,1]
	v_mul_f32_e32 v56, 0xbfb8aa3b, v67
	v_exp_f32_e32 v56, v56
	v_lshl_add_u64 v[64:65], s[44:45], 0, v[204:205]
	v_lshlrev_b64 v[64:65], 7, v[64:65]
	v_lshl_add_u64 v[64:65], s[6:7], 0, v[64:65]
	v_add_f32_e32 v56, 1.0, v56
	v_rcp_f32_e32 v56, v56
	s_nop 0
	v_mul_f32_e32 v56, v67, v56
	v_mul_f32_e32 v60, v66, v56
	v_mov_b32_e32 v56, v61
	v_pk_fma_f32 v[56:57], v[194:195], v[208:209], v[56:57] op_sel_hi:[0,1,1] neg_lo:[1,0,0] neg_hi:[1,0,0]
	v_pk_fma_f32 v[56:57], v[198:199], v[56:57], v[132:133] op_sel_hi:[0,1,1]
	v_mul_f32_e32 v61, 0xbfb8aa3b, v57
	v_exp_f32_e32 v61, v61
	s_nop 0
	v_add_f32_e32 v61, 1.0, v61
	v_rcp_f32_e32 v61, v61
	s_nop 0
	v_mul_f32_e32 v57, v57, v61
	v_mul_f32_e32 v61, v56, v57
	v_mov_b32_e32 v56, v62
	v_mov_b32_e32 v57, v58
	v_pk_fma_f32 v[56:57], v[194:195], v[156:157], v[56:57] op_sel_hi:[0,1,1] neg_lo:[1,0,0] neg_hi:[1,0,0]
	v_pk_fma_f32 v[56:57], v[198:199], v[56:57], v[140:141] op_sel_hi:[0,1,1]
	v_mul_f32_e32 v58, 0xbfb8aa3b, v57
	v_exp_f32_e32 v58, v58
	s_nop 0
	v_add_f32_e32 v58, 1.0, v58
	v_rcp_f32_e32 v58, v58
	s_nop 0
	v_mul_f32_e32 v57, v57, v58
	v_mov_b32_e32 v58, v63
	v_mul_f32_e32 v62, v56, v57
	v_pk_fma_f32 v[56:57], v[194:195], v[210:211], v[58:59] op_sel_hi:[0,1,1] neg_lo:[1,0,0] neg_hi:[1,0,0]
	v_pk_fma_f32 v[56:57], v[198:199], v[56:57], v[134:135] op_sel_hi:[0,1,1]
	v_mul_f32_e32 v58, 0xbfb8aa3b, v57
	v_exp_f32_e32 v58, v58
	s_nop 0
	v_add_f32_e32 v58, 1.0, v58
	v_rcp_f32_e32 v58, v58
	s_nop 0
	v_mul_f32_e32 v57, v57, v58
	v_mul_f32_e32 v58, v56, v57
	v_mov_b32_e32 v56, v52
	v_mov_b32_e32 v57, v48
	v_pk_fma_f32 v[56:57], v[194:195], v[142:143], v[56:57] op_sel_hi:[0,1,1] neg_lo:[1,0,0] neg_hi:[1,0,0]
	v_pk_fma_f32 v[56:57], v[198:199], v[56:57], v[144:145] op_sel_hi:[0,1,1]
	v_mul_f32_e32 v48, 0xbfb8aa3b, v57
	v_exp_f32_e32 v48, v48
	s_nop 0
	v_add_f32_e32 v48, 1.0, v48
	v_rcp_f32_e32 v48, v48
	s_nop 0
	v_mul_f32_e32 v48, v57, v48
	v_mul_f32_e32 v56, v56, v48
	v_mov_b32_e32 v48, v53
	v_pk_fma_f32 v[48:49], v[194:195], v[112:113], v[48:49] op_sel_hi:[0,1,1] neg_lo:[1,0,0] neg_hi:[1,0,0]
	v_pk_fma_f32 v[48:49], v[198:199], v[48:49], v[116:117] op_sel_hi:[0,1,1]
	v_mul_f32_e32 v52, 0xbfb8aa3b, v49
	v_exp_f32_e32 v52, v52
	s_nop 0
	v_add_f32_e32 v52, 1.0, v52
	v_rcp_f32_e32 v52, v52
	s_nop 0
	v_mul_f32_e32 v49, v49, v52
	v_mul_f32_e32 v57, v48, v49
	v_mov_b32_e32 v48, v54
	v_mov_b32_e32 v49, v50
	v_pk_fma_f32 v[48:49], v[194:195], v[120:121], v[48:49] op_sel_hi:[0,1,1] neg_lo:[1,0,0] neg_hi:[1,0,0]
	v_pk_fma_f32 v[48:49], v[198:199], v[48:49], v[124:125] op_sel_hi:[0,1,1]
	v_mul_f32_e32 v50, 0xbfb8aa3b, v49
	v_exp_f32_e32 v50, v50
	v_lshl_add_u64 v[52:53], v[64:65], 0, v[122:123]
	v_add_f32_e32 v50, 1.0, v50
	v_rcp_f32_e32 v50, v50
	s_nop 0
	v_mul_f32_e32 v49, v49, v50
	v_mov_b32_e32 v50, v55
	v_mul_f32_e32 v54, v48, v49
	v_pk_fma_f32 v[48:49], v[194:195], v[114:115], v[50:51] op_sel_hi:[0,1,1] neg_lo:[1,0,0] neg_hi:[1,0,0]
	v_pk_fma_f32 v[48:49], v[198:199], v[48:49], v[118:119] op_sel_hi:[0,1,1]
	v_mul_f32_e32 v50, 0xbfb8aa3b, v49
	v_exp_f32_e32 v50, v50
	s_nop 0
	v_add_f32_e32 v50, 1.0, v50
	v_rcp_f32_e32 v50, v50
	s_nop 0
	v_mul_f32_e32 v49, v49, v50
	v_mul_f32_e32 v51, v48, v49
	v_cvt_pk_bf16_f32 v50, v56, v57
	v_cvt_pk_bf16_f32 v51, v54, v51
	v_cvt_pk_bf16_f32 v48, v60, v61
	v_cvt_pk_bf16_f32 v49, v62, v58
	global_store_dwordx4 v[52:53], v[48:51], off sc1
	s_nop 1
	v_mov_b32_e32 v50, v44
	v_mov_b32_e32 v51, v40
	v_pk_fma_f32 v[50:51], v[186:187], v[206:207], v[50:51] op_sel_hi:[0,1,1] neg_lo:[1,0,0] neg_hi:[1,0,0]
	v_pk_fma_f32 v[50:51], v[190:191], v[50:51], v[192:193] op_sel_hi:[0,1,1]
	v_mul_f32_e32 v40, 0xbfb8aa3b, v51
	v_exp_f32_e32 v40, v40
	v_lshl_add_u64 v[48:49], s[44:45], 0, v[196:197]
	v_lshlrev_b64 v[48:49], 7, v[48:49]
	v_lshl_add_u64 v[48:49], s[6:7], 0, v[48:49]
	v_add_f32_e32 v40, 1.0, v40
	v_rcp_f32_e32 v40, v40
	s_nop 0
	v_mul_f32_e32 v40, v51, v40
	v_mul_f32_e32 v44, v50, v40
; __device__ __forceinline__ unsigned cvt_pk_bf16(float lo, float hi) { unsigned r; asm("v_cvt_pk_bf16_f32 %0, %1, %2" : "=v"(r) : "v"(lo), "v"(hi)); return r; }
; __device__ __forceinline__ f32x4 ln_fix(const f32x4& a, float mu, float rs, const f32x4& cs, const f32x4& cb) { return (a - cs * mu) * rs + cb; }
; __device__ __forceinline__ float fast_sigmoid(float v) { return __builtin_amdgcn_rcpf(1.0f + __builtin_amdgcn_exp2f(-1.4426950408889634f * v)); }
;     __device__ __forceinline__ void operator()(const f32x4 (&acc)[2][2][4][2], const Unit& u, int wr, int wc, int fr_in, int fq_in) const {
;     ...
;             for (int m = 0; m < 4; ++m) { bf16_t* rowp = H + ((size_t)kt * mrows + (row0 + ai * HALF + m * 16)) * 64 + cin;
;                 float h[8];
; #pragma unroll
;                 for (int n = 0; n < 2; ++n) { f32x4 g = acc[ai][0][m][n], uu = acc[ai][1][m][n];
;                     if constexpr (LN) { g = ln_fix(g, rst.mu[ai][m], rst.rs[ai][m], csv[0][n], cbv[0][n]); uu = ln_fix(uu, rst.mu[ai][m], rst.rs[ai][m], csv[1][n], cbv[1][n]); }
; #pragma unroll
;                     for (int j = 0; j < 4; ++j) h[4 * n + j] = g[j] * fast_sigmoid(g[j]) * uu[j]; }
;                 u32x4 w; w.x = cvt_pk_bf16(h[0], h[1]); w.y = cvt_pk_bf16(h[2], h[3]); w.z = cvt_pk_bf16(h[4], h[5]); w.w = cvt_pk_bf16(h[6], h[7]);
;                 *(u32x4*)rowp = w; }
	v_mov_b32_e32 v40, v45
	v_pk_fma_f32 v[40:41], v[186:187], v[208:209], v[40:41] op_sel_hi:[0,1,1] neg_lo:[1,0,0] neg_hi:[1,0,0]
	v_pk_fma_f32 v[40:41], v[190:191], v[40:41], v[132:133] op_sel_hi:[0,1,1]
	v_mul_f32_e32 v45, 0xbfb8aa3b, v41
	v_exp_f32_e32 v45, v45
	s_nop 0
	v_add_f32_e32 v45, 1.0, v45
	v_rcp_f32_e32 v45, v45
	s_nop 0
	v_mul_f32_e32 v41, v41, v45
	v_mul_f32_e32 v45, v40, v41
	v_mov_b32_e32 v40, v46
	v_mov_b32_e32 v41, v42
	v_pk_fma_f32 v[40:41], v[186:187], v[156:157], v[40:41] op_sel_hi:[0,1,1] neg_lo:[1,0,0] neg_hi:[1,0,0]
	v_pk_fma_f32 v[40:41], v[190:191], v[40:41], v[140:141] op_sel_hi:[0,1,1]
	v_mul_f32_e32 v42, 0xbfb8aa3b, v41
	v_exp_f32_e32 v42, v42
	s_nop 0
	v_add_f32_e32 v42, 1.0, v42
	v_rcp_f32_e32 v42, v42
	s_nop 0
	v_mul_f32_e32 v41, v41, v42
	v_mov_b32_e32 v42, v47
	v_mul_f32_e32 v46, v40, v41
	v_pk_fma_f32 v[40:41], v[186:187], v[210:211], v[42:43] op_sel_hi:[0,1,1] neg_lo:[1,0,0] neg_hi:[1,0,0]
	v_pk_fma_f32 v[40:41], v[190:191], v[40:41], v[134:135] op_sel_hi:[0,1,1]
	v_mul_f32_e32 v42, 0xbfb8aa3b, v41
	v_exp_f32_e32 v42, v42
	s_nop 0
	v_add_f32_e32 v42, 1.0, v42
	v_rcp_f32_e32 v42, v42
	s_nop 0
	v_mul_f32_e32 v41, v41, v42
	v_mul_f32_e32 v42, v40, v41
	v_mov_b32_e32 v40, v36
	v_mov_b32_e32 v41, v32
	v_pk_fma_f32 v[40:41], v[186:187], v[142:143], v[40:41] op_sel_hi:[0,1,1] neg_lo:[1,0,0] neg_hi:[1,0,0]
	v_pk_fma_f32 v[40:41], v[190:191], v[40:41], v[144:145] op_sel_hi:[0,1,1]
	v_mul_f32_e32 v32, 0xbfb8aa3b, v41
	v_exp_f32_e32 v32, v32
	s_nop 0
	v_add_f32_e32 v32, 1.0, v32
	v_rcp_f32_e32 v32, v32
	s_nop 0
	v_mul_f32_e32 v32, v41, v32
	v_mul_f32_e32 v40, v40, v32
	v_mov_b32_e32 v32, v37
	v_pk_fma_f32 v[32:33], v[186:187], v[112:113], v[32:33] op_sel_hi:[0,1,1] neg_lo:[1,0,0] neg_hi:[1,0,0]
	v_pk_fma_f32 v[32:33], v[190:191], v[32:33], v[116:117] op_sel_hi:[0,1,1]
	v_mul_f32_e32 v36, 0xbfb8aa3b, v33
	v_exp_f32_e32 v36, v36
	s_nop 0
	v_add_f32_e32 v36, 1.0, v36
	v_rcp_f32_e32 v36, v36
	s_nop 0
	v_mul_f32_e32 v33, v33, v36
	v_mul_f32_e32 v41, v32, v33
	v_mov_b32_e32 v32, v38
	v_mov_b32_e32 v33, v34
	v_pk_fma_f32 v[32:33], v[186:187], v[120:121], v[32:33] op_sel_hi:[0,1,1] neg_lo:[1,0,0] neg_hi:[1,0,0]
	v_pk_fma_f32 v[32:33], v[190:191], v[32:33], v[124:125] op_sel_hi:[0,1,1]
	v_mul_f32_e32 v34, 0xbfb8aa3b, v33
	v_exp_f32_e32 v34, v34
	v_lshl_add_u64 v[36:37], v[48:49], 0, v[122:123]
	v_add_f32_e32 v34, 1.0, v34
	v_rcp_f32_e32 v34, v34
	s_nop 0
	v_mul_f32_e32 v33, v33, v34
	v_mov_b32_e32 v34, v39
	v_mul_f32_e32 v38, v32, v33
	v_pk_fma_f32 v[32:33], v[186:187], v[114:115], v[34:35] op_sel_hi:[0,1,1] neg_lo:[1,0,0] neg_hi:[1,0,0]
	v_pk_fma_f32 v[32:33], v[190:191], v[32:33], v[118:119] op_sel_hi:[0,1,1]
	v_mul_f32_e32 v34, 0xbfb8aa3b, v33
	v_exp_f32_e32 v34, v34
	s_nop 0
	v_add_f32_e32 v34, 1.0, v34
	v_rcp_f32_e32 v34, v34
	s_nop 0
	v_mul_f32_e32 v33, v33, v34
	v_mul_f32_e32 v35, v32, v33
	v_cvt_pk_bf16_f32 v34, v40, v41
	v_cvt_pk_bf16_f32 v35, v38, v35
	v_cvt_pk_bf16_f32 v32, v44, v45
	v_cvt_pk_bf16_f32 v33, v46, v42
	global_store_dwordx4 v[36:37], v[32:35], off sc1
	s_nop 1
	v_mov_b32_e32 v34, v28
	v_mov_b32_e32 v35, v24
	v_pk_fma_f32 v[34:35], v[180:181], v[206:207], v[34:35] op_sel_hi:[0,1,1] neg_lo:[1,0,0] neg_hi:[1,0,0]
	v_pk_fma_f32 v[34:35], v[184:185], v[34:35], v[192:193] op_sel_hi:[0,1,1]
	v_mul_f32_e32 v24, 0xbfb8aa3b, v35
	v_exp_f32_e32 v24, v24
	v_lshl_add_u64 v[32:33], s[44:45], 0, v[188:189]
	v_lshlrev_b64 v[32:33], 7, v[32:33]
	v_lshl_add_u64 v[32:33], s[6:7], 0, v[32:33]
	v_add_f32_e32 v24, 1.0, v24
	v_rcp_f32_e32 v24, v24
	s_nop 0
	v_mul_f32_e32 v24, v35, v24
	v_mul_f32_e32 v28, v34, v24
	v_mov_b32_e32 v24, v29
	v_pk_fma_f32 v[24:25], v[180:181], v[208:209], v[24:25] op_sel_hi:[0,1,1] neg_lo:[1,0,0] neg_hi:[1,0,0]
	v_pk_fma_f32 v[24:25], v[184:185], v[24:25], v[132:133] op_sel_hi:[0,1,1]
	v_mul_f32_e32 v29, 0xbfb8aa3b, v25
	v_exp_f32_e32 v29, v29
	s_nop 0
	v_add_f32_e32 v29, 1.0, v29
	v_rcp_f32_e32 v29, v29
	s_nop 0
	v_mul_f32_e32 v25, v25, v29
	v_mul_f32_e32 v29, v24, v25
	v_mov_b32_e32 v24, v30
	v_mov_b32_e32 v25, v26
	v_pk_fma_f32 v[24:25], v[180:181], v[156:157], v[24:25] op_sel_hi:[0,1,1] neg_lo:[1,0,0] neg_hi:[1,0,0]
	v_pk_fma_f32 v[24:25], v[184:185], v[24:25], v[140:141] op_sel_hi:[0,1,1]
	v_mul_f32_e32 v26, 0xbfb8aa3b, v25
	v_exp_f32_e32 v26, v26
	s_nop 0
	v_add_f32_e32 v26, 1.0, v26
	v_rcp_f32_e32 v26, v26
	s_nop 0
	v_mul_f32_e32 v25, v25, v26
	v_mov_b32_e32 v26, v31
	v_mul_f32_e32 v30, v24, v25
	v_pk_fma_f32 v[24:25], v[180:181], v[210:211], v[26:27] op_sel_hi:[0,1,1] neg_lo:[1,0,0] neg_hi:[1,0,0]
	v_pk_fma_f32 v[24:25], v[184:185], v[24:25], v[134:135] op_sel_hi:[0,1,1]
	v_mul_f32_e32 v26, 0xbfb8aa3b, v25
	v_exp_f32_e32 v26, v26
	s_nop 0
	v_add_f32_e32 v26, 1.0, v26
	v_rcp_f32_e32 v26, v26
	s_nop 0
	v_mul_f32_e32 v25, v25, v26
	v_mul_f32_e32 v26, v24, v25
	v_mov_b32_e32 v24, v20
	v_mov_b32_e32 v25, v16
	v_pk_fma_f32 v[24:25], v[180:181], v[142:143], v[24:25] op_sel_hi:[0,1,1] neg_lo:[1,0,0] neg_hi:[1,0,0]
	v_pk_fma_f32 v[24:25], v[184:185], v[24:25], v[144:145] op_sel_hi:[0,1,1]
	v_mul_f32_e32 v16, 0xbfb8aa3b, v25
	v_exp_f32_e32 v16, v16
	s_nop 0
	v_add_f32_e32 v16, 1.0, v16
	v_rcp_f32_e32 v16, v16
	s_nop 0
	v_mul_f32_e32 v16, v25, v16
	v_mul_f32_e32 v24, v24, v16
	v_mov_b32_e32 v16, v21
; __device__ __forceinline__ unsigned cvt_pk_bf16(float lo, float hi) { unsigned r; asm("v_cvt_pk_bf16_f32 %0, %1, %2" : "=v"(r) : "v"(lo), "v"(hi)); return r; }
; __device__ __forceinline__ f32x4 ln_fix(const f32x4& a, float mu, float rs, const f32x4& cs, const f32x4& cb) { return (a - cs * mu) * rs + cb; }
; __device__ __forceinline__ float fast_sigmoid(float v) { return __builtin_amdgcn_rcpf(1.0f + __builtin_amdgcn_exp2f(-1.4426950408889634f * v)); }
;     __device__ __forceinline__ void operator()(const f32x4 (&acc)[2][2][4][2], const Unit& u, int wr, int wc, int fr_in, int fq_in) const {
;     ...
;             for (int m = 0; m < 4; ++m) { bf16_t* rowp = H + ((size_t)kt * mrows + (row0 + ai * HALF + m * 16)) * 64 + cin;
;                 float h[8];
; #pragma unroll
;                 for (int n = 0; n < 2; ++n) { f32x4 g = acc[ai][0][m][n], uu = acc[ai][1][m][n];
;                     if constexpr (LN) { g = ln_fix(g, rst.mu[ai][m], rst.rs[ai][m], csv[0][n], cbv[0][n]); uu = ln_fix(uu, rst.mu[ai][m], rst.rs[ai][m], csv[1][n], cbv[1][n]); }
; #pragma unroll
;                     for (int j = 0; j < 4; ++j) h[4 * n + j] = g[j] * fast_sigmoid(g[j]) * uu[j]; }
;                 u32x4 w; w.x = cvt_pk_bf16(h[0], h[1]); w.y = cvt_pk_bf16(h[2], h[3]); w.z = cvt_pk_bf16(h[4], h[5]); w.w = cvt_pk_bf16(h[6], h[7]);
;                 *(u32x4*)rowp = w; }
	v_pk_fma_f32 v[16:17], v[180:181], v[112:113], v[16:17] op_sel_hi:[0,1,1] neg_lo:[1,0,0] neg_hi:[1,0,0]
	v_pk_fma_f32 v[16:17], v[184:185], v[16:17], v[116:117] op_sel_hi:[0,1,1]
	v_mul_f32_e32 v20, 0xbfb8aa3b, v17
	v_exp_f32_e32 v20, v20
	s_nop 0
	v_add_f32_e32 v20, 1.0, v20
	v_rcp_f32_e32 v20, v20
	s_nop 0
	v_mul_f32_e32 v17, v17, v20
	v_mul_f32_e32 v25, v16, v17
	v_mov_b32_e32 v16, v22
	v_mov_b32_e32 v17, v18
	v_pk_fma_f32 v[16:17], v[180:181], v[120:121], v[16:17] op_sel_hi:[0,1,1] neg_lo:[1,0,0] neg_hi:[1,0,0]
	v_pk_fma_f32 v[16:17], v[184:185], v[16:17], v[124:125] op_sel_hi:[0,1,1]
	v_mul_f32_e32 v18, 0xbfb8aa3b, v17
	v_exp_f32_e32 v18, v18
	v_lshl_add_u64 v[20:21], v[32:33], 0, v[122:123]
	v_add_f32_e32 v18, 1.0, v18
	v_rcp_f32_e32 v18, v18
	s_nop 0
	v_mul_f32_e32 v17, v17, v18
	v_mov_b32_e32 v18, v23
	v_mul_f32_e32 v22, v16, v17
	v_pk_fma_f32 v[16:17], v[180:181], v[114:115], v[18:19] op_sel_hi:[0,1,1] neg_lo:[1,0,0] neg_hi:[1,0,0]
	v_pk_fma_f32 v[16:17], v[184:185], v[16:17], v[118:119] op_sel_hi:[0,1,1]
	v_mul_f32_e32 v18, 0xbfb8aa3b, v17
	v_exp_f32_e32 v18, v18
	v_mov_b32_e32 v23, v8
	v_add_f32_e32 v18, 1.0, v18
	v_rcp_f32_e32 v18, v18
	s_nop 0
	v_mul_f32_e32 v17, v17, v18
	v_mul_f32_e32 v19, v16, v17
	v_cvt_pk_bf16_f32 v18, v24, v25
	v_cvt_pk_bf16_f32 v19, v22, v19
	v_cvt_pk_bf16_f32 v16, v28, v29
	v_cvt_pk_bf16_f32 v17, v30, v26
	global_store_dwordx4 v[20:21], v[16:19], off sc1
	v_mov_b32_e32 v20, v136
	v_mov_b32_e32 v21, v176
	v_mov_b32_e32 v18, v176
	v_mov_b32_e32 v19, v128
	v_mov_b32_e32 v22, v12
	v_pk_fma_f32 v[18:19], v[18:19], v[20:21], v[22:23] neg_lo:[1,0,0] neg_hi:[1,0,0]
	v_mov_b32_e32 v128, v176
	v_pk_fma_f32 v[18:19], v[18:19], v[178:179], v[192:193] op_sel_hi:[1,0,1]
	v_lshl_add_u64 v[16:17], s[44:45], 0, v[182:183]
	v_mul_f32_e32 v8, 0xbfb8aa3b, v19
	v_exp_f32_e32 v8, v8
	v_lshlrev_b64 v[16:17], 7, v[16:17]
	v_lshl_add_u64 v[16:17], s[6:7], 0, v[16:17]
	s_mov_b64 s[44:45], -1
	v_add_f32_e32 v8, 1.0, v8
	v_rcp_f32_e32 v8, v8
	s_nop 0
	v_mul_f32_e32 v8, v19, v8
	v_mul_f32_e32 v20, v18, v8
	v_pk_mov_b32 v[18:19], v[136:137], v[176:177] op_sel:[1,0]
	v_mov_b32_e32 v8, v13
	v_pk_fma_f32 v[8:9], v[128:129], v[18:19], v[8:9] neg_lo:[1,0,0] neg_hi:[1,0,0]
	v_mov_b32_e32 v13, v176
	v_pk_fma_f32 v[8:9], v[8:9], v[178:179], v[132:133] op_sel_hi:[1,0,1]
	v_mov_b32_e32 v18, v14
	v_mul_f32_e32 v12, 0xbfb8aa3b, v9
	v_exp_f32_e32 v12, v12
	v_mov_b32_e32 v19, v10
	v_add_f32_e32 v12, 1.0, v12
	v_rcp_f32_e32 v12, v12
	s_nop 0
	v_mul_f32_e32 v9, v9, v12
	v_mul_f32_e32 v21, v8, v9
	v_mov_b32_e32 v8, v176
	v_mov_b32_e32 v9, v130
	v_mov_b32_e32 v12, v138
	v_pk_fma_f32 v[8:9], v[8:9], v[12:13], v[18:19] neg_lo:[1,0,0] neg_hi:[1,0,0]
	v_mov_b32_e32 v130, v176
	v_pk_fma_f32 v[8:9], v[8:9], v[178:179], v[140:141] op_sel_hi:[1,0,1]
	s_nop 0
	v_mul_f32_e32 v10, 0xbfb8aa3b, v9
	v_exp_f32_e32 v10, v10
	s_nop 0
	v_add_f32_e32 v10, 1.0, v10
	v_rcp_f32_e32 v10, v10
	s_nop 0
	v_mul_f32_e32 v9, v9, v10
	v_mul_f32_e32 v12, v8, v9
	v_pk_mov_b32 v[8:9], v[138:139], v[176:177] op_sel:[1,0]
	v_mov_b32_e32 v10, v15
	v_pk_fma_f32 v[8:9], v[130:131], v[8:9], v[10:11] neg_lo:[1,0,0] neg_hi:[1,0,0]
	s_nop 0
	v_pk_fma_f32 v[8:9], v[8:9], v[178:179], v[134:135] op_sel_hi:[1,0,1]
	s_nop 0
	v_mul_f32_e32 v10, 0xbfb8aa3b, v9
	v_exp_f32_e32 v10, v10
	s_nop 0
	v_add_f32_e32 v10, 1.0, v10
	v_rcp_f32_e32 v10, v10
	s_nop 0
	v_mul_f32_e32 v9, v9, v10
	v_mul_f32_e32 v10, v8, v9
	v_mov_b32_e32 v8, v0
	v_mov_b32_e32 v9, v4
	v_pk_fma_f32 v[8:9], v[176:177], v[142:143], v[8:9] op_sel_hi:[0,1,1] neg_lo:[1,0,0] neg_hi:[1,0,0]
	v_pk_fma_f32 v[8:9], v[178:179], v[8:9], v[144:145] op_sel_hi:[0,1,1]
	v_mul_f32_e32 v0, 0xbfb8aa3b, v9
	v_exp_f32_e32 v0, v0
	v_mov_b32_e32 v4, v1
	v_add_f32_e32 v0, 1.0, v0
	v_rcp_f32_e32 v0, v0
	s_nop 0
	v_mul_f32_e32 v0, v9, v0
	v_mul_f32_e32 v8, v8, v0
	v_pk_fma_f32 v[0:1], v[176:177], v[112:113], v[4:5] op_sel_hi:[0,1,1] neg_lo:[1,0,0] neg_hi:[1,0,0]
	v_pk_fma_f32 v[0:1], v[178:179], v[0:1], v[116:117] op_sel_hi:[0,1,1]
	v_mul_f32_e32 v4, 0xbfb8aa3b, v1
	v_exp_f32_e32 v4, v4
	s_nop 0
	v_add_f32_e32 v4, 1.0, v4
	v_rcp_f32_e32 v4, v4
	s_nop 0
	v_mul_f32_e32 v1, v1, v4
	v_mul_f32_e32 v9, v0, v1
	v_mov_b32_e32 v0, v2
	v_mov_b32_e32 v1, v6
	v_pk_fma_f32 v[0:1], v[176:177], v[120:121], v[0:1] op_sel_hi:[0,1,1] neg_lo:[1,0,0] neg_hi:[1,0,0]
	v_pk_fma_f32 v[0:1], v[178:179], v[0:1], v[124:125] op_sel_hi:[0,1,1]
	v_mul_f32_e32 v2, 0xbfb8aa3b, v1
	v_exp_f32_e32 v2, v2
	v_mov_b32_e32 v6, v3
	v_lshl_add_u64 v[4:5], v[16:17], 0, v[122:123]
	v_add_f32_e32 v2, 1.0, v2
	v_rcp_f32_e32 v2, v2
	s_nop 0
	v_mul_f32_e32 v1, v1, v2
	v_mul_f32_e32 v11, v0, v1
	v_pk_fma_f32 v[0:1], v[176:177], v[114:115], v[6:7] op_sel_hi:[0,1,1] neg_lo:[1,0,0] neg_hi:[1,0,0]
	v_pk_fma_f32 v[0:1], v[178:179], v[0:1], v[118:119] op_sel_hi:[0,1,1]
	v_mul_f32_e32 v2, 0xbfb8aa3b, v1
	v_exp_f32_e32 v2, v2
	s_nop 0
	v_add_f32_e32 v2, 1.0, v2
	v_rcp_f32_e32 v2, v2
	s_nop 0
	v_mul_f32_e32 v1, v1, v2
	v_mul_f32_e32 v3, v0, v1
	v_cvt_pk_bf16_f32 v0, v20, v21
	v_cvt_pk_bf16_f32 v1, v12, v10
	v_cvt_pk_bf16_f32 v2, v8, v9
	v_cvt_pk_bf16_f32 v3, v11, v3
	global_store_dwordx4 v[4:5], v[0:3], off sc1
	s_cbranch_vccnz .LBB0_1987
	s_andn2_b64 vcc, exec, s[4:5]
	s_cbranch_vccnz .LBB0_1986
	s_barrier
	s_branch .LBB0_1986

; __device__ __forceinline__ unsigned cvt_pk_bf16(float lo, float hi) { unsigned r; asm("v_cvt_pk_bf16_f32 %0, %1, %2" : "=v"(r) : "v"(lo), "v"(hi)); return r; }
;     __device__ __forceinline__ void operator()(const f32x4 (&acc)[2][2][4][2], const Unit& u, int wr, int wc, int fr_in, int fq_in) const {
;     ...
;             for (int m = 0; m < 4; ++m) { bf16_t* rowp = base + (size_t)(row0 + ai * HALF + m * 16) * ldc + col0;
; #pragma unroll
;                 for (int bj = 0; bj < 2; ++bj) { f32x4 v0 = acc[ai][bj][m][0] + bv[bj][0], v1 = acc[ai][bj][m][1] + bv[bj][1];
;                     if (ACT == 1) { f32x2 a = gelu_pk((f32x2){v0[0], v0[1]}), b = gelu_pk((f32x2){v0[2], v0[3]}), c = gelu_pk((f32x2){v1[0], v1[1]}), d = gelu_pk((f32x2){v1[2], v1[3]});
;                         v0 = (f32x4){a.x, a.y, b.x, b.y}; v1 = (f32x4){c.x, c.y, d.x, d.y}; }
;                     v0 = v0 * sc; v1 = v1 * sc; u32x4 w; w.x = cvt_pk_bf16(v0[0], v0[1]); w.y = cvt_pk_bf16(v0[2], v0[3]); w.z = cvt_pk_bf16(v1[0], v1[1]); w.w = cvt_pk_bf16(v1[2], v1[3]);
;                     *(u32x4*)(rowp + bj * HALF) = w; } }
.LBB0_2072:
	v_mov_b32_e32 v17, v153
	v_mov_b32_e32 v16, v152
	s_lshl_b32 s8, s8, 8
	s_lshl_b32 s9, s34, 8
	s_add_i32 s9, s9, s54
	s_or_b32 s8, s8, s55
	v_add_u32_e32 v16, s9, v16
	v_lshl_add_u32 v18, v17, 3, s8
	v_ashrrev_i32_e32 v19, 31, v18
	v_ashrrev_i32_e32 v17, 31, v16
	v_lshl_add_u64 v[18:19], v[18:19], 1, s[22:23]
	v_lshlrev_b64 v[16:17], 11, v[16:17]
	v_lshl_add_u64 v[24:25], v[18:19], 0, v[16:17]
	v_cvt_pk_bf16_f32 v17, v126, v127
	s_mov_b64 s[8:9], 0x8000
	v_cvt_pk_bf16_f32 v16, v124, v125
	v_cvt_pk_bf16_f32 v18, v120, v121
	v_cvt_pk_bf16_f32 v19, v122, v123
	global_store_dwordx4 v[24:25], v[16:19], off sc1
	v_lshl_add_u64 v[26:27], v[24:25], 0, s[8:9]
	s_mov_b32 s8, 0x8000
	v_cvt_pk_bf16_f32 v17, v144, v145
	v_cvt_pk_bf16_f32 v16, v146, v147
	v_cvt_pk_bf16_f32 v18, v150, v151
	v_cvt_pk_bf16_f32 v19, v148, v149
	global_store_dwordx4 v[24:25], v[16:19], off offset:256 sc1
	v_cvt_pk_bf16_f32 v4, v4, v5
	v_cvt_pk_bf16_f32 v5, v6, v7
	v_cvt_pk_bf16_f32 v6, v0, v1
	v_cvt_pk_bf16_f32 v7, v2, v3
	s_nop 1
	v_cvt_pk_bf16_f32 v17, v100, v101
	v_add_co_u32_e32 v100, vcc, s8, v24
	v_cvt_pk_bf16_f32 v16, v102, v103
	v_cvt_pk_bf16_f32 v18, v110, v111
	v_cvt_pk_bf16_f32 v19, v108, v109
	s_mov_b64 s[8:9], 0x10000
	s_nop 0
	v_addc_co_u32_e32 v101, vcc, 0, v25, vcc
	global_store_dwordx4 v[100:101], v[16:19], off sc1
	s_nop 1
	v_cvt_pk_bf16_f32 v16, v114, v115
	v_cvt_pk_bf16_f32 v17, v112, v113
	v_cvt_pk_bf16_f32 v18, v118, v119
	v_cvt_pk_bf16_f32 v19, v116, v117
	global_store_dwordx4 v[26:27], v[16:19], off offset:256 sc1
	v_lshl_add_u64 v[26:27], v[24:25], 0, s[8:9]
	s_mov_b32 s8, 0x10000
	v_cvt_pk_bf16_f32 v17, v84, v85
	v_add_co_u32_e32 v84, vcc, s8, v24
	v_cvt_pk_bf16_f32 v16, v86, v87
	v_cvt_pk_bf16_f32 v18, v94, v95
	v_cvt_pk_bf16_f32 v19, v92, v93
	s_mov_b64 s[8:9], 0x18000
	s_nop 0
	v_addc_co_u32_e32 v85, vcc, 0, v25, vcc
	global_store_dwordx4 v[84:85], v[16:19], off sc1
	s_nop 1
	v_cvt_pk_bf16_f32 v16, v98, v99
	v_cvt_pk_bf16_f32 v17, v96, v97
	v_cvt_pk_bf16_f32 v18, v106, v107
	v_cvt_pk_bf16_f32 v19, v104, v105
	global_store_dwordx4 v[26:27], v[16:19], off offset:256 sc1
	v_lshl_add_u64 v[26:27], v[24:25], 0, s[8:9]
	s_mov_b32 s8, 0x18000
	v_cvt_pk_bf16_f32 v17, v72, v73
	v_add_co_u32_e32 v72, vcc, s8, v24
	v_cvt_pk_bf16_f32 v16, v74, v75
	v_cvt_pk_bf16_f32 v18, v78, v79
	v_cvt_pk_bf16_f32 v19, v76, v77
	s_mov_b64 s[8:9], 0x40000
	s_nop 0
	v_addc_co_u32_e32 v73, vcc, 0, v25, vcc
	global_store_dwordx4 v[72:73], v[16:19], off sc1
	s_nop 1
	v_cvt_pk_bf16_f32 v16, v68, v69
	v_cvt_pk_bf16_f32 v17, v70, v71
	v_cvt_pk_bf16_f32 v18, v64, v65
	v_cvt_pk_bf16_f32 v19, v66, v67
	global_store_dwordx4 v[26:27], v[16:19], off offset:256 sc1
	v_lshl_add_u64 v[26:27], v[24:25], 0, s[8:9]
	s_mov_b32 s8, 0x40000
	v_cvt_pk_bf16_f32 v18, v56, v57
	v_add_co_u32_e32 v56, vcc, s8, v24
	v_cvt_pk_bf16_f32 v16, v60, v61
	v_cvt_pk_bf16_f32 v17, v62, v63
	v_cvt_pk_bf16_f32 v19, v58, v59
	s_mov_b64 s[8:9], 0x48000
	s_nop 0
	v_addc_co_u32_e32 v57, vcc, 0, v25, vcc
	global_store_dwordx4 v[56:57], v[16:19], off sc1
	s_nop 1
	v_cvt_pk_bf16_f32 v16, v82, v83
	v_cvt_pk_bf16_f32 v17, v80, v81
	v_cvt_pk_bf16_f32 v18, v90, v91
	v_cvt_pk_bf16_f32 v19, v88, v89
	global_store_dwordx4 v[26:27], v[16:19], off offset:256 sc1
	v_lshl_add_u64 v[26:27], v[24:25], 0, s[8:9]
	s_mov_b32 s8, 0x48000
	v_cvt_pk_bf16_f32 v17, v36, v37
	v_add_co_u32_e32 v36, vcc, s8, v24
	v_cvt_pk_bf16_f32 v16, v38, v39
	v_cvt_pk_bf16_f32 v18, v46, v47
	v_cvt_pk_bf16_f32 v19, v44, v45
	s_mov_b64 s[8:9], 0x50000
	s_nop 0
	v_addc_co_u32_e32 v37, vcc, 0, v25, vcc
	global_store_dwordx4 v[36:37], v[16:19], off sc1
	s_nop 1
	v_cvt_pk_bf16_f32 v16, v50, v51
	v_cvt_pk_bf16_f32 v17, v48, v49
	v_cvt_pk_bf16_f32 v18, v54, v55
	v_cvt_pk_bf16_f32 v19, v52, v53
	global_store_dwordx4 v[26:27], v[16:19], off offset:256 sc1
	v_lshl_add_u64 v[26:27], v[24:25], 0, s[8:9]
	s_mov_b32 s8, 0x50000
	v_cvt_pk_bf16_f32 v17, v20, v21
	v_add_co_u32_e32 v20, vcc, s8, v24
	v_cvt_pk_bf16_f32 v16, v22, v23
	v_cvt_pk_bf16_f32 v18, v30, v31
	v_cvt_pk_bf16_f32 v19, v28, v29
	s_mov_b64 s[8:9], 0x58000
	s_nop 0
	v_addc_co_u32_e32 v21, vcc, 0, v25, vcc
	global_store_dwordx4 v[20:21], v[16:19], off sc1
	v_lshl_add_u64 v[20:21], v[24:25], 0, s[8:9]
	s_mov_b64 s[8:9], -1
	v_cvt_pk_bf16_f32 v17, v32, v33
	v_cvt_pk_bf16_f32 v16, v34, v35
	v_cvt_pk_bf16_f32 v18, v42, v43
	v_cvt_pk_bf16_f32 v19, v40, v41
	global_store_dwordx4 v[26:27], v[16:19], off offset:256 sc1
	global_store_dwordx4 v[20:21], v[4:7], off offset:256 sc1
	s_nop 0
	v_cvt_pk_bf16_f32 v17, v8, v9
	v_add_co_u32_e32 v8, vcc, 0x58000, v24
	v_cvt_pk_bf16_f32 v16, v10, v11
	v_cvt_pk_bf16_f32 v18, v14, v15
	v_cvt_pk_bf16_f32 v19, v12, v13
	s_nop 1
	v_addc_co_u32_e32 v9, vcc, 0, v25, vcc
	s_andn2_b64 vcc, exec, s[38:39]
	global_store_dwordx4 v[8:9], v[16:19], off sc1
	s_cbranch_vccnz .LBB0_2059
	s_andn2_b64 vcc, exec, s[12:13]
	s_cbranch_vccnz .LBB0_2058
	s_barrier
	s_branch .LBB0_2058
